# plus rsqrt denormal guard removed where the argument is ssq/N + 1e-6 (never below FLT_MIN): plain v_rsq_f32, same value
# speedup vs baseline: 1.0018x; 1.0018x over previous
; __device__ __forceinline__ unsigned pk2(float lo, float hi) { return pg8::cvt_pk_bf16(lo, hi); }
; __device__ __forceinline__ void p0_prologue(const Args& a, LAS unsigned char* lds, int gw, int NGW, int wave, int lane) {
;     ...
;     for (int m = gw; m < NB * NMEM; m += NGW) {
;         const f32x4* xr = (const f32x4*)(a.in[I_MEM] + (size_t)m * D) + lane; const f32x4* gr = (const f32x4*)(a.in[I_MEMNORM]) + lane; f32x4 v[4]; float s = 0.f;
; #pragma unroll
;         for (int j = 0; j < 4; ++j) { v[j] = xr[64 * j]; s += (v[j][0] * v[j][0] + v[j][1] * v[j][1]) + (v[j][2] * v[j][2] + v[j][3] * v[j][3]); }
;         s = wave_sum(s); const float rs = rsqrtf(s * (1.f / D) + EPS);
;         v2u* o = (v2u*)((bf16*)(ws + WS_MEMN) + (size_t)m * D) + lane;
; #pragma unroll
;         for (int j = 0; j < 4; ++j) { const f32x4 g = gr[64 * j]; v2u w; w.x = pk2(v[j][0] * rs * g[0], v[j][1] * rs * g[1]); w.y = pk2(v[j][2] * rs * g[2], v[j][3] * rs * g[3]); o[64 * j] = w; }
.LBB0_55:
	global_load_dwordx4 v[14:17], v[4:5], off offset:-3072
	global_load_dwordx4 v[18:21], v[4:5], off offset:-2048
	global_load_dwordx4 v[22:25], v[4:5], off offset:-1024
	global_load_dwordx4 v[26:29], v[4:5], off
	global_load_dwordx4 v[30:33], v[0:1], off
	s_add_i32 s9, s9, s58
	v_lshl_add_u64 v[4:5], v[4:5], 0, s[6:7]
	s_cmpk_gt_i32 s9, 0x3ff
	s_waitcnt vmcnt(4)
	v_pk_mul_f32 v[34:35], v[16:17], v[16:17]
	v_pk_mul_f32 v[36:37], v[14:15], v[14:15]
	s_waitcnt vmcnt(3)
	v_pk_mul_f32 v[38:39], v[20:21], v[20:21]
	v_pk_mul_f32 v[40:41], v[18:19], v[18:19]
	v_pk_mov_b32 v[46:47], v[36:37], v[34:35] op_sel:[1,0]
	v_mov_b32_e32 v37, v35
	v_pk_mov_b32 v[34:35], v[40:41], v[38:39] op_sel:[1,0]
	v_mov_b32_e32 v41, v39
	s_waitcnt vmcnt(1)
	v_mul_f32_e32 v45, v27, v27
	v_mul_f32_e32 v42, v23, v23
	v_mul_f32_e32 v44, v25, v25
	v_pk_add_f32 v[36:37], v[46:47], v[36:37]
	v_pk_add_f32 v[34:35], v[34:35], v[40:41]
	v_mul_f32_e32 v13, v26, v26
	v_mul_f32_e32 v48, v28, v28
	v_mul_f32_e32 v49, v29, v29
	v_pk_fma_f32 v[38:39], v[22:23], v[22:23], v[42:43] op_sel_hi:[1,1,0]
	v_pk_fma_f32 v[42:43], v[24:25], v[24:25], v[44:45] op_sel_hi:[1,1,0]
	v_pk_add_f32 v[36:37], v[36:37], v[36:37] op_sel:[0,1] op_sel_hi:[1,0]
	v_pk_add_f32 v[34:35], v[34:35], v[34:35] op_sel:[0,1] op_sel_hi:[1,0]
	v_mov_b32_e32 v39, v48
	v_mov_b32_e32 v43, v49
	v_mov_b32_e32 v37, v13
	v_mov_b32_e32 v35, v45
	v_pk_add_f32 v[38:39], v[38:39], v[42:43]
	v_pk_add_f32 v[34:35], v[36:37], v[34:35]
	s_nop 0
	v_pk_add_f32 v[34:35], v[34:35], v[38:39]
	s_nop 0
	v_add_f32_e32 v13, v34, v35
	ds_bpermute_b32 v34, v6, v13
	s_waitcnt lgkmcnt(0)
	v_add_f32_e32 v13, v13, v34
	ds_bpermute_b32 v34, v7, v13
	s_waitcnt lgkmcnt(0)
	v_add_f32_e32 v13, v13, v34
	ds_bpermute_b32 v34, v8, v13
	s_waitcnt lgkmcnt(0)
	v_add_f32_e32 v13, v13, v34
	ds_bpermute_b32 v34, v9, v13
	s_waitcnt lgkmcnt(0)
	v_add_f32_e32 v13, v13, v34
	ds_bpermute_b32 v34, v10, v13
	s_waitcnt lgkmcnt(0)
	v_add_f32_e32 v13, v13, v34
	ds_bpermute_b32 v34, v11, v13
	s_waitcnt lgkmcnt(0)
	v_add_f32_e32 v13, v13, v34
	v_fmamk_f32 v13, v13, 0x3a800000, v12
	v_rsq_f32_e32 v13, v13
	s_nop 0
	v_mov_b32_e32 v34, v13
	v_pk_mul_f32 v[14:15], v[14:15], v[34:35] op_sel_hi:[1,0]
	v_pk_mul_f32 v[16:17], v[16:17], v[34:35] op_sel_hi:[1,0]
	s_waitcnt vmcnt(0)
	v_pk_mul_f32 v[14:15], v[30:31], v[14:15]
	v_pk_mul_f32 v[16:17], v[32:33], v[16:17]
	v_cvt_pk_bf16_f32 v14, v14, v15
	v_cvt_pk_bf16_f32 v15, v16, v17
	global_store_dwordx2 v[2:3], v[14:15], off
	global_load_dwordx4 v[14:17], v[0:1], off offset:1024
	v_pk_mul_f32 v[18:19], v[18:19], v[34:35] op_sel_hi:[1,0]
	v_pk_mul_f32 v[20:21], v[20:21], v[34:35] op_sel_hi:[1,0]
	s_waitcnt vmcnt(0)
	v_pk_mul_f32 v[14:15], v[14:15], v[18:19]
	v_pk_mul_f32 v[16:17], v[16:17], v[20:21]
	v_cvt_pk_bf16_f32 v14, v14, v15
	v_cvt_pk_bf16_f32 v15, v16, v17
	global_store_dwordx2 v[2:3], v[14:15], off offset:512
	global_load_dwordx4 v[14:17], v[0:1], off offset:2048
	v_pk_mul_f32 v[18:19], v[22:23], v[34:35] op_sel_hi:[1,0]
	v_pk_mul_f32 v[20:21], v[24:25], v[34:35] op_sel_hi:[1,0]
	s_waitcnt vmcnt(0)
	v_pk_mul_f32 v[14:15], v[14:15], v[18:19]
	v_pk_mul_f32 v[16:17], v[16:17], v[20:21]
	v_cvt_pk_bf16_f32 v14, v14, v15
	v_cvt_pk_bf16_f32 v15, v16, v17
	global_store_dwordx2 v[2:3], v[14:15], off offset:1024
	global_load_dwordx4 v[14:17], v[0:1], off offset:3072
	v_pk_mul_f32 v[18:19], v[26:27], v[34:35] op_sel_hi:[1,0]
	v_pk_mul_f32 v[20:21], v[28:29], v[34:35] op_sel_hi:[1,0]
	s_waitcnt vmcnt(0)
	v_pk_mul_f32 v[14:15], v[14:15], v[18:19]
	v_pk_mul_f32 v[16:17], v[16:17], v[20:21]
	v_cvt_pk_bf16_f32 v14, v14, v15
	v_cvt_pk_bf16_f32 v15, v16, v17
	global_store_dwordx2 v[2:3], v[14:15], off offset:1536
	v_lshl_add_u64 v[2:3], v[2:3], 0, s[4:5]
	s_cbranch_scc0 .LBB0_55

; __device__ __forceinline__ unsigned cvt_pk_bf16(float lo, float hi) { cvf32x2_t v = {lo, hi}; cvbf16x2_t b = __builtin_convertvector(v, cvbf16x2_t); return __builtin_bit_cast(unsigned, b); }
; __device__ __forceinline__ float fsilu(float x) { return x * fsigm(x); }
; __device__ __forceinline__ float row_rs(const float* ssq, int row) { return ssq ? rsqrtf(ssq[row] * (1.f / 1024.f) + RMS_EPS) : 1.f; }
;     __device__ __forceinline__ void operator()(const f32x4 (&acc)[2][2][4][2], const Unit& u, int wr, int wc, int fr, int fq) const {
;     ...
;             for (int m = 0; m < 4; ++m) { const int row = row0 + ai * HALF + m * 16; const float rs = row_rs(ssq, row);
;                 u32x4 w; unsigned pk[4];
; #pragma unroll
;                 for (int n = 0; n < 2; ++n) { const f32x4 g = acc[ai][0][m][n] * rs, up = acc[ai][1][m][n] * rs;
;                     pk[2 * n] = cvt_pk_bf16(fsilu(g[0]) * up[0], fsilu(g[1]) * up[1]); pk[2 * n + 1] = cvt_pk_bf16(fsilu(g[2]) * up[2], fsilu(g[3]) * up[3]); }
;                 w.x = pk[0]; w.y = pk[1]; w.z = pk[2]; w.w = pk[3];
;                 st_wt16(H + (size_t)row * ldh + col0, w); }
.LBB0_146:
	v_cndmask_b32_e64 v144, 0, 1, s[12:13]
	v_mov_b32_e32 v150, 1.0
	v_cmp_ne_u32_e64 s[6:7], 1, v144
	s_andn2_b64 vcc, exec, s[12:13]
	v_mov_b32_e32 v152, 1.0
	s_cbranch_vccnz .LBB0_148
	s_waitcnt vmcnt(0)
	v_fmamk_f32 v144, v172, 0x3a800000, v166
	v_rsq_f32_e32 v144, v144
	s_nop 0
	v_mov_b32_e32 v152, v144
.LBB0_148:
	v_pk_mul_f32 v[124:125], v[124:125], v[152:153] op_sel_hi:[1,0]
	v_pk_mul_f32 v[126:127], v[126:127], v[152:153] op_sel_hi:[1,0]
	v_mul_f32_e32 v147, 0xbfb8aa3b, v124
	v_exp_f32_e32 v147, v147
	v_mul_f32_e32 v167, 0xbfb8aa3b, v125
	v_exp_f32_e32 v167, v167
	v_mul_f32_e32 v169, 0xbfb8aa3b, v127
	v_add_f32_e32 v147, 1.0, v147
	v_rcp_f32_e32 v168, v147
	v_add_f32_e32 v147, 1.0, v167
	v_mul_f32_e32 v167, 0xbfb8aa3b, v126
	v_exp_f32_e32 v167, v167
	v_exp_f32_e32 v171, v169
	v_rcp_f32_e32 v169, v147
	v_pk_mul_f32 v[120:121], v[120:121], v[152:153] op_sel_hi:[1,0]
	v_add_f32_e32 v147, 1.0, v167
	v_rcp_f32_e32 v170, v147
	v_add_f32_e32 v147, 1.0, v171
	v_rcp_f32_e32 v171, v147
	v_pk_mul_f32 v[124:125], v[124:125], v[168:169]
	v_pk_mul_f32 v[122:123], v[122:123], v[152:153] op_sel_hi:[1,0]
	v_pk_mul_f32 v[120:121], v[120:121], v[124:125]
	v_pk_mul_f32 v[124:125], v[126:127], v[170:171]
	v_pk_mul_f32 v[116:117], v[116:117], v[152:153] op_sel_hi:[1,0]
	v_pk_mul_f32 v[122:123], v[122:123], v[124:125]
	v_cvt_pk_bf16_f32 v120, v120, v121
	v_cvt_pk_bf16_f32 v121, v122, v123
	v_mul_f32_e32 v122, 0xbfb8aa3b, v116
	v_mul_f32_e32 v123, 0xbfb8aa3b, v117
	v_pk_mul_f32 v[118:119], v[118:119], v[152:153] op_sel_hi:[1,0]
	v_exp_f32_e32 v122, v122
	v_exp_f32_e32 v123, v123
	v_mul_f32_e32 v124, 0xbfb8aa3b, v118
	v_mul_f32_e32 v125, 0xbfb8aa3b, v119
	v_exp_f32_e32 v124, v124
	v_exp_f32_e32 v125, v125
	v_add_f32_e32 v122, 1.0, v122
	v_add_f32_e32 v123, 1.0, v123
	v_rcp_f32_e32 v122, v122
	v_rcp_f32_e32 v123, v123
	v_add_f32_e32 v124, 1.0, v124
	v_add_f32_e32 v125, 1.0, v125
	v_rcp_f32_e32 v124, v124
	v_rcp_f32_e32 v125, v125
	v_pk_mul_f32 v[112:113], v[112:113], v[152:153] op_sel_hi:[1,0]
	v_pk_mul_f32 v[116:117], v[116:117], v[122:123]
	v_pk_mul_f32 v[114:115], v[114:115], v[152:153] op_sel_hi:[1,0]
	v_pk_mul_f32 v[112:113], v[112:113], v[116:117]
	v_lshl_or_b32 v144, s36, 7, v162
	v_cvt_pk_bf16_f32 v122, v112, v113
	v_pk_mul_f32 v[112:113], v[118:119], v[124:125]
	v_ashrrev_i32_e32 v145, 31, v144
	v_pk_mul_f32 v[112:113], v[114:115], v[112:113]
	s_and_b64 vcc, exec, s[6:7]
	v_cvt_pk_bf16_f32 v123, v112, v113
	v_mov_b64_e32 v[112:113], s[56:57]
	v_mad_i64_i32 v[112:113], s[38:39], v146, s81, v[112:113]
	v_lshl_add_u64 v[112:113], v[144:145], 1, v[112:113]
	global_store_dwordx4 v[112:113], v[120:123], off
	s_cbranch_vccnz .LBB0_150
	v_fmamk_f32 v112, v173, 0x3a800000, v166
	v_rsq_f32_e32 v112, v112
	s_nop 0
	v_mov_b32_e32 v150, v112
.LBB0_150:
	v_pk_mul_f32 v[108:109], v[108:109], v[150:151] op_sel_hi:[1,0]
	v_pk_mul_f32 v[112:113], v[106:107], v[150:151] op_sel_hi:[1,0]
	v_pk_mul_f32 v[106:107], v[104:105], v[150:151] op_sel_hi:[1,0]
	v_mul_f32_e32 v104, 0xbfb8aa3b, v108
	v_exp_f32_e32 v105, v104
	v_mul_f32_e32 v104, 0xbfb8aa3b, v109
	v_exp_f32_e32 v115, v104
	v_pk_mul_f32 v[110:111], v[110:111], v[150:151] op_sel_hi:[1,0]
	v_add_f32_e32 v105, 1.0, v105
	v_rcp_f32_e32 v114, v105
	v_add_f32_e32 v105, 1.0, v115
	v_mul_f32_e32 v115, 0xbfb8aa3b, v110
	v_exp_f32_e32 v116, v115
	v_mul_f32_e32 v115, 0xbfb8aa3b, v111
	v_exp_f32_e32 v117, v115
	v_rcp_f32_e32 v115, v105
	v_add_f32_e32 v105, 1.0, v116
	v_rcp_f32_e32 v116, v105
	v_add_f32_e32 v105, 1.0, v117
	v_rcp_f32_e32 v117, v105
	v_pk_mul_f32 v[108:109], v[108:109], v[114:115]
	v_pk_mul_f32 v[100:101], v[100:101], v[150:151] op_sel_hi:[1,0]
	v_pk_mul_f32 v[106:107], v[106:107], v[108:109]
	v_pk_mul_f32 v[108:109], v[110:111], v[116:117]
	v_mul_f32_e32 v105, 0xbfb8aa3b, v100
	v_pk_mul_f32 v[108:109], v[112:113], v[108:109]
	v_cvt_pk_bf16_f32 v106, v106, v107
	v_cvt_pk_bf16_f32 v107, v108, v109
	v_exp_f32_e32 v105, v105
	v_mul_f32_e32 v108, 0xbfb8aa3b, v101
	v_exp_f32_e32 v109, v108
	v_pk_mul_f32 v[102:103], v[102:103], v[150:151] op_sel_hi:[1,0]
	v_add_f32_e32 v105, 1.0, v105
	v_rcp_f32_e32 v108, v105
	v_add_f32_e32 v105, 1.0, v109
	v_mul_f32_e32 v109, 0xbfb8aa3b, v102
	v_exp_f32_e32 v110, v109
	v_mul_f32_e32 v109, 0xbfb8aa3b, v103
	v_exp_f32_e32 v111, v109
	v_rcp_f32_e32 v109, v105
	v_add_f32_e32 v105, 1.0, v110
	v_rcp_f32_e32 v110, v105
	v_add_f32_e32 v105, 1.0, v111
	v_rcp_f32_e32 v111, v105
	v_pk_mul_f32 v[96:97], v[96:97], v[150:151] op_sel_hi:[1,0]
	v_pk_mul_f32 v[100:101], v[100:101], v[108:109]
	v_pk_mul_f32 v[98:99], v[98:99], v[150:151] op_sel_hi:[1,0]
	v_pk_mul_f32 v[96:97], v[96:97], v[100:101]
	v_or_b32_e32 v118, 16, v146
	v_cvt_pk_bf16_f32 v108, v96, v97
	v_pk_mul_f32 v[96:97], v[102:103], v[110:111]
	v_mov_b32_e32 v104, 1.0
	v_pk_mul_f32 v[96:97], v[98:99], v[96:97]
	s_and_b64 vcc, exec, s[6:7]
	v_cvt_pk_bf16_f32 v109, v96, v97
	v_mov_b64_e32 v[96:97], s[56:57]
	v_mad_i64_i32 v[96:97], s[38:39], v118, s81, v[96:97]
	v_lshl_add_u64 v[96:97], v[144:145], 1, v[96:97]
	global_store_dwordx4 v[96:97], v[106:109], off
	v_mov_b32_e32 v96, 1.0
	s_cbranch_vccnz .LBB0_152
	v_fmamk_f32 v96, v174, 0x3a800000, v166
	v_rsq_f32_e32 v96, v96
	s_nop 0
; __device__ __forceinline__ unsigned cvt_pk_bf16(float lo, float hi) { cvf32x2_t v = {lo, hi}; cvbf16x2_t b = __builtin_convertvector(v, cvbf16x2_t); return __builtin_bit_cast(unsigned, b); }
; __device__ __forceinline__ float fsigm(float x) { return __builtin_amdgcn_rcpf(1.f + __expf(-x)); }
; __device__ __forceinline__ float fsilu(float x) { return x * fsigm(x); }
; __device__ __forceinline__ float row_rs(const float* ssq, int row) { return ssq ? rsqrtf(ssq[row] * (1.f / 1024.f) + RMS_EPS) : 1.f; }
;     __device__ __forceinline__ void operator()(const f32x4 (&acc)[2][2][4][2], const Unit& u, int wr, int wc, int fr, int fq) const {
;     ...
;             for (int m = 0; m < 4; ++m) { const int row = row0 + ai * HALF + m * 16; const float rs = row_rs(ssq, row);
;                 u32x4 w; unsigned pk[4];
; #pragma unroll
;                 for (int n = 0; n < 2; ++n) { const f32x4 g = acc[ai][0][m][n] * rs, up = acc[ai][1][m][n] * rs;
;                     pk[2 * n] = cvt_pk_bf16(fsilu(g[0]) * up[0], fsilu(g[1]) * up[1]); pk[2 * n + 1] = cvt_pk_bf16(fsilu(g[2]) * up[2], fsilu(g[3]) * up[3]); }
;                 w.x = pk[0]; w.y = pk[1]; w.z = pk[2]; w.w = pk[3];
;                 st_wt16(H + (size_t)row * ldh + col0, w); }
.LBB0_152:
	v_or_b32_e32 v97, 32, v146
	v_pk_mul_f32 v[92:93], v[92:93], v[96:97] op_sel_hi:[1,0]
	v_pk_mul_f32 v[94:95], v[94:95], v[96:97] op_sel_hi:[1,0]
	v_mul_f32_e32 v98, 0xbfb8aa3b, v92
	v_mul_f32_e32 v99, 0xbfb8aa3b, v93
	v_exp_f32_e32 v98, v98
	v_exp_f32_e32 v99, v99
	v_mul_f32_e32 v100, 0xbfb8aa3b, v94
	v_mul_f32_e32 v101, 0xbfb8aa3b, v95
	v_exp_f32_e32 v100, v100
	v_exp_f32_e32 v101, v101
	v_add_f32_e32 v98, 1.0, v98
	v_add_f32_e32 v99, 1.0, v99
	v_rcp_f32_e32 v98, v98
	v_rcp_f32_e32 v99, v99
	v_add_f32_e32 v100, 1.0, v100
	v_add_f32_e32 v101, 1.0, v101
	v_rcp_f32_e32 v100, v100
	v_rcp_f32_e32 v101, v101
	v_pk_mul_f32 v[88:89], v[88:89], v[96:97] op_sel_hi:[1,0]
	v_pk_mul_f32 v[92:93], v[92:93], v[98:99]
	v_pk_mul_f32 v[90:91], v[90:91], v[96:97] op_sel_hi:[1,0]
	v_pk_mul_f32 v[88:89], v[88:89], v[92:93]
	v_pk_mul_f32 v[92:93], v[94:95], v[100:101]
	v_pk_mul_f32 v[84:85], v[84:85], v[96:97] op_sel_hi:[1,0]
	v_pk_mul_f32 v[90:91], v[90:91], v[92:93]
	v_cvt_pk_bf16_f32 v88, v88, v89
	v_cvt_pk_bf16_f32 v89, v90, v91
	v_mul_f32_e32 v90, 0xbfb8aa3b, v84
	v_mul_f32_e32 v91, 0xbfb8aa3b, v85
	v_pk_mul_f32 v[86:87], v[86:87], v[96:97] op_sel_hi:[1,0]
	v_exp_f32_e32 v90, v90
	v_exp_f32_e32 v91, v91
	v_mul_f32_e32 v92, 0xbfb8aa3b, v86
	v_mul_f32_e32 v93, 0xbfb8aa3b, v87
	v_exp_f32_e32 v92, v92
	v_exp_f32_e32 v93, v93
	v_add_f32_e32 v90, 1.0, v90
	v_add_f32_e32 v91, 1.0, v91
	v_rcp_f32_e32 v90, v90
	v_rcp_f32_e32 v91, v91
	v_add_f32_e32 v92, 1.0, v92
	v_add_f32_e32 v93, 1.0, v93
	v_rcp_f32_e32 v92, v92
	v_rcp_f32_e32 v93, v93
	v_pk_mul_f32 v[80:81], v[80:81], v[96:97] op_sel_hi:[1,0]
	v_pk_mul_f32 v[84:85], v[84:85], v[90:91]
	v_pk_mul_f32 v[82:83], v[82:83], v[96:97] op_sel_hi:[1,0]
	v_pk_mul_f32 v[80:81], v[80:81], v[84:85]
	s_and_b64 vcc, exec, s[6:7]
	v_cvt_pk_bf16_f32 v90, v80, v81
	v_pk_mul_f32 v[80:81], v[86:87], v[92:93]
	s_nop 0
	v_pk_mul_f32 v[80:81], v[82:83], v[80:81]
	s_nop 0
	v_cvt_pk_bf16_f32 v91, v80, v81
	v_mov_b64_e32 v[80:81], s[56:57]
	v_mad_i64_i32 v[80:81], s[38:39], v97, s81, v[80:81]
	v_lshl_add_u64 v[80:81], v[144:145], 1, v[80:81]
	global_store_dwordx4 v[80:81], v[88:91], off
	s_cbranch_vccnz .LBB0_154
	v_fmamk_f32 v80, v175, 0x3a800000, v166
	v_rsq_f32_e32 v80, v80
	s_nop 0
	v_mov_b32_e32 v104, v80
.LBB0_154:
	v_pk_mul_f32 v[76:77], v[76:77], v[104:105] op_sel_hi:[1,0]
	v_pk_mul_f32 v[80:81], v[74:75], v[104:105] op_sel_hi:[1,0]
	v_pk_mul_f32 v[74:75], v[72:73], v[104:105] op_sel_hi:[1,0]
	v_mul_f32_e32 v72, 0xbfb8aa3b, v76
	v_exp_f32_e32 v73, v72
	v_mul_f32_e32 v72, 0xbfb8aa3b, v77
	v_exp_f32_e32 v83, v72
	v_pk_mul_f32 v[78:79], v[78:79], v[104:105] op_sel_hi:[1,0]
	v_add_f32_e32 v73, 1.0, v73
	v_rcp_f32_e32 v82, v73
	v_add_f32_e32 v73, 1.0, v83
	v_mul_f32_e32 v83, 0xbfb8aa3b, v78
	v_exp_f32_e32 v84, v83
	v_mul_f32_e32 v83, 0xbfb8aa3b, v79
	v_exp_f32_e32 v85, v83
	v_rcp_f32_e32 v83, v73
	v_add_f32_e32 v73, 1.0, v84
	v_rcp_f32_e32 v84, v73
	v_add_f32_e32 v73, 1.0, v85
	v_rcp_f32_e32 v85, v73
	v_pk_mul_f32 v[76:77], v[76:77], v[82:83]
	v_pk_mul_f32 v[68:69], v[68:69], v[104:105] op_sel_hi:[1,0]
	v_pk_mul_f32 v[74:75], v[74:75], v[76:77]
	v_pk_mul_f32 v[76:77], v[78:79], v[84:85]
	v_mul_f32_e32 v73, 0xbfb8aa3b, v68
	v_pk_mul_f32 v[76:77], v[80:81], v[76:77]
	v_cvt_pk_bf16_f32 v74, v74, v75
	v_cvt_pk_bf16_f32 v75, v76, v77
	v_exp_f32_e32 v73, v73
	v_mul_f32_e32 v76, 0xbfb8aa3b, v69
	v_exp_f32_e32 v77, v76
	v_pk_mul_f32 v[70:71], v[70:71], v[104:105] op_sel_hi:[1,0]
	v_add_f32_e32 v73, 1.0, v73
	v_rcp_f32_e32 v76, v73
	v_add_f32_e32 v73, 1.0, v77
	v_mul_f32_e32 v77, 0xbfb8aa3b, v70
	v_exp_f32_e32 v78, v77
	v_mul_f32_e32 v77, 0xbfb8aa3b, v71
	v_exp_f32_e32 v79, v77
	v_rcp_f32_e32 v77, v73
	v_add_f32_e32 v73, 1.0, v78
	v_rcp_f32_e32 v78, v73
	v_add_f32_e32 v73, 1.0, v79
	v_rcp_f32_e32 v79, v73
	v_pk_mul_f32 v[64:65], v[64:65], v[104:105] op_sel_hi:[1,0]
	v_pk_mul_f32 v[68:69], v[68:69], v[76:77]
	v_pk_mul_f32 v[66:67], v[66:67], v[104:105] op_sel_hi:[1,0]
	v_pk_mul_f32 v[64:65], v[64:65], v[68:69]
	v_or_b32_e32 v86, 48, v146
	v_cvt_pk_bf16_f32 v76, v64, v65
	v_pk_mul_f32 v[64:65], v[70:71], v[78:79]
	v_mov_b32_e32 v72, 1.0
	v_pk_mul_f32 v[64:65], v[66:67], v[64:65]
	s_and_b64 vcc, exec, s[6:7]
	v_cvt_pk_bf16_f32 v77, v64, v65
	v_mov_b64_e32 v[64:65], s[56:57]
	v_mad_i64_i32 v[64:65], s[38:39], v86, s81, v[64:65]
	v_lshl_add_u64 v[64:65], v[144:145], 1, v[64:65]
	global_store_dwordx4 v[64:65], v[74:77], off
	v_mov_b32_e32 v64, 1.0
	s_cbranch_vccnz .LBB0_156
	v_fmamk_f32 v64, v176, 0x3a800000, v166
	v_rsq_f32_e32 v64, v64
	s_nop 0
; __device__ __forceinline__ unsigned cvt_pk_bf16(float lo, float hi) { cvf32x2_t v = {lo, hi}; cvbf16x2_t b = __builtin_convertvector(v, cvbf16x2_t); return __builtin_bit_cast(unsigned, b); }
; __device__ __forceinline__ float fsigm(float x) { return __builtin_amdgcn_rcpf(1.f + __expf(-x)); }
; __device__ __forceinline__ float fsilu(float x) { return x * fsigm(x); }
; __device__ __forceinline__ float row_rs(const float* ssq, int row) { return ssq ? rsqrtf(ssq[row] * (1.f / 1024.f) + RMS_EPS) : 1.f; }
;     __device__ __forceinline__ void operator()(const f32x4 (&acc)[2][2][4][2], const Unit& u, int wr, int wc, int fr, int fq) const {
;     ...
;             for (int m = 0; m < 4; ++m) { const int row = row0 + ai * HALF + m * 16; const float rs = row_rs(ssq, row);
;                 u32x4 w; unsigned pk[4];
; #pragma unroll
;                 for (int n = 0; n < 2; ++n) { const f32x4 g = acc[ai][0][m][n] * rs, up = acc[ai][1][m][n] * rs;
;                     pk[2 * n] = cvt_pk_bf16(fsilu(g[0]) * up[0], fsilu(g[1]) * up[1]); pk[2 * n + 1] = cvt_pk_bf16(fsilu(g[2]) * up[2], fsilu(g[3]) * up[3]); }
;                 w.x = pk[0]; w.y = pk[1]; w.z = pk[2]; w.w = pk[3];
;                 st_wt16(H + (size_t)row * ldh + col0, w); }
.LBB0_156:
	v_add_u32_e32 v65, 0x80, v146
	v_pk_mul_f32 v[60:61], v[60:61], v[64:65] op_sel_hi:[1,0]
	v_pk_mul_f32 v[62:63], v[62:63], v[64:65] op_sel_hi:[1,0]
	v_mul_f32_e32 v66, 0xbfb8aa3b, v60
	v_mul_f32_e32 v67, 0xbfb8aa3b, v61
	v_exp_f32_e32 v66, v66
	v_exp_f32_e32 v67, v67
	v_mul_f32_e32 v68, 0xbfb8aa3b, v62
	v_mul_f32_e32 v69, 0xbfb8aa3b, v63
	v_exp_f32_e32 v68, v68
	v_exp_f32_e32 v69, v69
	v_add_f32_e32 v66, 1.0, v66
	v_add_f32_e32 v67, 1.0, v67
	v_rcp_f32_e32 v66, v66
	v_rcp_f32_e32 v67, v67
	v_add_f32_e32 v68, 1.0, v68
	v_add_f32_e32 v69, 1.0, v69
	v_rcp_f32_e32 v68, v68
	v_rcp_f32_e32 v69, v69
	v_pk_mul_f32 v[56:57], v[56:57], v[64:65] op_sel_hi:[1,0]
	v_pk_mul_f32 v[60:61], v[60:61], v[66:67]
	v_pk_mul_f32 v[58:59], v[58:59], v[64:65] op_sel_hi:[1,0]
	v_pk_mul_f32 v[56:57], v[56:57], v[60:61]
	v_pk_mul_f32 v[60:61], v[62:63], v[68:69]
	v_pk_mul_f32 v[52:53], v[52:53], v[64:65] op_sel_hi:[1,0]
	v_pk_mul_f32 v[58:59], v[58:59], v[60:61]
	v_cvt_pk_bf16_f32 v56, v56, v57
	v_cvt_pk_bf16_f32 v57, v58, v59
	v_mul_f32_e32 v58, 0xbfb8aa3b, v52
	v_mul_f32_e32 v59, 0xbfb8aa3b, v53
	v_pk_mul_f32 v[54:55], v[54:55], v[64:65] op_sel_hi:[1,0]
	v_exp_f32_e32 v58, v58
	v_exp_f32_e32 v59, v59
	v_mul_f32_e32 v60, 0xbfb8aa3b, v54
	v_mul_f32_e32 v61, 0xbfb8aa3b, v55
	v_exp_f32_e32 v60, v60
	v_exp_f32_e32 v61, v61
	v_add_f32_e32 v58, 1.0, v58
	v_add_f32_e32 v59, 1.0, v59
	v_rcp_f32_e32 v58, v58
	v_rcp_f32_e32 v59, v59
	v_add_f32_e32 v60, 1.0, v60
	v_add_f32_e32 v61, 1.0, v61
	v_rcp_f32_e32 v60, v60
	v_rcp_f32_e32 v61, v61
	v_pk_mul_f32 v[48:49], v[48:49], v[64:65] op_sel_hi:[1,0]
	v_pk_mul_f32 v[52:53], v[52:53], v[58:59]
	v_pk_mul_f32 v[50:51], v[50:51], v[64:65] op_sel_hi:[1,0]
	v_pk_mul_f32 v[48:49], v[48:49], v[52:53]
	s_and_b64 vcc, exec, s[6:7]
	v_cvt_pk_bf16_f32 v58, v48, v49
	v_pk_mul_f32 v[48:49], v[54:55], v[60:61]
	s_nop 0
	v_pk_mul_f32 v[48:49], v[50:51], v[48:49]
	s_nop 0
	v_cvt_pk_bf16_f32 v59, v48, v49
	v_mov_b64_e32 v[48:49], s[56:57]
	v_mad_i64_i32 v[48:49], s[38:39], v65, s81, v[48:49]
	v_lshl_add_u64 v[48:49], v[144:145], 1, v[48:49]
	global_store_dwordx4 v[48:49], v[56:59], off
	s_cbranch_vccnz .LBB0_158
	v_fmamk_f32 v48, v177, 0x3a800000, v166
	v_rsq_f32_e32 v48, v48
	s_nop 0
	v_mov_b32_e32 v72, v48
.LBB0_158:
	v_pk_mul_f32 v[44:45], v[44:45], v[72:73] op_sel_hi:[1,0]
	v_pk_mul_f32 v[48:49], v[42:43], v[72:73] op_sel_hi:[1,0]
	v_pk_mul_f32 v[42:43], v[40:41], v[72:73] op_sel_hi:[1,0]
	v_mul_f32_e32 v40, 0xbfb8aa3b, v44
	v_exp_f32_e32 v41, v40
	v_mul_f32_e32 v40, 0xbfb8aa3b, v45
	v_exp_f32_e32 v51, v40
	v_pk_mul_f32 v[46:47], v[46:47], v[72:73] op_sel_hi:[1,0]
	v_add_f32_e32 v41, 1.0, v41
	v_rcp_f32_e32 v50, v41
	v_add_f32_e32 v41, 1.0, v51
	v_mul_f32_e32 v51, 0xbfb8aa3b, v46
	v_exp_f32_e32 v52, v51
	v_mul_f32_e32 v51, 0xbfb8aa3b, v47
	v_exp_f32_e32 v53, v51
	v_rcp_f32_e32 v51, v41
	v_add_f32_e32 v41, 1.0, v52
	v_rcp_f32_e32 v52, v41
	v_add_f32_e32 v41, 1.0, v53
	v_rcp_f32_e32 v53, v41
	v_pk_mul_f32 v[44:45], v[44:45], v[50:51]
	v_pk_mul_f32 v[36:37], v[36:37], v[72:73] op_sel_hi:[1,0]
	v_pk_mul_f32 v[42:43], v[42:43], v[44:45]
	v_pk_mul_f32 v[44:45], v[46:47], v[52:53]
	v_mul_f32_e32 v41, 0xbfb8aa3b, v36
	v_pk_mul_f32 v[44:45], v[48:49], v[44:45]
	v_cvt_pk_bf16_f32 v42, v42, v43
	v_cvt_pk_bf16_f32 v43, v44, v45
	v_exp_f32_e32 v41, v41
	v_mul_f32_e32 v44, 0xbfb8aa3b, v37
	v_exp_f32_e32 v45, v44
	v_pk_mul_f32 v[38:39], v[38:39], v[72:73] op_sel_hi:[1,0]
	v_add_f32_e32 v41, 1.0, v41
	v_rcp_f32_e32 v44, v41
	v_add_f32_e32 v41, 1.0, v45
	v_mul_f32_e32 v45, 0xbfb8aa3b, v38
	v_exp_f32_e32 v46, v45
	v_mul_f32_e32 v45, 0xbfb8aa3b, v39
	v_exp_f32_e32 v47, v45
	v_rcp_f32_e32 v45, v41
	v_add_f32_e32 v41, 1.0, v46
	v_rcp_f32_e32 v46, v41
	v_add_f32_e32 v41, 1.0, v47
	v_rcp_f32_e32 v47, v41
	v_pk_mul_f32 v[32:33], v[32:33], v[72:73] op_sel_hi:[1,0]
	v_pk_mul_f32 v[36:37], v[36:37], v[44:45]
	v_pk_mul_f32 v[34:35], v[34:35], v[72:73] op_sel_hi:[1,0]
	v_pk_mul_f32 v[32:33], v[32:33], v[36:37]
	v_add_u32_e32 v54, 0x90, v146
	v_cvt_pk_bf16_f32 v44, v32, v33
	v_pk_mul_f32 v[32:33], v[38:39], v[46:47]
	v_mov_b32_e32 v40, 1.0
	v_pk_mul_f32 v[32:33], v[34:35], v[32:33]
	s_and_b64 vcc, exec, s[6:7]
	v_cvt_pk_bf16_f32 v45, v32, v33
	v_mov_b64_e32 v[32:33], s[56:57]
	v_mad_i64_i32 v[32:33], s[38:39], v54, s81, v[32:33]
	v_lshl_add_u64 v[32:33], v[144:145], 1, v[32:33]
	global_store_dwordx4 v[32:33], v[42:45], off
	v_mov_b32_e32 v32, 1.0
	s_cbranch_vccnz .LBB0_160
	v_fmamk_f32 v32, v178, 0x3a800000, v166
	v_rsq_f32_e32 v32, v32
	s_nop 0
.LBB0_160:
	v_add_u32_e32 v33, 0xa0, v146
	v_pk_mul_f32 v[28:29], v[28:29], v[32:33] op_sel_hi:[1,0]
	v_pk_mul_f32 v[30:31], v[30:31], v[32:33] op_sel_hi:[1,0]
	v_mul_f32_e32 v34, 0xbfb8aa3b, v28
	v_mul_f32_e32 v35, 0xbfb8aa3b, v29
	v_exp_f32_e32 v34, v34
	v_exp_f32_e32 v35, v35
	v_mul_f32_e32 v36, 0xbfb8aa3b, v30
	v_mul_f32_e32 v37, 0xbfb8aa3b, v31
	v_exp_f32_e32 v36, v36
	v_exp_f32_e32 v37, v37
	v_add_f32_e32 v34, 1.0, v34
	v_add_f32_e32 v35, 1.0, v35
	v_rcp_f32_e32 v34, v34
	v_rcp_f32_e32 v35, v35
	v_add_f32_e32 v36, 1.0, v36
	v_add_f32_e32 v37, 1.0, v37
	v_rcp_f32_e32 v36, v36
	v_rcp_f32_e32 v37, v37
	v_pk_mul_f32 v[24:25], v[24:25], v[32:33] op_sel_hi:[1,0]
	v_pk_mul_f32 v[28:29], v[28:29], v[34:35]
	v_pk_mul_f32 v[26:27], v[26:27], v[32:33] op_sel_hi:[1,0]
	v_pk_mul_f32 v[24:25], v[24:25], v[28:29]
	v_pk_mul_f32 v[28:29], v[30:31], v[36:37]
	v_pk_mul_f32 v[20:21], v[20:21], v[32:33] op_sel_hi:[1,0]
	v_pk_mul_f32 v[26:27], v[26:27], v[28:29]
	v_cvt_pk_bf16_f32 v24, v24, v25
	v_cvt_pk_bf16_f32 v25, v26, v27
	v_mul_f32_e32 v26, 0xbfb8aa3b, v20
	v_mul_f32_e32 v27, 0xbfb8aa3b, v21
	v_pk_mul_f32 v[22:23], v[22:23], v[32:33] op_sel_hi:[1,0]
	v_exp_f32_e32 v26, v26
	v_exp_f32_e32 v27, v27
	v_mul_f32_e32 v28, 0xbfb8aa3b, v22
	v_mul_f32_e32 v29, 0xbfb8aa3b, v23
	v_exp_f32_e32 v28, v28
	v_exp_f32_e32 v29, v29
	v_add_f32_e32 v26, 1.0, v26
	v_add_f32_e32 v27, 1.0, v27
	v_rcp_f32_e32 v26, v26
	v_rcp_f32_e32 v27, v27
	v_add_f32_e32 v28, 1.0, v28
	v_add_f32_e32 v29, 1.0, v29
	v_rcp_f32_e32 v28, v28
	v_rcp_f32_e32 v29, v29
	v_pk_mul_f32 v[16:17], v[16:17], v[32:33] op_sel_hi:[1,0]
	v_pk_mul_f32 v[20:21], v[20:21], v[26:27]
	v_pk_mul_f32 v[18:19], v[18:19], v[32:33] op_sel_hi:[1,0]
	v_pk_mul_f32 v[16:17], v[16:17], v[20:21]
	s_and_b64 vcc, exec, s[6:7]
	v_cvt_pk_bf16_f32 v26, v16, v17
	v_pk_mul_f32 v[16:17], v[22:23], v[28:29]
	s_nop 0
	v_pk_mul_f32 v[16:17], v[18:19], v[16:17]
	s_nop 0
	v_cvt_pk_bf16_f32 v27, v16, v17
	v_mov_b64_e32 v[16:17], s[56:57]
	v_mad_i64_i32 v[16:17], s[38:39], v33, s81, v[16:17]
	v_lshl_add_u64 v[16:17], v[144:145], 1, v[16:17]
	global_store_dwordx4 v[16:17], v[24:27], off
	s_cbranch_vccnz .LBB0_162
	v_fmamk_f32 v16, v179, 0x3a800000, v166
	v_rsq_f32_e32 v16, v16
	s_nop 0
	v_mov_b32_e32 v40, v16

; __device__ __forceinline__ unsigned cvt_pk_bf16(float lo, float hi) { cvf32x2_t v = {lo, hi}; cvbf16x2_t b = __builtin_convertvector(v, cvbf16x2_t); return __builtin_bit_cast(unsigned, b); }
; __device__ __forceinline__ float fsilu(float x) { return x * fsigm(x); }
; __device__ __forceinline__ float row_rs(const float* ssq, int row) { return ssq ? rsqrtf(ssq[row] * (1.f / 1024.f) + RMS_EPS) : 1.f; }
;     __device__ __forceinline__ void operator()(const f32x4 (&acc)[2][2][4][2], const Unit& u, int wr, int wc, int fr, int fq) const {
;     ...
;         bf16_t* dst = grp == 0 ? QS : (grp == 2 ? VV : (grp == 3 ? GS : BC)); const bool act = (grp == 0) || (grp == 3);
; #pragma unroll
;         for (int ai = 0; ai < 2; ++ai)
; #pragma unroll
;             for (int m = 0; m < 4; ++m) { const int row = row0 + ai * HALF + m * 16; const float rs = row_rs(ssq, row);
; #pragma unroll
;                 for (int bj = 0; bj < 2; ++bj) { f32x4 p0 = acc[ai][bj][m][0] * rs, p1 = acc[ai][bj][m][1] * rs;
;                     if (act) { p0[0] = fsilu(p0[0]); p0[1] = fsilu(p0[1]); p0[2] = fsilu(p0[2]); p0[3] = fsilu(p0[3]); p1[0] = fsilu(p1[0]); p1[1] = fsilu(p1[1]); p1[2] = fsilu(p1[2]); p1[3] = fsilu(p1[3]); }
;                     u32x4 w; w.x = cvt_pk_bf16(p0[0], p0[1]); w.y = cvt_pk_bf16(p0[2], p0[3]); w.z = cvt_pk_bf16(p1[0], p1[1]); w.w = cvt_pk_bf16(p1[2], p1[3]);
;                     *(u32x4*)(dst + (size_t)row * 512 + cbase + bj * HALF) = w; } }
.LBB0_478:
	v_ashrrev_i32_e32 v149, 31, v148
	v_lshl_add_u64 v[150:151], v[148:149], 2, s[30:31]
	global_load_dword v136, v[150:151], off
	global_load_dword v210, v[150:151], off offset:64
	global_load_dword v211, v[150:151], off offset:128
	global_load_dword v212, v[150:151], off offset:192
	global_load_dword v213, v[150:151], off offset:512
	global_load_dword v214, v[150:151], off offset:576
	global_load_dword v215, v[150:151], off offset:640
	global_load_dword v216, v[150:151], off offset:704
	s_cmp_eq_u32 s65, 3
	s_cselect_b64 s[52:53], -1, 0
	s_or_b64 s[52:53], s[6:7], s[52:53]
	s_andn2_b64 vcc, exec, s[52:53]
	s_waitcnt vmcnt(0)
	v_fmamk_f32 v136, v136, 0x3a800000, v170
	v_rsq_f32_e32 v136, v136
	v_cndmask_b32_e64 v152, 0, 1, s[52:53]
	v_cmp_ne_u32_e64 s[6:7], 1, v152
	v_mov_b32_e32 v154, v136
	v_pk_mul_f32 v[160:161], v[126:127], v[154:155] op_sel_hi:[1,0]
	v_pk_mul_f32 v[164:165], v[124:125], v[154:155] op_sel_hi:[1,0]
	v_pk_mul_f32 v[158:159], v[122:123], v[154:155] op_sel_hi:[1,0]
	v_pk_mul_f32 v[162:163], v[120:121], v[154:155] op_sel_hi:[1,0]
	s_cbranch_vccnz .LBB0_480
	v_mul_f32_e32 v136, 0xbfb8aa3b, v164
	v_exp_f32_e32 v136, v136
	v_mul_f32_e32 v152, 0xbfb8aa3b, v165
	v_mul_f32_e32 v153, 0xbfb8aa3b, v160
	v_exp_f32_e32 v155, v152
	v_exp_f32_e32 v156, v153
	v_add_f32_e32 v136, 1.0, v136
	v_rcp_f32_e32 v152, v136
	v_add_f32_e32 v136, 1.0, v155
	v_mul_f32_e32 v155, 0xbfb8aa3b, v161
	v_rcp_f32_e32 v153, v136
	v_add_f32_e32 v136, 1.0, v156
	v_exp_f32_e32 v155, v155
	v_mul_f32_e32 v156, 0xbfb8aa3b, v162
	v_exp_f32_e32 v172, v156
	v_rcp_f32_e32 v156, v136
	v_add_f32_e32 v136, 1.0, v155
	v_rcp_f32_e32 v157, v136
	v_add_f32_e32 v136, 1.0, v172
	v_mul_f32_e32 v155, 0xbfb8aa3b, v158
	v_rcp_f32_e32 v172, v136
	v_mul_f32_e32 v136, 0xbfb8aa3b, v163
	v_exp_f32_e32 v155, v155
	v_mul_f32_e32 v173, 0xbfb8aa3b, v159
	v_exp_f32_e32 v136, v136
	v_exp_f32_e32 v173, v173
	v_add_f32_e32 v155, 1.0, v155
	v_rcp_f32_e32 v174, v155
	v_add_f32_e32 v136, 1.0, v136
	v_add_f32_e32 v155, 1.0, v173
	v_rcp_f32_e32 v175, v155
	v_rcp_f32_e32 v173, v136
	v_pk_mul_f32 v[160:161], v[160:161], v[156:157]
	v_pk_mul_f32 v[164:165], v[164:165], v[152:153]
	v_pk_mul_f32 v[158:159], v[158:159], v[174:175]
	v_pk_mul_f32 v[162:163], v[162:163], v[172:173]

; __device__ __forceinline__ unsigned cvt_pk_bf16(float lo, float hi) { cvf32x2_t v = {lo, hi}; cvbf16x2_t b = __builtin_convertvector(v, cvbf16x2_t); return __builtin_bit_cast(unsigned, b); }
; __device__ __forceinline__ float fsilu(float x) { return x * fsigm(x); }
; __device__ __forceinline__ float row_rs(const float* ssq, int row) { return ssq ? rsqrtf(ssq[row] * (1.f / 1024.f) + RMS_EPS) : 1.f; }
;     __device__ __forceinline__ void operator()(const f32x4 (&acc)[2][2][4][2], const Unit& u, int wr, int wc, int fr, int fq) const {
;     ...
;         bf16_t* dst = grp == 0 ? QS : (grp == 2 ? VV : (grp == 3 ? GS : BC)); const bool act = (grp == 0) || (grp == 3);
; #pragma unroll
;         for (int ai = 0; ai < 2; ++ai)
; #pragma unroll
;             for (int m = 0; m < 4; ++m) { const int row = row0 + ai * HALF + m * 16; const float rs = row_rs(ssq, row);
; #pragma unroll
;                 for (int bj = 0; bj < 2; ++bj) { f32x4 p0 = acc[ai][bj][m][0] * rs, p1 = acc[ai][bj][m][1] * rs;
;                     if (act) { p0[0] = fsilu(p0[0]); p0[1] = fsilu(p0[1]); p0[2] = fsilu(p0[2]); p0[3] = fsilu(p0[3]); p1[0] = fsilu(p1[0]); p1[1] = fsilu(p1[1]); p1[2] = fsilu(p1[2]); p1[3] = fsilu(p1[3]); }
;                     u32x4 w; w.x = cvt_pk_bf16(p0[0], p0[1]); w.y = cvt_pk_bf16(p0[2], p0[3]); w.z = cvt_pk_bf16(p1[0], p1[1]); w.w = cvt_pk_bf16(p1[2], p1[3]);
;                     *(u32x4*)(dst + (size_t)row * 512 + cbase + bj * HALF) = w; } }
.LBB0_482:
	s_nop 0
	v_cvt_pk_bf16_f32 v174, v154, v155
	v_or_b32_e32 v154, 16, v148
	v_cvt_pk_bf16_f32 v172, v160, v161
	v_cvt_pk_bf16_f32 v173, v158, v159
	v_cvt_pk_bf16_f32 v175, v162, v163
	v_ashrrev_i32_e32 v155, 31, v154
	global_store_dwordx4 v[156:157], v[172:175], off offset:256
	v_lshl_add_u64 v[156:157], v[154:155], 2, s[30:31]
	s_and_b64 vcc, exec, s[6:7]
	v_fmamk_f32 v136, v210, 0x3a800000, v170
	v_rsq_f32_e32 v136, v136
	s_nop 0
	v_mov_b32_e32 v156, v136
	v_pk_mul_f32 v[160:161], v[110:111], v[156:157] op_sel_hi:[1,0]
	v_pk_mul_f32 v[164:165], v[108:109], v[156:157] op_sel_hi:[1,0]
	v_pk_mul_f32 v[158:159], v[106:107], v[156:157] op_sel_hi:[1,0]
	v_pk_mul_f32 v[162:163], v[104:105], v[156:157] op_sel_hi:[1,0]
	s_cbranch_vccnz .LBB0_484
	v_mul_f32_e32 v136, 0xbfb8aa3b, v164
	v_exp_f32_e32 v136, v136
	v_mul_f32_e32 v157, 0xbfb8aa3b, v165
	v_mul_f32_e32 v172, 0xbfb8aa3b, v160
	v_exp_f32_e32 v157, v157
	v_exp_f32_e32 v174, v172
	v_add_f32_e32 v136, 1.0, v136
	v_rcp_f32_e32 v172, v136
	v_add_f32_e32 v136, 1.0, v157
	v_mul_f32_e32 v157, 0xbfb8aa3b, v161
	v_rcp_f32_e32 v173, v136
	v_add_f32_e32 v136, 1.0, v174
	v_exp_f32_e32 v157, v157
	v_mul_f32_e32 v174, 0xbfb8aa3b, v162
	v_exp_f32_e32 v176, v174
	v_rcp_f32_e32 v174, v136
	v_add_f32_e32 v136, 1.0, v157
	v_rcp_f32_e32 v175, v136
	v_add_f32_e32 v136, 1.0, v176
	v_mul_f32_e32 v157, 0xbfb8aa3b, v158
	v_rcp_f32_e32 v176, v136
	v_mul_f32_e32 v136, 0xbfb8aa3b, v163
	v_exp_f32_e32 v157, v157
	v_mul_f32_e32 v177, 0xbfb8aa3b, v159
	v_exp_f32_e32 v136, v136
	v_exp_f32_e32 v177, v177
	v_add_f32_e32 v157, 1.0, v157
	v_rcp_f32_e32 v178, v157
	v_add_f32_e32 v136, 1.0, v136
	v_add_f32_e32 v157, 1.0, v177
	v_rcp_f32_e32 v179, v157
	v_rcp_f32_e32 v177, v136
	v_pk_mul_f32 v[160:161], v[160:161], v[174:175]
	v_pk_mul_f32 v[164:165], v[164:165], v[172:173]
	v_pk_mul_f32 v[158:159], v[158:159], v[178:179]
	v_pk_mul_f32 v[162:163], v[162:163], v[176:177]

; __device__ __forceinline__ unsigned cvt_pk_bf16(float lo, float hi) { cvf32x2_t v = {lo, hi}; cvbf16x2_t b = __builtin_convertvector(v, cvbf16x2_t); return __builtin_bit_cast(unsigned, b); }
; __device__ __forceinline__ float fsilu(float x) { return x * fsigm(x); }
; __device__ __forceinline__ float row_rs(const float* ssq, int row) { return ssq ? rsqrtf(ssq[row] * (1.f / 1024.f) + RMS_EPS) : 1.f; }
;     __device__ __forceinline__ void operator()(const f32x4 (&acc)[2][2][4][2], const Unit& u, int wr, int wc, int fr, int fq) const {
;     ...
;         bf16_t* dst = grp == 0 ? QS : (grp == 2 ? VV : (grp == 3 ? GS : BC)); const bool act = (grp == 0) || (grp == 3);
; #pragma unroll
;         for (int ai = 0; ai < 2; ++ai)
; #pragma unroll
;             for (int m = 0; m < 4; ++m) { const int row = row0 + ai * HALF + m * 16; const float rs = row_rs(ssq, row);
; #pragma unroll
;                 for (int bj = 0; bj < 2; ++bj) { f32x4 p0 = acc[ai][bj][m][0] * rs, p1 = acc[ai][bj][m][1] * rs;
;                     if (act) { p0[0] = fsilu(p0[0]); p0[1] = fsilu(p0[1]); p0[2] = fsilu(p0[2]); p0[3] = fsilu(p0[3]); p1[0] = fsilu(p1[0]); p1[1] = fsilu(p1[1]); p1[2] = fsilu(p1[2]); p1[3] = fsilu(p1[3]); }
;                     u32x4 w; w.x = cvt_pk_bf16(p0[0], p0[1]); w.y = cvt_pk_bf16(p0[2], p0[3]); w.z = cvt_pk_bf16(p1[0], p1[1]); w.w = cvt_pk_bf16(p1[2], p1[3]);
;                     *(u32x4*)(dst + (size_t)row * 512 + cbase + bj * HALF) = w; } }
.LBB0_486:
	s_nop 0
	v_cvt_pk_bf16_f32 v172, v160, v161
	v_cvt_pk_bf16_f32 v173, v158, v159
	v_cvt_pk_bf16_f32 v174, v156, v157
	v_cvt_pk_bf16_f32 v175, v162, v163
	global_store_dwordx4 v[154:155], v[172:175], off offset:256
	v_or_b32_e32 v154, 32, v148
	v_ashrrev_i32_e32 v155, 31, v154
	v_lshl_add_u64 v[156:157], v[154:155], 2, s[30:31]
	s_and_b64 vcc, exec, s[6:7]
	v_fmamk_f32 v136, v211, 0x3a800000, v170
	v_rsq_f32_e32 v136, v136
	s_nop 0
	v_mov_b32_e32 v156, v136
	v_pk_mul_f32 v[160:161], v[94:95], v[156:157] op_sel_hi:[1,0]
	v_pk_mul_f32 v[164:165], v[92:93], v[156:157] op_sel_hi:[1,0]
	v_pk_mul_f32 v[158:159], v[90:91], v[156:157] op_sel_hi:[1,0]
	v_pk_mul_f32 v[162:163], v[88:89], v[156:157] op_sel_hi:[1,0]
	s_cbranch_vccnz .LBB0_488
	v_mul_f32_e32 v136, 0xbfb8aa3b, v164
	v_exp_f32_e32 v136, v136
	v_mul_f32_e32 v157, 0xbfb8aa3b, v165
	v_mul_f32_e32 v172, 0xbfb8aa3b, v160
	v_exp_f32_e32 v157, v157
	v_exp_f32_e32 v174, v172
	v_add_f32_e32 v136, 1.0, v136
	v_rcp_f32_e32 v172, v136
	v_add_f32_e32 v136, 1.0, v157
	v_mul_f32_e32 v157, 0xbfb8aa3b, v161
	v_rcp_f32_e32 v173, v136
	v_add_f32_e32 v136, 1.0, v174
	v_exp_f32_e32 v157, v157
	v_mul_f32_e32 v174, 0xbfb8aa3b, v162
	v_exp_f32_e32 v176, v174
	v_rcp_f32_e32 v174, v136
	v_add_f32_e32 v136, 1.0, v157
	v_rcp_f32_e32 v175, v136
	v_add_f32_e32 v136, 1.0, v176
	v_mul_f32_e32 v157, 0xbfb8aa3b, v158
	v_rcp_f32_e32 v176, v136
	v_mul_f32_e32 v136, 0xbfb8aa3b, v163
	v_exp_f32_e32 v157, v157
	v_mul_f32_e32 v177, 0xbfb8aa3b, v159
	v_exp_f32_e32 v136, v136
	v_exp_f32_e32 v177, v177
	v_add_f32_e32 v157, 1.0, v157
	v_rcp_f32_e32 v178, v157
	v_add_f32_e32 v136, 1.0, v136
	v_add_f32_e32 v157, 1.0, v177
	v_rcp_f32_e32 v179, v157
	v_rcp_f32_e32 v177, v136
	v_pk_mul_f32 v[160:161], v[160:161], v[174:175]
	v_pk_mul_f32 v[164:165], v[164:165], v[172:173]
	v_pk_mul_f32 v[158:159], v[158:159], v[178:179]
	v_pk_mul_f32 v[162:163], v[162:163], v[176:177]

; __device__ __forceinline__ unsigned cvt_pk_bf16(float lo, float hi) { cvf32x2_t v = {lo, hi}; cvbf16x2_t b = __builtin_convertvector(v, cvbf16x2_t); return __builtin_bit_cast(unsigned, b); }
; __device__ __forceinline__ float fsilu(float x) { return x * fsigm(x); }
; __device__ __forceinline__ float row_rs(const float* ssq, int row) { return ssq ? rsqrtf(ssq[row] * (1.f / 1024.f) + RMS_EPS) : 1.f; }
;     __device__ __forceinline__ void operator()(const f32x4 (&acc)[2][2][4][2], const Unit& u, int wr, int wc, int fr, int fq) const {
;     ...
;         bf16_t* dst = grp == 0 ? QS : (grp == 2 ? VV : (grp == 3 ? GS : BC)); const bool act = (grp == 0) || (grp == 3);
; #pragma unroll
;         for (int ai = 0; ai < 2; ++ai)
; #pragma unroll
;             for (int m = 0; m < 4; ++m) { const int row = row0 + ai * HALF + m * 16; const float rs = row_rs(ssq, row);
; #pragma unroll
;                 for (int bj = 0; bj < 2; ++bj) { f32x4 p0 = acc[ai][bj][m][0] * rs, p1 = acc[ai][bj][m][1] * rs;
;                     if (act) { p0[0] = fsilu(p0[0]); p0[1] = fsilu(p0[1]); p0[2] = fsilu(p0[2]); p0[3] = fsilu(p0[3]); p1[0] = fsilu(p1[0]); p1[1] = fsilu(p1[1]); p1[2] = fsilu(p1[2]); p1[3] = fsilu(p1[3]); }
;                     u32x4 w; w.x = cvt_pk_bf16(p0[0], p0[1]); w.y = cvt_pk_bf16(p0[2], p0[3]); w.z = cvt_pk_bf16(p1[0], p1[1]); w.w = cvt_pk_bf16(p1[2], p1[3]);
;                     *(u32x4*)(dst + (size_t)row * 512 + cbase + bj * HALF) = w; } }
.LBB0_490:
	s_nop 0
	v_cvt_pk_bf16_f32 v172, v160, v161
	v_cvt_pk_bf16_f32 v173, v158, v159
	v_cvt_pk_bf16_f32 v174, v156, v157
	v_cvt_pk_bf16_f32 v175, v162, v163
	global_store_dwordx4 v[154:155], v[172:175], off offset:256
	v_or_b32_e32 v154, 48, v148
	v_ashrrev_i32_e32 v155, 31, v154
	v_lshl_add_u64 v[156:157], v[154:155], 2, s[30:31]
	s_and_b64 vcc, exec, s[6:7]
	v_fmamk_f32 v136, v212, 0x3a800000, v170
	v_rsq_f32_e32 v136, v136
	s_nop 0
	v_mov_b32_e32 v156, v136
	v_pk_mul_f32 v[160:161], v[78:79], v[156:157] op_sel_hi:[1,0]
	v_pk_mul_f32 v[164:165], v[76:77], v[156:157] op_sel_hi:[1,0]
	v_pk_mul_f32 v[158:159], v[74:75], v[156:157] op_sel_hi:[1,0]
	v_pk_mul_f32 v[162:163], v[72:73], v[156:157] op_sel_hi:[1,0]
	s_cbranch_vccnz .LBB0_492
	v_mul_f32_e32 v136, 0xbfb8aa3b, v164
	v_exp_f32_e32 v136, v136
	v_mul_f32_e32 v157, 0xbfb8aa3b, v165
	v_mul_f32_e32 v172, 0xbfb8aa3b, v160
	v_exp_f32_e32 v157, v157
	v_exp_f32_e32 v174, v172
	v_add_f32_e32 v136, 1.0, v136
	v_rcp_f32_e32 v172, v136
	v_add_f32_e32 v136, 1.0, v157
	v_mul_f32_e32 v157, 0xbfb8aa3b, v161
	v_rcp_f32_e32 v173, v136
	v_add_f32_e32 v136, 1.0, v174
	v_exp_f32_e32 v157, v157
	v_mul_f32_e32 v174, 0xbfb8aa3b, v162
	v_exp_f32_e32 v176, v174
	v_rcp_f32_e32 v174, v136
	v_add_f32_e32 v136, 1.0, v157
	v_rcp_f32_e32 v175, v136
	v_add_f32_e32 v136, 1.0, v176
	v_mul_f32_e32 v157, 0xbfb8aa3b, v158
	v_rcp_f32_e32 v176, v136
	v_mul_f32_e32 v136, 0xbfb8aa3b, v163
	v_exp_f32_e32 v157, v157
	v_mul_f32_e32 v177, 0xbfb8aa3b, v159
	v_exp_f32_e32 v136, v136
	v_exp_f32_e32 v177, v177
	v_add_f32_e32 v157, 1.0, v157
	v_rcp_f32_e32 v178, v157
	v_add_f32_e32 v136, 1.0, v136
	v_add_f32_e32 v157, 1.0, v177
	v_rcp_f32_e32 v179, v157
	v_rcp_f32_e32 v177, v136
	v_pk_mul_f32 v[160:161], v[160:161], v[174:175]
	v_pk_mul_f32 v[164:165], v[164:165], v[172:173]
	v_pk_mul_f32 v[158:159], v[158:159], v[178:179]
	v_pk_mul_f32 v[162:163], v[162:163], v[176:177]

; __device__ __forceinline__ unsigned cvt_pk_bf16(float lo, float hi) { cvf32x2_t v = {lo, hi}; cvbf16x2_t b = __builtin_convertvector(v, cvbf16x2_t); return __builtin_bit_cast(unsigned, b); }
; __device__ __forceinline__ float fsilu(float x) { return x * fsigm(x); }
; __device__ __forceinline__ float row_rs(const float* ssq, int row) { return ssq ? rsqrtf(ssq[row] * (1.f / 1024.f) + RMS_EPS) : 1.f; }
;     __device__ __forceinline__ void operator()(const f32x4 (&acc)[2][2][4][2], const Unit& u, int wr, int wc, int fr, int fq) const {
;     ...
;         bf16_t* dst = grp == 0 ? QS : (grp == 2 ? VV : (grp == 3 ? GS : BC)); const bool act = (grp == 0) || (grp == 3);
; #pragma unroll
;         for (int ai = 0; ai < 2; ++ai)
; #pragma unroll
;             for (int m = 0; m < 4; ++m) { const int row = row0 + ai * HALF + m * 16; const float rs = row_rs(ssq, row);
; #pragma unroll
;                 for (int bj = 0; bj < 2; ++bj) { f32x4 p0 = acc[ai][bj][m][0] * rs, p1 = acc[ai][bj][m][1] * rs;
;                     if (act) { p0[0] = fsilu(p0[0]); p0[1] = fsilu(p0[1]); p0[2] = fsilu(p0[2]); p0[3] = fsilu(p0[3]); p1[0] = fsilu(p1[0]); p1[1] = fsilu(p1[1]); p1[2] = fsilu(p1[2]); p1[3] = fsilu(p1[3]); }
;                     u32x4 w; w.x = cvt_pk_bf16(p0[0], p0[1]); w.y = cvt_pk_bf16(p0[2], p0[3]); w.z = cvt_pk_bf16(p1[0], p1[1]); w.w = cvt_pk_bf16(p1[2], p1[3]);
;                     *(u32x4*)(dst + (size_t)row * 512 + cbase + bj * HALF) = w; } }
.LBB0_494:
	s_nop 0
	v_cvt_pk_bf16_f32 v172, v160, v161
	v_cvt_pk_bf16_f32 v173, v158, v159
	v_cvt_pk_bf16_f32 v174, v156, v157
	v_cvt_pk_bf16_f32 v175, v162, v163
	global_store_dwordx4 v[154:155], v[172:175], off offset:256
	s_and_b64 vcc, exec, s[6:7]
	v_fmamk_f32 v136, v213, 0x3a800000, v170
	v_rsq_f32_e32 v136, v136
	s_nop 0
	v_mov_b32_e32 v154, v136
	v_pk_mul_f32 v[160:161], v[62:63], v[154:155] op_sel_hi:[1,0]
	v_pk_mul_f32 v[164:165], v[60:61], v[154:155] op_sel_hi:[1,0]
	v_pk_mul_f32 v[158:159], v[58:59], v[154:155] op_sel_hi:[1,0]
	v_pk_mul_f32 v[162:163], v[56:57], v[154:155] op_sel_hi:[1,0]
	s_cbranch_vccnz .LBB0_496
	v_mul_f32_e32 v136, 0xbfb8aa3b, v164
	v_exp_f32_e32 v136, v136
	v_mul_f32_e32 v155, 0xbfb8aa3b, v165
	v_mul_f32_e32 v156, 0xbfb8aa3b, v160
	v_exp_f32_e32 v155, v155
	v_exp_f32_e32 v172, v156
	v_add_f32_e32 v136, 1.0, v136
	v_rcp_f32_e32 v156, v136
	v_add_f32_e32 v136, 1.0, v155
	v_mul_f32_e32 v155, 0xbfb8aa3b, v161
	v_rcp_f32_e32 v157, v136
	v_add_f32_e32 v136, 1.0, v172
	v_exp_f32_e32 v155, v155
	v_mul_f32_e32 v172, 0xbfb8aa3b, v162
	v_exp_f32_e32 v174, v172
	v_rcp_f32_e32 v172, v136
	v_add_f32_e32 v136, 1.0, v155
	v_rcp_f32_e32 v173, v136
	v_add_f32_e32 v136, 1.0, v174
	v_mul_f32_e32 v155, 0xbfb8aa3b, v158
	v_rcp_f32_e32 v174, v136
	v_mul_f32_e32 v136, 0xbfb8aa3b, v163
	v_exp_f32_e32 v155, v155
	v_mul_f32_e32 v175, 0xbfb8aa3b, v159
	v_exp_f32_e32 v136, v136
	v_exp_f32_e32 v175, v175
	v_add_f32_e32 v155, 1.0, v155
	v_rcp_f32_e32 v176, v155
	v_add_f32_e32 v136, 1.0, v136
	v_add_f32_e32 v155, 1.0, v175
	v_rcp_f32_e32 v177, v155
	v_rcp_f32_e32 v175, v136
	v_pk_mul_f32 v[160:161], v[160:161], v[172:173]
	v_pk_mul_f32 v[164:165], v[164:165], v[156:157]
	v_pk_mul_f32 v[158:159], v[158:159], v[176:177]
	v_pk_mul_f32 v[162:163], v[162:163], v[174:175]

; __device__ __forceinline__ unsigned cvt_pk_bf16(float lo, float hi) { cvf32x2_t v = {lo, hi}; cvbf16x2_t b = __builtin_convertvector(v, cvbf16x2_t); return __builtin_bit_cast(unsigned, b); }
; __device__ __forceinline__ float fsilu(float x) { return x * fsigm(x); }
; __device__ __forceinline__ float row_rs(const float* ssq, int row) { return ssq ? rsqrtf(ssq[row] * (1.f / 1024.f) + RMS_EPS) : 1.f; }
;     __device__ __forceinline__ void operator()(const f32x4 (&acc)[2][2][4][2], const Unit& u, int wr, int wc, int fr, int fq) const {
;     ...
;         bf16_t* dst = grp == 0 ? QS : (grp == 2 ? VV : (grp == 3 ? GS : BC)); const bool act = (grp == 0) || (grp == 3);
; #pragma unroll
;         for (int ai = 0; ai < 2; ++ai)
; #pragma unroll
;             for (int m = 0; m < 4; ++m) { const int row = row0 + ai * HALF + m * 16; const float rs = row_rs(ssq, row);
; #pragma unroll
;                 for (int bj = 0; bj < 2; ++bj) { f32x4 p0 = acc[ai][bj][m][0] * rs, p1 = acc[ai][bj][m][1] * rs;
;                     if (act) { p0[0] = fsilu(p0[0]); p0[1] = fsilu(p0[1]); p0[2] = fsilu(p0[2]); p0[3] = fsilu(p0[3]); p1[0] = fsilu(p1[0]); p1[1] = fsilu(p1[1]); p1[2] = fsilu(p1[2]); p1[3] = fsilu(p1[3]); }
;                     u32x4 w; w.x = cvt_pk_bf16(p0[0], p0[1]); w.y = cvt_pk_bf16(p0[2], p0[3]); w.z = cvt_pk_bf16(p1[0], p1[1]); w.w = cvt_pk_bf16(p1[2], p1[3]);
;                     *(u32x4*)(dst + (size_t)row * 512 + cbase + bj * HALF) = w; } }
.LBB0_498:
	v_lshl_add_u64 v[164:165], v[156:157], 0, s[38:39]
	v_cvt_pk_bf16_f32 v156, v160, v161
	v_cvt_pk_bf16_f32 v157, v158, v159
	v_cvt_pk_bf16_f32 v158, v154, v155
	v_cvt_pk_bf16_f32 v159, v162, v163
	global_store_dwordx4 v[164:165], v[156:159], off offset:256
	s_and_b64 vcc, exec, s[6:7]
	v_fmamk_f32 v136, v214, 0x3a800000, v170
	v_rsq_f32_e32 v136, v136
	s_nop 0
	v_mov_b32_e32 v154, v136
	v_pk_mul_f32 v[160:161], v[46:47], v[154:155] op_sel_hi:[1,0]
	v_pk_mul_f32 v[164:165], v[44:45], v[154:155] op_sel_hi:[1,0]
	v_pk_mul_f32 v[158:159], v[42:43], v[154:155] op_sel_hi:[1,0]
	v_pk_mul_f32 v[162:163], v[40:41], v[154:155] op_sel_hi:[1,0]
	s_cbranch_vccnz .LBB0_500
	v_mul_f32_e32 v136, 0xbfb8aa3b, v164
	v_exp_f32_e32 v136, v136
	v_mul_f32_e32 v155, 0xbfb8aa3b, v165
	v_mul_f32_e32 v156, 0xbfb8aa3b, v160
	v_exp_f32_e32 v155, v155
	v_exp_f32_e32 v172, v156
	v_add_f32_e32 v136, 1.0, v136
	v_rcp_f32_e32 v156, v136
	v_add_f32_e32 v136, 1.0, v155
	v_mul_f32_e32 v155, 0xbfb8aa3b, v161
	v_rcp_f32_e32 v157, v136
	v_add_f32_e32 v136, 1.0, v172
	v_exp_f32_e32 v155, v155
	v_mul_f32_e32 v172, 0xbfb8aa3b, v162
	v_exp_f32_e32 v174, v172
	v_rcp_f32_e32 v172, v136
	v_add_f32_e32 v136, 1.0, v155
	v_rcp_f32_e32 v173, v136
	v_add_f32_e32 v136, 1.0, v174
	v_mul_f32_e32 v155, 0xbfb8aa3b, v158
	v_rcp_f32_e32 v174, v136
	v_mul_f32_e32 v136, 0xbfb8aa3b, v163
	v_exp_f32_e32 v155, v155
	v_mul_f32_e32 v175, 0xbfb8aa3b, v159
	v_exp_f32_e32 v136, v136
	v_exp_f32_e32 v175, v175
	v_add_f32_e32 v155, 1.0, v155
	v_rcp_f32_e32 v176, v155
	v_add_f32_e32 v136, 1.0, v136
	v_add_f32_e32 v155, 1.0, v175
	v_rcp_f32_e32 v177, v155
	v_rcp_f32_e32 v175, v136
	v_pk_mul_f32 v[160:161], v[160:161], v[172:173]
	v_pk_mul_f32 v[164:165], v[164:165], v[156:157]
	v_pk_mul_f32 v[158:159], v[158:159], v[176:177]
	v_pk_mul_f32 v[162:163], v[162:163], v[174:175]

; __device__ __forceinline__ unsigned cvt_pk_bf16(float lo, float hi) { cvf32x2_t v = {lo, hi}; cvbf16x2_t b = __builtin_convertvector(v, cvbf16x2_t); return __builtin_bit_cast(unsigned, b); }
; __device__ __forceinline__ float fsilu(float x) { return x * fsigm(x); }
; __device__ __forceinline__ float row_rs(const float* ssq, int row) { return ssq ? rsqrtf(ssq[row] * (1.f / 1024.f) + RMS_EPS) : 1.f; }
;     __device__ __forceinline__ void operator()(const f32x4 (&acc)[2][2][4][2], const Unit& u, int wr, int wc, int fr, int fq) const {
;     ...
;         bf16_t* dst = grp == 0 ? QS : (grp == 2 ? VV : (grp == 3 ? GS : BC)); const bool act = (grp == 0) || (grp == 3);
; #pragma unroll
;         for (int ai = 0; ai < 2; ++ai)
; #pragma unroll
;             for (int m = 0; m < 4; ++m) { const int row = row0 + ai * HALF + m * 16; const float rs = row_rs(ssq, row);
; #pragma unroll
;                 for (int bj = 0; bj < 2; ++bj) { f32x4 p0 = acc[ai][bj][m][0] * rs, p1 = acc[ai][bj][m][1] * rs;
;                     if (act) { p0[0] = fsilu(p0[0]); p0[1] = fsilu(p0[1]); p0[2] = fsilu(p0[2]); p0[3] = fsilu(p0[3]); p1[0] = fsilu(p1[0]); p1[1] = fsilu(p1[1]); p1[2] = fsilu(p1[2]); p1[3] = fsilu(p1[3]); }
;                     u32x4 w; w.x = cvt_pk_bf16(p0[0], p0[1]); w.y = cvt_pk_bf16(p0[2], p0[3]); w.z = cvt_pk_bf16(p1[0], p1[1]); w.w = cvt_pk_bf16(p1[2], p1[3]);
;                     *(u32x4*)(dst + (size_t)row * 512 + cbase + bj * HALF) = w; } }
.LBB0_502:
	v_lshl_add_u64 v[164:165], v[156:157], 0, s[40:41]
	v_cvt_pk_bf16_f32 v156, v160, v161
	v_cvt_pk_bf16_f32 v157, v158, v159
	v_cvt_pk_bf16_f32 v158, v154, v155
	v_cvt_pk_bf16_f32 v159, v162, v163
	global_store_dwordx4 v[164:165], v[156:159], off offset:256
	s_and_b64 vcc, exec, s[6:7]
	v_fmamk_f32 v136, v215, 0x3a800000, v170
	v_rsq_f32_e32 v136, v136
	s_nop 0
	v_mov_b32_e32 v154, v136
	v_pk_mul_f32 v[160:161], v[30:31], v[154:155] op_sel_hi:[1,0]
	v_pk_mul_f32 v[164:165], v[28:29], v[154:155] op_sel_hi:[1,0]
	v_pk_mul_f32 v[158:159], v[26:27], v[154:155] op_sel_hi:[1,0]
	v_pk_mul_f32 v[162:163], v[24:25], v[154:155] op_sel_hi:[1,0]
	s_cbranch_vccnz .LBB0_504
	v_mul_f32_e32 v136, 0xbfb8aa3b, v164
	v_exp_f32_e32 v136, v136
	v_mul_f32_e32 v155, 0xbfb8aa3b, v165
	v_mul_f32_e32 v156, 0xbfb8aa3b, v160
	v_exp_f32_e32 v155, v155
	v_exp_f32_e32 v172, v156
	v_add_f32_e32 v136, 1.0, v136
	v_rcp_f32_e32 v156, v136
	v_add_f32_e32 v136, 1.0, v155
	v_mul_f32_e32 v155, 0xbfb8aa3b, v161
	v_rcp_f32_e32 v157, v136
	v_add_f32_e32 v136, 1.0, v172
	v_exp_f32_e32 v155, v155
	v_mul_f32_e32 v172, 0xbfb8aa3b, v162
	v_exp_f32_e32 v174, v172
	v_rcp_f32_e32 v172, v136
	v_add_f32_e32 v136, 1.0, v155
	v_rcp_f32_e32 v173, v136
	v_add_f32_e32 v136, 1.0, v174
	v_mul_f32_e32 v155, 0xbfb8aa3b, v158
	v_rcp_f32_e32 v174, v136
	v_mul_f32_e32 v136, 0xbfb8aa3b, v163
	v_exp_f32_e32 v155, v155
	v_mul_f32_e32 v175, 0xbfb8aa3b, v159
	v_exp_f32_e32 v136, v136
	v_exp_f32_e32 v175, v175
	v_add_f32_e32 v155, 1.0, v155
	v_rcp_f32_e32 v176, v155
	v_add_f32_e32 v136, 1.0, v136
	v_add_f32_e32 v155, 1.0, v175
	v_rcp_f32_e32 v177, v155
	v_rcp_f32_e32 v175, v136
	v_pk_mul_f32 v[160:161], v[160:161], v[172:173]
	v_pk_mul_f32 v[164:165], v[164:165], v[156:157]
	v_pk_mul_f32 v[158:159], v[158:159], v[176:177]
	v_pk_mul_f32 v[162:163], v[162:163], v[174:175]

; __device__ __forceinline__ unsigned cvt_pk_bf16(float lo, float hi) { cvf32x2_t v = {lo, hi}; cvbf16x2_t b = __builtin_convertvector(v, cvbf16x2_t); return __builtin_bit_cast(unsigned, b); }
; __device__ __forceinline__ float fsilu(float x) { return x * fsigm(x); }
; __device__ __forceinline__ float row_rs(const float* ssq, int row) { return ssq ? rsqrtf(ssq[row] * (1.f / 1024.f) + RMS_EPS) : 1.f; }
;     __device__ __forceinline__ void operator()(const f32x4 (&acc)[2][2][4][2], const Unit& u, int wr, int wc, int fr, int fq) const {
;     ...
;         bf16_t* dst = grp == 0 ? QS : (grp == 2 ? VV : (grp == 3 ? GS : BC)); const bool act = (grp == 0) || (grp == 3);
; #pragma unroll
;         for (int ai = 0; ai < 2; ++ai)
; #pragma unroll
;             for (int m = 0; m < 4; ++m) { const int row = row0 + ai * HALF + m * 16; const float rs = row_rs(ssq, row);
; #pragma unroll
;                 for (int bj = 0; bj < 2; ++bj) { f32x4 p0 = acc[ai][bj][m][0] * rs, p1 = acc[ai][bj][m][1] * rs;
;                     if (act) { p0[0] = fsilu(p0[0]); p0[1] = fsilu(p0[1]); p0[2] = fsilu(p0[2]); p0[3] = fsilu(p0[3]); p1[0] = fsilu(p1[0]); p1[1] = fsilu(p1[1]); p1[2] = fsilu(p1[2]); p1[3] = fsilu(p1[3]); }
;                     u32x4 w; w.x = cvt_pk_bf16(p0[0], p0[1]); w.y = cvt_pk_bf16(p0[2], p0[3]); w.z = cvt_pk_bf16(p1[0], p1[1]); w.w = cvt_pk_bf16(p1[2], p1[3]);
;                     *(u32x4*)(dst + (size_t)row * 512 + cbase + bj * HALF) = w; } }
.LBB0_506:
	v_lshl_add_u64 v[164:165], v[156:157], 0, s[42:43]
	v_cvt_pk_bf16_f32 v156, v160, v161
	v_cvt_pk_bf16_f32 v157, v158, v159
	v_cvt_pk_bf16_f32 v158, v154, v155
	v_cvt_pk_bf16_f32 v159, v162, v163
	global_store_dwordx4 v[164:165], v[156:159], off offset:256
	s_and_b64 vcc, exec, s[6:7]
	v_fmamk_f32 v136, v216, 0x3a800000, v170
	v_rsq_f32_e32 v136, v136
	s_nop 0
	v_mov_b32_e32 v150, v136
	v_pk_mul_f32 v[156:157], v[14:15], v[150:151] op_sel_hi:[1,0]
	v_pk_mul_f32 v[160:161], v[12:13], v[150:151] op_sel_hi:[1,0]
	v_pk_mul_f32 v[154:155], v[10:11], v[150:151] op_sel_hi:[1,0]
	v_pk_mul_f32 v[158:159], v[8:9], v[150:151] op_sel_hi:[1,0]
	s_cbranch_vccnz .LBB0_508
	v_mul_f32_e32 v136, 0xbfb8aa3b, v160
	v_exp_f32_e32 v136, v136
	v_mul_f32_e32 v151, 0xbfb8aa3b, v161
	v_mul_f32_e32 v162, 0xbfb8aa3b, v156
	v_exp_f32_e32 v151, v151
	v_exp_f32_e32 v164, v162
	v_add_f32_e32 v136, 1.0, v136
	v_rcp_f32_e32 v162, v136
	v_add_f32_e32 v136, 1.0, v151
	v_mul_f32_e32 v151, 0xbfb8aa3b, v157
	v_rcp_f32_e32 v163, v136
	v_add_f32_e32 v136, 1.0, v164
	v_exp_f32_e32 v151, v151
	v_mul_f32_e32 v164, 0xbfb8aa3b, v158
	v_exp_f32_e32 v172, v164
	v_rcp_f32_e32 v164, v136
	v_add_f32_e32 v136, 1.0, v151
	v_rcp_f32_e32 v165, v136
	v_add_f32_e32 v136, 1.0, v172
	v_mul_f32_e32 v151, 0xbfb8aa3b, v154
	v_rcp_f32_e32 v172, v136
	v_mul_f32_e32 v136, 0xbfb8aa3b, v159
	v_exp_f32_e32 v151, v151
	v_mul_f32_e32 v173, 0xbfb8aa3b, v155
	v_exp_f32_e32 v136, v136
	v_exp_f32_e32 v173, v173
	v_add_f32_e32 v151, 1.0, v151
	v_rcp_f32_e32 v174, v151
	v_add_f32_e32 v136, 1.0, v136
	v_add_f32_e32 v151, 1.0, v173
	v_rcp_f32_e32 v175, v151
	v_rcp_f32_e32 v173, v136
	v_pk_mul_f32 v[156:157], v[156:157], v[164:165]
	v_pk_mul_f32 v[160:161], v[160:161], v[162:163]
	v_pk_mul_f32 v[154:155], v[154:155], v[174:175]
	v_pk_mul_f32 v[158:159], v[158:159], v[172:173]

; __device__ __forceinline__ float fsigm(float x) { return __builtin_amdgcn_rcpf(1.f + __expf(-x)); }
; __device__ __forceinline__ float row_rs(const float* ssq, int row) { return ssq ? rsqrtf(ssq[row] * (1.f / 1024.f) + RMS_EPS) : 1.f; }
;     __device__ __forceinline__ void operator()(const f32x4 (&acc)[2][2][4][2], const Unit& u, int wr, int wc, int fr, int fq) const {
;     ...
;         if (grp == 1) {
;             float lb[2][2][4];
; #pragma unroll
;             for (int bj = 0; bj < 2; ++bj)
; #pragma unroll
;                 for (int n = 0; n < 2; ++n) { const int c = cbase + bj * HALF + n * 4; const f32x4 l0 = *(const f32x4*)(lbl + c), l1 = *(const f32x4*)(lbl + 512 + c);
; #pragma unroll
;                     for (int j = 0; j < 4; ++j) lb[bj][n][j] = fsigm(l0[j] - l1[j]); }
; #pragma unroll
;             for (int ai = 0; ai < 2; ++ai)
; #pragma unroll
;                 for (int m = 0; m < 4; ++m) { const int row = row0 + ai * HALF + m * 16; const float rs = row_rs(ssq, row);
; #pragma unroll
;                     for (int bj = 0; bj < 2; ++bj) { f16x4 o[2];
; #pragma unroll
;                         for (int n = 0; n < 2; ++n) { const f32x4 p = acc[ai][bj][m][n] * rs;
; #pragma unroll
;                             for (int j = 0; j < 4; ++j) { const float l = lb[bj][n][j]; const float f = l + (1.f - l) * fsigm(p[j]); o[n][j] = (_Float16)__logf(f); } }
;                         const u32x2 a0 = __builtin_bit_cast(u32x2, o[0]), a1 = __builtin_bit_cast(u32x2, o[1]); u32x4 w; w.x = a0.x; w.y = a0.y; w.z = a1.x; w.w = a1.y;
;                         *(u32x4*)(LF + (size_t)row * 512 + cbase + bj * HALF) = w; } }
.LBB0_511:
	s_and_b64 vcc, exec, s[6:7]
	s_cbranch_vccz .LBB0_513
	v_ashrrev_i32_e32 v149, 31, v148
	v_lshlrev_b32_e32 v136, 2, v181
	v_lshl_add_u64 v[150:151], v[148:149], 2, s[30:31]
	global_load_dwordx4 v[152:155], v136, s[12:13] offset:2048
	global_load_dwordx4 v[156:159], v136, s[12:13]
	global_load_dwordx4 v[160:163], v136, s[12:13] offset:16
	global_load_dwordx4 v[172:175], v136, s[12:13] offset:2064
	global_load_dwordx4 v[176:179], v136, s[12:13] offset:2560
	global_load_dwordx4 v[182:185], v136, s[12:13] offset:512
	global_load_dwordx4 v[186:189], v136, s[12:13] offset:528
	global_load_dwordx4 v[190:193], v136, s[12:13] offset:2576
	s_waitcnt vmcnt(0)
	v_sub_f32_e32 v152, v156, v152
	global_load_dword v136, v[150:151], off
	global_load_dword v210, v[150:151], off offset:64
	global_load_dword v211, v[150:151], off offset:128
	global_load_dword v212, v[150:151], off offset:192
	global_load_dword v213, v[150:151], off offset:512
	global_load_dword v214, v[150:151], off offset:576
	global_load_dword v215, v[150:151], off offset:640
	global_load_dword v216, v[150:151], off offset:704
	v_sub_f32_e32 v153, v157, v153
	v_sub_f32_e32 v156, v160, v172
	v_sub_f32_e32 v160, v182, v176
	v_mul_f32_e32 v153, 0xbfb8aa3b, v153
	v_sub_f32_e32 v172, v188, v192
	v_mul_f32_e32 v176, 0xbfb8aa3b, v172
	v_exp_f32_e32 v153, v153
	v_sub_f32_e32 v154, v158, v154
	v_sub_f32_e32 v158, v162, v174
	v_mul_f32_e32 v152, 0xbfb8aa3b, v152
	v_add_f32_e32 v153, 1.0, v153
	v_rcp_f32_e32 v174, v153
	v_exp_f32_e32 v152, v152
	v_sub_f32_e32 v157, v161, v173
	v_sub_f32_e32 v161, v183, v177
	v_sub_f32_e32 v155, v159, v155
	v_mul_f32_e32 v160, 0xbfb8aa3b, v160
	v_mul_f32_e32 v161, 0xbfb8aa3b, v161
	v_add_f32_e32 v152, 1.0, v152
	v_sub_f32_e32 v159, v163, v175
	v_mul_f32_e32 v155, 0xbfb8aa3b, v155
	v_exp_f32_e32 v160, v160
	v_exp_f32_e32 v161, v161
	v_rcp_f32_e32 v175, v152
	v_exp_f32_e32 v155, v155
	v_exp_f32_e32 v152, v176
	v_add_f32_e32 v160, 1.0, v160
	v_add_f32_e32 v177, 1.0, v161
	v_sub_f32_e32 v176, 1.0, v175
	v_sub_f32_e32 v162, v184, v178
	v_add_f32_e32 v155, 1.0, v155
	v_rcp_f32_e32 v161, v160
	v_rcp_f32_e32 v160, v177
	v_add_f32_e32 v152, 1.0, v152
	v_mul_f32_e32 v159, 0xbfb8aa3b, v159
	v_mul_f32_e32 v162, 0xbfb8aa3b, v162
	v_mul_f32_e32 v154, 0xbfb8aa3b, v154
	v_exp_f32_e32 v159, v159
	v_exp_f32_e32 v162, v162
	v_exp_f32_e32 v154, v154
	v_sub_f32_e32 v163, v185, v179
	v_add_f32_e32 v159, 1.0, v159
	v_add_f32_e32 v178, 1.0, v162
	v_mul_f32_e32 v158, 0xbfb8aa3b, v158
	v_mul_f32_e32 v163, 0xbfb8aa3b, v163
	v_add_f32_e32 v154, 1.0, v154
	v_rcp_f32_e32 v162, v159
	v_rcp_f32_e32 v159, v178
	v_exp_f32_e32 v158, v158
	v_exp_f32_e32 v163, v163
	v_rcp_f32_e32 v173, v154
	v_sub_f32_e32 v164, v186, v190
	v_add_f32_e32 v158, 1.0, v158
	v_add_f32_e32 v179, 1.0, v163
	v_rcp_f32_e32 v163, v158
	v_rcp_f32_e32 v158, v179
	v_mul_f32_e32 v157, 0xbfb8aa3b, v157
	v_mul_f32_e32 v164, 0xbfb8aa3b, v164
	v_exp_f32_e32 v157, v157
	v_exp_f32_e32 v164, v164
	v_sub_f32_e32 v165, v187, v191
	v_mul_f32_e32 v156, 0xbfb8aa3b, v156
	v_add_f32_e32 v157, 1.0, v157
	v_add_f32_e32 v180, 1.0, v164
	v_mul_f32_e32 v165, 0xbfb8aa3b, v165
	v_rcp_f32_e32 v164, v157
	v_rcp_f32_e32 v157, v180
	v_exp_f32_e32 v156, v156
	v_exp_f32_e32 v165, v165
	v_add_f32_e32 v156, 1.0, v156
	v_add_f32_e32 v182, 1.0, v165
	v_rcp_f32_e32 v165, v156
	v_rcp_f32_e32 v156, v182
	s_waitcnt vmcnt(0)
	v_fmamk_f32 v136, v136, 0x3a800000, v170
	v_rsq_f32_e32 v136, v136
	v_rcp_f32_e32 v172, v155
	v_rcp_f32_e32 v155, v152
	v_sub_f32_e32 v152, v189, v193
	v_mov_b32_e32 v194, v136
	v_mul_f32_e32 v136, v124, v194
	v_mul_f32_e32 v136, 0xbfb8aa3b, v136
	v_exp_f32_e32 v136, v136
	v_mul_f32_e32 v177, v125, v194
	v_mul_f32_e32 v177, 0xbfb8aa3b, v177
	v_mul_f32_e32 v152, 0xbfb8aa3b, v152
	v_add_f32_e32 v136, 1.0, v136
	v_rcp_f32_e32 v136, v136
	v_exp_f32_e32 v177, v177
	v_exp_f32_e32 v152, v152
	v_sub_f32_e32 v183, 1.0, v172
	v_fma_f32 v136, v176, v136, v175
	v_cmp_gt_f32_e32 vcc, s87, v136
	v_add_f32_e32 v177, 1.0, v177
	v_add_f32_e32 v152, 1.0, v152
	v_cndmask_b32_e64 v153, 0, 32, vcc
	v_ldexp_f32 v136, v136, v153
	v_log_f32_e32 v136, v136
	v_rcp_f32_e32 v178, v177
	v_rcp_f32_e32 v154, v152
	v_lshlrev_b64 v[152:153], 10, v[148:149]
	v_mul_f32_e32 v149, 0x3f317217, v136
	v_fma_f32 v149, v136, s92, -v149
	v_fmac_f32_e32 v149, 0x3377d1cf, v136
	v_sub_f32_e32 v177, 1.0, v174
	v_fmac_f32_e32 v149, 0x3f317217, v136
	v_cmp_lt_f32_e64 s[6:7], |v136|, s93
	v_fma_f32 v178, v177, v178, v174
	v_lshl_add_u64 v[152:153], s[28:29], 0, v[152:153]
	v_cndmask_b32_e64 v136, v136, v149, s[6:7]
	v_cndmask_b32_e32 v149, 0, v171, vcc
	v_cmp_gt_f32_e32 vcc, s87, v178
	v_sub_f32_e32 v136, v136, v149
	s_nop 0
	v_cndmask_b32_e64 v179, 0, 32, vcc
	v_ldexp_f32 v178, v178, v179
	v_log_f32_e32 v179, v178
	v_mul_f32_e32 v178, v126, v194
	v_mul_f32_e32 v178, 0xbfb8aa3b, v178
	v_exp_f32_e32 v178, v178
	v_mul_f32_e32 v149, 0x3f317217, v179
	v_fma_f32 v149, v179, s92, -v149
	v_fmac_f32_e32 v149, 0x3377d1cf, v179
	v_add_f32_e32 v178, 1.0, v178
	v_rcp_f32_e32 v180, v178
	v_sub_f32_e32 v178, 1.0, v173
	v_fmac_f32_e32 v149, 0x3f317217, v179
	v_cmp_lt_f32_e64 s[8:9], |v179|, s93
	v_fma_f32 v180, v178, v180, v173
	v_cmp_gt_f32_e64 s[6:7], s87, v180
	v_cndmask_b32_e64 v149, v179, v149, s[8:9]
	v_cndmask_b32_e32 v179, 0, v171, vcc
	v_cndmask_b32_e64 v182, 0, 32, s[6:7]
	v_ldexp_f32 v180, v180, v182
	v_sub_f32_e32 v182, v149, v179
	v_mul_f32_e32 v179, v127, v194
	v_mul_f32_e32 v179, 0xbfb8aa3b, v179
	v_exp_f32_e32 v179, v179
	v_log_f32_e32 v180, v180
	v_add_f32_e32 v179, 1.0, v179
	v_rcp_f32_e32 v179, v179
	v_mul_f32_e32 v149, 0x3f317217, v180
	v_fma_f32 v149, v180, s92, -v149
; __device__ __forceinline__ float fsigm(float x) { return __builtin_amdgcn_rcpf(1.f + __expf(-x)); }
; __device__ __forceinline__ float row_rs(const float* ssq, int row) { return ssq ? rsqrtf(ssq[row] * (1.f / 1024.f) + RMS_EPS) : 1.f; }
;     __device__ __forceinline__ void operator()(const f32x4 (&acc)[2][2][4][2], const Unit& u, int wr, int wc, int fr, int fq) const {
;     ...
;                 for (int m = 0; m < 4; ++m) { const int row = row0 + ai * HALF + m * 16; const float rs = row_rs(ssq, row);
; #pragma unroll
;                     for (int bj = 0; bj < 2; ++bj) { f16x4 o[2];
; #pragma unroll
;                         for (int n = 0; n < 2; ++n) { const f32x4 p = acc[ai][bj][m][n] * rs;
; #pragma unroll
;                             for (int j = 0; j < 4; ++j) { const float l = lb[bj][n][j]; const float f = l + (1.f - l) * fsigm(p[j]); o[n][j] = (_Float16)__logf(f); } }
;                         const u32x2 a0 = __builtin_bit_cast(u32x2, o[0]), a1 = __builtin_bit_cast(u32x2, o[1]); u32x4 w; w.x = a0.x; w.y = a0.y; w.z = a1.x; w.w = a1.y;
;                         *(u32x4*)(LF + (size_t)row * 512 + cbase + bj * HALF) = w; } }
	v_fmac_f32_e32 v149, 0x3377d1cf, v180
	v_fmac_f32_e32 v149, 0x3f317217, v180
	v_cmp_lt_f32_e64 vcc, |v180|, s93
	v_fma_f32 v179, v183, v179, v172
	s_nop 0
	v_cndmask_b32_e32 v149, v180, v149, vcc
	v_cmp_gt_f32_e32 vcc, s87, v179
	v_cndmask_b32_e64 v180, 0, v171, s[6:7]
	v_sub_f32_e32 v185, v149, v180
	v_cndmask_b32_e64 v184, 0, 32, vcc
	v_ldexp_f32 v179, v179, v184
	v_mul_f32_e32 v184, v120, v194
	v_log_f32_e32 v179, v179
	v_mul_f32_e32 v184, 0xbfb8aa3b, v184
	v_exp_f32_e32 v184, v184
	v_mul_f32_e32 v149, 0x3f317217, v179
	v_fma_f32 v180, v179, s92, -v149
	v_add_f32_e32 v149, 1.0, v184
	v_rcp_f32_e32 v184, v149
	v_sub_f32_e32 v149, 1.0, v165
	v_fmac_f32_e32 v180, 0x3377d1cf, v179
	v_fmac_f32_e32 v180, 0x3f317217, v179
	v_fma_f32 v184, v149, v184, v165
	v_cmp_gt_f32_e64 s[6:7], s87, v184
	v_cmp_lt_f32_e64 s[8:9], |v179|, s93
	s_nop 0
	v_cndmask_b32_e64 v186, 0, 32, s[6:7]
	v_cndmask_b32_e64 v179, v179, v180, s[8:9]
	v_cndmask_b32_e32 v180, 0, v171, vcc
	v_ldexp_f32 v184, v184, v186
	v_sub_f32_e32 v186, v179, v180
	v_mul_f32_e32 v180, v121, v194
	v_mul_f32_e32 v180, 0xbfb8aa3b, v180
	v_log_f32_e32 v184, v184
	v_exp_f32_e32 v180, v180
	v_cndmask_b32_e64 v187, 0, v171, s[6:7]
	v_mul_f32_e32 v179, 0x3f317217, v184
	v_add_f32_e32 v180, 1.0, v180
	v_fma_f32 v179, v184, s92, -v179
	v_rcp_f32_e32 v180, v180
	v_fmac_f32_e32 v179, 0x3377d1cf, v184
	v_fmac_f32_e32 v179, 0x3f317217, v184
	v_cmp_lt_f32_e64 vcc, |v184|, s93
	s_nop 1
	v_cndmask_b32_e32 v184, v184, v179, vcc
	v_sub_f32_e32 v179, 1.0, v164
	v_fma_f32 v180, v179, v180, v164
	v_cmp_gt_f32_e32 vcc, s87, v180
	v_sub_f32_e32 v184, v184, v187
	s_nop 0
	v_cndmask_b32_e64 v188, 0, 32, vcc
	v_ldexp_f32 v180, v180, v188
	v_log_f32_e32 v188, v180
	v_mul_f32_e32 v180, v122, v194
	v_mul_f32_e32 v180, 0xbfb8aa3b, v180
	v_exp_f32_e32 v180, v180
	v_mul_f32_e32 v187, 0x3f317217, v188
	v_fma_f32 v187, v188, s92, -v187
	v_fmac_f32_e32 v187, 0x3377d1cf, v188
	v_add_f32_e32 v180, 1.0, v180
	v_rcp_f32_e32 v189, v180
	v_sub_f32_e32 v180, 1.0, v163
	v_fmac_f32_e32 v187, 0x3f317217, v188
	v_cmp_lt_f32_e64 s[8:9], |v188|, s93
	v_fma_f32 v189, v180, v189, v163
	v_cmp_gt_f32_e64 s[6:7], s87, v189
	v_cndmask_b32_e64 v187, v188, v187, s[8:9]
	v_cndmask_b32_e32 v188, 0, v171, vcc
	v_cndmask_b32_e64 v190, 0, 32, s[6:7]
	v_ldexp_f32 v189, v189, v190
	v_mul_f32_e32 v190, v123, v194
	v_mul_f32_e32 v190, 0xbfb8aa3b, v190
	v_log_f32_e32 v189, v189
	v_exp_f32_e32 v190, v190
	v_sub_f32_e32 v187, v187, v188
	v_cndmask_b32_e64 v191, 0, v171, s[6:7]
	v_mul_f32_e32 v188, 0x3f317217, v189
	v_add_f32_e32 v190, 1.0, v190
	v_fma_f32 v188, v189, s92, -v188
	v_rcp_f32_e32 v190, v190
	v_fmac_f32_e32 v188, 0x3377d1cf, v189
	v_fmac_f32_e32 v188, 0x3f317217, v189
	v_cmp_lt_f32_e64 vcc, |v189|, s93
	s_nop 1
	v_cndmask_b32_e32 v189, v189, v188, vcc
	v_sub_f32_e32 v188, 1.0, v162
	v_fma_f32 v190, v188, v190, v162
	v_cmp_gt_f32_e32 vcc, s87, v190
	v_sub_f32_e32 v189, v189, v191
	v_cvt_pk_f16_f32 v191, v185, v186
	v_cndmask_b32_e64 v192, 0, 32, vcc
	v_ldexp_f32 v190, v190, v192
	v_log_f32_e32 v192, v190
	v_cvt_pk_f16_f32 v190, v136, v182
	v_cndmask_b32_e32 v182, 0, v171, vcc
	v_mul_f32_e32 v136, 0x3f317217, v192
	v_fma_f32 v136, v192, s92, -v136
	v_fmac_f32_e32 v136, 0x3377d1cf, v192
	v_fmac_f32_e32 v136, 0x3f317217, v192
	v_cmp_lt_f32_e64 s[6:7], |v192|, s93
	s_nop 1
	v_cndmask_b32_e64 v136, v192, v136, s[6:7]
	v_sub_f32_e32 v136, v136, v182
	v_mul_f32_e32 v182, v116, v194
	v_mul_f32_e32 v182, 0xbfb8aa3b, v182
	v_exp_f32_e32 v182, v182
	v_cvt_pk_f16_f32 v193, v189, v136
	v_cvt_pk_f16_f32 v192, v184, v187
	v_sub_f32_e32 v184, 1.0, v161
	v_add_f32_e32 v136, 1.0, v182
	v_rcp_f32_e32 v182, v136
	v_lshlrev_b32_e32 v136, 1, v181
	v_lshl_add_u64 v[152:153], v[152:153], 0, v[136:137]
	global_store_dwordx4 v[152:153], v[190:193], off
	v_fma_f32 v181, v184, v182, v161
	v_cmp_gt_f32_e32 vcc, s87, v181
	s_nop 1
	v_cndmask_b32_e64 v182, 0, 32, vcc
	v_ldexp_f32 v181, v181, v182
	v_log_f32_e32 v182, v181
	v_mul_f32_e32 v181, v117, v194
	v_mul_f32_e32 v181, 0xbfb8aa3b, v181
	v_exp_f32_e32 v181, v181
	v_mul_f32_e32 v185, 0x3f317217, v182
	v_fma_f32 v185, v182, s92, -v185
	v_fmac_f32_e32 v185, 0x3377d1cf, v182
	v_add_f32_e32 v181, 1.0, v181
	v_rcp_f32_e32 v186, v181
	v_sub_f32_e32 v181, 1.0, v160
	v_fmac_f32_e32 v185, 0x3f317217, v182
	v_cmp_lt_f32_e64 s[8:9], |v182|, s93
	v_fma_f32 v186, v181, v186, v160
	v_cmp_gt_f32_e64 s[6:7], s87, v186
	v_cndmask_b32_e64 v182, v182, v185, s[8:9]
	v_cndmask_b32_e32 v185, 0, v171, vcc
	v_cndmask_b32_e64 v187, 0, 32, s[6:7]
	v_ldexp_f32 v186, v186, v187
	v_mul_f32_e32 v187, v118, v194
	v_mul_f32_e32 v187, 0xbfb8aa3b, v187
	v_log_f32_e32 v186, v186
	v_exp_f32_e32 v187, v187
	v_sub_f32_e32 v182, v182, v185
	v_cndmask_b32_e64 v189, 0, v171, s[6:7]
	v_mul_f32_e32 v185, 0x3f317217, v186
	v_add_f32_e32 v187, 1.0, v187
	v_fma_f32 v185, v186, s92, -v185
	v_rcp_f32_e32 v187, v187
	v_fmac_f32_e32 v185, 0x3377d1cf, v186
	v_fmac_f32_e32 v185, 0x3f317217, v186
	v_cmp_lt_f32_e64 vcc, |v186|, s93
	s_nop 1
	v_cndmask_b32_e32 v186, v186, v185, vcc
	v_sub_f32_e32 v185, 1.0, v159
	v_fma_f32 v187, v185, v187, v159
	v_cmp_gt_f32_e32 vcc, s87, v187
	v_sub_f32_e32 v189, v186, v189
	s_nop 0
	v_cndmask_b32_e64 v190, 0, 32, vcc
	v_ldexp_f32 v187, v187, v190
	v_mul_f32_e32 v190, v119, v194
	v_log_f32_e32 v187, v187
	v_mul_f32_e32 v190, 0xbfb8aa3b, v190
	v_exp_f32_e32 v190, v190
	v_mul_f32_e32 v186, 0x3f317217, v187
	v_fma_f32 v191, v187, s92, -v186
	v_add_f32_e32 v186, 1.0, v190
	v_rcp_f32_e32 v190, v186
	v_sub_f32_e32 v186, 1.0, v158
	v_fmac_f32_e32 v191, 0x3377d1cf, v187
	v_fmac_f32_e32 v191, 0x3f317217, v187
	v_fma_f32 v190, v186, v190, v158
; __device__ __forceinline__ float fsigm(float x) { return __builtin_amdgcn_rcpf(1.f + __expf(-x)); }
; __device__ __forceinline__ float row_rs(const float* ssq, int row) { return ssq ? rsqrtf(ssq[row] * (1.f / 1024.f) + RMS_EPS) : 1.f; }
;     __device__ __forceinline__ void operator()(const f32x4 (&acc)[2][2][4][2], const Unit& u, int wr, int wc, int fr, int fq) const {
;     ...
;                 for (int m = 0; m < 4; ++m) { const int row = row0 + ai * HALF + m * 16; const float rs = row_rs(ssq, row);
; #pragma unroll
;                     for (int bj = 0; bj < 2; ++bj) { f16x4 o[2];
; #pragma unroll
;                         for (int n = 0; n < 2; ++n) { const f32x4 p = acc[ai][bj][m][n] * rs;
; #pragma unroll
;                             for (int j = 0; j < 4; ++j) { const float l = lb[bj][n][j]; const float f = l + (1.f - l) * fsigm(p[j]); o[n][j] = (_Float16)__logf(f); } }
;                         const u32x2 a0 = __builtin_bit_cast(u32x2, o[0]), a1 = __builtin_bit_cast(u32x2, o[1]); u32x4 w; w.x = a0.x; w.y = a0.y; w.z = a1.x; w.w = a1.y;
;                         *(u32x4*)(LF + (size_t)row * 512 + cbase + bj * HALF) = w; } }
	v_cmp_gt_f32_e64 s[6:7], s87, v190
	v_cmp_lt_f32_e64 s[8:9], |v187|, s93
	s_nop 0
	v_cndmask_b32_e64 v192, 0, 32, s[6:7]
	v_ldexp_f32 v190, v190, v192
	v_log_f32_e32 v190, v190
	v_mul_f32_e32 v192, v112, v194
	v_mul_f32_e32 v192, 0xbfb8aa3b, v192
	v_exp_f32_e32 v192, v192
	v_cndmask_b32_e64 v187, v187, v191, s[8:9]
	v_cndmask_b32_e32 v191, 0, v171, vcc
	v_sub_f32_e32 v187, v187, v191
	v_mul_f32_e32 v191, 0x3f317217, v190
	v_fma_f32 v191, v190, s92, -v191
	v_fmac_f32_e32 v191, 0x3377d1cf, v190
	v_add_f32_e32 v192, 1.0, v192
	v_fmac_f32_e32 v191, 0x3f317217, v190
	v_cmp_lt_f32_e64 vcc, |v190|, s93
	v_rcp_f32_e32 v192, v192
	s_nop 0
	v_cndmask_b32_e32 v190, v190, v191, vcc
	v_cndmask_b32_e64 v191, 0, v171, s[6:7]
	v_sub_f32_e32 v190, v190, v191
	v_cvt_pk_f16_f32 v193, v187, v190
	v_sub_f32_e32 v187, 1.0, v157
	v_fma_f32 v190, v187, v192, v157
	v_cmp_gt_f32_e32 vcc, s87, v190
	v_cvt_pk_f16_f32 v192, v182, v189
	s_nop 0
	v_cndmask_b32_e64 v191, 0, 32, vcc
	v_ldexp_f32 v190, v190, v191
	v_mul_f32_e32 v191, v113, v194
	v_log_f32_e32 v190, v190
	v_mul_f32_e32 v191, 0xbfb8aa3b, v191
	v_exp_f32_e32 v191, v191
	v_mul_f32_e32 v182, 0x3f317217, v190
	v_fma_f32 v189, v190, s92, -v182
	v_add_f32_e32 v182, 1.0, v191
	v_rcp_f32_e32 v191, v182
	v_fmac_f32_e32 v189, 0x3377d1cf, v190
	v_sub_f32_e32 v182, 1.0, v156
	v_fmac_f32_e32 v189, 0x3f317217, v190
	v_fma_f32 v191, v182, v191, v156
	v_cmp_lt_f32_e64 s[8:9], |v190|, s93
	v_cmp_gt_f32_e64 s[6:7], s87, v191
	s_nop 0
	v_cndmask_b32_e64 v189, v190, v189, s[8:9]
	v_cndmask_b32_e32 v190, 0, v171, vcc
	v_cndmask_b32_e64 v195, 0, 32, s[6:7]
	v_sub_f32_e32 v196, v189, v190
	v_mul_f32_e32 v190, v114, v194
	v_ldexp_f32 v191, v191, v195
	v_mul_f32_e32 v190, 0xbfb8aa3b, v190
	v_log_f32_e32 v191, v191
	v_exp_f32_e32 v190, v190
	v_cndmask_b32_e64 v195, 0, v171, s[6:7]
	v_mul_f32_e32 v189, 0x3f317217, v191
	v_add_f32_e32 v190, 1.0, v190
	v_fma_f32 v189, v191, s92, -v189
	v_rcp_f32_e32 v190, v190
	v_fmac_f32_e32 v189, 0x3377d1cf, v191
	v_fmac_f32_e32 v189, 0x3f317217, v191
	v_cmp_lt_f32_e64 vcc, |v191|, s93
	s_nop 1
	v_cndmask_b32_e32 v191, v191, v189, vcc
	v_sub_f32_e32 v189, 1.0, v155
	v_fma_f32 v190, v189, v190, v155
	v_cmp_gt_f32_e32 vcc, s87, v190
	v_sub_f32_e32 v191, v191, v195
	s_nop 0
	v_cndmask_b32_e64 v197, 0, 32, vcc
	v_ldexp_f32 v190, v190, v197
	v_log_f32_e32 v197, v190
	v_mul_f32_e32 v190, v115, v194
	v_mul_f32_e32 v190, 0xbfb8aa3b, v190
	v_exp_f32_e32 v190, v190
	v_mul_f32_e32 v194, 0x3f317217, v197
	v_fma_f32 v194, v197, s92, -v194
	v_fmac_f32_e32 v194, 0x3377d1cf, v197
	v_add_f32_e32 v190, 1.0, v190
	v_rcp_f32_e32 v195, v190
	v_sub_f32_e32 v190, 1.0, v154
	v_fmac_f32_e32 v194, 0x3f317217, v197
	v_cmp_lt_f32_e64 s[8:9], |v197|, s93
	v_fma_f32 v195, v190, v195, v154
	v_cmp_gt_f32_e64 s[6:7], s87, v195
	v_cndmask_b32_e64 v194, v197, v194, s[8:9]
	v_cndmask_b32_e32 v197, 0, v171, vcc
	v_cndmask_b32_e64 v198, 0, 32, s[6:7]
	v_ldexp_f32 v195, v195, v198
	v_log_f32_e32 v195, v195
	v_sub_f32_e32 v194, v194, v197
	v_mul_f32_e32 v197, 0x3f317217, v195
	v_fma_f32 v197, v195, s92, -v197
	v_fmac_f32_e32 v197, 0x3377d1cf, v195
	v_fmac_f32_e32 v197, 0x3f317217, v195
	v_cmp_lt_f32_e64 vcc, |v195|, s93
	s_nop 1
	v_cndmask_b32_e32 v195, v195, v197, vcc
	v_cndmask_b32_e64 v197, 0, v171, s[6:7]
	v_sub_f32_e32 v195, v195, v197
	v_cvt_pk_f16_f32 v195, v194, v195
	v_cvt_pk_f16_f32 v194, v196, v191
	global_store_dwordx4 v[152:153], v[192:195], off offset:256
	s_nop 1
	v_or_b32_e32 v192, 16, v148
	v_ashrrev_i32_e32 v193, 31, v192
	v_lshl_add_u64 v[194:195], v[192:193], 2, s[30:31]
	v_lshlrev_b64 v[196:197], 10, v[192:193]
	v_lshl_add_u64 v[196:197], s[28:29], 0, v[196:197]
	v_lshl_add_u64 v[196:197], v[196:197], 0, v[136:137]
	v_fmamk_f32 v191, v210, 0x3a800000, v170
	v_rsq_f32_e32 v191, v191
	s_nop 0
	v_mul_f32_e32 v194, v108, v191
	v_mul_f32_e32 v194, 0xbfb8aa3b, v194
	v_exp_f32_e32 v194, v194
	v_mul_f32_e32 v193, v109, v191
	v_mul_f32_e32 v193, 0xbfb8aa3b, v193
	v_exp_f32_e32 v193, v193
	v_add_f32_e32 v194, 1.0, v194
	v_rcp_f32_e32 v194, v194
	v_add_f32_e32 v193, 1.0, v193
	v_rcp_f32_e32 v193, v193
	v_fma_f32 v194, v176, v194, v175
	v_cmp_gt_f32_e32 vcc, s87, v194
	v_fma_f32 v193, v177, v193, v174
	s_nop 0
	v_cndmask_b32_e64 v195, 0, 32, vcc
	v_ldexp_f32 v194, v194, v195
	v_log_f32_e32 v194, v194
	s_nop 0
	v_mul_f32_e32 v192, 0x3f317217, v194
	v_fma_f32 v192, v194, s92, -v192
	v_fmac_f32_e32 v192, 0x3377d1cf, v194
	v_fmac_f32_e32 v192, 0x3f317217, v194
	v_cmp_lt_f32_e64 s[6:7], |v194|, s93
	s_nop 1
	v_cndmask_b32_e64 v192, v194, v192, s[6:7]
	v_cndmask_b32_e32 v194, 0, v171, vcc
	v_cmp_gt_f32_e32 vcc, s87, v193
	v_sub_f32_e32 v192, v192, v194
	s_nop 0
	v_cndmask_b32_e64 v194, 0, 32, vcc
	v_ldexp_f32 v193, v193, v194
	v_mul_f32_e32 v194, v110, v191
	v_mul_f32_e32 v194, 0xbfb8aa3b, v194
	v_exp_f32_e32 v194, v194
	v_log_f32_e32 v193, v193
	v_cndmask_b32_e32 v198, 0, v171, vcc
	v_add_f32_e32 v194, 1.0, v194
	v_rcp_f32_e32 v194, v194
	v_mul_f32_e32 v195, 0x3f317217, v193
	v_fma_f32 v195, v193, s92, -v195
	v_fmac_f32_e32 v195, 0x3377d1cf, v193
	v_fmac_f32_e32 v195, 0x3f317217, v193
	v_cmp_lt_f32_e64 s[6:7], |v193|, s93
	v_fma_f32 v194, v178, v194, v173
	s_nop 0
	v_cndmask_b32_e64 v193, v193, v195, s[6:7]
	v_cmp_gt_f32_e64 s[6:7], s87, v194
	v_sub_f32_e32 v198, v193, v198
	v_cvt_pk_f16_f32 v192, v192, v198
	v_cndmask_b32_e64 v195, 0, 32, s[6:7]
	v_ldexp_f32 v194, v194, v195
	v_mul_f32_e32 v195, v111, v191
	v_mul_f32_e32 v195, 0xbfb8aa3b, v195
	v_exp_f32_e32 v195, v195
	v_log_f32_e32 v194, v194
	v_add_f32_e32 v195, 1.0, v195
	v_rcp_f32_e32 v195, v195
	v_mul_f32_e32 v193, 0x3f317217, v194
	v_fma_f32 v193, v194, s92, -v193
; __device__ __forceinline__ float fsigm(float x) { return __builtin_amdgcn_rcpf(1.f + __expf(-x)); }
; __device__ __forceinline__ float row_rs(const float* ssq, int row) { return ssq ? rsqrtf(ssq[row] * (1.f / 1024.f) + RMS_EPS) : 1.f; }
;     __device__ __forceinline__ void operator()(const f32x4 (&acc)[2][2][4][2], const Unit& u, int wr, int wc, int fr, int fq) const {
;     ...
;                 for (int m = 0; m < 4; ++m) { const int row = row0 + ai * HALF + m * 16; const float rs = row_rs(ssq, row);
; #pragma unroll
;                     for (int bj = 0; bj < 2; ++bj) { f16x4 o[2];
; #pragma unroll
;                         for (int n = 0; n < 2; ++n) { const f32x4 p = acc[ai][bj][m][n] * rs;
; #pragma unroll
;                             for (int j = 0; j < 4; ++j) { const float l = lb[bj][n][j]; const float f = l + (1.f - l) * fsigm(p[j]); o[n][j] = (_Float16)__logf(f); } }
;                         const u32x2 a0 = __builtin_bit_cast(u32x2, o[0]), a1 = __builtin_bit_cast(u32x2, o[1]); u32x4 w; w.x = a0.x; w.y = a0.y; w.z = a1.x; w.w = a1.y;
;                         *(u32x4*)(LF + (size_t)row * 512 + cbase + bj * HALF) = w; } }
	v_fmac_f32_e32 v193, 0x3377d1cf, v194
	v_fma_f32 v195, v183, v195, v172
	v_cmp_gt_f32_e32 vcc, s87, v195
	v_fmac_f32_e32 v193, 0x3f317217, v194
	v_cmp_lt_f32_e64 s[8:9], |v194|, s93
	v_cndmask_b32_e64 v199, 0, 32, vcc
	v_ldexp_f32 v195, v195, v199
	v_mul_f32_e32 v199, v104, v191
	v_mul_f32_e32 v199, 0xbfb8aa3b, v199
	v_log_f32_e32 v195, v195
	v_exp_f32_e32 v199, v199
	v_cndmask_b32_e64 v193, v194, v193, s[8:9]
	v_cndmask_b32_e64 v194, 0, v171, s[6:7]
	v_sub_f32_e32 v193, v193, v194
	v_mul_f32_e32 v194, 0x3f317217, v195
	v_add_f32_e32 v199, 1.0, v199
	v_fma_f32 v194, v195, s92, -v194
	v_rcp_f32_e32 v199, v199
	v_fmac_f32_e32 v194, 0x3377d1cf, v195
	v_fmac_f32_e32 v194, 0x3f317217, v195
	v_cmp_lt_f32_e64 s[6:7], |v195|, s93
	v_fma_f32 v199, v149, v199, v165
	s_nop 0
	v_cndmask_b32_e64 v194, v195, v194, s[6:7]
	v_cndmask_b32_e32 v195, 0, v171, vcc
	v_sub_f32_e32 v194, v194, v195
	v_mul_f32_e32 v195, v105, v191
	v_cmp_gt_f32_e32 vcc, s87, v199
	v_mul_f32_e32 v195, 0xbfb8aa3b, v195
	v_exp_f32_e32 v195, v195
	v_cndmask_b32_e64 v200, 0, 32, vcc
	v_ldexp_f32 v199, v199, v200
	v_log_f32_e32 v199, v199
	v_add_f32_e32 v195, 1.0, v195
	v_rcp_f32_e32 v195, v195
	v_cvt_pk_f16_f32 v193, v193, v194
	v_mul_f32_e32 v194, 0x3f317217, v199
	v_fma_f32 v194, v199, s92, -v194
	v_fmac_f32_e32 v194, 0x3377d1cf, v199
	v_fmac_f32_e32 v194, 0x3f317217, v199
	v_cmp_lt_f32_e64 s[6:7], |v199|, s93
	v_fma_f32 v195, v179, v195, v164
	v_cndmask_b32_e32 v198, 0, v171, vcc
	v_cndmask_b32_e64 v194, v199, v194, s[6:7]
	v_cmp_gt_f32_e32 vcc, s87, v195
	v_sub_f32_e32 v194, v194, v198
	s_nop 0
	v_cndmask_b32_e64 v198, 0, 32, vcc
	v_ldexp_f32 v195, v195, v198
	v_mul_f32_e32 v198, v106, v191
	v_mul_f32_e32 v198, 0xbfb8aa3b, v198
	v_exp_f32_e32 v198, v198
	v_log_f32_e32 v195, v195
	v_cndmask_b32_e32 v200, 0, v171, vcc
	v_add_f32_e32 v198, 1.0, v198
	v_rcp_f32_e32 v198, v198
	v_mul_f32_e32 v199, 0x3f317217, v195
	v_fma_f32 v199, v195, s92, -v199
	v_fmac_f32_e32 v199, 0x3377d1cf, v195
	v_fmac_f32_e32 v199, 0x3f317217, v195
	v_cmp_lt_f32_e64 s[6:7], |v195|, s93
	v_fma_f32 v198, v180, v198, v163
	s_nop 0
	v_cndmask_b32_e64 v195, v195, v199, s[6:7]
	v_cmp_gt_f32_e64 s[6:7], s87, v198
	v_sub_f32_e32 v200, v195, v200
	v_cvt_pk_f16_f32 v194, v194, v200
	v_cndmask_b32_e64 v199, 0, 32, s[6:7]
	v_ldexp_f32 v198, v198, v199
	v_mul_f32_e32 v199, v107, v191
	v_mul_f32_e32 v199, 0xbfb8aa3b, v199
	v_exp_f32_e32 v199, v199
	v_log_f32_e32 v198, v198
	v_add_f32_e32 v199, 1.0, v199
	v_rcp_f32_e32 v199, v199
	v_mul_f32_e32 v195, 0x3f317217, v198
	v_fma_f32 v195, v198, s92, -v195
	v_fmac_f32_e32 v195, 0x3377d1cf, v198
	v_fma_f32 v199, v188, v199, v162
	v_cmp_gt_f32_e32 vcc, s87, v199
	v_fmac_f32_e32 v195, 0x3f317217, v198
	v_cmp_lt_f32_e64 s[8:9], |v198|, s93
	v_cndmask_b32_e64 v201, 0, 32, vcc
	v_ldexp_f32 v199, v199, v201
	v_log_f32_e32 v199, v199
	v_mul_f32_e32 v201, v100, v191
	v_mul_f32_e32 v201, 0xbfb8aa3b, v201
	v_exp_f32_e32 v201, v201
	v_cndmask_b32_e64 v195, v198, v195, s[8:9]
	v_cndmask_b32_e64 v198, 0, v171, s[6:7]
	v_sub_f32_e32 v195, v195, v198
	v_mul_f32_e32 v198, 0x3f317217, v199
	v_fma_f32 v198, v199, s92, -v198
	v_fmac_f32_e32 v198, 0x3377d1cf, v199
	v_add_f32_e32 v201, 1.0, v201
	v_fmac_f32_e32 v198, 0x3f317217, v199
	v_cmp_lt_f32_e64 s[6:7], |v199|, s93
	v_rcp_f32_e32 v201, v201
	s_nop 0
	v_cndmask_b32_e64 v198, v199, v198, s[6:7]
	v_cndmask_b32_e32 v199, 0, v171, vcc
	v_sub_f32_e32 v198, v198, v199
	v_cvt_pk_f16_f32 v195, v195, v198
	v_fma_f32 v198, v184, v201, v161
	global_store_dwordx4 v[196:197], v[192:195], off
	v_cmp_gt_f32_e32 vcc, s87, v198
	s_nop 0
	v_mul_f32_e32 v193, v101, v191
	v_mul_f32_e32 v193, 0xbfb8aa3b, v193
	v_cndmask_b32_e64 v199, 0, 32, vcc
	v_exp_f32_e32 v193, v193
	v_ldexp_f32 v198, v198, v199
	v_log_f32_e32 v198, v198
	v_cndmask_b32_e32 v194, 0, v171, vcc
	v_add_f32_e32 v193, 1.0, v193
	v_rcp_f32_e32 v193, v193
	v_mul_f32_e32 v192, 0x3f317217, v198
	v_fma_f32 v192, v198, s92, -v192
	v_fmac_f32_e32 v192, 0x3377d1cf, v198
	v_fmac_f32_e32 v192, 0x3f317217, v198
	v_cmp_lt_f32_e64 s[6:7], |v198|, s93
	v_fma_f32 v193, v181, v193, v160
	v_cmp_gt_f32_e32 vcc, s87, v193
	v_cndmask_b32_e64 v192, v198, v192, s[6:7]
	v_sub_f32_e32 v192, v192, v194
	v_cndmask_b32_e64 v194, 0, 32, vcc
	v_ldexp_f32 v193, v193, v194
	v_mul_f32_e32 v194, v102, v191
	v_mul_f32_e32 v194, 0xbfb8aa3b, v194
	v_exp_f32_e32 v194, v194
	v_log_f32_e32 v193, v193
	v_cndmask_b32_e32 v198, 0, v171, vcc
	v_add_f32_e32 v194, 1.0, v194
	v_rcp_f32_e32 v194, v194
	v_mul_f32_e32 v195, 0x3f317217, v193
	v_fma_f32 v195, v193, s92, -v195
	v_fmac_f32_e32 v195, 0x3377d1cf, v193
	v_fmac_f32_e32 v195, 0x3f317217, v193
	v_cmp_lt_f32_e64 s[6:7], |v193|, s93
	v_fma_f32 v194, v185, v194, v159
	s_nop 0
	v_cndmask_b32_e64 v193, v193, v195, s[6:7]
	v_cmp_gt_f32_e64 s[6:7], s87, v194
	v_sub_f32_e32 v198, v193, v198
	v_cvt_pk_f16_f32 v192, v192, v198
	v_cndmask_b32_e64 v195, 0, 32, s[6:7]
	v_ldexp_f32 v194, v194, v195
	v_mul_f32_e32 v195, v103, v191
	v_mul_f32_e32 v195, 0xbfb8aa3b, v195
	v_exp_f32_e32 v195, v195
	v_log_f32_e32 v194, v194
	v_add_f32_e32 v195, 1.0, v195
	v_rcp_f32_e32 v195, v195
	v_mul_f32_e32 v193, 0x3f317217, v194
	v_fma_f32 v193, v194, s92, -v193
	v_fmac_f32_e32 v193, 0x3377d1cf, v194
	v_fma_f32 v195, v186, v195, v158
	v_cmp_gt_f32_e32 vcc, s87, v195
	v_fmac_f32_e32 v193, 0x3f317217, v194
	v_cmp_lt_f32_e64 s[8:9], |v194|, s93
	v_cndmask_b32_e64 v199, 0, 32, vcc
	v_ldexp_f32 v195, v195, v199
	v_mul_f32_e32 v199, v96, v191
	v_mul_f32_e32 v199, 0xbfb8aa3b, v199
	v_log_f32_e32 v195, v195
	v_exp_f32_e32 v199, v199
	v_cndmask_b32_e64 v193, v194, v193, s[8:9]
	v_cndmask_b32_e64 v194, 0, v171, s[6:7]
; __device__ __forceinline__ float fsigm(float x) { return __builtin_amdgcn_rcpf(1.f + __expf(-x)); }
; __device__ __forceinline__ float row_rs(const float* ssq, int row) { return ssq ? rsqrtf(ssq[row] * (1.f / 1024.f) + RMS_EPS) : 1.f; }
;     __device__ __forceinline__ void operator()(const f32x4 (&acc)[2][2][4][2], const Unit& u, int wr, int wc, int fr, int fq) const {
;     ...
;                 for (int m = 0; m < 4; ++m) { const int row = row0 + ai * HALF + m * 16; const float rs = row_rs(ssq, row);
; #pragma unroll
;                     for (int bj = 0; bj < 2; ++bj) { f16x4 o[2];
; #pragma unroll
;                         for (int n = 0; n < 2; ++n) { const f32x4 p = acc[ai][bj][m][n] * rs;
; #pragma unroll
;                             for (int j = 0; j < 4; ++j) { const float l = lb[bj][n][j]; const float f = l + (1.f - l) * fsigm(p[j]); o[n][j] = (_Float16)__logf(f); } }
;                         const u32x2 a0 = __builtin_bit_cast(u32x2, o[0]), a1 = __builtin_bit_cast(u32x2, o[1]); u32x4 w; w.x = a0.x; w.y = a0.y; w.z = a1.x; w.w = a1.y;
;                         *(u32x4*)(LF + (size_t)row * 512 + cbase + bj * HALF) = w; } }
	v_sub_f32_e32 v193, v193, v194
	v_mul_f32_e32 v194, 0x3f317217, v195
	v_add_f32_e32 v199, 1.0, v199
	v_fma_f32 v194, v195, s92, -v194
	v_rcp_f32_e32 v199, v199
	v_fmac_f32_e32 v194, 0x3377d1cf, v195
	v_fmac_f32_e32 v194, 0x3f317217, v195
	v_cmp_lt_f32_e64 s[6:7], |v195|, s93
	v_fma_f32 v199, v187, v199, v157
	s_nop 0
	v_cndmask_b32_e64 v194, v195, v194, s[6:7]
	v_cndmask_b32_e32 v195, 0, v171, vcc
	v_sub_f32_e32 v194, v194, v195
	v_mul_f32_e32 v195, v97, v191
	v_cmp_gt_f32_e32 vcc, s87, v199
	v_mul_f32_e32 v195, 0xbfb8aa3b, v195
	v_exp_f32_e32 v195, v195
	v_cndmask_b32_e64 v200, 0, 32, vcc
	v_ldexp_f32 v199, v199, v200
	v_log_f32_e32 v199, v199
	v_add_f32_e32 v195, 1.0, v195
	v_rcp_f32_e32 v195, v195
	v_cvt_pk_f16_f32 v193, v193, v194
	v_mul_f32_e32 v194, 0x3f317217, v199
	v_fma_f32 v194, v199, s92, -v194
	v_fmac_f32_e32 v194, 0x3377d1cf, v199
	v_fmac_f32_e32 v194, 0x3f317217, v199
	v_cmp_lt_f32_e64 s[6:7], |v199|, s93
	v_fma_f32 v195, v182, v195, v156
	v_cndmask_b32_e32 v198, 0, v171, vcc
	v_cndmask_b32_e64 v194, v199, v194, s[6:7]
	v_cmp_gt_f32_e32 vcc, s87, v195
	v_sub_f32_e32 v194, v194, v198
	s_nop 0
	v_cndmask_b32_e64 v198, 0, 32, vcc
	v_ldexp_f32 v195, v195, v198
	v_mul_f32_e32 v198, v98, v191
	v_mul_f32_e32 v198, 0xbfb8aa3b, v198
	v_exp_f32_e32 v198, v198
	v_log_f32_e32 v195, v195
	v_mul_f32_e32 v191, v99, v191
	v_mul_f32_e32 v191, 0xbfb8aa3b, v191
	v_add_f32_e32 v198, 1.0, v198
	v_rcp_f32_e32 v198, v198
	v_exp_f32_e32 v191, v191
	v_mul_f32_e32 v199, 0x3f317217, v195
	v_fma_f32 v199, v195, s92, -v199
	v_fmac_f32_e32 v199, 0x3377d1cf, v195
	v_fmac_f32_e32 v199, 0x3f317217, v195
	v_cmp_lt_f32_e64 s[6:7], |v195|, s93
	v_fma_f32 v198, v189, v198, v155
	v_add_f32_e32 v191, 1.0, v191
	v_cndmask_b32_e64 v195, v195, v199, s[6:7]
	v_cmp_gt_f32_e64 s[6:7], s87, v198
	v_rcp_f32_e32 v191, v191
	s_nop 0
	v_cndmask_b32_e64 v199, 0, 32, s[6:7]
	v_ldexp_f32 v198, v198, v199
	v_log_f32_e32 v198, v198
	v_fma_f32 v191, v190, v191, v154
	v_cndmask_b32_e32 v199, 0, v171, vcc
	v_cmp_gt_f32_e32 vcc, s87, v191
	v_sub_f32_e32 v199, v195, v199
	v_mul_f32_e32 v195, 0x3f317217, v198
	v_cndmask_b32_e64 v200, 0, 32, vcc
	v_ldexp_f32 v191, v191, v200
	v_fma_f32 v195, v198, s92, -v195
	v_log_f32_e32 v191, v191
	v_fmac_f32_e32 v195, 0x3377d1cf, v198
	v_fmac_f32_e32 v195, 0x3f317217, v198
	v_cmp_lt_f32_e64 s[8:9], |v198|, s93
	v_cvt_pk_f16_f32 v194, v194, v199
	s_nop 0
	v_cndmask_b32_e64 v195, v198, v195, s[8:9]
	v_cndmask_b32_e64 v198, 0, v171, s[6:7]
	v_sub_f32_e32 v195, v195, v198
	v_mul_f32_e32 v198, 0x3f317217, v191
	v_fma_f32 v198, v191, s92, -v198
	v_fmac_f32_e32 v198, 0x3377d1cf, v191
	v_fmac_f32_e32 v198, 0x3f317217, v191
	v_cmp_lt_f32_e64 s[6:7], |v191|, s93
	s_nop 1
	v_cndmask_b32_e64 v191, v191, v198, s[6:7]
	v_cndmask_b32_e32 v198, 0, v171, vcc
	v_sub_f32_e32 v191, v191, v198
	v_cvt_pk_f16_f32 v195, v195, v191
	global_store_dwordx4 v[196:197], v[192:195], off offset:256
	s_nop 1
	v_or_b32_e32 v192, 32, v148
	v_ashrrev_i32_e32 v193, 31, v192
	v_lshl_add_u64 v[194:195], v[192:193], 2, s[30:31]
	v_lshlrev_b64 v[196:197], 10, v[192:193]
	v_lshl_add_u64 v[196:197], s[28:29], 0, v[196:197]
	v_lshl_add_u64 v[196:197], v[196:197], 0, v[136:137]
	v_fmamk_f32 v191, v211, 0x3a800000, v170
	v_rsq_f32_e32 v191, v191
	s_nop 0
	v_mul_f32_e32 v194, v92, v191
	v_mul_f32_e32 v194, 0xbfb8aa3b, v194
	v_exp_f32_e32 v194, v194
	v_mul_f32_e32 v193, v93, v191
	v_mul_f32_e32 v193, 0xbfb8aa3b, v193
	v_exp_f32_e32 v193, v193
	v_add_f32_e32 v194, 1.0, v194
	v_rcp_f32_e32 v194, v194
	v_add_f32_e32 v193, 1.0, v193
	v_rcp_f32_e32 v193, v193
	v_fma_f32 v194, v176, v194, v175
	v_cmp_gt_f32_e32 vcc, s87, v194
	v_fma_f32 v193, v177, v193, v174
	s_nop 0
	v_cndmask_b32_e64 v195, 0, 32, vcc
	v_ldexp_f32 v194, v194, v195
	v_log_f32_e32 v194, v194
	s_nop 0
	v_mul_f32_e32 v192, 0x3f317217, v194
	v_fma_f32 v192, v194, s92, -v192
	v_fmac_f32_e32 v192, 0x3377d1cf, v194
	v_fmac_f32_e32 v192, 0x3f317217, v194
	v_cmp_lt_f32_e64 s[6:7], |v194|, s93
	s_nop 1
	v_cndmask_b32_e64 v192, v194, v192, s[6:7]
	v_cndmask_b32_e32 v194, 0, v171, vcc
	v_cmp_gt_f32_e32 vcc, s87, v193
	v_sub_f32_e32 v192, v192, v194
	s_nop 0
	v_cndmask_b32_e64 v194, 0, 32, vcc
	v_ldexp_f32 v193, v193, v194
	v_mul_f32_e32 v194, v94, v191
	v_mul_f32_e32 v194, 0xbfb8aa3b, v194
	v_exp_f32_e32 v194, v194
	v_log_f32_e32 v193, v193
	v_cndmask_b32_e32 v198, 0, v171, vcc
	v_add_f32_e32 v194, 1.0, v194
	v_rcp_f32_e32 v194, v194
	v_mul_f32_e32 v195, 0x3f317217, v193
	v_fma_f32 v195, v193, s92, -v195
	v_fmac_f32_e32 v195, 0x3377d1cf, v193
	v_fmac_f32_e32 v195, 0x3f317217, v193
	v_cmp_lt_f32_e64 s[6:7], |v193|, s93
	v_fma_f32 v194, v178, v194, v173
	s_nop 0
	v_cndmask_b32_e64 v193, v193, v195, s[6:7]
	v_cmp_gt_f32_e64 s[6:7], s87, v194
	v_sub_f32_e32 v198, v193, v198
	v_cvt_pk_f16_f32 v192, v192, v198
	v_cndmask_b32_e64 v195, 0, 32, s[6:7]
	v_ldexp_f32 v194, v194, v195
	v_mul_f32_e32 v195, v95, v191
	v_mul_f32_e32 v195, 0xbfb8aa3b, v195
	v_exp_f32_e32 v195, v195
	v_log_f32_e32 v194, v194
	v_add_f32_e32 v195, 1.0, v195
	v_rcp_f32_e32 v195, v195
	v_mul_f32_e32 v193, 0x3f317217, v194
	v_fma_f32 v193, v194, s92, -v193
	v_fmac_f32_e32 v193, 0x3377d1cf, v194
	v_fma_f32 v195, v183, v195, v172
	v_cmp_gt_f32_e32 vcc, s87, v195
	v_fmac_f32_e32 v193, 0x3f317217, v194
	v_cmp_lt_f32_e64 s[8:9], |v194|, s93
	v_cndmask_b32_e64 v199, 0, 32, vcc
	v_ldexp_f32 v195, v195, v199
	v_mul_f32_e32 v199, v88, v191
	v_mul_f32_e32 v199, 0xbfb8aa3b, v199
	v_log_f32_e32 v195, v195
	v_exp_f32_e32 v199, v199
	v_cndmask_b32_e64 v193, v194, v193, s[8:9]
	v_cndmask_b32_e64 v194, 0, v171, s[6:7]
	v_sub_f32_e32 v193, v193, v194
	v_mul_f32_e32 v194, 0x3f317217, v195
; __device__ __forceinline__ float fsigm(float x) { return __builtin_amdgcn_rcpf(1.f + __expf(-x)); }
; __device__ __forceinline__ float row_rs(const float* ssq, int row) { return ssq ? rsqrtf(ssq[row] * (1.f / 1024.f) + RMS_EPS) : 1.f; }
;     __device__ __forceinline__ void operator()(const f32x4 (&acc)[2][2][4][2], const Unit& u, int wr, int wc, int fr, int fq) const {
;     ...
;                 for (int m = 0; m < 4; ++m) { const int row = row0 + ai * HALF + m * 16; const float rs = row_rs(ssq, row);
; #pragma unroll
;                     for (int bj = 0; bj < 2; ++bj) { f16x4 o[2];
; #pragma unroll
;                         for (int n = 0; n < 2; ++n) { const f32x4 p = acc[ai][bj][m][n] * rs;
; #pragma unroll
;                             for (int j = 0; j < 4; ++j) { const float l = lb[bj][n][j]; const float f = l + (1.f - l) * fsigm(p[j]); o[n][j] = (_Float16)__logf(f); } }
;                         const u32x2 a0 = __builtin_bit_cast(u32x2, o[0]), a1 = __builtin_bit_cast(u32x2, o[1]); u32x4 w; w.x = a0.x; w.y = a0.y; w.z = a1.x; w.w = a1.y;
;                         *(u32x4*)(LF + (size_t)row * 512 + cbase + bj * HALF) = w; } }
	v_add_f32_e32 v199, 1.0, v199
	v_fma_f32 v194, v195, s92, -v194
	v_rcp_f32_e32 v199, v199
	v_fmac_f32_e32 v194, 0x3377d1cf, v195
	v_fmac_f32_e32 v194, 0x3f317217, v195
	v_cmp_lt_f32_e64 s[6:7], |v195|, s93
	v_fma_f32 v199, v149, v199, v165
	s_nop 0
	v_cndmask_b32_e64 v194, v195, v194, s[6:7]
	v_cndmask_b32_e32 v195, 0, v171, vcc
	v_sub_f32_e32 v194, v194, v195
	v_mul_f32_e32 v195, v89, v191
	v_cmp_gt_f32_e32 vcc, s87, v199
	v_mul_f32_e32 v195, 0xbfb8aa3b, v195
	v_exp_f32_e32 v195, v195
	v_cndmask_b32_e64 v200, 0, 32, vcc
	v_ldexp_f32 v199, v199, v200
	v_log_f32_e32 v199, v199
	v_add_f32_e32 v195, 1.0, v195
	v_rcp_f32_e32 v195, v195
	v_cvt_pk_f16_f32 v193, v193, v194
	v_mul_f32_e32 v194, 0x3f317217, v199
	v_fma_f32 v194, v199, s92, -v194
	v_fmac_f32_e32 v194, 0x3377d1cf, v199
	v_fmac_f32_e32 v194, 0x3f317217, v199
	v_cmp_lt_f32_e64 s[6:7], |v199|, s93
	v_fma_f32 v195, v179, v195, v164
	v_cndmask_b32_e32 v198, 0, v171, vcc
	v_cndmask_b32_e64 v194, v199, v194, s[6:7]
	v_cmp_gt_f32_e32 vcc, s87, v195
	v_sub_f32_e32 v194, v194, v198
	s_nop 0
	v_cndmask_b32_e64 v198, 0, 32, vcc
	v_ldexp_f32 v195, v195, v198
	v_mul_f32_e32 v198, v90, v191
	v_mul_f32_e32 v198, 0xbfb8aa3b, v198
	v_exp_f32_e32 v198, v198
	v_log_f32_e32 v195, v195
	v_cndmask_b32_e32 v200, 0, v171, vcc
	v_add_f32_e32 v198, 1.0, v198
	v_rcp_f32_e32 v198, v198
	v_mul_f32_e32 v199, 0x3f317217, v195
	v_fma_f32 v199, v195, s92, -v199
	v_fmac_f32_e32 v199, 0x3377d1cf, v195
	v_fmac_f32_e32 v199, 0x3f317217, v195
	v_cmp_lt_f32_e64 s[6:7], |v195|, s93
	v_fma_f32 v198, v180, v198, v163
	s_nop 0
	v_cndmask_b32_e64 v195, v195, v199, s[6:7]
	v_cmp_gt_f32_e64 s[6:7], s87, v198
	v_sub_f32_e32 v200, v195, v200
	v_cvt_pk_f16_f32 v194, v194, v200
	v_cndmask_b32_e64 v199, 0, 32, s[6:7]
	v_ldexp_f32 v198, v198, v199
	v_mul_f32_e32 v199, v91, v191
	v_mul_f32_e32 v199, 0xbfb8aa3b, v199
	v_exp_f32_e32 v199, v199
	v_log_f32_e32 v198, v198
	v_add_f32_e32 v199, 1.0, v199
	v_rcp_f32_e32 v199, v199
	v_mul_f32_e32 v195, 0x3f317217, v198
	v_fma_f32 v195, v198, s92, -v195
	v_fmac_f32_e32 v195, 0x3377d1cf, v198
	v_fma_f32 v199, v188, v199, v162
	v_cmp_gt_f32_e32 vcc, s87, v199
	v_fmac_f32_e32 v195, 0x3f317217, v198
	v_cmp_lt_f32_e64 s[8:9], |v198|, s93
	v_cndmask_b32_e64 v201, 0, 32, vcc
	v_ldexp_f32 v199, v199, v201
	v_log_f32_e32 v199, v199
	v_mul_f32_e32 v201, v84, v191
	v_mul_f32_e32 v201, 0xbfb8aa3b, v201
	v_exp_f32_e32 v201, v201
	v_cndmask_b32_e64 v195, v198, v195, s[8:9]
	v_cndmask_b32_e64 v198, 0, v171, s[6:7]
	v_sub_f32_e32 v195, v195, v198
	v_mul_f32_e32 v198, 0x3f317217, v199
	v_fma_f32 v198, v199, s92, -v198
	v_fmac_f32_e32 v198, 0x3377d1cf, v199
	v_add_f32_e32 v201, 1.0, v201
	v_fmac_f32_e32 v198, 0x3f317217, v199
	v_cmp_lt_f32_e64 s[6:7], |v199|, s93
	v_rcp_f32_e32 v201, v201
	s_nop 0
	v_cndmask_b32_e64 v198, v199, v198, s[6:7]
	v_cndmask_b32_e32 v199, 0, v171, vcc
	v_sub_f32_e32 v198, v198, v199
	v_cvt_pk_f16_f32 v195, v195, v198
	v_fma_f32 v198, v184, v201, v161
	global_store_dwordx4 v[196:197], v[192:195], off
	v_cmp_gt_f32_e32 vcc, s87, v198
	s_nop 0
	v_mul_f32_e32 v193, v85, v191
	v_mul_f32_e32 v193, 0xbfb8aa3b, v193
	v_cndmask_b32_e64 v199, 0, 32, vcc
	v_exp_f32_e32 v193, v193
	v_ldexp_f32 v198, v198, v199
	v_log_f32_e32 v198, v198
	v_cndmask_b32_e32 v194, 0, v171, vcc
	v_add_f32_e32 v193, 1.0, v193
	v_rcp_f32_e32 v193, v193
	v_mul_f32_e32 v192, 0x3f317217, v198
	v_fma_f32 v192, v198, s92, -v192
	v_fmac_f32_e32 v192, 0x3377d1cf, v198
	v_fmac_f32_e32 v192, 0x3f317217, v198
	v_cmp_lt_f32_e64 s[6:7], |v198|, s93
	v_fma_f32 v193, v181, v193, v160
	v_cmp_gt_f32_e32 vcc, s87, v193
	v_cndmask_b32_e64 v192, v198, v192, s[6:7]
	v_sub_f32_e32 v192, v192, v194
	v_cndmask_b32_e64 v194, 0, 32, vcc
	v_ldexp_f32 v193, v193, v194
	v_mul_f32_e32 v194, v86, v191
	v_mul_f32_e32 v194, 0xbfb8aa3b, v194
	v_exp_f32_e32 v194, v194
	v_log_f32_e32 v193, v193
	v_cndmask_b32_e32 v198, 0, v171, vcc
	v_add_f32_e32 v194, 1.0, v194
	v_rcp_f32_e32 v194, v194
	v_mul_f32_e32 v195, 0x3f317217, v193
	v_fma_f32 v195, v193, s92, -v195
	v_fmac_f32_e32 v195, 0x3377d1cf, v193
	v_fmac_f32_e32 v195, 0x3f317217, v193
	v_cmp_lt_f32_e64 s[6:7], |v193|, s93
	v_fma_f32 v194, v185, v194, v159
	s_nop 0
	v_cndmask_b32_e64 v193, v193, v195, s[6:7]
	v_cmp_gt_f32_e64 s[6:7], s87, v194
	v_sub_f32_e32 v198, v193, v198
	v_cvt_pk_f16_f32 v192, v192, v198
	v_cndmask_b32_e64 v195, 0, 32, s[6:7]
	v_ldexp_f32 v194, v194, v195
	v_mul_f32_e32 v195, v87, v191
	v_mul_f32_e32 v195, 0xbfb8aa3b, v195
	v_exp_f32_e32 v195, v195
	v_log_f32_e32 v194, v194
	v_add_f32_e32 v195, 1.0, v195
	v_rcp_f32_e32 v195, v195
	v_mul_f32_e32 v193, 0x3f317217, v194
	v_fma_f32 v193, v194, s92, -v193
	v_fmac_f32_e32 v193, 0x3377d1cf, v194
	v_fma_f32 v195, v186, v195, v158
	v_cmp_gt_f32_e32 vcc, s87, v195
	v_fmac_f32_e32 v193, 0x3f317217, v194
	v_cmp_lt_f32_e64 s[8:9], |v194|, s93
	v_cndmask_b32_e64 v199, 0, 32, vcc
	v_ldexp_f32 v195, v195, v199
	v_mul_f32_e32 v199, v80, v191
	v_mul_f32_e32 v199, 0xbfb8aa3b, v199
	v_log_f32_e32 v195, v195
	v_exp_f32_e32 v199, v199
	v_cndmask_b32_e64 v193, v194, v193, s[8:9]
	v_cndmask_b32_e64 v194, 0, v171, s[6:7]
	v_sub_f32_e32 v193, v193, v194
	v_mul_f32_e32 v194, 0x3f317217, v195
	v_add_f32_e32 v199, 1.0, v199
	v_fma_f32 v194, v195, s92, -v194
	v_rcp_f32_e32 v199, v199
	v_fmac_f32_e32 v194, 0x3377d1cf, v195
	v_fmac_f32_e32 v194, 0x3f317217, v195
	v_cmp_lt_f32_e64 s[6:7], |v195|, s93
	v_fma_f32 v199, v187, v199, v157
	s_nop 0
	v_cndmask_b32_e64 v194, v195, v194, s[6:7]
	v_cndmask_b32_e32 v195, 0, v171, vcc
	v_sub_f32_e32 v194, v194, v195
	v_mul_f32_e32 v195, v81, v191
	v_cmp_gt_f32_e32 vcc, s87, v199
	v_mul_f32_e32 v195, 0xbfb8aa3b, v195
; __device__ __forceinline__ float fsigm(float x) { return __builtin_amdgcn_rcpf(1.f + __expf(-x)); }
; __device__ __forceinline__ float row_rs(const float* ssq, int row) { return ssq ? rsqrtf(ssq[row] * (1.f / 1024.f) + RMS_EPS) : 1.f; }
;     __device__ __forceinline__ void operator()(const f32x4 (&acc)[2][2][4][2], const Unit& u, int wr, int wc, int fr, int fq) const {
;     ...
;                 for (int m = 0; m < 4; ++m) { const int row = row0 + ai * HALF + m * 16; const float rs = row_rs(ssq, row);
; #pragma unroll
;                     for (int bj = 0; bj < 2; ++bj) { f16x4 o[2];
; #pragma unroll
;                         for (int n = 0; n < 2; ++n) { const f32x4 p = acc[ai][bj][m][n] * rs;
; #pragma unroll
;                             for (int j = 0; j < 4; ++j) { const float l = lb[bj][n][j]; const float f = l + (1.f - l) * fsigm(p[j]); o[n][j] = (_Float16)__logf(f); } }
;                         const u32x2 a0 = __builtin_bit_cast(u32x2, o[0]), a1 = __builtin_bit_cast(u32x2, o[1]); u32x4 w; w.x = a0.x; w.y = a0.y; w.z = a1.x; w.w = a1.y;
;                         *(u32x4*)(LF + (size_t)row * 512 + cbase + bj * HALF) = w; } }
	v_exp_f32_e32 v195, v195
	v_cndmask_b32_e64 v200, 0, 32, vcc
	v_ldexp_f32 v199, v199, v200
	v_log_f32_e32 v199, v199
	v_add_f32_e32 v195, 1.0, v195
	v_rcp_f32_e32 v195, v195
	v_cvt_pk_f16_f32 v193, v193, v194
	v_mul_f32_e32 v194, 0x3f317217, v199
	v_fma_f32 v194, v199, s92, -v194
	v_fmac_f32_e32 v194, 0x3377d1cf, v199
	v_fmac_f32_e32 v194, 0x3f317217, v199
	v_cmp_lt_f32_e64 s[6:7], |v199|, s93
	v_fma_f32 v195, v182, v195, v156
	v_cndmask_b32_e32 v198, 0, v171, vcc
	v_cndmask_b32_e64 v194, v199, v194, s[6:7]
	v_cmp_gt_f32_e32 vcc, s87, v195
	v_sub_f32_e32 v194, v194, v198
	s_nop 0
	v_cndmask_b32_e64 v198, 0, 32, vcc
	v_ldexp_f32 v195, v195, v198
	v_mul_f32_e32 v198, v82, v191
	v_mul_f32_e32 v198, 0xbfb8aa3b, v198
	v_exp_f32_e32 v198, v198
	v_log_f32_e32 v195, v195
	v_mul_f32_e32 v191, v83, v191
	v_mul_f32_e32 v191, 0xbfb8aa3b, v191
	v_add_f32_e32 v198, 1.0, v198
	v_rcp_f32_e32 v198, v198
	v_exp_f32_e32 v191, v191
	v_mul_f32_e32 v199, 0x3f317217, v195
	v_fma_f32 v199, v195, s92, -v199
	v_fmac_f32_e32 v199, 0x3377d1cf, v195
	v_fmac_f32_e32 v199, 0x3f317217, v195
	v_cmp_lt_f32_e64 s[6:7], |v195|, s93
	v_fma_f32 v198, v189, v198, v155
	v_add_f32_e32 v191, 1.0, v191
	v_cndmask_b32_e64 v195, v195, v199, s[6:7]
	v_cmp_gt_f32_e64 s[6:7], s87, v198
	v_rcp_f32_e32 v191, v191
	s_nop 0
	v_cndmask_b32_e64 v199, 0, 32, s[6:7]
	v_ldexp_f32 v198, v198, v199
	v_log_f32_e32 v198, v198
	v_fma_f32 v191, v190, v191, v154
	v_cndmask_b32_e32 v199, 0, v171, vcc
	v_cmp_gt_f32_e32 vcc, s87, v191
	v_sub_f32_e32 v199, v195, v199
	v_mul_f32_e32 v195, 0x3f317217, v198
	v_cndmask_b32_e64 v200, 0, 32, vcc
	v_ldexp_f32 v191, v191, v200
	v_fma_f32 v195, v198, s92, -v195
	v_log_f32_e32 v191, v191
	v_fmac_f32_e32 v195, 0x3377d1cf, v198
	v_fmac_f32_e32 v195, 0x3f317217, v198
	v_cmp_lt_f32_e64 s[8:9], |v198|, s93
	v_cvt_pk_f16_f32 v194, v194, v199
	s_nop 0
	v_cndmask_b32_e64 v195, v198, v195, s[8:9]
	v_cndmask_b32_e64 v198, 0, v171, s[6:7]
	v_sub_f32_e32 v195, v195, v198
	v_mul_f32_e32 v198, 0x3f317217, v191
	v_fma_f32 v198, v191, s92, -v198
	v_fmac_f32_e32 v198, 0x3377d1cf, v191
	v_fmac_f32_e32 v198, 0x3f317217, v191
	v_cmp_lt_f32_e64 s[6:7], |v191|, s93
	s_nop 1
	v_cndmask_b32_e64 v191, v191, v198, s[6:7]
	v_cndmask_b32_e32 v198, 0, v171, vcc
	v_sub_f32_e32 v191, v191, v198
	v_cvt_pk_f16_f32 v195, v195, v191
	global_store_dwordx4 v[196:197], v[192:195], off offset:256
	s_nop 1
	v_or_b32_e32 v192, 48, v148
	v_ashrrev_i32_e32 v193, 31, v192
	v_lshl_add_u64 v[194:195], v[192:193], 2, s[30:31]
	v_lshlrev_b64 v[196:197], 10, v[192:193]
	v_lshl_add_u64 v[196:197], s[28:29], 0, v[196:197]
	v_lshl_add_u64 v[196:197], v[196:197], 0, v[136:137]
	v_fmamk_f32 v191, v212, 0x3a800000, v170
	v_rsq_f32_e32 v191, v191
	s_nop 0
	v_mul_f32_e32 v194, v76, v191
	v_mul_f32_e32 v194, 0xbfb8aa3b, v194
	v_exp_f32_e32 v194, v194
	v_mul_f32_e32 v193, v77, v191
	v_mul_f32_e32 v193, 0xbfb8aa3b, v193
	v_exp_f32_e32 v193, v193
	v_add_f32_e32 v194, 1.0, v194
	v_rcp_f32_e32 v194, v194
	v_add_f32_e32 v193, 1.0, v193
	v_rcp_f32_e32 v193, v193
	v_fma_f32 v194, v176, v194, v175
	v_cmp_gt_f32_e32 vcc, s87, v194
	v_fma_f32 v193, v177, v193, v174
	s_nop 0
	v_cndmask_b32_e64 v195, 0, 32, vcc
	v_ldexp_f32 v194, v194, v195
	v_log_f32_e32 v194, v194
	s_nop 0
	v_mul_f32_e32 v192, 0x3f317217, v194
	v_fma_f32 v192, v194, s92, -v192
	v_fmac_f32_e32 v192, 0x3377d1cf, v194
	v_fmac_f32_e32 v192, 0x3f317217, v194
	v_cmp_lt_f32_e64 s[6:7], |v194|, s93
	s_nop 1
	v_cndmask_b32_e64 v192, v194, v192, s[6:7]
	v_cndmask_b32_e32 v194, 0, v171, vcc
	v_cmp_gt_f32_e32 vcc, s87, v193
	v_sub_f32_e32 v192, v192, v194
	s_nop 0
	v_cndmask_b32_e64 v194, 0, 32, vcc
	v_ldexp_f32 v193, v193, v194
	v_mul_f32_e32 v194, v78, v191
	v_mul_f32_e32 v194, 0xbfb8aa3b, v194
	v_exp_f32_e32 v194, v194
	v_log_f32_e32 v193, v193
	v_cndmask_b32_e32 v198, 0, v171, vcc
	v_add_f32_e32 v194, 1.0, v194
	v_rcp_f32_e32 v194, v194
	v_mul_f32_e32 v195, 0x3f317217, v193
	v_fma_f32 v195, v193, s92, -v195
	v_fmac_f32_e32 v195, 0x3377d1cf, v193
	v_fmac_f32_e32 v195, 0x3f317217, v193
	v_cmp_lt_f32_e64 s[6:7], |v193|, s93
	v_fma_f32 v194, v178, v194, v173
	s_nop 0
	v_cndmask_b32_e64 v193, v193, v195, s[6:7]
	v_cmp_gt_f32_e64 s[6:7], s87, v194
	v_sub_f32_e32 v198, v193, v198
	v_cvt_pk_f16_f32 v192, v192, v198
	v_cndmask_b32_e64 v195, 0, 32, s[6:7]
	v_ldexp_f32 v194, v194, v195
	v_mul_f32_e32 v195, v79, v191
	v_mul_f32_e32 v195, 0xbfb8aa3b, v195
	v_exp_f32_e32 v195, v195
	v_log_f32_e32 v194, v194
	v_add_f32_e32 v195, 1.0, v195
	v_rcp_f32_e32 v195, v195
	v_mul_f32_e32 v193, 0x3f317217, v194
	v_fma_f32 v193, v194, s92, -v193
	v_fmac_f32_e32 v193, 0x3377d1cf, v194
	v_fma_f32 v195, v183, v195, v172
	v_cmp_gt_f32_e32 vcc, s87, v195
	v_fmac_f32_e32 v193, 0x3f317217, v194
	v_cmp_lt_f32_e64 s[8:9], |v194|, s93
	v_cndmask_b32_e64 v199, 0, 32, vcc
	v_ldexp_f32 v195, v195, v199
	v_mul_f32_e32 v199, v72, v191
	v_mul_f32_e32 v199, 0xbfb8aa3b, v199
	v_log_f32_e32 v195, v195
	v_exp_f32_e32 v199, v199
	v_cndmask_b32_e64 v193, v194, v193, s[8:9]
	v_cndmask_b32_e64 v194, 0, v171, s[6:7]
	v_sub_f32_e32 v193, v193, v194
	v_mul_f32_e32 v194, 0x3f317217, v195
	v_add_f32_e32 v199, 1.0, v199
	v_fma_f32 v194, v195, s92, -v194
	v_rcp_f32_e32 v199, v199
	v_fmac_f32_e32 v194, 0x3377d1cf, v195
	v_fmac_f32_e32 v194, 0x3f317217, v195
	v_cmp_lt_f32_e64 s[6:7], |v195|, s93
	v_fma_f32 v199, v149, v199, v165
	s_nop 0
	v_cndmask_b32_e64 v194, v195, v194, s[6:7]
	v_cndmask_b32_e32 v195, 0, v171, vcc
	v_sub_f32_e32 v194, v194, v195
	v_mul_f32_e32 v195, v73, v191
	v_cmp_gt_f32_e32 vcc, s87, v199
	v_mul_f32_e32 v195, 0xbfb8aa3b, v195
	v_exp_f32_e32 v195, v195
	v_cndmask_b32_e64 v200, 0, 32, vcc
	v_ldexp_f32 v199, v199, v200
; __device__ __forceinline__ float fsigm(float x) { return __builtin_amdgcn_rcpf(1.f + __expf(-x)); }
; __device__ __forceinline__ float row_rs(const float* ssq, int row) { return ssq ? rsqrtf(ssq[row] * (1.f / 1024.f) + RMS_EPS) : 1.f; }
;     __device__ __forceinline__ void operator()(const f32x4 (&acc)[2][2][4][2], const Unit& u, int wr, int wc, int fr, int fq) const {
;     ...
;                 for (int m = 0; m < 4; ++m) { const int row = row0 + ai * HALF + m * 16; const float rs = row_rs(ssq, row);
; #pragma unroll
;                     for (int bj = 0; bj < 2; ++bj) { f16x4 o[2];
; #pragma unroll
;                         for (int n = 0; n < 2; ++n) { const f32x4 p = acc[ai][bj][m][n] * rs;
; #pragma unroll
;                             for (int j = 0; j < 4; ++j) { const float l = lb[bj][n][j]; const float f = l + (1.f - l) * fsigm(p[j]); o[n][j] = (_Float16)__logf(f); } }
;                         const u32x2 a0 = __builtin_bit_cast(u32x2, o[0]), a1 = __builtin_bit_cast(u32x2, o[1]); u32x4 w; w.x = a0.x; w.y = a0.y; w.z = a1.x; w.w = a1.y;
;                         *(u32x4*)(LF + (size_t)row * 512 + cbase + bj * HALF) = w; } }
	v_log_f32_e32 v199, v199
	v_add_f32_e32 v195, 1.0, v195
	v_rcp_f32_e32 v195, v195
	v_cvt_pk_f16_f32 v193, v193, v194
	v_mul_f32_e32 v194, 0x3f317217, v199
	v_fma_f32 v194, v199, s92, -v194
	v_fmac_f32_e32 v194, 0x3377d1cf, v199
	v_fmac_f32_e32 v194, 0x3f317217, v199
	v_cmp_lt_f32_e64 s[6:7], |v199|, s93
	v_fma_f32 v195, v179, v195, v164
	v_cndmask_b32_e32 v198, 0, v171, vcc
	v_cndmask_b32_e64 v194, v199, v194, s[6:7]
	v_cmp_gt_f32_e32 vcc, s87, v195
	v_sub_f32_e32 v194, v194, v198
	s_nop 0
	v_cndmask_b32_e64 v198, 0, 32, vcc
	v_ldexp_f32 v195, v195, v198
	v_mul_f32_e32 v198, v74, v191
	v_mul_f32_e32 v198, 0xbfb8aa3b, v198
	v_exp_f32_e32 v198, v198
	v_log_f32_e32 v195, v195
	v_cndmask_b32_e32 v200, 0, v171, vcc
	v_add_f32_e32 v198, 1.0, v198
	v_rcp_f32_e32 v198, v198
	v_mul_f32_e32 v199, 0x3f317217, v195
	v_fma_f32 v199, v195, s92, -v199
	v_fmac_f32_e32 v199, 0x3377d1cf, v195
	v_fmac_f32_e32 v199, 0x3f317217, v195
	v_cmp_lt_f32_e64 s[6:7], |v195|, s93
	v_fma_f32 v198, v180, v198, v163
	s_nop 0
	v_cndmask_b32_e64 v195, v195, v199, s[6:7]
	v_cmp_gt_f32_e64 s[6:7], s87, v198
	v_sub_f32_e32 v200, v195, v200
	v_cvt_pk_f16_f32 v194, v194, v200
	v_cndmask_b32_e64 v199, 0, 32, s[6:7]
	v_ldexp_f32 v198, v198, v199
	v_mul_f32_e32 v199, v75, v191
	v_mul_f32_e32 v199, 0xbfb8aa3b, v199
	v_exp_f32_e32 v199, v199
	v_log_f32_e32 v198, v198
	v_add_f32_e32 v199, 1.0, v199
	v_rcp_f32_e32 v199, v199
	v_mul_f32_e32 v195, 0x3f317217, v198
	v_fma_f32 v195, v198, s92, -v195
	v_fmac_f32_e32 v195, 0x3377d1cf, v198
	v_fma_f32 v199, v188, v199, v162
	v_cmp_gt_f32_e32 vcc, s87, v199
	v_fmac_f32_e32 v195, 0x3f317217, v198
	v_cmp_lt_f32_e64 s[8:9], |v198|, s93
	v_cndmask_b32_e64 v201, 0, 32, vcc
	v_ldexp_f32 v199, v199, v201
	v_log_f32_e32 v199, v199
	v_mul_f32_e32 v201, v68, v191
	v_mul_f32_e32 v201, 0xbfb8aa3b, v201
	v_exp_f32_e32 v201, v201
	v_cndmask_b32_e64 v195, v198, v195, s[8:9]
	v_cndmask_b32_e64 v198, 0, v171, s[6:7]
	v_sub_f32_e32 v195, v195, v198
	v_mul_f32_e32 v198, 0x3f317217, v199
	v_fma_f32 v198, v199, s92, -v198
	v_fmac_f32_e32 v198, 0x3377d1cf, v199
	v_add_f32_e32 v201, 1.0, v201
	v_fmac_f32_e32 v198, 0x3f317217, v199
	v_cmp_lt_f32_e64 s[6:7], |v199|, s93
	v_rcp_f32_e32 v201, v201
	s_nop 0
	v_cndmask_b32_e64 v198, v199, v198, s[6:7]
	v_cndmask_b32_e32 v199, 0, v171, vcc
	v_sub_f32_e32 v198, v198, v199
	v_cvt_pk_f16_f32 v195, v195, v198
	v_fma_f32 v198, v184, v201, v161
	global_store_dwordx4 v[196:197], v[192:195], off
	v_cmp_gt_f32_e32 vcc, s87, v198
	s_nop 0
	v_mul_f32_e32 v192, v69, v191
	v_mul_f32_e32 v192, 0xbfb8aa3b, v192
	v_cndmask_b32_e64 v199, 0, 32, vcc
	v_exp_f32_e32 v192, v192
	v_ldexp_f32 v198, v198, v199
	v_log_f32_e32 v198, v198
	v_cndmask_b32_e32 v193, 0, v171, vcc
	v_add_f32_e32 v192, 1.0, v192
	v_rcp_f32_e32 v192, v192
	v_mul_f32_e32 v136, 0x3f317217, v198
	v_fma_f32 v136, v198, s92, -v136
	v_fmac_f32_e32 v136, 0x3377d1cf, v198
	v_fmac_f32_e32 v136, 0x3f317217, v198
	v_cmp_lt_f32_e64 s[6:7], |v198|, s93
	v_fma_f32 v192, v181, v192, v160
	v_cmp_gt_f32_e32 vcc, s87, v192
	v_cndmask_b32_e64 v136, v198, v136, s[6:7]
	v_sub_f32_e32 v136, v136, v193
	v_cndmask_b32_e64 v193, 0, 32, vcc
	v_ldexp_f32 v192, v192, v193
	v_mul_f32_e32 v193, v70, v191
	v_mul_f32_e32 v193, 0xbfb8aa3b, v193
	v_exp_f32_e32 v193, v193
	v_log_f32_e32 v192, v192
	v_cndmask_b32_e32 v195, 0, v171, vcc
	v_add_f32_e32 v193, 1.0, v193
	v_rcp_f32_e32 v193, v193
	v_mul_f32_e32 v194, 0x3f317217, v192
	v_fma_f32 v194, v192, s92, -v194
	v_fmac_f32_e32 v194, 0x3377d1cf, v192
	v_fmac_f32_e32 v194, 0x3f317217, v192
	v_cmp_lt_f32_e64 s[6:7], |v192|, s93
	v_fma_f32 v193, v185, v193, v159
	s_nop 0
	v_cndmask_b32_e64 v192, v192, v194, s[6:7]
	v_cmp_gt_f32_e64 s[6:7], s87, v193
	v_sub_f32_e32 v192, v192, v195
	v_cvt_pk_f16_f32 v192, v136, v192
	v_cndmask_b32_e64 v194, 0, 32, s[6:7]
	v_ldexp_f32 v193, v193, v194
	v_mul_f32_e32 v194, v71, v191
	v_mul_f32_e32 v194, 0xbfb8aa3b, v194
	v_exp_f32_e32 v194, v194
	v_log_f32_e32 v193, v193
	v_add_f32_e32 v194, 1.0, v194
	v_rcp_f32_e32 v194, v194
	v_mul_f32_e32 v195, 0x3f317217, v193
	v_fma_f32 v195, v193, s92, -v195
	v_fmac_f32_e32 v195, 0x3377d1cf, v193
	v_fma_f32 v194, v186, v194, v158
	v_cmp_gt_f32_e32 vcc, s87, v194
	v_fmac_f32_e32 v195, 0x3f317217, v193
	v_cmp_lt_f32_e64 s[8:9], |v193|, s93
	v_cndmask_b32_e64 v198, 0, 32, vcc
	v_ldexp_f32 v194, v194, v198
	v_mul_f32_e32 v198, v64, v191
	v_log_f32_e32 v194, v194
	v_mul_f32_e32 v198, 0xbfb8aa3b, v198
	v_exp_f32_e32 v198, v198
	v_cndmask_b32_e64 v193, v193, v195, s[8:9]
	v_cndmask_b32_e64 v195, 0, v171, s[6:7]
	v_sub_f32_e32 v193, v193, v195
	v_mul_f32_e32 v195, 0x3f317217, v194
	v_fma_f32 v195, v194, s92, -v195
	v_add_f32_e32 v198, 1.0, v198
	v_fmac_f32_e32 v195, 0x3377d1cf, v194
	v_rcp_f32_e32 v198, v198
	v_fmac_f32_e32 v195, 0x3f317217, v194
	v_cmp_lt_f32_e64 s[6:7], |v194|, s93
	v_fma_f32 v198, v187, v198, v157
	s_nop 0
	v_cndmask_b32_e64 v194, v194, v195, s[6:7]
	v_cndmask_b32_e32 v195, 0, v171, vcc
	v_sub_f32_e32 v194, v194, v195
	v_cvt_pk_f16_f32 v193, v193, v194
	v_mul_f32_e32 v194, v65, v191
	v_cmp_gt_f32_e32 vcc, s87, v198
	v_mul_f32_e32 v194, 0xbfb8aa3b, v194
	v_exp_f32_e32 v194, v194
	v_cndmask_b32_e64 v199, 0, 32, vcc
	v_ldexp_f32 v198, v198, v199
	v_log_f32_e32 v198, v198
	v_add_f32_e32 v194, 1.0, v194
	v_rcp_f32_e32 v194, v194
	v_cndmask_b32_e32 v195, 0, v171, vcc
	v_mul_f32_e32 v136, 0x3f317217, v198
	v_fma_f32 v136, v198, s92, -v136
	v_fmac_f32_e32 v136, 0x3377d1cf, v198
	v_fmac_f32_e32 v136, 0x3f317217, v198
	v_cmp_lt_f32_e64 s[6:7], |v198|, s93
	v_fma_f32 v194, v182, v194, v156
	v_cmp_gt_f32_e32 vcc, s87, v194
	v_cndmask_b32_e64 v136, v198, v136, s[6:7]
	v_sub_f32_e32 v136, v136, v195
; __device__ __forceinline__ float fsigm(float x) { return __builtin_amdgcn_rcpf(1.f + __expf(-x)); }
; __device__ __forceinline__ float row_rs(const float* ssq, int row) { return ssq ? rsqrtf(ssq[row] * (1.f / 1024.f) + RMS_EPS) : 1.f; }
;     __device__ __forceinline__ void operator()(const f32x4 (&acc)[2][2][4][2], const Unit& u, int wr, int wc, int fr, int fq) const {
;     ...
;                 for (int m = 0; m < 4; ++m) { const int row = row0 + ai * HALF + m * 16; const float rs = row_rs(ssq, row);
; #pragma unroll
;                     for (int bj = 0; bj < 2; ++bj) { f16x4 o[2];
; #pragma unroll
;                         for (int n = 0; n < 2; ++n) { const f32x4 p = acc[ai][bj][m][n] * rs;
; #pragma unroll
;                             for (int j = 0; j < 4; ++j) { const float l = lb[bj][n][j]; const float f = l + (1.f - l) * fsigm(p[j]); o[n][j] = (_Float16)__logf(f); } }
;                         const u32x2 a0 = __builtin_bit_cast(u32x2, o[0]), a1 = __builtin_bit_cast(u32x2, o[1]); u32x4 w; w.x = a0.x; w.y = a0.y; w.z = a1.x; w.w = a1.y;
;                         *(u32x4*)(LF + (size_t)row * 512 + cbase + bj * HALF) = w; } }
	v_cndmask_b32_e64 v195, 0, 32, vcc
	v_ldexp_f32 v194, v194, v195
	v_mul_f32_e32 v195, v66, v191
	v_mul_f32_e32 v195, 0xbfb8aa3b, v195
	v_exp_f32_e32 v195, v195
	v_log_f32_e32 v194, v194
	v_mul_f32_e32 v191, v67, v191
	v_mul_f32_e32 v191, 0xbfb8aa3b, v191
	v_add_f32_e32 v195, 1.0, v195
	v_rcp_f32_e32 v195, v195
	v_exp_f32_e32 v191, v191
	v_mul_f32_e32 v198, 0x3f317217, v194
	v_fma_f32 v198, v194, s92, -v198
	v_fmac_f32_e32 v198, 0x3377d1cf, v194
	v_fmac_f32_e32 v198, 0x3f317217, v194
	v_cmp_lt_f32_e64 s[6:7], |v194|, s93
	v_fma_f32 v195, v189, v195, v155
	v_add_f32_e32 v191, 1.0, v191
	v_cndmask_b32_e64 v194, v194, v198, s[6:7]
	v_cmp_gt_f32_e64 s[6:7], s87, v195
	v_rcp_f32_e32 v191, v191
	s_nop 0
	v_cndmask_b32_e64 v198, 0, 32, s[6:7]
	v_ldexp_f32 v195, v195, v198
	v_log_f32_e32 v195, v195
	v_fma_f32 v191, v190, v191, v154
	v_cndmask_b32_e32 v198, 0, v171, vcc
	v_cmp_gt_f32_e32 vcc, s87, v191
	v_sub_f32_e32 v194, v194, v198
	v_mul_f32_e32 v198, 0x3f317217, v195
	v_cndmask_b32_e64 v199, 0, 32, vcc
	v_ldexp_f32 v191, v191, v199
	v_fma_f32 v198, v195, s92, -v198
	v_log_f32_e32 v191, v191
	v_fmac_f32_e32 v198, 0x3377d1cf, v195
	v_fmac_f32_e32 v198, 0x3f317217, v195
	v_cmp_lt_f32_e64 s[8:9], |v195|, s93
	v_cvt_pk_f16_f32 v194, v136, v194
	s_nop 0
	v_cndmask_b32_e64 v195, v195, v198, s[8:9]
	v_cndmask_b32_e64 v198, 0, v171, s[6:7]
	v_sub_f32_e32 v195, v195, v198
	v_mul_f32_e32 v198, 0x3f317217, v191
	v_fma_f32 v198, v191, s92, -v198
	v_fmac_f32_e32 v198, 0x3377d1cf, v191
	v_fmac_f32_e32 v198, 0x3f317217, v191
	v_cmp_lt_f32_e64 s[6:7], |v191|, s93
	s_nop 1
	v_cndmask_b32_e64 v191, v191, v198, s[6:7]
	v_cndmask_b32_e32 v198, 0, v171, vcc
	v_sub_f32_e32 v191, v191, v198
	v_cvt_pk_f16_f32 v195, v195, v191
	global_store_dwordx4 v[196:197], v[192:195], off offset:256
	v_fmamk_f32 v136, v213, 0x3a800000, v170
	v_rsq_f32_e32 v136, v136
	s_nop 0
	v_mul_f32_e32 v191, v60, v136
	v_mul_f32_e32 v191, 0xbfb8aa3b, v191
	v_exp_f32_e32 v191, v191
	v_mul_f32_e32 v193, v61, v136
	v_mul_f32_e32 v193, 0xbfb8aa3b, v193
	v_exp_f32_e32 v193, v193
	v_add_f32_e32 v191, 1.0, v191
	v_rcp_f32_e32 v191, v191
	v_add_f32_e32 v193, 1.0, v193
	v_rcp_f32_e32 v193, v193
	v_fma_f32 v191, v176, v191, v175
	v_cmp_gt_f32_e32 vcc, s87, v191
	s_nop 1
	v_cndmask_b32_e64 v192, 0, 32, vcc
	v_ldexp_f32 v191, v191, v192
	v_log_f32_e32 v191, v191
	s_nop 0
	v_mul_f32_e32 v192, 0x3f317217, v191
	v_fma_f32 v192, v191, s92, -v192
	v_fmac_f32_e32 v192, 0x3377d1cf, v191
	v_fmac_f32_e32 v192, 0x3f317217, v191
	v_cmp_lt_f32_e64 s[6:7], |v191|, s93
	s_nop 1
	v_cndmask_b32_e64 v191, v191, v192, s[6:7]
	v_cndmask_b32_e32 v192, 0, v171, vcc
	v_sub_f32_e32 v191, v191, v192
	v_fma_f32 v192, v177, v193, v174
	v_cmp_gt_f32_e32 vcc, s87, v192
	s_nop 1
	v_cndmask_b32_e64 v193, 0, 32, vcc
	v_ldexp_f32 v192, v192, v193
	v_mul_f32_e32 v193, v62, v136
	v_mul_f32_e32 v193, 0xbfb8aa3b, v193
	v_exp_f32_e32 v193, v193
	v_log_f32_e32 v192, v192
	v_cndmask_b32_e32 v195, 0, v171, vcc
	v_add_f32_e32 v193, 1.0, v193
	v_rcp_f32_e32 v193, v193
	v_mul_f32_e32 v194, 0x3f317217, v192
	v_fma_f32 v194, v192, s92, -v194
	v_fmac_f32_e32 v194, 0x3377d1cf, v192
	v_fmac_f32_e32 v194, 0x3f317217, v192
	v_cmp_lt_f32_e64 s[6:7], |v192|, s93
	v_fma_f32 v193, v178, v193, v173
	s_nop 0
	v_cndmask_b32_e64 v192, v192, v194, s[6:7]
	v_cmp_gt_f32_e64 s[6:7], s87, v193
	v_sub_f32_e32 v192, v192, v195
	v_cvt_pk_f16_f32 v192, v191, v192
	v_cndmask_b32_e64 v194, 0, 32, s[6:7]
	v_ldexp_f32 v193, v193, v194
	v_mul_f32_e32 v194, v63, v136
	v_mul_f32_e32 v194, 0xbfb8aa3b, v194
	v_exp_f32_e32 v194, v194
	v_log_f32_e32 v193, v193
	v_add_f32_e32 v194, 1.0, v194
	v_rcp_f32_e32 v194, v194
	v_mul_f32_e32 v195, 0x3f317217, v193
	v_fma_f32 v195, v193, s92, -v195
	v_fmac_f32_e32 v195, 0x3377d1cf, v193
	v_fma_f32 v194, v183, v194, v172
	v_cmp_gt_f32_e32 vcc, s87, v194
	v_fmac_f32_e32 v195, 0x3f317217, v193
	v_cmp_lt_f32_e64 s[8:9], |v193|, s93
	v_cndmask_b32_e64 v196, 0, 32, vcc
	v_ldexp_f32 v194, v194, v196
	v_mul_f32_e32 v196, v56, v136
	v_log_f32_e32 v194, v194
	v_mul_f32_e32 v196, 0xbfb8aa3b, v196
	v_exp_f32_e32 v196, v196
	v_cndmask_b32_e64 v193, v193, v195, s[8:9]
	v_cndmask_b32_e64 v195, 0, v171, s[6:7]
	v_sub_f32_e32 v193, v193, v195
	v_mul_f32_e32 v195, 0x3f317217, v194
	v_fma_f32 v195, v194, s92, -v195
	v_add_f32_e32 v196, 1.0, v196
	v_fmac_f32_e32 v195, 0x3377d1cf, v194
	v_rcp_f32_e32 v196, v196
	v_fmac_f32_e32 v195, 0x3f317217, v194
	v_cmp_lt_f32_e64 s[6:7], |v194|, s93
	v_fma_f32 v196, v149, v196, v165
	s_nop 0
	v_cndmask_b32_e64 v194, v194, v195, s[6:7]
	v_cndmask_b32_e32 v195, 0, v171, vcc
	v_sub_f32_e32 v194, v194, v195
	v_cvt_pk_f16_f32 v193, v193, v194
	v_mul_f32_e32 v194, v57, v136
	v_cmp_gt_f32_e32 vcc, s87, v196
	v_mul_f32_e32 v194, 0xbfb8aa3b, v194
	v_exp_f32_e32 v194, v194
	v_cndmask_b32_e64 v197, 0, 32, vcc
	v_ldexp_f32 v196, v196, v197
	v_log_f32_e32 v196, v196
	v_add_f32_e32 v194, 1.0, v194
	v_rcp_f32_e32 v194, v194
	v_cndmask_b32_e32 v195, 0, v171, vcc
	v_mul_f32_e32 v191, 0x3f317217, v196
	v_fma_f32 v191, v196, s92, -v191
	v_fmac_f32_e32 v191, 0x3377d1cf, v196
	v_fmac_f32_e32 v191, 0x3f317217, v196
	v_cmp_lt_f32_e64 s[6:7], |v196|, s93
	v_fma_f32 v194, v179, v194, v164
	v_cmp_gt_f32_e32 vcc, s87, v194
	v_cndmask_b32_e64 v191, v196, v191, s[6:7]
	v_sub_f32_e32 v191, v191, v195
	v_cndmask_b32_e64 v195, 0, 32, vcc
	v_ldexp_f32 v194, v194, v195
	v_mul_f32_e32 v195, v58, v136
	v_mul_f32_e32 v195, 0xbfb8aa3b, v195
	v_exp_f32_e32 v195, v195
	v_log_f32_e32 v194, v194
	v_cndmask_b32_e32 v197, 0, v171, vcc
	v_add_f32_e32 v195, 1.0, v195
	v_rcp_f32_e32 v195, v195
	v_mul_f32_e32 v196, 0x3f317217, v194
	v_fma_f32 v196, v194, s92, -v196
; __device__ __forceinline__ float fsigm(float x) { return __builtin_amdgcn_rcpf(1.f + __expf(-x)); }
; __device__ __forceinline__ float row_rs(const float* ssq, int row) { return ssq ? rsqrtf(ssq[row] * (1.f / 1024.f) + RMS_EPS) : 1.f; }
;     __device__ __forceinline__ void operator()(const f32x4 (&acc)[2][2][4][2], const Unit& u, int wr, int wc, int fr, int fq) const {
;     ...
;                 for (int m = 0; m < 4; ++m) { const int row = row0 + ai * HALF + m * 16; const float rs = row_rs(ssq, row);
; #pragma unroll
;                     for (int bj = 0; bj < 2; ++bj) { f16x4 o[2];
; #pragma unroll
;                         for (int n = 0; n < 2; ++n) { const f32x4 p = acc[ai][bj][m][n] * rs;
; #pragma unroll
;                             for (int j = 0; j < 4; ++j) { const float l = lb[bj][n][j]; const float f = l + (1.f - l) * fsigm(p[j]); o[n][j] = (_Float16)__logf(f); } }
;                         const u32x2 a0 = __builtin_bit_cast(u32x2, o[0]), a1 = __builtin_bit_cast(u32x2, o[1]); u32x4 w; w.x = a0.x; w.y = a0.y; w.z = a1.x; w.w = a1.y;
;                         *(u32x4*)(LF + (size_t)row * 512 + cbase + bj * HALF) = w; } }
	v_fmac_f32_e32 v196, 0x3377d1cf, v194
	v_fmac_f32_e32 v196, 0x3f317217, v194
	v_cmp_lt_f32_e64 s[6:7], |v194|, s93
	v_fma_f32 v195, v180, v195, v163
	s_nop 0
	v_cndmask_b32_e64 v194, v194, v196, s[6:7]
	v_cmp_gt_f32_e64 s[6:7], s87, v195
	v_sub_f32_e32 v194, v194, v197
	v_cvt_pk_f16_f32 v194, v191, v194
	v_cndmask_b32_e64 v196, 0, 32, s[6:7]
	v_ldexp_f32 v195, v195, v196
	v_mul_f32_e32 v196, v59, v136
	v_mul_f32_e32 v196, 0xbfb8aa3b, v196
	v_exp_f32_e32 v196, v196
	v_log_f32_e32 v195, v195
	v_add_f32_e32 v196, 1.0, v196
	v_rcp_f32_e32 v196, v196
	v_mul_f32_e32 v197, 0x3f317217, v195
	v_fma_f32 v197, v195, s92, -v197
	v_fmac_f32_e32 v197, 0x3377d1cf, v195
	v_fma_f32 v196, v188, v196, v162
	v_cmp_gt_f32_e32 vcc, s87, v196
	v_fmac_f32_e32 v197, 0x3f317217, v195
	v_cmp_lt_f32_e64 s[8:9], |v195|, s93
	v_cndmask_b32_e64 v198, 0, 32, vcc
	v_ldexp_f32 v196, v196, v198
	v_log_f32_e32 v196, v196
	v_cndmask_b32_e64 v195, v195, v197, s[8:9]
	v_cndmask_b32_e64 v197, 0, v171, s[6:7]
	v_mul_f32_e32 v198, v52, v136
	v_sub_f32_e32 v195, v195, v197
	v_mul_f32_e32 v197, 0x3f317217, v196
	v_mul_f32_e32 v198, 0xbfb8aa3b, v198
	v_fma_f32 v197, v196, s92, -v197
	v_exp_f32_e32 v198, v198
	v_fmac_f32_e32 v197, 0x3377d1cf, v196
	v_fmac_f32_e32 v197, 0x3f317217, v196
	v_cmp_lt_f32_e64 s[6:7], |v196|, s93
	s_nop 1
	v_cndmask_b32_e64 v196, v196, v197, s[6:7]
	v_cndmask_b32_e32 v197, 0, v171, vcc
	v_sub_f32_e32 v196, v196, v197
	v_add_f32_e32 v197, 1.0, v198
	v_rcp_f32_e32 v198, v197
	v_cvt_pk_f16_f32 v195, v195, v196
	v_lshl_add_u64 v[196:197], v[152:153], 0, s[38:39]
	v_fma_f32 v191, v184, v198, v161
	v_cmp_gt_f32_e32 vcc, s87, v191
	s_nop 1
	v_cndmask_b32_e64 v198, 0, 32, vcc
	v_ldexp_f32 v191, v191, v198
	v_add_co_u32_e64 v198, s[6:7], s88, v152
	v_log_f32_e32 v191, v191
	s_nop 0
	v_addc_co_u32_e64 v199, s[6:7], 0, v153, s[6:7]
	global_store_dwordx4 v[198:199], v[192:195], off
	v_cmp_lt_f32_e64 s[6:7], |v191|, s93
	s_nop 0
	v_mul_f32_e32 v193, v53, v136
	v_mul_f32_e32 v193, 0xbfb8aa3b, v193
	v_exp_f32_e32 v193, v193
	v_mul_f32_e32 v192, 0x3f317217, v191
	v_fma_f32 v192, v191, s92, -v192
	v_fmac_f32_e32 v192, 0x3377d1cf, v191
	v_add_f32_e32 v193, 1.0, v193
	v_rcp_f32_e32 v193, v193
	v_fmac_f32_e32 v192, 0x3f317217, v191
	v_cndmask_b32_e64 v191, v191, v192, s[6:7]
	v_cndmask_b32_e32 v192, 0, v171, vcc
	v_sub_f32_e32 v191, v191, v192
	v_fma_f32 v192, v181, v193, v160
	v_cmp_gt_f32_e32 vcc, s87, v192
	s_nop 1
	v_cndmask_b32_e64 v193, 0, 32, vcc
	v_ldexp_f32 v192, v192, v193
	v_mul_f32_e32 v193, v54, v136
	v_mul_f32_e32 v193, 0xbfb8aa3b, v193
	v_exp_f32_e32 v193, v193
	v_log_f32_e32 v192, v192
	v_cndmask_b32_e32 v195, 0, v171, vcc
	v_add_f32_e32 v193, 1.0, v193
	v_rcp_f32_e32 v193, v193
	v_mul_f32_e32 v194, 0x3f317217, v192
	v_fma_f32 v194, v192, s92, -v194
	v_fmac_f32_e32 v194, 0x3377d1cf, v192
	v_fmac_f32_e32 v194, 0x3f317217, v192
	v_cmp_lt_f32_e64 s[6:7], |v192|, s93
	v_fma_f32 v193, v185, v193, v159
	s_nop 0
	v_cndmask_b32_e64 v192, v192, v194, s[6:7]
	v_cmp_gt_f32_e64 s[6:7], s87, v193
	v_sub_f32_e32 v192, v192, v195
	v_cvt_pk_f16_f32 v192, v191, v192
	v_cndmask_b32_e64 v194, 0, 32, s[6:7]
	v_ldexp_f32 v193, v193, v194
	v_mul_f32_e32 v194, v55, v136
	v_mul_f32_e32 v194, 0xbfb8aa3b, v194
	v_exp_f32_e32 v194, v194
	v_log_f32_e32 v193, v193
	v_add_f32_e32 v194, 1.0, v194
	v_rcp_f32_e32 v194, v194
	v_mul_f32_e32 v195, 0x3f317217, v193
	v_fma_f32 v195, v193, s92, -v195
	v_fmac_f32_e32 v195, 0x3377d1cf, v193
	v_fma_f32 v194, v186, v194, v158
	v_cmp_gt_f32_e32 vcc, s87, v194
	v_fmac_f32_e32 v195, 0x3f317217, v193
	v_cmp_lt_f32_e64 s[8:9], |v193|, s93
	v_cndmask_b32_e64 v198, 0, 32, vcc
	v_ldexp_f32 v194, v194, v198
	v_mul_f32_e32 v198, v48, v136
	v_log_f32_e32 v194, v194
	v_mul_f32_e32 v198, 0xbfb8aa3b, v198
	v_exp_f32_e32 v198, v198
	v_cndmask_b32_e64 v193, v193, v195, s[8:9]
	v_cndmask_b32_e64 v195, 0, v171, s[6:7]
	v_sub_f32_e32 v193, v193, v195
	v_mul_f32_e32 v195, 0x3f317217, v194
	v_fma_f32 v195, v194, s92, -v195
	v_add_f32_e32 v198, 1.0, v198
	v_fmac_f32_e32 v195, 0x3377d1cf, v194
	v_rcp_f32_e32 v198, v198
	v_fmac_f32_e32 v195, 0x3f317217, v194
	v_cmp_lt_f32_e64 s[6:7], |v194|, s93
	v_fma_f32 v198, v187, v198, v157
	s_nop 0
	v_cndmask_b32_e64 v194, v194, v195, s[6:7]
	v_cndmask_b32_e32 v195, 0, v171, vcc
	v_sub_f32_e32 v194, v194, v195
	v_cvt_pk_f16_f32 v193, v193, v194
	v_mul_f32_e32 v194, v49, v136
	v_cmp_gt_f32_e32 vcc, s87, v198
	v_mul_f32_e32 v194, 0xbfb8aa3b, v194
	v_exp_f32_e32 v194, v194
	v_cndmask_b32_e64 v199, 0, 32, vcc
	v_ldexp_f32 v198, v198, v199
	v_log_f32_e32 v198, v198
	v_add_f32_e32 v194, 1.0, v194
	v_rcp_f32_e32 v194, v194
	v_cndmask_b32_e32 v195, 0, v171, vcc
	v_mul_f32_e32 v191, 0x3f317217, v198
	v_fma_f32 v191, v198, s92, -v191
	v_fmac_f32_e32 v191, 0x3377d1cf, v198
	v_fmac_f32_e32 v191, 0x3f317217, v198
	v_cmp_lt_f32_e64 s[6:7], |v198|, s93
	v_fma_f32 v194, v182, v194, v156
	v_cmp_gt_f32_e32 vcc, s87, v194
	v_cndmask_b32_e64 v191, v198, v191, s[6:7]
	v_sub_f32_e32 v191, v191, v195
	v_cndmask_b32_e64 v195, 0, 32, vcc
	v_ldexp_f32 v194, v194, v195
	v_mul_f32_e32 v195, v50, v136
	v_mul_f32_e32 v195, 0xbfb8aa3b, v195
	v_exp_f32_e32 v195, v195
	v_log_f32_e32 v194, v194
	v_mul_f32_e32 v136, v51, v136
	v_mul_f32_e32 v136, 0xbfb8aa3b, v136
	v_add_f32_e32 v195, 1.0, v195
	v_rcp_f32_e32 v195, v195
	v_exp_f32_e32 v136, v136
	v_mul_f32_e32 v198, 0x3f317217, v194
	v_fma_f32 v198, v194, s92, -v198
	v_fmac_f32_e32 v198, 0x3377d1cf, v194
	v_fmac_f32_e32 v198, 0x3f317217, v194
	v_cmp_lt_f32_e64 s[6:7], |v194|, s93
	v_fma_f32 v195, v189, v195, v155
	v_add_f32_e32 v136, 1.0, v136
	v_cndmask_b32_e64 v194, v194, v198, s[6:7]
	v_cmp_gt_f32_e64 s[6:7], s87, v195
; __device__ __forceinline__ float fsigm(float x) { return __builtin_amdgcn_rcpf(1.f + __expf(-x)); }
; __device__ __forceinline__ float row_rs(const float* ssq, int row) { return ssq ? rsqrtf(ssq[row] * (1.f / 1024.f) + RMS_EPS) : 1.f; }
;     __device__ __forceinline__ void operator()(const f32x4 (&acc)[2][2][4][2], const Unit& u, int wr, int wc, int fr, int fq) const {
;     ...
;                 for (int m = 0; m < 4; ++m) { const int row = row0 + ai * HALF + m * 16; const float rs = row_rs(ssq, row);
; #pragma unroll
;                     for (int bj = 0; bj < 2; ++bj) { f16x4 o[2];
; #pragma unroll
;                         for (int n = 0; n < 2; ++n) { const f32x4 p = acc[ai][bj][m][n] * rs;
; #pragma unroll
;                             for (int j = 0; j < 4; ++j) { const float l = lb[bj][n][j]; const float f = l + (1.f - l) * fsigm(p[j]); o[n][j] = (_Float16)__logf(f); } }
;                         const u32x2 a0 = __builtin_bit_cast(u32x2, o[0]), a1 = __builtin_bit_cast(u32x2, o[1]); u32x4 w; w.x = a0.x; w.y = a0.y; w.z = a1.x; w.w = a1.y;
;                         *(u32x4*)(LF + (size_t)row * 512 + cbase + bj * HALF) = w; } }
	v_rcp_f32_e32 v136, v136
	s_nop 0
	v_cndmask_b32_e64 v198, 0, 32, s[6:7]
	v_ldexp_f32 v195, v195, v198
	v_log_f32_e32 v195, v195
	v_fma_f32 v136, v190, v136, v154
	v_cndmask_b32_e32 v198, 0, v171, vcc
	v_cmp_gt_f32_e32 vcc, s87, v136
	v_sub_f32_e32 v194, v194, v198
	v_mul_f32_e32 v198, 0x3f317217, v195
	v_cndmask_b32_e64 v199, 0, 32, vcc
	v_ldexp_f32 v136, v136, v199
	v_fma_f32 v198, v195, s92, -v198
	v_log_f32_e32 v136, v136
	v_fmac_f32_e32 v198, 0x3377d1cf, v195
	v_fmac_f32_e32 v198, 0x3f317217, v195
	v_cmp_lt_f32_e64 s[8:9], |v195|, s93
	v_cvt_pk_f16_f32 v194, v191, v194
	s_nop 0
	v_cndmask_b32_e64 v195, v195, v198, s[8:9]
	v_cndmask_b32_e64 v198, 0, v171, s[6:7]
	v_sub_f32_e32 v195, v195, v198
	v_mul_f32_e32 v198, 0x3f317217, v136
	v_fma_f32 v198, v136, s92, -v198
	v_fmac_f32_e32 v198, 0x3377d1cf, v136
	v_fmac_f32_e32 v198, 0x3f317217, v136
	v_cmp_lt_f32_e64 s[6:7], |v136|, s93
	s_nop 1
	v_cndmask_b32_e64 v136, v136, v198, s[6:7]
	v_cndmask_b32_e32 v198, 0, v171, vcc
	v_sub_f32_e32 v136, v136, v198
	v_cvt_pk_f16_f32 v195, v195, v136
	global_store_dwordx4 v[196:197], v[192:195], off offset:256
	v_fmamk_f32 v136, v214, 0x3a800000, v170
	v_rsq_f32_e32 v136, v136
	s_nop 0
	v_mul_f32_e32 v191, v44, v136
	v_mul_f32_e32 v191, 0xbfb8aa3b, v191
	v_exp_f32_e32 v191, v191
	v_mul_f32_e32 v193, v45, v136
	v_mul_f32_e32 v193, 0xbfb8aa3b, v193
	v_exp_f32_e32 v193, v193
	v_add_f32_e32 v191, 1.0, v191
	v_rcp_f32_e32 v191, v191
	v_add_f32_e32 v193, 1.0, v193
	v_rcp_f32_e32 v193, v193
	v_fma_f32 v191, v176, v191, v175
	v_cmp_gt_f32_e32 vcc, s87, v191
	s_nop 1
	v_cndmask_b32_e64 v192, 0, 32, vcc
	v_ldexp_f32 v191, v191, v192
	v_log_f32_e32 v191, v191
	s_nop 0
	v_mul_f32_e32 v192, 0x3f317217, v191
	v_fma_f32 v192, v191, s92, -v192
	v_fmac_f32_e32 v192, 0x3377d1cf, v191
	v_fmac_f32_e32 v192, 0x3f317217, v191
	v_cmp_lt_f32_e64 s[6:7], |v191|, s93
	s_nop 1
	v_cndmask_b32_e64 v191, v191, v192, s[6:7]
	v_cndmask_b32_e32 v192, 0, v171, vcc
	v_sub_f32_e32 v191, v191, v192
	v_fma_f32 v192, v177, v193, v174
	v_cmp_gt_f32_e32 vcc, s87, v192
	s_nop 1
	v_cndmask_b32_e64 v193, 0, 32, vcc
	v_ldexp_f32 v192, v192, v193
	v_mul_f32_e32 v193, v46, v136
	v_mul_f32_e32 v193, 0xbfb8aa3b, v193
	v_exp_f32_e32 v193, v193
	v_log_f32_e32 v192, v192
	v_cndmask_b32_e32 v195, 0, v171, vcc
	v_add_f32_e32 v193, 1.0, v193
	v_rcp_f32_e32 v193, v193
	v_mul_f32_e32 v194, 0x3f317217, v192
	v_fma_f32 v194, v192, s92, -v194
	v_fmac_f32_e32 v194, 0x3377d1cf, v192
	v_fmac_f32_e32 v194, 0x3f317217, v192
	v_cmp_lt_f32_e64 s[6:7], |v192|, s93
	v_fma_f32 v193, v178, v193, v173
	s_nop 0
	v_cndmask_b32_e64 v192, v192, v194, s[6:7]
	v_cmp_gt_f32_e64 s[6:7], s87, v193
	v_sub_f32_e32 v192, v192, v195
	v_cvt_pk_f16_f32 v192, v191, v192
	v_cndmask_b32_e64 v194, 0, 32, s[6:7]
	v_ldexp_f32 v193, v193, v194
	v_mul_f32_e32 v194, v47, v136
	v_mul_f32_e32 v194, 0xbfb8aa3b, v194
	v_exp_f32_e32 v194, v194
	v_log_f32_e32 v193, v193
	v_add_f32_e32 v194, 1.0, v194
	v_rcp_f32_e32 v194, v194
	v_mul_f32_e32 v195, 0x3f317217, v193
	v_fma_f32 v195, v193, s92, -v195
	v_fmac_f32_e32 v195, 0x3377d1cf, v193
	v_fma_f32 v194, v183, v194, v172
	v_cmp_gt_f32_e32 vcc, s87, v194
	v_fmac_f32_e32 v195, 0x3f317217, v193
	v_cmp_lt_f32_e64 s[8:9], |v193|, s93
	v_cndmask_b32_e64 v196, 0, 32, vcc
	v_ldexp_f32 v194, v194, v196
	v_mul_f32_e32 v196, v40, v136
	v_log_f32_e32 v194, v194
	v_mul_f32_e32 v196, 0xbfb8aa3b, v196
	v_exp_f32_e32 v196, v196
	v_cndmask_b32_e64 v193, v193, v195, s[8:9]
	v_cndmask_b32_e64 v195, 0, v171, s[6:7]
	v_sub_f32_e32 v193, v193, v195
	v_mul_f32_e32 v195, 0x3f317217, v194
	v_fma_f32 v195, v194, s92, -v195
	v_add_f32_e32 v196, 1.0, v196
	v_fmac_f32_e32 v195, 0x3377d1cf, v194
	v_rcp_f32_e32 v196, v196
	v_fmac_f32_e32 v195, 0x3f317217, v194
	v_cmp_lt_f32_e64 s[6:7], |v194|, s93
	v_fma_f32 v196, v149, v196, v165
	s_nop 0
	v_cndmask_b32_e64 v194, v194, v195, s[6:7]
	v_cndmask_b32_e32 v195, 0, v171, vcc
	v_sub_f32_e32 v194, v194, v195
	v_cvt_pk_f16_f32 v193, v193, v194
	v_mul_f32_e32 v194, v41, v136
	v_cmp_gt_f32_e32 vcc, s87, v196
	v_mul_f32_e32 v194, 0xbfb8aa3b, v194
	v_exp_f32_e32 v194, v194
	v_cndmask_b32_e64 v197, 0, 32, vcc
	v_ldexp_f32 v196, v196, v197
	v_log_f32_e32 v196, v196
	v_add_f32_e32 v194, 1.0, v194
	v_rcp_f32_e32 v194, v194
	v_cndmask_b32_e32 v195, 0, v171, vcc
	v_mul_f32_e32 v191, 0x3f317217, v196
	v_fma_f32 v191, v196, s92, -v191
	v_fmac_f32_e32 v191, 0x3377d1cf, v196
	v_fmac_f32_e32 v191, 0x3f317217, v196
	v_cmp_lt_f32_e64 s[6:7], |v196|, s93
	v_fma_f32 v194, v179, v194, v164
	v_cmp_gt_f32_e32 vcc, s87, v194
	v_cndmask_b32_e64 v191, v196, v191, s[6:7]
	v_sub_f32_e32 v191, v191, v195
	v_cndmask_b32_e64 v195, 0, 32, vcc
	v_ldexp_f32 v194, v194, v195
	v_mul_f32_e32 v195, v42, v136
	v_mul_f32_e32 v195, 0xbfb8aa3b, v195
	v_exp_f32_e32 v195, v195
	v_log_f32_e32 v194, v194
	v_cndmask_b32_e32 v197, 0, v171, vcc
	v_add_f32_e32 v195, 1.0, v195
	v_rcp_f32_e32 v195, v195
	v_mul_f32_e32 v196, 0x3f317217, v194
	v_fma_f32 v196, v194, s92, -v196
	v_fmac_f32_e32 v196, 0x3377d1cf, v194
	v_fmac_f32_e32 v196, 0x3f317217, v194
	v_cmp_lt_f32_e64 s[6:7], |v194|, s93
	v_fma_f32 v195, v180, v195, v163
	s_nop 0
	v_cndmask_b32_e64 v194, v194, v196, s[6:7]
	v_cmp_gt_f32_e64 s[6:7], s87, v195
	v_sub_f32_e32 v194, v194, v197
	v_cvt_pk_f16_f32 v194, v191, v194
	v_cndmask_b32_e64 v196, 0, 32, s[6:7]
	v_ldexp_f32 v195, v195, v196
	v_mul_f32_e32 v196, v43, v136
	v_mul_f32_e32 v196, 0xbfb8aa3b, v196
	v_exp_f32_e32 v196, v196
	v_log_f32_e32 v195, v195
	v_add_f32_e32 v196, 1.0, v196
	v_rcp_f32_e32 v196, v196
	v_mul_f32_e32 v197, 0x3f317217, v195
	v_fma_f32 v197, v195, s92, -v197
	v_fmac_f32_e32 v197, 0x3377d1cf, v195
; __device__ __forceinline__ float fsigm(float x) { return __builtin_amdgcn_rcpf(1.f + __expf(-x)); }
; __device__ __forceinline__ float row_rs(const float* ssq, int row) { return ssq ? rsqrtf(ssq[row] * (1.f / 1024.f) + RMS_EPS) : 1.f; }
;     __device__ __forceinline__ void operator()(const f32x4 (&acc)[2][2][4][2], const Unit& u, int wr, int wc, int fr, int fq) const {
;     ...
;                 for (int m = 0; m < 4; ++m) { const int row = row0 + ai * HALF + m * 16; const float rs = row_rs(ssq, row);
; #pragma unroll
;                     for (int bj = 0; bj < 2; ++bj) { f16x4 o[2];
; #pragma unroll
;                         for (int n = 0; n < 2; ++n) { const f32x4 p = acc[ai][bj][m][n] * rs;
; #pragma unroll
;                             for (int j = 0; j < 4; ++j) { const float l = lb[bj][n][j]; const float f = l + (1.f - l) * fsigm(p[j]); o[n][j] = (_Float16)__logf(f); } }
;                         const u32x2 a0 = __builtin_bit_cast(u32x2, o[0]), a1 = __builtin_bit_cast(u32x2, o[1]); u32x4 w; w.x = a0.x; w.y = a0.y; w.z = a1.x; w.w = a1.y;
;                         *(u32x4*)(LF + (size_t)row * 512 + cbase + bj * HALF) = w; } }
	v_fma_f32 v196, v188, v196, v162
	v_cmp_gt_f32_e32 vcc, s87, v196
	v_fmac_f32_e32 v197, 0x3f317217, v195
	v_cmp_lt_f32_e64 s[8:9], |v195|, s93
	v_cndmask_b32_e64 v198, 0, 32, vcc
	v_ldexp_f32 v196, v196, v198
	v_log_f32_e32 v196, v196
	v_cndmask_b32_e64 v195, v195, v197, s[8:9]
	v_cndmask_b32_e64 v197, 0, v171, s[6:7]
	v_mul_f32_e32 v198, v36, v136
	v_sub_f32_e32 v195, v195, v197
	v_mul_f32_e32 v197, 0x3f317217, v196
	v_mul_f32_e32 v198, 0xbfb8aa3b, v198
	v_fma_f32 v197, v196, s92, -v197
	v_exp_f32_e32 v198, v198
	v_fmac_f32_e32 v197, 0x3377d1cf, v196
	v_fmac_f32_e32 v197, 0x3f317217, v196
	v_cmp_lt_f32_e64 s[6:7], |v196|, s93
	s_nop 1
	v_cndmask_b32_e64 v196, v196, v197, s[6:7]
	v_cndmask_b32_e32 v197, 0, v171, vcc
	v_sub_f32_e32 v196, v196, v197
	v_add_f32_e32 v197, 1.0, v198
	v_rcp_f32_e32 v198, v197
	v_cvt_pk_f16_f32 v195, v195, v196
	v_lshl_add_u64 v[196:197], v[152:153], 0, s[40:41]
	v_fma_f32 v191, v184, v198, v161
	v_cmp_gt_f32_e32 vcc, s87, v191
	s_nop 1
	v_cndmask_b32_e64 v198, 0, 32, vcc
	v_ldexp_f32 v191, v191, v198
	v_add_co_u32_e64 v198, s[6:7], s89, v152
	v_log_f32_e32 v191, v191
	s_nop 0
	v_addc_co_u32_e64 v199, s[6:7], 0, v153, s[6:7]
	global_store_dwordx4 v[198:199], v[192:195], off
	v_cmp_lt_f32_e64 s[6:7], |v191|, s93
	s_nop 0
	v_mul_f32_e32 v193, v37, v136
	v_mul_f32_e32 v193, 0xbfb8aa3b, v193
	v_exp_f32_e32 v193, v193
	v_mul_f32_e32 v192, 0x3f317217, v191
	v_fma_f32 v192, v191, s92, -v192
	v_fmac_f32_e32 v192, 0x3377d1cf, v191
	v_add_f32_e32 v193, 1.0, v193
	v_rcp_f32_e32 v193, v193
	v_fmac_f32_e32 v192, 0x3f317217, v191
	v_cndmask_b32_e64 v191, v191, v192, s[6:7]
	v_cndmask_b32_e32 v192, 0, v171, vcc
	v_sub_f32_e32 v191, v191, v192
	v_fma_f32 v192, v181, v193, v160
	v_cmp_gt_f32_e32 vcc, s87, v192
	s_nop 1
	v_cndmask_b32_e64 v193, 0, 32, vcc
	v_ldexp_f32 v192, v192, v193
	v_mul_f32_e32 v193, v38, v136
	v_mul_f32_e32 v193, 0xbfb8aa3b, v193
	v_exp_f32_e32 v193, v193
	v_log_f32_e32 v192, v192
	v_cndmask_b32_e32 v195, 0, v171, vcc
	v_add_f32_e32 v193, 1.0, v193
	v_rcp_f32_e32 v193, v193
	v_mul_f32_e32 v194, 0x3f317217, v192
	v_fma_f32 v194, v192, s92, -v194
	v_fmac_f32_e32 v194, 0x3377d1cf, v192
	v_fmac_f32_e32 v194, 0x3f317217, v192
	v_cmp_lt_f32_e64 s[6:7], |v192|, s93
	v_fma_f32 v193, v185, v193, v159
	s_nop 0
	v_cndmask_b32_e64 v192, v192, v194, s[6:7]
	v_cmp_gt_f32_e64 s[6:7], s87, v193
	v_sub_f32_e32 v192, v192, v195
	v_cvt_pk_f16_f32 v192, v191, v192
	v_cndmask_b32_e64 v194, 0, 32, s[6:7]
	v_ldexp_f32 v193, v193, v194
	v_mul_f32_e32 v194, v39, v136
	v_mul_f32_e32 v194, 0xbfb8aa3b, v194
	v_exp_f32_e32 v194, v194
	v_log_f32_e32 v193, v193
	v_add_f32_e32 v194, 1.0, v194
	v_rcp_f32_e32 v194, v194
	v_mul_f32_e32 v195, 0x3f317217, v193
	v_fma_f32 v195, v193, s92, -v195
	v_fmac_f32_e32 v195, 0x3377d1cf, v193
	v_fma_f32 v194, v186, v194, v158
	v_cmp_gt_f32_e32 vcc, s87, v194
	v_fmac_f32_e32 v195, 0x3f317217, v193
	v_cmp_lt_f32_e64 s[8:9], |v193|, s93
	v_cndmask_b32_e64 v198, 0, 32, vcc
	v_ldexp_f32 v194, v194, v198
	v_mul_f32_e32 v198, v32, v136
	v_log_f32_e32 v194, v194
	v_mul_f32_e32 v198, 0xbfb8aa3b, v198
	v_exp_f32_e32 v198, v198
	v_cndmask_b32_e64 v193, v193, v195, s[8:9]
	v_cndmask_b32_e64 v195, 0, v171, s[6:7]
	v_sub_f32_e32 v193, v193, v195
	v_mul_f32_e32 v195, 0x3f317217, v194
	v_fma_f32 v195, v194, s92, -v195
	v_add_f32_e32 v198, 1.0, v198
	v_fmac_f32_e32 v195, 0x3377d1cf, v194
	v_rcp_f32_e32 v198, v198
	v_fmac_f32_e32 v195, 0x3f317217, v194
	v_cmp_lt_f32_e64 s[6:7], |v194|, s93
	v_fma_f32 v198, v187, v198, v157
	s_nop 0
	v_cndmask_b32_e64 v194, v194, v195, s[6:7]
	v_cndmask_b32_e32 v195, 0, v171, vcc
	v_sub_f32_e32 v194, v194, v195
	v_cvt_pk_f16_f32 v193, v193, v194
	v_mul_f32_e32 v194, v33, v136
	v_cmp_gt_f32_e32 vcc, s87, v198
	v_mul_f32_e32 v194, 0xbfb8aa3b, v194
	v_exp_f32_e32 v194, v194
	v_cndmask_b32_e64 v199, 0, 32, vcc
	v_ldexp_f32 v198, v198, v199
	v_log_f32_e32 v198, v198
	v_add_f32_e32 v194, 1.0, v194
	v_rcp_f32_e32 v194, v194
	v_cndmask_b32_e32 v195, 0, v171, vcc
	v_mul_f32_e32 v191, 0x3f317217, v198
	v_fma_f32 v191, v198, s92, -v191
	v_fmac_f32_e32 v191, 0x3377d1cf, v198
	v_fmac_f32_e32 v191, 0x3f317217, v198
	v_cmp_lt_f32_e64 s[6:7], |v198|, s93
	v_fma_f32 v194, v182, v194, v156
	v_cmp_gt_f32_e32 vcc, s87, v194
	v_cndmask_b32_e64 v191, v198, v191, s[6:7]
	v_sub_f32_e32 v191, v191, v195
	v_cndmask_b32_e64 v195, 0, 32, vcc
	v_ldexp_f32 v194, v194, v195
	v_mul_f32_e32 v195, v34, v136
	v_mul_f32_e32 v195, 0xbfb8aa3b, v195
	v_exp_f32_e32 v195, v195
	v_log_f32_e32 v194, v194
	v_mul_f32_e32 v136, v35, v136
	v_mul_f32_e32 v136, 0xbfb8aa3b, v136
	v_add_f32_e32 v195, 1.0, v195
	v_rcp_f32_e32 v195, v195
	v_exp_f32_e32 v136, v136
	v_mul_f32_e32 v198, 0x3f317217, v194
	v_fma_f32 v198, v194, s92, -v198
	v_fmac_f32_e32 v198, 0x3377d1cf, v194
	v_fmac_f32_e32 v198, 0x3f317217, v194
	v_cmp_lt_f32_e64 s[6:7], |v194|, s93
	v_fma_f32 v195, v189, v195, v155
	v_add_f32_e32 v136, 1.0, v136
	v_cndmask_b32_e64 v194, v194, v198, s[6:7]
	v_cmp_gt_f32_e64 s[6:7], s87, v195
	v_rcp_f32_e32 v136, v136
	s_nop 0
	v_cndmask_b32_e64 v198, 0, 32, s[6:7]
	v_ldexp_f32 v195, v195, v198
	v_log_f32_e32 v195, v195
	v_fma_f32 v136, v190, v136, v154
	v_cndmask_b32_e32 v198, 0, v171, vcc
	v_cmp_gt_f32_e32 vcc, s87, v136
	v_sub_f32_e32 v194, v194, v198
	v_mul_f32_e32 v198, 0x3f317217, v195
	v_cndmask_b32_e64 v199, 0, 32, vcc
	v_ldexp_f32 v136, v136, v199
	v_fma_f32 v198, v195, s92, -v198
	v_log_f32_e32 v136, v136
	v_fmac_f32_e32 v198, 0x3377d1cf, v195
	v_fmac_f32_e32 v198, 0x3f317217, v195
	v_cmp_lt_f32_e64 s[8:9], |v195|, s93
	v_cvt_pk_f16_f32 v194, v191, v194
	s_nop 0
	v_cndmask_b32_e64 v195, v195, v198, s[8:9]
	v_cndmask_b32_e64 v198, 0, v171, s[6:7]
; __device__ __forceinline__ float fsigm(float x) { return __builtin_amdgcn_rcpf(1.f + __expf(-x)); }
; __device__ __forceinline__ float row_rs(const float* ssq, int row) { return ssq ? rsqrtf(ssq[row] * (1.f / 1024.f) + RMS_EPS) : 1.f; }
;     __device__ __forceinline__ void operator()(const f32x4 (&acc)[2][2][4][2], const Unit& u, int wr, int wc, int fr, int fq) const {
;     ...
;                 for (int m = 0; m < 4; ++m) { const int row = row0 + ai * HALF + m * 16; const float rs = row_rs(ssq, row);
; #pragma unroll
;                     for (int bj = 0; bj < 2; ++bj) { f16x4 o[2];
; #pragma unroll
;                         for (int n = 0; n < 2; ++n) { const f32x4 p = acc[ai][bj][m][n] * rs;
; #pragma unroll
;                             for (int j = 0; j < 4; ++j) { const float l = lb[bj][n][j]; const float f = l + (1.f - l) * fsigm(p[j]); o[n][j] = (_Float16)__logf(f); } }
;                         const u32x2 a0 = __builtin_bit_cast(u32x2, o[0]), a1 = __builtin_bit_cast(u32x2, o[1]); u32x4 w; w.x = a0.x; w.y = a0.y; w.z = a1.x; w.w = a1.y;
;                         *(u32x4*)(LF + (size_t)row * 512 + cbase + bj * HALF) = w; } }
	v_sub_f32_e32 v195, v195, v198
	v_mul_f32_e32 v198, 0x3f317217, v136
	v_fma_f32 v198, v136, s92, -v198
	v_fmac_f32_e32 v198, 0x3377d1cf, v136
	v_fmac_f32_e32 v198, 0x3f317217, v136
	v_cmp_lt_f32_e64 s[6:7], |v136|, s93
	s_nop 1
	v_cndmask_b32_e64 v136, v136, v198, s[6:7]
	v_cndmask_b32_e32 v198, 0, v171, vcc
	v_sub_f32_e32 v136, v136, v198
	v_cvt_pk_f16_f32 v195, v195, v136
	global_store_dwordx4 v[196:197], v[192:195], off offset:256
	v_fmamk_f32 v136, v215, 0x3a800000, v170
	v_rsq_f32_e32 v136, v136
	s_nop 0
	v_mul_f32_e32 v191, v28, v136
	v_mul_f32_e32 v191, 0xbfb8aa3b, v191
	v_exp_f32_e32 v191, v191
	v_mul_f32_e32 v193, v29, v136
	v_mul_f32_e32 v193, 0xbfb8aa3b, v193
	v_exp_f32_e32 v193, v193
	v_add_f32_e32 v191, 1.0, v191
	v_rcp_f32_e32 v191, v191
	v_add_f32_e32 v193, 1.0, v193
	v_rcp_f32_e32 v193, v193
	v_fma_f32 v191, v176, v191, v175
	v_cmp_gt_f32_e32 vcc, s87, v191
	s_nop 1
	v_cndmask_b32_e64 v192, 0, 32, vcc
	v_ldexp_f32 v191, v191, v192
	v_log_f32_e32 v191, v191
	s_nop 0
	v_mul_f32_e32 v192, 0x3f317217, v191
	v_fma_f32 v192, v191, s92, -v192
	v_fmac_f32_e32 v192, 0x3377d1cf, v191
	v_fmac_f32_e32 v192, 0x3f317217, v191
	v_cmp_lt_f32_e64 s[6:7], |v191|, s93
	s_nop 1
	v_cndmask_b32_e64 v191, v191, v192, s[6:7]
	v_cndmask_b32_e32 v192, 0, v171, vcc
	v_sub_f32_e32 v191, v191, v192
	v_fma_f32 v192, v177, v193, v174
	v_cmp_gt_f32_e32 vcc, s87, v192
	s_nop 1
	v_cndmask_b32_e64 v193, 0, 32, vcc
	v_ldexp_f32 v192, v192, v193
	v_mul_f32_e32 v193, v30, v136
	v_mul_f32_e32 v193, 0xbfb8aa3b, v193
	v_exp_f32_e32 v193, v193
	v_log_f32_e32 v192, v192
	v_cndmask_b32_e32 v195, 0, v171, vcc
	v_add_f32_e32 v193, 1.0, v193
	v_rcp_f32_e32 v193, v193
	v_mul_f32_e32 v194, 0x3f317217, v192
	v_fma_f32 v194, v192, s92, -v194
	v_fmac_f32_e32 v194, 0x3377d1cf, v192
	v_fmac_f32_e32 v194, 0x3f317217, v192
	v_cmp_lt_f32_e64 s[6:7], |v192|, s93
	v_fma_f32 v193, v178, v193, v173
	s_nop 0
	v_cndmask_b32_e64 v192, v192, v194, s[6:7]
	v_cmp_gt_f32_e64 s[6:7], s87, v193
	v_sub_f32_e32 v192, v192, v195
	v_cvt_pk_f16_f32 v192, v191, v192
	v_cndmask_b32_e64 v194, 0, 32, s[6:7]
	v_ldexp_f32 v193, v193, v194
	v_mul_f32_e32 v194, v31, v136
	v_mul_f32_e32 v194, 0xbfb8aa3b, v194
	v_exp_f32_e32 v194, v194
	v_log_f32_e32 v193, v193
	v_add_f32_e32 v194, 1.0, v194
	v_rcp_f32_e32 v194, v194
	v_mul_f32_e32 v195, 0x3f317217, v193
	v_fma_f32 v195, v193, s92, -v195
	v_fmac_f32_e32 v195, 0x3377d1cf, v193
	v_fma_f32 v194, v183, v194, v172
	v_cmp_gt_f32_e32 vcc, s87, v194
	v_fmac_f32_e32 v195, 0x3f317217, v193
	v_cmp_lt_f32_e64 s[8:9], |v193|, s93
	v_cndmask_b32_e64 v196, 0, 32, vcc
	v_ldexp_f32 v194, v194, v196
	v_mul_f32_e32 v196, v24, v136
	v_log_f32_e32 v194, v194
	v_mul_f32_e32 v196, 0xbfb8aa3b, v196
	v_exp_f32_e32 v196, v196
	v_cndmask_b32_e64 v193, v193, v195, s[8:9]
	v_cndmask_b32_e64 v195, 0, v171, s[6:7]
	v_sub_f32_e32 v193, v193, v195
	v_mul_f32_e32 v195, 0x3f317217, v194
	v_fma_f32 v195, v194, s92, -v195
	v_add_f32_e32 v196, 1.0, v196
	v_fmac_f32_e32 v195, 0x3377d1cf, v194
	v_rcp_f32_e32 v196, v196
	v_fmac_f32_e32 v195, 0x3f317217, v194
	v_cmp_lt_f32_e64 s[6:7], |v194|, s93
	v_fma_f32 v196, v149, v196, v165
	s_nop 0
	v_cndmask_b32_e64 v194, v194, v195, s[6:7]
	v_cndmask_b32_e32 v195, 0, v171, vcc
	v_sub_f32_e32 v194, v194, v195
	v_cvt_pk_f16_f32 v193, v193, v194
	v_mul_f32_e32 v194, v25, v136
	v_cmp_gt_f32_e32 vcc, s87, v196
	v_mul_f32_e32 v194, 0xbfb8aa3b, v194
	v_exp_f32_e32 v194, v194
	v_cndmask_b32_e64 v197, 0, 32, vcc
	v_ldexp_f32 v196, v196, v197
	v_log_f32_e32 v196, v196
	v_add_f32_e32 v194, 1.0, v194
	v_rcp_f32_e32 v194, v194
	v_cndmask_b32_e32 v195, 0, v171, vcc
	v_mul_f32_e32 v191, 0x3f317217, v196
	v_fma_f32 v191, v196, s92, -v191
	v_fmac_f32_e32 v191, 0x3377d1cf, v196
	v_fmac_f32_e32 v191, 0x3f317217, v196
	v_cmp_lt_f32_e64 s[6:7], |v196|, s93
	v_fma_f32 v194, v179, v194, v164
	v_cmp_gt_f32_e32 vcc, s87, v194
	v_cndmask_b32_e64 v191, v196, v191, s[6:7]
	v_sub_f32_e32 v191, v191, v195
	v_cndmask_b32_e64 v195, 0, 32, vcc
	v_ldexp_f32 v194, v194, v195
	v_mul_f32_e32 v195, v26, v136
	v_mul_f32_e32 v195, 0xbfb8aa3b, v195
	v_exp_f32_e32 v195, v195
	v_log_f32_e32 v194, v194
	v_cndmask_b32_e32 v197, 0, v171, vcc
	v_add_f32_e32 v195, 1.0, v195
	v_rcp_f32_e32 v195, v195
	v_mul_f32_e32 v196, 0x3f317217, v194
	v_fma_f32 v196, v194, s92, -v196
	v_fmac_f32_e32 v196, 0x3377d1cf, v194
	v_fmac_f32_e32 v196, 0x3f317217, v194
	v_cmp_lt_f32_e64 s[6:7], |v194|, s93
	v_fma_f32 v195, v180, v195, v163
	s_nop 0
	v_cndmask_b32_e64 v194, v194, v196, s[6:7]
	v_cmp_gt_f32_e64 s[6:7], s87, v195
	v_sub_f32_e32 v194, v194, v197
	v_cvt_pk_f16_f32 v194, v191, v194
	v_cndmask_b32_e64 v196, 0, 32, s[6:7]
	v_ldexp_f32 v195, v195, v196
	v_mul_f32_e32 v196, v27, v136
	v_mul_f32_e32 v196, 0xbfb8aa3b, v196
	v_exp_f32_e32 v196, v196
	v_log_f32_e32 v195, v195
	v_add_f32_e32 v196, 1.0, v196
	v_rcp_f32_e32 v196, v196
	v_mul_f32_e32 v197, 0x3f317217, v195
	v_fma_f32 v197, v195, s92, -v197
	v_fmac_f32_e32 v197, 0x3377d1cf, v195
	v_fma_f32 v196, v188, v196, v162
	v_cmp_gt_f32_e32 vcc, s87, v196
	v_fmac_f32_e32 v197, 0x3f317217, v195
	v_cmp_lt_f32_e64 s[8:9], |v195|, s93
	v_cndmask_b32_e64 v198, 0, 32, vcc
	v_ldexp_f32 v196, v196, v198
	v_log_f32_e32 v196, v196
	v_cndmask_b32_e64 v195, v195, v197, s[8:9]
	v_cndmask_b32_e64 v197, 0, v171, s[6:7]
	v_mul_f32_e32 v198, v20, v136
	v_sub_f32_e32 v195, v195, v197
	v_mul_f32_e32 v197, 0x3f317217, v196
	v_mul_f32_e32 v198, 0xbfb8aa3b, v198
	v_fma_f32 v197, v196, s92, -v197
	v_exp_f32_e32 v198, v198
	v_fmac_f32_e32 v197, 0x3377d1cf, v196
	v_fmac_f32_e32 v197, 0x3f317217, v196
	v_cmp_lt_f32_e64 s[6:7], |v196|, s93
	s_nop 1
	v_cndmask_b32_e64 v196, v196, v197, s[6:7]
; __device__ __forceinline__ float fsigm(float x) { return __builtin_amdgcn_rcpf(1.f + __expf(-x)); }
; __device__ __forceinline__ float row_rs(const float* ssq, int row) { return ssq ? rsqrtf(ssq[row] * (1.f / 1024.f) + RMS_EPS) : 1.f; }
;     __device__ __forceinline__ void operator()(const f32x4 (&acc)[2][2][4][2], const Unit& u, int wr, int wc, int fr, int fq) const {
;     ...
;                 for (int m = 0; m < 4; ++m) { const int row = row0 + ai * HALF + m * 16; const float rs = row_rs(ssq, row);
; #pragma unroll
;                     for (int bj = 0; bj < 2; ++bj) { f16x4 o[2];
; #pragma unroll
;                         for (int n = 0; n < 2; ++n) { const f32x4 p = acc[ai][bj][m][n] * rs;
; #pragma unroll
;                             for (int j = 0; j < 4; ++j) { const float l = lb[bj][n][j]; const float f = l + (1.f - l) * fsigm(p[j]); o[n][j] = (_Float16)__logf(f); } }
;                         const u32x2 a0 = __builtin_bit_cast(u32x2, o[0]), a1 = __builtin_bit_cast(u32x2, o[1]); u32x4 w; w.x = a0.x; w.y = a0.y; w.z = a1.x; w.w = a1.y;
;                         *(u32x4*)(LF + (size_t)row * 512 + cbase + bj * HALF) = w; } }
	v_cndmask_b32_e32 v197, 0, v171, vcc
	v_sub_f32_e32 v196, v196, v197
	v_add_f32_e32 v197, 1.0, v198
	v_rcp_f32_e32 v198, v197
	v_cvt_pk_f16_f32 v195, v195, v196
	v_lshl_add_u64 v[196:197], v[152:153], 0, s[42:43]
	v_fma_f32 v191, v184, v198, v161
	v_cmp_gt_f32_e32 vcc, s87, v191
	s_nop 1
	v_cndmask_b32_e64 v198, 0, 32, vcc
	v_ldexp_f32 v191, v191, v198
	v_add_co_u32_e64 v198, s[6:7], s90, v152
	v_log_f32_e32 v191, v191
	s_nop 0
	v_addc_co_u32_e64 v199, s[6:7], 0, v153, s[6:7]
	global_store_dwordx4 v[198:199], v[192:195], off
	v_cmp_lt_f32_e64 s[6:7], |v191|, s93
	s_nop 0
	v_mul_f32_e32 v193, v21, v136
	v_mul_f32_e32 v193, 0xbfb8aa3b, v193
	v_exp_f32_e32 v193, v193
	v_mul_f32_e32 v192, 0x3f317217, v191
	v_fma_f32 v192, v191, s92, -v192
	v_fmac_f32_e32 v192, 0x3377d1cf, v191
	v_add_f32_e32 v193, 1.0, v193
	v_rcp_f32_e32 v193, v193
	v_fmac_f32_e32 v192, 0x3f317217, v191
	v_cndmask_b32_e64 v191, v191, v192, s[6:7]
	v_cndmask_b32_e32 v192, 0, v171, vcc
	v_sub_f32_e32 v191, v191, v192
	v_fma_f32 v192, v181, v193, v160
	v_cmp_gt_f32_e32 vcc, s87, v192
	s_nop 1
	v_cndmask_b32_e64 v193, 0, 32, vcc
	v_ldexp_f32 v192, v192, v193
	v_mul_f32_e32 v193, v22, v136
	v_mul_f32_e32 v193, 0xbfb8aa3b, v193
	v_exp_f32_e32 v193, v193
	v_log_f32_e32 v192, v192
	v_cndmask_b32_e32 v195, 0, v171, vcc
	v_add_f32_e32 v193, 1.0, v193
	v_rcp_f32_e32 v193, v193
	v_mul_f32_e32 v194, 0x3f317217, v192
	v_fma_f32 v194, v192, s92, -v194
	v_fmac_f32_e32 v194, 0x3377d1cf, v192
	v_fmac_f32_e32 v194, 0x3f317217, v192
	v_cmp_lt_f32_e64 s[6:7], |v192|, s93
	v_fma_f32 v193, v185, v193, v159
	s_nop 0
	v_cndmask_b32_e64 v192, v192, v194, s[6:7]
	v_cmp_gt_f32_e64 s[6:7], s87, v193
	v_sub_f32_e32 v192, v192, v195
	v_cvt_pk_f16_f32 v192, v191, v192
	v_cndmask_b32_e64 v194, 0, 32, s[6:7]
	v_ldexp_f32 v193, v193, v194
	v_mul_f32_e32 v194, v23, v136
	v_mul_f32_e32 v194, 0xbfb8aa3b, v194
	v_exp_f32_e32 v194, v194
	v_log_f32_e32 v193, v193
	v_add_f32_e32 v194, 1.0, v194
	v_rcp_f32_e32 v194, v194
	v_mul_f32_e32 v195, 0x3f317217, v193
	v_fma_f32 v195, v193, s92, -v195
	v_fmac_f32_e32 v195, 0x3377d1cf, v193
	v_fma_f32 v194, v186, v194, v158
	v_cmp_gt_f32_e32 vcc, s87, v194
	v_fmac_f32_e32 v195, 0x3f317217, v193
	v_cmp_lt_f32_e64 s[8:9], |v193|, s93
	v_cndmask_b32_e64 v198, 0, 32, vcc
	v_ldexp_f32 v194, v194, v198
	v_mul_f32_e32 v198, v16, v136
	v_log_f32_e32 v194, v194
	v_mul_f32_e32 v198, 0xbfb8aa3b, v198
	v_exp_f32_e32 v198, v198
	v_cndmask_b32_e64 v193, v193, v195, s[8:9]
	v_cndmask_b32_e64 v195, 0, v171, s[6:7]
	v_sub_f32_e32 v193, v193, v195
	v_mul_f32_e32 v195, 0x3f317217, v194
	v_fma_f32 v195, v194, s92, -v195
	v_add_f32_e32 v198, 1.0, v198
	v_fmac_f32_e32 v195, 0x3377d1cf, v194
	v_rcp_f32_e32 v198, v198
	v_fmac_f32_e32 v195, 0x3f317217, v194
	v_cmp_lt_f32_e64 s[6:7], |v194|, s93
	v_fma_f32 v198, v187, v198, v157
	s_nop 0
	v_cndmask_b32_e64 v194, v194, v195, s[6:7]
	v_cndmask_b32_e32 v195, 0, v171, vcc
	v_sub_f32_e32 v194, v194, v195
	v_cvt_pk_f16_f32 v193, v193, v194
	v_mul_f32_e32 v194, v17, v136
	v_cmp_gt_f32_e32 vcc, s87, v198
	v_mul_f32_e32 v194, 0xbfb8aa3b, v194
	v_exp_f32_e32 v194, v194
	v_cndmask_b32_e64 v199, 0, 32, vcc
	v_ldexp_f32 v198, v198, v199
	v_log_f32_e32 v198, v198
	v_add_f32_e32 v194, 1.0, v194
	v_rcp_f32_e32 v194, v194
	v_cndmask_b32_e32 v195, 0, v171, vcc
	v_mul_f32_e32 v191, 0x3f317217, v198
	v_fma_f32 v191, v198, s92, -v191
	v_fmac_f32_e32 v191, 0x3377d1cf, v198
	v_fmac_f32_e32 v191, 0x3f317217, v198
	v_cmp_lt_f32_e64 s[6:7], |v198|, s93
	v_fma_f32 v194, v182, v194, v156
	v_cmp_gt_f32_e32 vcc, s87, v194
	v_cndmask_b32_e64 v191, v198, v191, s[6:7]
	v_sub_f32_e32 v191, v191, v195
	v_cndmask_b32_e64 v195, 0, 32, vcc
	v_ldexp_f32 v194, v194, v195
	v_mul_f32_e32 v195, v18, v136
	v_mul_f32_e32 v195, 0xbfb8aa3b, v195
	v_exp_f32_e32 v195, v195
	v_log_f32_e32 v194, v194
	v_mul_f32_e32 v136, v19, v136
	v_mul_f32_e32 v136, 0xbfb8aa3b, v136
	v_add_f32_e32 v195, 1.0, v195
	v_rcp_f32_e32 v195, v195
	v_exp_f32_e32 v136, v136
	v_mul_f32_e32 v198, 0x3f317217, v194
	v_fma_f32 v198, v194, s92, -v198
	v_fmac_f32_e32 v198, 0x3377d1cf, v194
	v_fmac_f32_e32 v198, 0x3f317217, v194
	v_cmp_lt_f32_e64 s[6:7], |v194|, s93
	v_fma_f32 v195, v189, v195, v155
	v_add_f32_e32 v136, 1.0, v136
	v_cndmask_b32_e64 v194, v194, v198, s[6:7]
	v_cmp_gt_f32_e64 s[6:7], s87, v195
	v_rcp_f32_e32 v136, v136
	s_nop 0
	v_cndmask_b32_e64 v198, 0, 32, s[6:7]
	v_ldexp_f32 v195, v195, v198
	v_log_f32_e32 v195, v195
	v_fma_f32 v136, v190, v136, v154
	v_cndmask_b32_e32 v198, 0, v171, vcc
	v_cmp_gt_f32_e32 vcc, s87, v136
	v_sub_f32_e32 v194, v194, v198
	v_mul_f32_e32 v198, 0x3f317217, v195
	v_cndmask_b32_e64 v199, 0, 32, vcc
	v_ldexp_f32 v136, v136, v199
	v_fma_f32 v198, v195, s92, -v198
	v_log_f32_e32 v136, v136
	v_fmac_f32_e32 v198, 0x3377d1cf, v195
	v_fmac_f32_e32 v198, 0x3f317217, v195
	v_cmp_lt_f32_e64 s[8:9], |v195|, s93
	v_cvt_pk_f16_f32 v194, v191, v194
	s_nop 0
	v_cndmask_b32_e64 v195, v195, v198, s[8:9]
	v_cndmask_b32_e64 v198, 0, v171, s[6:7]
	v_sub_f32_e32 v195, v195, v198
	v_mul_f32_e32 v198, 0x3f317217, v136
	v_fma_f32 v198, v136, s92, -v198
	v_fmac_f32_e32 v198, 0x3377d1cf, v136
	v_fmac_f32_e32 v198, 0x3f317217, v136
	v_cmp_lt_f32_e64 s[6:7], |v136|, s93
	s_nop 1
	v_cndmask_b32_e64 v136, v136, v198, s[6:7]
	v_cndmask_b32_e32 v198, 0, v171, vcc
	v_sub_f32_e32 v136, v136, v198
	v_cvt_pk_f16_f32 v195, v195, v136
	global_store_dwordx4 v[196:197], v[192:195], off offset:256
	v_fmamk_f32 v136, v216, 0x3a800000, v170
	v_rsq_f32_e32 v136, v136
	s_nop 0
	v_mul_f32_e32 v150, v12, v136
	v_mul_f32_e32 v150, 0xbfb8aa3b, v150
	v_exp_f32_e32 v150, v150
	s_nop 0
	v_add_f32_e32 v150, 1.0, v150
	v_rcp_f32_e32 v150, v150
; __device__ __forceinline__ float fsigm(float x) { return __builtin_amdgcn_rcpf(1.f + __expf(-x)); }
; __device__ __forceinline__ float row_rs(const float* ssq, int row) { return ssq ? rsqrtf(ssq[row] * (1.f / 1024.f) + RMS_EPS) : 1.f; }
;     __device__ __forceinline__ void operator()(const f32x4 (&acc)[2][2][4][2], const Unit& u, int wr, int wc, int fr, int fq) const {
;     ...
;                 for (int m = 0; m < 4; ++m) { const int row = row0 + ai * HALF + m * 16; const float rs = row_rs(ssq, row);
; #pragma unroll
;                     for (int bj = 0; bj < 2; ++bj) { f16x4 o[2];
; #pragma unroll
;                         for (int n = 0; n < 2; ++n) { const f32x4 p = acc[ai][bj][m][n] * rs;
; #pragma unroll
;                             for (int j = 0; j < 4; ++j) { const float l = lb[bj][n][j]; const float f = l + (1.f - l) * fsigm(p[j]); o[n][j] = (_Float16)__logf(f); } }
;                         const u32x2 a0 = __builtin_bit_cast(u32x2, o[0]), a1 = __builtin_bit_cast(u32x2, o[1]); u32x4 w; w.x = a0.x; w.y = a0.y; w.z = a1.x; w.w = a1.y;
;                         *(u32x4*)(LF + (size_t)row * 512 + cbase + bj * HALF) = w; } }
	s_nop 0
	v_fmac_f32_e32 v175, v176, v150
	v_cmp_gt_f32_e32 vcc, s87, v175
	s_nop 1
	v_cndmask_b32_e64 v150, 0, 32, vcc
	v_ldexp_f32 v150, v175, v150
	v_mul_f32_e32 v175, v13, v136
	v_mul_f32_e32 v175, 0xbfb8aa3b, v175
	v_exp_f32_e32 v175, v175
	v_log_f32_e32 v150, v150
	v_add_f32_e32 v175, 1.0, v175
	v_rcp_f32_e32 v175, v175
	v_mul_f32_e32 v151, 0x3f317217, v150
	v_fma_f32 v151, v150, s92, -v151
	v_fmac_f32_e32 v151, 0x3377d1cf, v150
	v_fmac_f32_e32 v151, 0x3f317217, v150
	v_cmp_lt_f32_e64 s[6:7], |v150|, s93
	v_fmac_f32_e32 v174, v177, v175
	s_nop 0
	v_cndmask_b32_e64 v150, v150, v151, s[6:7]
	v_cndmask_b32_e32 v151, 0, v171, vcc
	v_cmp_gt_f32_e32 vcc, s87, v174
	v_sub_f32_e32 v150, v150, v151
	s_nop 0
	v_cndmask_b32_e64 v151, 0, 32, vcc
	v_ldexp_f32 v151, v174, v151
	v_mul_f32_e32 v174, v14, v136
	v_mul_f32_e32 v174, 0xbfb8aa3b, v174
	v_exp_f32_e32 v174, v174
	v_log_f32_e32 v151, v151
	v_add_f32_e32 v174, 1.0, v174
	v_rcp_f32_e32 v174, v174
	v_mul_f32_e32 v175, 0x3f317217, v151
	v_fma_f32 v175, v151, s92, -v175
	v_fmac_f32_e32 v175, 0x3377d1cf, v151
	v_fmac_f32_e32 v175, 0x3f317217, v151
	v_cmp_lt_f32_e64 s[6:7], |v151|, s93
	v_fmac_f32_e32 v173, v178, v174
	s_nop 0
	v_cndmask_b32_e64 v151, v151, v175, s[6:7]
	v_cmp_gt_f32_e64 s[6:7], s87, v173
	v_cndmask_b32_e32 v175, 0, v171, vcc
	v_sub_f32_e32 v151, v151, v175
	v_cndmask_b32_e64 v174, 0, 32, s[6:7]
	v_ldexp_f32 v173, v173, v174
	v_mul_f32_e32 v174, v15, v136
	v_mul_f32_e32 v174, 0xbfb8aa3b, v174
	v_exp_f32_e32 v174, v174
	v_log_f32_e32 v173, v173
	v_add_f32_e32 v174, 1.0, v174
	v_mul_f32_e32 v175, 0x3f317217, v173
	v_rcp_f32_e32 v174, v174
	v_fma_f32 v175, v173, s92, -v175
	v_fmac_f32_e32 v175, 0x3377d1cf, v173
	v_fmac_f32_e32 v175, 0x3f317217, v173
	v_cmp_lt_f32_e64 s[8:9], |v173|, s93
	v_fmac_f32_e32 v172, v183, v174
	v_cmp_gt_f32_e32 vcc, s87, v172
	v_cndmask_b32_e64 v173, v173, v175, s[8:9]
	v_mul_f32_e32 v175, v8, v136
	v_mul_f32_e32 v175, 0xbfb8aa3b, v175
	v_cndmask_b32_e64 v174, 0, 32, vcc
	v_exp_f32_e32 v175, v175
	v_ldexp_f32 v172, v172, v174
	v_log_f32_e32 v172, v172
	v_cndmask_b32_e64 v174, 0, v171, s[6:7]
	v_add_f32_e32 v175, 1.0, v175
	v_rcp_f32_e32 v175, v175
	v_sub_f32_e32 v173, v173, v174
	v_mul_f32_e32 v174, 0x3f317217, v172
	v_fma_f32 v174, v172, s92, -v174
	v_fmac_f32_e32 v174, 0x3377d1cf, v172
	v_fmac_f32_e32 v174, 0x3f317217, v172
	v_cmp_lt_f32_e64 s[6:7], |v172|, s93
	v_fmac_f32_e32 v165, v149, v175
	s_nop 0
	v_cndmask_b32_e64 v172, v172, v174, s[6:7]
	v_cndmask_b32_e32 v174, 0, v171, vcc
	v_cmp_gt_f32_e32 vcc, s87, v165
	s_nop 1
	v_cndmask_b32_e64 v149, 0, 32, vcc
	v_ldexp_f32 v149, v165, v149
	v_sub_f32_e32 v165, v172, v174
	v_cvt_pk_f16_f32 v172, v150, v151
	v_mul_f32_e32 v151, v9, v136
	v_mul_f32_e32 v151, 0xbfb8aa3b, v151
	v_exp_f32_e32 v151, v151
	v_log_f32_e32 v149, v149
	v_cvt_pk_f16_f32 v173, v173, v165
	v_add_f32_e32 v151, 1.0, v151
	v_rcp_f32_e32 v151, v151
	v_mul_f32_e32 v150, 0x3f317217, v149
	v_fma_f32 v150, v149, s92, -v150
	v_fmac_f32_e32 v150, 0x3377d1cf, v149
	v_fmac_f32_e32 v150, 0x3f317217, v149
	v_cmp_lt_f32_e64 s[6:7], |v149|, s93
	v_fmac_f32_e32 v164, v179, v151
	v_mul_f32_e32 v151, v10, v136
	v_cndmask_b32_e64 v149, v149, v150, s[6:7]
	v_cndmask_b32_e32 v150, 0, v171, vcc
	v_cmp_gt_f32_e32 vcc, s87, v164
	v_mul_f32_e32 v151, 0xbfb8aa3b, v151
	v_sub_f32_e32 v149, v149, v150
	v_cndmask_b32_e64 v150, 0, 32, vcc
	v_exp_f32_e32 v151, v151
	v_ldexp_f32 v150, v164, v150
	v_log_f32_e32 v150, v150
	v_add_f32_e32 v151, 1.0, v151
	v_rcp_f32_e32 v151, v151
	v_mul_f32_e32 v164, 0x3f317217, v150
	v_fma_f32 v164, v150, s92, -v164
	v_fmac_f32_e32 v164, 0x3377d1cf, v150
	v_fmac_f32_e32 v164, 0x3f317217, v150
	v_cmp_lt_f32_e64 s[6:7], |v150|, s93
	v_fmac_f32_e32 v163, v180, v151
	s_nop 0
	v_cndmask_b32_e64 v150, v150, v164, s[6:7]
	v_cmp_gt_f32_e64 s[6:7], s87, v163
	v_cndmask_b32_e32 v164, 0, v171, vcc
	v_sub_f32_e32 v150, v150, v164
	v_cndmask_b32_e64 v151, 0, 32, s[6:7]
	v_ldexp_f32 v151, v163, v151
	v_mul_f32_e32 v163, v11, v136
	v_mul_f32_e32 v163, 0xbfb8aa3b, v163
	v_exp_f32_e32 v163, v163
	v_log_f32_e32 v151, v151
	v_cvt_pk_f16_f32 v174, v149, v150
	v_add_f32_e32 v163, 1.0, v163
	v_rcp_f32_e32 v163, v163
	v_mul_f32_e32 v164, 0x3f317217, v151
	v_fma_f32 v164, v151, s92, -v164
	v_fmac_f32_e32 v164, 0x3377d1cf, v151
	v_fmac_f32_e32 v162, v188, v163
	v_cmp_gt_f32_e32 vcc, s87, v162
	v_fmac_f32_e32 v164, 0x3f317217, v151
	v_cmp_lt_f32_e64 s[8:9], |v151|, s93
	v_cndmask_b32_e64 v163, 0, 32, vcc
	v_ldexp_f32 v162, v162, v163
	v_log_f32_e32 v162, v162
	v_cndmask_b32_e64 v151, v151, v164, s[8:9]
	v_cndmask_b32_e64 v163, 0, v171, s[6:7]
	v_mul_f32_e32 v164, v4, v136
	v_sub_f32_e32 v151, v151, v163
	v_mul_f32_e32 v163, 0x3f317217, v162
	v_mul_f32_e32 v164, 0xbfb8aa3b, v164
	v_fma_f32 v163, v162, s92, -v163
	v_exp_f32_e32 v164, v164
	v_fmac_f32_e32 v163, 0x3377d1cf, v162
	v_fmac_f32_e32 v163, 0x3f317217, v162
	v_cmp_lt_f32_e64 s[6:7], |v162|, s93
	s_nop 1
	v_cndmask_b32_e64 v162, v162, v163, s[6:7]
	v_cndmask_b32_e32 v163, 0, v171, vcc
	v_sub_f32_e32 v162, v162, v163
	v_add_f32_e32 v163, 1.0, v164
	v_rcp_f32_e32 v164, v163
	v_add_co_u32_e64 v150, s[6:7], s91, v152
; __device__ __forceinline__ float fsigm(float x) { return __builtin_amdgcn_rcpf(1.f + __expf(-x)); }
; __device__ __forceinline__ float row_rs(const float* ssq, int row) { return ssq ? rsqrtf(ssq[row] * (1.f / 1024.f) + RMS_EPS) : 1.f; }
;     __device__ __forceinline__ void operator()(const f32x4 (&acc)[2][2][4][2], const Unit& u, int wr, int wc, int fr, int fq) const {
;     ...
;                 for (int m = 0; m < 4; ++m) { const int row = row0 + ai * HALF + m * 16; const float rs = row_rs(ssq, row);
; #pragma unroll
;                     for (int bj = 0; bj < 2; ++bj) { f16x4 o[2];
; #pragma unroll
;                         for (int n = 0; n < 2; ++n) { const f32x4 p = acc[ai][bj][m][n] * rs;
; #pragma unroll
;                             for (int j = 0; j < 4; ++j) { const float l = lb[bj][n][j]; const float f = l + (1.f - l) * fsigm(p[j]); o[n][j] = (_Float16)__logf(f); } }
;                         const u32x2 a0 = __builtin_bit_cast(u32x2, o[0]), a1 = __builtin_bit_cast(u32x2, o[1]); u32x4 w; w.x = a0.x; w.y = a0.y; w.z = a1.x; w.w = a1.y;
;                         *(u32x4*)(LF + (size_t)row * 512 + cbase + bj * HALF) = w; } }
	v_cvt_pk_f16_f32 v175, v151, v162
	s_nop 0
	v_addc_co_u32_e64 v151, s[6:7], 0, v153, s[6:7]
	v_fmac_f32_e32 v161, v184, v164
	global_store_dwordx4 v[150:151], v[172:175], off
	v_mul_f32_e32 v151, v5, v136
	v_cmp_gt_f32_e32 vcc, s87, v161
	v_mul_f32_e32 v151, 0xbfb8aa3b, v151
	v_exp_f32_e32 v151, v151
	v_cndmask_b32_e64 v149, 0, 32, vcc
	v_ldexp_f32 v149, v161, v149
	v_log_f32_e32 v149, v149
	v_add_f32_e32 v151, 1.0, v151
	v_rcp_f32_e32 v151, v151
	v_lshl_add_u64 v[162:163], v[152:153], 0, s[62:63]
	v_mul_f32_e32 v150, 0x3f317217, v149
	v_fma_f32 v150, v149, s92, -v150
	v_fmac_f32_e32 v150, 0x3377d1cf, v149
	v_fmac_f32_e32 v150, 0x3f317217, v149
	v_cmp_lt_f32_e64 s[6:7], |v149|, s93
	v_fmac_f32_e32 v160, v181, v151
	v_mul_f32_e32 v151, v6, v136
	v_cndmask_b32_e64 v149, v149, v150, s[6:7]
	v_cndmask_b32_e32 v150, 0, v171, vcc
	v_cmp_gt_f32_e32 vcc, s87, v160
	v_sub_f32_e32 v149, v149, v150
	v_mul_f32_e32 v151, 0xbfb8aa3b, v151
	v_cndmask_b32_e64 v150, 0, 32, vcc
	v_ldexp_f32 v150, v160, v150
	v_log_f32_e32 v150, v150
	v_exp_f32_e32 v151, v151
	v_cndmask_b32_e32 v153, 0, v171, vcc
	v_mul_f32_e32 v152, 0x3f317217, v150
	v_fma_f32 v152, v150, s92, -v152
	v_fmac_f32_e32 v152, 0x3377d1cf, v150
	v_fmac_f32_e32 v152, 0x3f317217, v150
	v_cmp_lt_f32_e64 s[6:7], |v150|, s93
	v_add_f32_e32 v151, 1.0, v151
	v_rcp_f32_e32 v151, v151
	v_cndmask_b32_e64 v150, v150, v152, s[6:7]
	v_mul_f32_e32 v152, v7, v136
	v_mul_f32_e32 v152, 0xbfb8aa3b, v152
	v_exp_f32_e32 v152, v152
	v_fmac_f32_e32 v159, v185, v151
	v_cmp_gt_f32_e64 s[6:7], s87, v159
	v_sub_f32_e32 v150, v150, v153
	v_add_f32_e32 v152, 1.0, v152
	v_rcp_f32_e32 v152, v152
	v_cndmask_b32_e64 v151, 0, 32, s[6:7]
	v_ldexp_f32 v151, v159, v151
	v_log_f32_e32 v151, v151
	v_fmac_f32_e32 v158, v186, v152
	v_cmp_gt_f32_e32 vcc, s87, v158
	v_cvt_pk_f16_f32 v150, v149, v150
	v_mul_f32_e32 v153, 0x3f317217, v151
	v_cndmask_b32_e64 v152, 0, 32, vcc
	v_ldexp_f32 v152, v158, v152
	v_mul_f32_e32 v158, v0, v136
	v_mul_f32_e32 v158, 0xbfb8aa3b, v158
	v_exp_f32_e32 v158, v158
	v_fma_f32 v153, v151, s92, -v153
	v_log_f32_e32 v152, v152
	v_fmac_f32_e32 v153, 0x3377d1cf, v151
	v_fmac_f32_e32 v153, 0x3f317217, v151
	v_cmp_lt_f32_e64 s[8:9], |v151|, s93
	v_add_f32_e32 v158, 1.0, v158
	v_rcp_f32_e32 v158, v158
	v_cndmask_b32_e64 v151, v151, v153, s[8:9]
	v_cndmask_b32_e64 v153, 0, v171, s[6:7]
	v_sub_f32_e32 v151, v151, v153
	v_mul_f32_e32 v153, 0x3f317217, v152
	v_fma_f32 v153, v152, s92, -v153
	v_fmac_f32_e32 v153, 0x3377d1cf, v152
	v_fmac_f32_e32 v153, 0x3f317217, v152
	v_cmp_lt_f32_e64 s[6:7], |v152|, s93
	v_fmac_f32_e32 v157, v187, v158
	s_nop 0
	v_cndmask_b32_e64 v152, v152, v153, s[6:7]
	v_cndmask_b32_e32 v153, 0, v171, vcc
	v_cmp_gt_f32_e32 vcc, s87, v157
	v_sub_f32_e32 v152, v152, v153
	v_cvt_pk_f16_f32 v151, v151, v152
	v_cndmask_b32_e64 v158, 0, 32, vcc
	v_mul_f32_e32 v152, v1, v136
	v_ldexp_f32 v157, v157, v158
	v_mul_f32_e32 v152, 0xbfb8aa3b, v152
	v_log_f32_e32 v157, v157
	v_exp_f32_e32 v152, v152
	v_cndmask_b32_e32 v153, 0, v171, vcc
	v_mul_f32_e32 v149, 0x3f317217, v157
	v_add_f32_e32 v152, 1.0, v152
	v_fma_f32 v149, v157, s92, -v149
	v_rcp_f32_e32 v152, v152
	v_fmac_f32_e32 v149, 0x3377d1cf, v157
	v_fmac_f32_e32 v149, 0x3f317217, v157
	v_cmp_lt_f32_e64 s[6:7], |v157|, s93
	v_fmac_f32_e32 v156, v182, v152
	v_cmp_gt_f32_e32 vcc, s87, v156
	v_cndmask_b32_e64 v149, v157, v149, s[6:7]
	v_sub_f32_e32 v149, v149, v153
	v_mul_f32_e32 v153, v2, v136
	v_mul_f32_e32 v153, 0xbfb8aa3b, v153
	v_cndmask_b32_e64 v152, 0, 32, vcc
	v_exp_f32_e32 v153, v153
	v_ldexp_f32 v152, v156, v152
	v_log_f32_e32 v152, v152
	v_mul_f32_e32 v136, v3, v136
	v_add_f32_e32 v153, 1.0, v153
	v_mul_f32_e32 v136, 0xbfb8aa3b, v136
	v_rcp_f32_e32 v153, v153
	v_exp_f32_e32 v136, v136
	v_mul_f32_e32 v156, 0x3f317217, v152
	v_fma_f32 v156, v152, s92, -v156
	v_fmac_f32_e32 v156, 0x3377d1cf, v152
	v_fmac_f32_e32 v156, 0x3f317217, v152
	v_cmp_lt_f32_e64 s[6:7], |v152|, s93
	v_fmac_f32_e32 v155, v189, v153
	v_add_f32_e32 v136, 1.0, v136
	v_cndmask_b32_e64 v152, v152, v156, s[6:7]
	v_cmp_gt_f32_e64 s[6:7], s87, v155
	v_rcp_f32_e32 v136, v136
	s_nop 0
	v_cndmask_b32_e64 v153, 0, 32, s[6:7]
	v_ldexp_f32 v153, v155, v153
	v_log_f32_e32 v153, v153
	v_fmac_f32_e32 v154, v190, v136
	v_cndmask_b32_e32 v155, 0, v171, vcc
	v_cmp_gt_f32_e32 vcc, s87, v154
	v_sub_f32_e32 v152, v152, v155
	v_mul_f32_e32 v155, 0x3f317217, v153
	v_cndmask_b32_e64 v136, 0, 32, vcc
	v_ldexp_f32 v136, v154, v136
	v_fma_f32 v155, v153, s92, -v155
	v_log_f32_e32 v136, v136
	v_fmac_f32_e32 v155, 0x3377d1cf, v153
	v_fmac_f32_e32 v155, 0x3f317217, v153
	v_cmp_lt_f32_e64 s[8:9], |v153|, s93
	v_cndmask_b32_e64 v154, 0, v171, s[6:7]
	v_cmp_lt_f32_e64 s[6:7], |v136|, s93
	v_cndmask_b32_e64 v153, v153, v155, s[8:9]
	v_sub_f32_e32 v153, v153, v154
	v_mul_f32_e32 v154, 0x3f317217, v136
	v_fma_f32 v154, v136, s92, -v154
	v_fmac_f32_e32 v154, 0x3377d1cf, v136
	v_fmac_f32_e32 v154, 0x3f317217, v136
	v_cndmask_b32_e64 v136, v136, v154, s[6:7]
	v_cndmask_b32_e32 v154, 0, v171, vcc
	v_sub_f32_e32 v136, v136, v154
	v_cvt_pk_f16_f32 v153, v153, v136
	v_cvt_pk_f16_f32 v152, v149, v152
	global_store_dwordx4 v[162:163], v[150:153], off offset:256

; __device__ __forceinline__ unsigned cvt_pk_bf16(float lo, float hi) { cvf32x2_t v = {lo, hi}; cvbf16x2_t b = __builtin_convertvector(v, cvbf16x2_t); return __builtin_bit_cast(unsigned, b); }
; __device__ __forceinline__ float row_rs(const float* ssq, int row) { return ssq ? rsqrtf(ssq[row] * (1.f / 1024.f) + RMS_EPS) : 1.f; }
;     __device__ __forceinline__ void operator()(const f32x4 (&acc)[2][2][4][2], const Unit& u, int wr, int wc, int fr, int fq) const {
;     ...
;         if (pn >= 10) {
; #pragma unroll
;             for (int ai = 0; ai < 2; ++ai)
; #pragma unroll
;                 for (int m = 0; m < 4; ++m) { const int row = row0 + ai * HALF + m * 16; const float rs = row_rs(ssq, row); const float rs2 = rs * rs;
;                     const f32x4 v0 = acc[ai][0][m][0] * acc[ai][1][m][0] * rs2, v1 = acc[ai][0][m][1] * acc[ai][1][m][1] * rs2; u32x4 w;
;                     w.x = cvt_pk_bf16(v0[0], v0[1]); w.y = cvt_pk_bf16(v0[2], v0[3]); w.z = cvt_pk_bf16(v1[0], v1[1]); w.w = cvt_pk_bf16(v1[2], v1[3]);
.LBB0_514:
	v_ashrrev_i32_e32 v149, 31, v148
	v_lshl_add_u64 v[150:151], v[148:149], 2, s[30:31]
	global_load_dword v152, v[150:151], off
	global_load_dword v210, v[150:151], off offset:64
	global_load_dword v211, v[150:151], off offset:128
	global_load_dword v212, v[150:151], off offset:192
	global_load_dword v213, v[150:151], off offset:512
	global_load_dword v214, v[150:151], off offset:576
	global_load_dword v215, v[150:151], off offset:640
	global_load_dword v216, v[150:151], off offset:704
	v_pk_mul_f32 v[116:117], v[124:125], v[116:117]
	v_pk_mul_f32 v[118:119], v[126:127], v[118:119]
	s_lshl_b32 s6, s14, 7
	v_pk_mul_f32 v[120:121], v[120:121], v[112:113]
	s_add_i32 s14, s6, 0xfffffb00
	v_lshlrev_b64 v[112:113], 10, v[148:149]
	v_pk_mul_f32 v[114:115], v[122:123], v[114:115]
	v_lshl_add_u64 v[112:113], s[26:27], 0, v[112:113]
	s_lshl_b64 s[6:7], s[14:15], 1
	v_lshlrev_b32_e32 v136, 1, v138
	v_or_b32_e32 v122, 16, v148
	v_lshl_add_u64 v[112:113], v[112:113], 0, s[6:7]
	v_ashrrev_i32_e32 v123, 31, v122
	v_lshl_add_u64 v[112:113], v[112:113], 0, v[136:137]
	v_pk_mul_f32 v[102:103], v[110:111], v[102:103]
	v_pk_mul_f32 v[98:99], v[106:107], v[98:99]
	v_lshlrev_b64 v[106:107], 10, v[122:123]
	v_pk_mul_f32 v[100:101], v[108:109], v[100:101]
	v_pk_mul_f32 v[96:97], v[104:105], v[96:97]
	v_lshl_add_u64 v[106:107], s[26:27], 0, v[106:107]
	v_or_b32_e32 v104, 32, v148
	v_lshl_add_u64 v[106:107], v[106:107], 0, s[6:7]
	v_ashrrev_i32_e32 v105, 31, v104
	v_lshl_add_u64 v[106:107], v[106:107], 0, v[136:137]
	v_lshl_add_u64 v[108:109], v[104:105], 2, s[30:31]
	v_pk_mul_f32 v[86:87], v[94:95], v[86:87]
	v_pk_mul_f32 v[82:83], v[90:91], v[82:83]
	v_lshlrev_b64 v[90:91], 10, v[104:105]
	v_pk_mul_f32 v[84:85], v[92:93], v[84:85]
	v_pk_mul_f32 v[80:81], v[88:89], v[80:81]
	v_lshl_add_u64 v[90:91], s[26:27], 0, v[90:91]
	v_or_b32_e32 v88, 48, v148
	v_lshl_add_u64 v[90:91], v[90:91], 0, s[6:7]
	v_ashrrev_i32_e32 v89, 31, v88
	v_lshl_add_u64 v[90:91], v[90:91], 0, v[136:137]
	v_lshl_add_u64 v[92:93], v[88:89], 2, s[30:31]
	v_pk_mul_f32 v[66:67], v[74:75], v[66:67]
	v_pk_mul_f32 v[64:65], v[72:73], v[64:65]
	v_lshlrev_b64 v[72:73], 10, v[88:89]
	v_pk_mul_f32 v[70:71], v[78:79], v[70:71]
	v_pk_mul_f32 v[68:69], v[76:77], v[68:69]
	v_lshl_add_u64 v[72:73], s[26:27], 0, v[72:73]
	v_lshl_add_u64 v[72:73], v[72:73], 0, s[6:7]
	v_lshl_add_u64 v[72:73], v[72:73], 0, v[136:137]
	v_pk_mul_f32 v[48:49], v[56:57], v[48:49]
	v_pk_mul_f32 v[50:51], v[58:59], v[50:51]
	v_pk_mul_f32 v[54:55], v[62:63], v[54:55]
	v_pk_mul_f32 v[52:53], v[60:61], v[52:53]
	v_pk_mul_f32 v[32:33], v[40:41], v[32:33]
	v_pk_mul_f32 v[34:35], v[42:43], v[34:35]
	v_pk_mul_f32 v[38:39], v[46:47], v[38:39]
	v_pk_mul_f32 v[36:37], v[44:45], v[36:37]
	v_pk_mul_f32 v[16:17], v[24:25], v[16:17]
	v_pk_mul_f32 v[18:19], v[26:27], v[18:19]
	v_pk_mul_f32 v[22:23], v[30:31], v[22:23]
	v_pk_mul_f32 v[20:21], v[28:29], v[20:21]
	v_pk_mul_f32 v[2:3], v[10:11], v[2:3]
	v_pk_mul_f32 v[0:1], v[8:9], v[0:1]
	v_pk_mul_f32 v[6:7], v[14:15], v[6:7]
	v_pk_mul_f32 v[4:5], v[12:13], v[4:5]
	s_waitcnt vmcnt(0)
; __device__ __forceinline__ unsigned cvt_pk_bf16(float lo, float hi) { cvf32x2_t v = {lo, hi}; cvbf16x2_t b = __builtin_convertvector(v, cvbf16x2_t); return __builtin_bit_cast(unsigned, b); }
; __device__ __forceinline__ float row_rs(const float* ssq, int row) { return ssq ? rsqrtf(ssq[row] * (1.f / 1024.f) + RMS_EPS) : 1.f; }
;     __device__ __forceinline__ void operator()(const f32x4 (&acc)[2][2][4][2], const Unit& u, int wr, int wc, int fr, int fq) const {
;     ...
;                 for (int m = 0; m < 4; ++m) { const int row = row0 + ai * HALF + m * 16; const float rs = row_rs(ssq, row); const float rs2 = rs * rs;
;                     const f32x4 v0 = acc[ai][0][m][0] * acc[ai][1][m][0] * rs2, v1 = acc[ai][0][m][1] * acc[ai][1][m][1] * rs2; u32x4 w;
;                     w.x = cvt_pk_bf16(v0[0], v0[1]); w.y = cvt_pk_bf16(v0[2], v0[3]); w.z = cvt_pk_bf16(v1[0], v1[1]); w.w = cvt_pk_bf16(v1[2], v1[3]);
;                     *(u32x4*)(CU + (size_t)row * 512 + (pn - 10) * HALF + cw) = w; }
	v_fmamk_f32 v124, v152, 0x3a800000, v170
	v_rsq_f32_e32 v126, v124
	v_lshl_add_u64 v[124:125], v[122:123], 2, s[30:31]
	v_mul_f32_e32 v126, v126, v126
	v_pk_mul_f32 v[118:119], v[118:119], v[126:127] op_sel_hi:[1,0]
	v_pk_mul_f32 v[116:117], v[116:117], v[126:127] op_sel_hi:[1,0]
	v_pk_mul_f32 v[152:153], v[114:115], v[126:127] op_sel_hi:[1,0]
	v_pk_mul_f32 v[120:121], v[120:121], v[126:127] op_sel_hi:[1,0]
	v_cvt_pk_bf16_f32 v114, v116, v117
	v_cvt_pk_bf16_f32 v115, v118, v119
	v_cvt_pk_bf16_f32 v116, v120, v121
	v_cvt_pk_bf16_f32 v117, v152, v153
	global_store_dwordx4 v[112:113], v[114:117], off
	v_fmamk_f32 v110, v210, 0x3a800000, v170
	v_rsq_f32_e32 v110, v110
	s_nop 0
	v_mul_f32_e32 v110, v110, v110
	v_pk_mul_f32 v[102:103], v[102:103], v[110:111] op_sel_hi:[1,0]
	v_pk_mul_f32 v[100:101], v[100:101], v[110:111] op_sel_hi:[1,0]
	v_pk_mul_f32 v[114:115], v[98:99], v[110:111] op_sel_hi:[1,0]
	v_pk_mul_f32 v[98:99], v[96:97], v[110:111] op_sel_hi:[1,0]
	v_cvt_pk_bf16_f32 v96, v100, v101
	v_cvt_pk_bf16_f32 v97, v102, v103
	v_cvt_pk_bf16_f32 v98, v98, v99
	v_cvt_pk_bf16_f32 v99, v114, v115
	global_store_dwordx4 v[106:107], v[96:99], off
	v_fmamk_f32 v94, v211, 0x3a800000, v170
	v_rsq_f32_e32 v94, v94
	s_nop 0
	v_mul_f32_e32 v94, v94, v94
	v_pk_mul_f32 v[86:87], v[86:87], v[94:95] op_sel_hi:[1,0]
	v_pk_mul_f32 v[84:85], v[84:85], v[94:95] op_sel_hi:[1,0]
	v_pk_mul_f32 v[96:97], v[82:83], v[94:95] op_sel_hi:[1,0]
	v_pk_mul_f32 v[82:83], v[80:81], v[94:95] op_sel_hi:[1,0]
	v_cvt_pk_bf16_f32 v80, v84, v85
	v_cvt_pk_bf16_f32 v81, v86, v87
	v_cvt_pk_bf16_f32 v82, v82, v83
	v_cvt_pk_bf16_f32 v83, v96, v97
	global_store_dwordx4 v[90:91], v[80:83], off
	v_fmamk_f32 v74, v212, 0x3a800000, v170
	v_rsq_f32_e32 v74, v74
	s_nop 0
	v_mul_f32_e32 v74, v74, v74
	v_pk_mul_f32 v[70:71], v[70:71], v[74:75] op_sel_hi:[1,0]
	v_pk_mul_f32 v[68:69], v[68:69], v[74:75] op_sel_hi:[1,0]
	v_pk_mul_f32 v[76:77], v[66:67], v[74:75] op_sel_hi:[1,0]
	v_pk_mul_f32 v[66:67], v[64:65], v[74:75] op_sel_hi:[1,0]
	v_cvt_pk_bf16_f32 v64, v68, v69
	v_cvt_pk_bf16_f32 v65, v70, v71
	v_cvt_pk_bf16_f32 v66, v66, v67
	v_cvt_pk_bf16_f32 v67, v76, v77
	global_store_dwordx4 v[72:73], v[64:67], off
	v_fmamk_f32 v56, v213, 0x3a800000, v170
	v_rsq_f32_e32 v58, v56
	v_add_co_u32_e64 v56, s[6:7], s88, v112
	v_mul_f32_e32 v58, v58, v58
	v_pk_mul_f32 v[54:55], v[54:55], v[58:59] op_sel_hi:[1,0]
	v_pk_mul_f32 v[52:53], v[52:53], v[58:59] op_sel_hi:[1,0]
	v_pk_mul_f32 v[60:61], v[50:51], v[58:59] op_sel_hi:[1,0]
	v_pk_mul_f32 v[50:51], v[48:49], v[58:59] op_sel_hi:[1,0]
	v_addc_co_u32_e64 v57, s[6:7], 0, v113, s[6:7]
	v_cvt_pk_bf16_f32 v48, v52, v53
	v_cvt_pk_bf16_f32 v49, v54, v55
	v_cvt_pk_bf16_f32 v50, v50, v51
	v_cvt_pk_bf16_f32 v51, v60, v61
	global_store_dwordx4 v[56:57], v[48:51], off
	v_fmamk_f32 v40, v214, 0x3a800000, v170
	v_rsq_f32_e32 v42, v40
	v_add_co_u32_e64 v40, s[6:7], s89, v112
	v_mul_f32_e32 v42, v42, v42
	v_pk_mul_f32 v[38:39], v[38:39], v[42:43] op_sel_hi:[1,0]
	v_pk_mul_f32 v[36:37], v[36:37], v[42:43] op_sel_hi:[1,0]
	v_pk_mul_f32 v[44:45], v[34:35], v[42:43] op_sel_hi:[1,0]
	v_pk_mul_f32 v[34:35], v[32:33], v[42:43] op_sel_hi:[1,0]
	v_addc_co_u32_e64 v41, s[6:7], 0, v113, s[6:7]
	v_cvt_pk_bf16_f32 v32, v36, v37
	v_cvt_pk_bf16_f32 v33, v38, v39
	v_cvt_pk_bf16_f32 v34, v34, v35
	v_cvt_pk_bf16_f32 v35, v44, v45
	global_store_dwordx4 v[40:41], v[32:35], off
	v_fmamk_f32 v24, v215, 0x3a800000, v170
	v_rsq_f32_e32 v26, v24
	v_add_co_u32_e64 v24, s[6:7], s90, v112
	v_mul_f32_e32 v26, v26, v26
	v_pk_mul_f32 v[22:23], v[22:23], v[26:27] op_sel_hi:[1,0]
	v_pk_mul_f32 v[20:21], v[20:21], v[26:27] op_sel_hi:[1,0]
	v_pk_mul_f32 v[28:29], v[18:19], v[26:27] op_sel_hi:[1,0]
	v_pk_mul_f32 v[18:19], v[16:17], v[26:27] op_sel_hi:[1,0]
	v_addc_co_u32_e64 v25, s[6:7], 0, v113, s[6:7]
	v_cvt_pk_bf16_f32 v16, v20, v21
	v_cvt_pk_bf16_f32 v17, v22, v23
	v_cvt_pk_bf16_f32 v18, v18, v19
	v_cvt_pk_bf16_f32 v19, v28, v29
	global_store_dwordx4 v[24:25], v[16:19], off
	v_add_co_u32_e32 v8, vcc, 0x2c000, v112
	v_fmamk_f32 v10, v216, 0x3a800000, v170
	v_rsq_f32_e32 v10, v10
	s_nop 0
	v_mov_b32_e32 v9, v10
	v_mul_f32_e32 v10, v9, v9
	v_pk_mul_f32 v[6:7], v[6:7], v[10:11] op_sel_hi:[1,0]
	v_pk_mul_f32 v[4:5], v[4:5], v[10:11] op_sel_hi:[1,0]
	v_pk_mul_f32 v[12:13], v[2:3], v[10:11] op_sel_hi:[1,0]
	v_pk_mul_f32 v[2:3], v[0:1], v[10:11] op_sel_hi:[1,0]
	v_cvt_pk_bf16_f32 v0, v4, v5
	v_cvt_pk_bf16_f32 v1, v6, v7
	v_cvt_pk_bf16_f32 v2, v2, v3
	v_cvt_pk_bf16_f32 v3, v12, v13
	v_addc_co_u32_e32 v9, vcc, 0, v113, vcc
	global_store_dwordx4 v[8:9], v[0:3], off
	s_andn2_b64 vcc, exec, s[4:5]
	s_mov_b64 s[4:5], -1
	s_cbranch_vccnz .LBB0_454

; __device__ __forceinline__ float fsigm(float x) { return __builtin_amdgcn_rcpf(1.f + __expf(-x)); }
; __device__ __forceinline__ float row_rs(const float* ssq, int row) { return ssq ? rsqrtf(ssq[row] * (1.f / 1024.f) + RMS_EPS) : 1.f; }
;     __device__ __forceinline__ void operator()(const f32x4 (&acc)[2][2][4][2], const Unit& u, int wr, int wc, int fr, int fq) const {
;     ...
;             float lb[2][2][4];
; #pragma unroll
;             for (int bj = 0; bj < 2; ++bj)
; #pragma unroll
;                 for (int n = 0; n < 2; ++n) { const int c = cbase + bj * HALF + n * 4; const f32x4 l0 = *(const f32x4*)(lbl + c), l1 = *(const f32x4*)(lbl + 512 + c);
; #pragma unroll
;                     for (int j = 0; j < 4; ++j) lb[bj][n][j] = fsigm(l0[j] - l1[j]); }
; #pragma unroll
;             for (int ai = 0; ai < 2; ++ai)
; #pragma unroll
;                 for (int m = 0; m < 4; ++m) { const int row = row0 + ai * HALF + m * 16; const float rs = row_rs(ssq, row);
; #pragma unroll
;                     for (int bj = 0; bj < 2; ++bj) { f16x4 o[2];
; #pragma unroll
;                         for (int n = 0; n < 2; ++n) { const f32x4 p = acc[ai][bj][m][n] * rs;
; #pragma unroll
;                             for (int j = 0; j < 4; ++j) { const float l = lb[bj][n][j]; const float f = l + (1.f - l) * fsigm(p[j]); o[n][j] = (_Float16)__logf(f); } }
.LBB0_645:
	s_and_b64 vcc, exec, s[6:7]
	s_cbranch_vccz .LBB0_647
	v_ashrrev_i32_e32 v149, 31, v148
	v_lshlrev_b32_e32 v136, 2, v181
	v_lshl_add_u64 v[150:151], v[148:149], 2, s[30:31]
	global_load_dwordx4 v[152:155], v136, s[16:17] offset:2048
	global_load_dwordx4 v[156:159], v136, s[16:17]
	global_load_dwordx4 v[160:163], v136, s[16:17] offset:16
	global_load_dwordx4 v[172:175], v136, s[16:17] offset:2064
	global_load_dwordx4 v[176:179], v136, s[16:17] offset:2560
	global_load_dwordx4 v[182:185], v136, s[16:17] offset:512
	global_load_dwordx4 v[186:189], v136, s[16:17] offset:528
	global_load_dwordx4 v[190:193], v136, s[16:17] offset:2576
	s_waitcnt vmcnt(0)
	v_sub_f32_e32 v152, v156, v152
	global_load_dword v136, v[150:151], off
	global_load_dword v210, v[150:151], off offset:64
	global_load_dword v211, v[150:151], off offset:128
	global_load_dword v212, v[150:151], off offset:192
	global_load_dword v213, v[150:151], off offset:512
	global_load_dword v214, v[150:151], off offset:576
	global_load_dword v215, v[150:151], off offset:640
	global_load_dword v216, v[150:151], off offset:704
	v_sub_f32_e32 v153, v157, v153
	v_sub_f32_e32 v156, v160, v172
	v_sub_f32_e32 v160, v182, v176
	v_mul_f32_e32 v153, 0xbfb8aa3b, v153
	v_sub_f32_e32 v172, v188, v192
	v_mul_f32_e32 v176, 0xbfb8aa3b, v172
	v_exp_f32_e32 v153, v153
	v_sub_f32_e32 v154, v158, v154
	v_sub_f32_e32 v158, v162, v174
	v_mul_f32_e32 v152, 0xbfb8aa3b, v152
	v_add_f32_e32 v153, 1.0, v153
	v_rcp_f32_e32 v174, v153
	v_exp_f32_e32 v152, v152
	v_sub_f32_e32 v157, v161, v173
	v_sub_f32_e32 v161, v183, v177
	v_sub_f32_e32 v155, v159, v155
	v_mul_f32_e32 v160, 0xbfb8aa3b, v160
	v_mul_f32_e32 v161, 0xbfb8aa3b, v161
	v_add_f32_e32 v152, 1.0, v152
	v_sub_f32_e32 v159, v163, v175
	v_mul_f32_e32 v155, 0xbfb8aa3b, v155
	v_exp_f32_e32 v160, v160
	v_exp_f32_e32 v161, v161
	v_rcp_f32_e32 v175, v152
	v_exp_f32_e32 v155, v155
	v_exp_f32_e32 v152, v176
	v_add_f32_e32 v160, 1.0, v160
	v_add_f32_e32 v177, 1.0, v161
	v_sub_f32_e32 v176, 1.0, v175
	v_sub_f32_e32 v162, v184, v178
	v_add_f32_e32 v155, 1.0, v155
	v_rcp_f32_e32 v161, v160
	v_rcp_f32_e32 v160, v177
	v_add_f32_e32 v152, 1.0, v152
	v_mul_f32_e32 v159, 0xbfb8aa3b, v159
	v_mul_f32_e32 v162, 0xbfb8aa3b, v162
	v_mul_f32_e32 v154, 0xbfb8aa3b, v154
	v_exp_f32_e32 v159, v159
	v_exp_f32_e32 v162, v162
	v_exp_f32_e32 v154, v154
	v_sub_f32_e32 v163, v185, v179
	v_add_f32_e32 v159, 1.0, v159
	v_add_f32_e32 v178, 1.0, v162
	v_mul_f32_e32 v158, 0xbfb8aa3b, v158
	v_mul_f32_e32 v163, 0xbfb8aa3b, v163
	v_add_f32_e32 v154, 1.0, v154
	v_rcp_f32_e32 v162, v159
	v_rcp_f32_e32 v159, v178
	v_exp_f32_e32 v158, v158
	v_exp_f32_e32 v163, v163
	v_rcp_f32_e32 v173, v154
	v_sub_f32_e32 v164, v186, v190
	v_add_f32_e32 v158, 1.0, v158
	v_add_f32_e32 v179, 1.0, v163
	v_rcp_f32_e32 v163, v158
	v_rcp_f32_e32 v158, v179
	v_mul_f32_e32 v157, 0xbfb8aa3b, v157
	v_mul_f32_e32 v164, 0xbfb8aa3b, v164
	v_exp_f32_e32 v157, v157
	v_exp_f32_e32 v164, v164
	v_sub_f32_e32 v165, v187, v191
	v_mul_f32_e32 v156, 0xbfb8aa3b, v156
	v_add_f32_e32 v157, 1.0, v157
	v_add_f32_e32 v180, 1.0, v164
	v_mul_f32_e32 v165, 0xbfb8aa3b, v165
	v_rcp_f32_e32 v164, v157
	v_rcp_f32_e32 v157, v180
	v_exp_f32_e32 v156, v156
	v_exp_f32_e32 v165, v165
	v_add_f32_e32 v156, 1.0, v156
	v_add_f32_e32 v182, 1.0, v165
	v_rcp_f32_e32 v165, v156
	v_rcp_f32_e32 v156, v182
	s_waitcnt vmcnt(0)
	v_fmamk_f32 v136, v136, 0x3a800000, v170
	v_rsq_f32_e32 v136, v136
	v_rcp_f32_e32 v172, v155
	v_rcp_f32_e32 v155, v152
	v_sub_f32_e32 v152, v189, v193
	v_mov_b32_e32 v194, v136
	v_mul_f32_e32 v136, v124, v194
	v_mul_f32_e32 v136, 0xbfb8aa3b, v136
	v_exp_f32_e32 v136, v136
	v_mul_f32_e32 v177, v125, v194
	v_mul_f32_e32 v177, 0xbfb8aa3b, v177
	v_mul_f32_e32 v152, 0xbfb8aa3b, v152
	v_add_f32_e32 v136, 1.0, v136
	v_rcp_f32_e32 v136, v136
	v_exp_f32_e32 v177, v177
	v_exp_f32_e32 v152, v152
	v_sub_f32_e32 v183, 1.0, v172
	v_fma_f32 v136, v176, v136, v175
	v_cmp_gt_f32_e32 vcc, s90, v136
	v_add_f32_e32 v177, 1.0, v177
	v_add_f32_e32 v152, 1.0, v152
	v_cndmask_b32_e64 v153, 0, 32, vcc
	v_ldexp_f32 v136, v136, v153
	v_log_f32_e32 v136, v136
	v_rcp_f32_e32 v178, v177
	v_rcp_f32_e32 v154, v152
	v_lshlrev_b64 v[152:153], 10, v[148:149]
	v_mul_f32_e32 v149, 0x3f317217, v136
	v_fma_f32 v149, v136, s95, -v149
	v_fmac_f32_e32 v149, 0x3377d1cf, v136
	v_sub_f32_e32 v177, 1.0, v174
	v_fmac_f32_e32 v149, 0x3f317217, v136
	v_cmp_lt_f32_e64 s[6:7], |v136|, s96
	v_fma_f32 v178, v177, v178, v174
	v_lshl_add_u64 v[152:153], s[10:11], 0, v[152:153]
	v_cndmask_b32_e64 v136, v136, v149, s[6:7]
	v_cndmask_b32_e32 v149, 0, v171, vcc
	v_cmp_gt_f32_e32 vcc, s90, v178
	v_sub_f32_e32 v136, v136, v149
	s_nop 0
	v_cndmask_b32_e64 v179, 0, 32, vcc
	v_ldexp_f32 v178, v178, v179
	v_log_f32_e32 v179, v178
	v_mul_f32_e32 v178, v126, v194
	v_mul_f32_e32 v178, 0xbfb8aa3b, v178
	v_exp_f32_e32 v178, v178
	v_mul_f32_e32 v149, 0x3f317217, v179
	v_fma_f32 v149, v179, s95, -v149
	v_fmac_f32_e32 v149, 0x3377d1cf, v179
	v_add_f32_e32 v178, 1.0, v178
	v_rcp_f32_e32 v180, v178
	v_sub_f32_e32 v178, 1.0, v173
	v_fmac_f32_e32 v149, 0x3f317217, v179
	v_cmp_lt_f32_e64 s[8:9], |v179|, s96
	v_fma_f32 v180, v178, v180, v173
	v_cmp_gt_f32_e64 s[6:7], s90, v180
	v_cndmask_b32_e64 v149, v179, v149, s[8:9]
	v_cndmask_b32_e32 v179, 0, v171, vcc
	v_cndmask_b32_e64 v182, 0, 32, s[6:7]
	v_ldexp_f32 v180, v180, v182
	v_sub_f32_e32 v182, v149, v179
	v_mul_f32_e32 v179, v127, v194
	v_mul_f32_e32 v179, 0xbfb8aa3b, v179
	v_exp_f32_e32 v179, v179
	v_log_f32_e32 v180, v180
	v_add_f32_e32 v179, 1.0, v179
	v_rcp_f32_e32 v179, v179
	v_mul_f32_e32 v149, 0x3f317217, v180
	v_fma_f32 v149, v180, s95, -v149
; __device__ __forceinline__ float fsigm(float x) { return __builtin_amdgcn_rcpf(1.f + __expf(-x)); }
; __device__ __forceinline__ float row_rs(const float* ssq, int row) { return ssq ? rsqrtf(ssq[row] * (1.f / 1024.f) + RMS_EPS) : 1.f; }
;     __device__ __forceinline__ void operator()(const f32x4 (&acc)[2][2][4][2], const Unit& u, int wr, int wc, int fr, int fq) const {
;     ...
;                 for (int m = 0; m < 4; ++m) { const int row = row0 + ai * HALF + m * 16; const float rs = row_rs(ssq, row);
; #pragma unroll
;                     for (int bj = 0; bj < 2; ++bj) { f16x4 o[2];
; #pragma unroll
;                         for (int n = 0; n < 2; ++n) { const f32x4 p = acc[ai][bj][m][n] * rs;
; #pragma unroll
;                             for (int j = 0; j < 4; ++j) { const float l = lb[bj][n][j]; const float f = l + (1.f - l) * fsigm(p[j]); o[n][j] = (_Float16)__logf(f); } }
;                         const u32x2 a0 = __builtin_bit_cast(u32x2, o[0]), a1 = __builtin_bit_cast(u32x2, o[1]); u32x4 w; w.x = a0.x; w.y = a0.y; w.z = a1.x; w.w = a1.y;
;                         *(u32x4*)(LF + (size_t)row * 512 + cbase + bj * HALF) = w; } }
	v_fmac_f32_e32 v149, 0x3377d1cf, v180
	v_fmac_f32_e32 v149, 0x3f317217, v180
	v_cmp_lt_f32_e64 vcc, |v180|, s96
	v_fma_f32 v179, v183, v179, v172
	s_nop 0
	v_cndmask_b32_e32 v149, v180, v149, vcc
	v_cmp_gt_f32_e32 vcc, s90, v179
	v_cndmask_b32_e64 v180, 0, v171, s[6:7]
	v_sub_f32_e32 v185, v149, v180
	v_cndmask_b32_e64 v184, 0, 32, vcc
	v_ldexp_f32 v179, v179, v184
	v_mul_f32_e32 v184, v120, v194
	v_log_f32_e32 v179, v179
	v_mul_f32_e32 v184, 0xbfb8aa3b, v184
	v_exp_f32_e32 v184, v184
	v_mul_f32_e32 v149, 0x3f317217, v179
	v_fma_f32 v180, v179, s95, -v149
	v_add_f32_e32 v149, 1.0, v184
	v_rcp_f32_e32 v184, v149
	v_sub_f32_e32 v149, 1.0, v165
	v_fmac_f32_e32 v180, 0x3377d1cf, v179
	v_fmac_f32_e32 v180, 0x3f317217, v179
	v_fma_f32 v184, v149, v184, v165
	v_cmp_gt_f32_e64 s[6:7], s90, v184
	v_cmp_lt_f32_e64 s[8:9], |v179|, s96
	s_nop 0
	v_cndmask_b32_e64 v186, 0, 32, s[6:7]
	v_cndmask_b32_e64 v179, v179, v180, s[8:9]
	v_cndmask_b32_e32 v180, 0, v171, vcc
	v_ldexp_f32 v184, v184, v186
	v_sub_f32_e32 v186, v179, v180
	v_mul_f32_e32 v180, v121, v194
	v_mul_f32_e32 v180, 0xbfb8aa3b, v180
	v_log_f32_e32 v184, v184
	v_exp_f32_e32 v180, v180
	v_cndmask_b32_e64 v187, 0, v171, s[6:7]
	v_mul_f32_e32 v179, 0x3f317217, v184
	v_add_f32_e32 v180, 1.0, v180
	v_fma_f32 v179, v184, s95, -v179
	v_rcp_f32_e32 v180, v180
	v_fmac_f32_e32 v179, 0x3377d1cf, v184
	v_fmac_f32_e32 v179, 0x3f317217, v184
	v_cmp_lt_f32_e64 vcc, |v184|, s96
	s_nop 1
	v_cndmask_b32_e32 v184, v184, v179, vcc
	v_sub_f32_e32 v179, 1.0, v164
	v_fma_f32 v180, v179, v180, v164
	v_cmp_gt_f32_e32 vcc, s90, v180
	v_sub_f32_e32 v184, v184, v187
	s_nop 0
	v_cndmask_b32_e64 v188, 0, 32, vcc
	v_ldexp_f32 v180, v180, v188
	v_log_f32_e32 v188, v180
	v_mul_f32_e32 v180, v122, v194
	v_mul_f32_e32 v180, 0xbfb8aa3b, v180
	v_exp_f32_e32 v180, v180
	v_mul_f32_e32 v187, 0x3f317217, v188
	v_fma_f32 v187, v188, s95, -v187
	v_fmac_f32_e32 v187, 0x3377d1cf, v188
	v_add_f32_e32 v180, 1.0, v180
	v_rcp_f32_e32 v189, v180
	v_sub_f32_e32 v180, 1.0, v163
	v_fmac_f32_e32 v187, 0x3f317217, v188
	v_cmp_lt_f32_e64 s[8:9], |v188|, s96
	v_fma_f32 v189, v180, v189, v163
	v_cmp_gt_f32_e64 s[6:7], s90, v189
	v_cndmask_b32_e64 v187, v188, v187, s[8:9]
	v_cndmask_b32_e32 v188, 0, v171, vcc
	v_cndmask_b32_e64 v190, 0, 32, s[6:7]
	v_ldexp_f32 v189, v189, v190
	v_mul_f32_e32 v190, v123, v194
	v_mul_f32_e32 v190, 0xbfb8aa3b, v190
	v_log_f32_e32 v189, v189
	v_exp_f32_e32 v190, v190
	v_sub_f32_e32 v187, v187, v188
	v_cndmask_b32_e64 v191, 0, v171, s[6:7]
	v_mul_f32_e32 v188, 0x3f317217, v189
	v_add_f32_e32 v190, 1.0, v190
	v_fma_f32 v188, v189, s95, -v188
	v_rcp_f32_e32 v190, v190
	v_fmac_f32_e32 v188, 0x3377d1cf, v189
	v_fmac_f32_e32 v188, 0x3f317217, v189
	v_cmp_lt_f32_e64 vcc, |v189|, s96
	s_nop 1
	v_cndmask_b32_e32 v189, v189, v188, vcc
	v_sub_f32_e32 v188, 1.0, v162
	v_fma_f32 v190, v188, v190, v162
	v_cmp_gt_f32_e32 vcc, s90, v190
	v_sub_f32_e32 v189, v189, v191
	v_cvt_pk_f16_f32 v191, v185, v186
	v_cndmask_b32_e64 v192, 0, 32, vcc
	v_ldexp_f32 v190, v190, v192
	v_log_f32_e32 v192, v190
	v_cvt_pk_f16_f32 v190, v136, v182
	v_cndmask_b32_e32 v182, 0, v171, vcc
	v_mul_f32_e32 v136, 0x3f317217, v192
	v_fma_f32 v136, v192, s95, -v136
	v_fmac_f32_e32 v136, 0x3377d1cf, v192
	v_fmac_f32_e32 v136, 0x3f317217, v192
	v_cmp_lt_f32_e64 s[6:7], |v192|, s96
	s_nop 1
	v_cndmask_b32_e64 v136, v192, v136, s[6:7]
	v_sub_f32_e32 v136, v136, v182
	v_mul_f32_e32 v182, v116, v194
	v_mul_f32_e32 v182, 0xbfb8aa3b, v182
	v_exp_f32_e32 v182, v182
	v_cvt_pk_f16_f32 v193, v189, v136
	v_cvt_pk_f16_f32 v192, v184, v187
	v_sub_f32_e32 v184, 1.0, v161
	v_add_f32_e32 v136, 1.0, v182
	v_rcp_f32_e32 v182, v136
	v_lshlrev_b32_e32 v136, 1, v181
	v_lshl_add_u64 v[152:153], v[152:153], 0, v[136:137]
	global_store_dwordx4 v[152:153], v[190:193], off
	v_fma_f32 v181, v184, v182, v161
	v_cmp_gt_f32_e32 vcc, s90, v181
	s_nop 1
	v_cndmask_b32_e64 v182, 0, 32, vcc
	v_ldexp_f32 v181, v181, v182
	v_log_f32_e32 v182, v181
	v_mul_f32_e32 v181, v117, v194
	v_mul_f32_e32 v181, 0xbfb8aa3b, v181
	v_exp_f32_e32 v181, v181
	v_mul_f32_e32 v185, 0x3f317217, v182
	v_fma_f32 v185, v182, s95, -v185
	v_fmac_f32_e32 v185, 0x3377d1cf, v182
	v_add_f32_e32 v181, 1.0, v181
	v_rcp_f32_e32 v186, v181
	v_sub_f32_e32 v181, 1.0, v160
	v_fmac_f32_e32 v185, 0x3f317217, v182
	v_cmp_lt_f32_e64 s[8:9], |v182|, s96
	v_fma_f32 v186, v181, v186, v160
	v_cmp_gt_f32_e64 s[6:7], s90, v186
	v_cndmask_b32_e64 v182, v182, v185, s[8:9]
	v_cndmask_b32_e32 v185, 0, v171, vcc
	v_cndmask_b32_e64 v187, 0, 32, s[6:7]
	v_ldexp_f32 v186, v186, v187
	v_mul_f32_e32 v187, v118, v194
	v_mul_f32_e32 v187, 0xbfb8aa3b, v187
	v_log_f32_e32 v186, v186
	v_exp_f32_e32 v187, v187
	v_sub_f32_e32 v182, v182, v185
	v_cndmask_b32_e64 v189, 0, v171, s[6:7]
	v_mul_f32_e32 v185, 0x3f317217, v186
	v_add_f32_e32 v187, 1.0, v187
	v_fma_f32 v185, v186, s95, -v185
	v_rcp_f32_e32 v187, v187
	v_fmac_f32_e32 v185, 0x3377d1cf, v186
	v_fmac_f32_e32 v185, 0x3f317217, v186
	v_cmp_lt_f32_e64 vcc, |v186|, s96
	s_nop 1
	v_cndmask_b32_e32 v186, v186, v185, vcc
	v_sub_f32_e32 v185, 1.0, v159
	v_fma_f32 v187, v185, v187, v159
	v_cmp_gt_f32_e32 vcc, s90, v187
	v_sub_f32_e32 v189, v186, v189
	s_nop 0
	v_cndmask_b32_e64 v190, 0, 32, vcc
	v_ldexp_f32 v187, v187, v190
	v_mul_f32_e32 v190, v119, v194
	v_log_f32_e32 v187, v187
	v_mul_f32_e32 v190, 0xbfb8aa3b, v190
	v_exp_f32_e32 v190, v190
	v_mul_f32_e32 v186, 0x3f317217, v187
	v_fma_f32 v191, v187, s95, -v186
	v_add_f32_e32 v186, 1.0, v190
	v_rcp_f32_e32 v190, v186
	v_sub_f32_e32 v186, 1.0, v158
	v_fmac_f32_e32 v191, 0x3377d1cf, v187
	v_fmac_f32_e32 v191, 0x3f317217, v187
	v_fma_f32 v190, v186, v190, v158
; __device__ __forceinline__ float fsigm(float x) { return __builtin_amdgcn_rcpf(1.f + __expf(-x)); }
; __device__ __forceinline__ float row_rs(const float* ssq, int row) { return ssq ? rsqrtf(ssq[row] * (1.f / 1024.f) + RMS_EPS) : 1.f; }
;     __device__ __forceinline__ void operator()(const f32x4 (&acc)[2][2][4][2], const Unit& u, int wr, int wc, int fr, int fq) const {
;     ...
;                 for (int m = 0; m < 4; ++m) { const int row = row0 + ai * HALF + m * 16; const float rs = row_rs(ssq, row);
; #pragma unroll
;                     for (int bj = 0; bj < 2; ++bj) { f16x4 o[2];
; #pragma unroll
;                         for (int n = 0; n < 2; ++n) { const f32x4 p = acc[ai][bj][m][n] * rs;
; #pragma unroll
;                             for (int j = 0; j < 4; ++j) { const float l = lb[bj][n][j]; const float f = l + (1.f - l) * fsigm(p[j]); o[n][j] = (_Float16)__logf(f); } }
;                         const u32x2 a0 = __builtin_bit_cast(u32x2, o[0]), a1 = __builtin_bit_cast(u32x2, o[1]); u32x4 w; w.x = a0.x; w.y = a0.y; w.z = a1.x; w.w = a1.y;
;                         *(u32x4*)(LF + (size_t)row * 512 + cbase + bj * HALF) = w; } }
	v_cmp_gt_f32_e64 s[6:7], s90, v190
	v_cmp_lt_f32_e64 s[8:9], |v187|, s96
	s_nop 0
	v_cndmask_b32_e64 v192, 0, 32, s[6:7]
	v_ldexp_f32 v190, v190, v192
	v_log_f32_e32 v190, v190
	v_mul_f32_e32 v192, v112, v194
	v_mul_f32_e32 v192, 0xbfb8aa3b, v192
	v_exp_f32_e32 v192, v192
	v_cndmask_b32_e64 v187, v187, v191, s[8:9]
	v_cndmask_b32_e32 v191, 0, v171, vcc
	v_sub_f32_e32 v187, v187, v191
	v_mul_f32_e32 v191, 0x3f317217, v190
	v_fma_f32 v191, v190, s95, -v191
	v_fmac_f32_e32 v191, 0x3377d1cf, v190
	v_add_f32_e32 v192, 1.0, v192
	v_fmac_f32_e32 v191, 0x3f317217, v190
	v_cmp_lt_f32_e64 vcc, |v190|, s96
	v_rcp_f32_e32 v192, v192
	s_nop 0
	v_cndmask_b32_e32 v190, v190, v191, vcc
	v_cndmask_b32_e64 v191, 0, v171, s[6:7]
	v_sub_f32_e32 v190, v190, v191
	v_cvt_pk_f16_f32 v193, v187, v190
	v_sub_f32_e32 v187, 1.0, v157
	v_fma_f32 v190, v187, v192, v157
	v_cmp_gt_f32_e32 vcc, s90, v190
	v_cvt_pk_f16_f32 v192, v182, v189
	s_nop 0
	v_cndmask_b32_e64 v191, 0, 32, vcc
	v_ldexp_f32 v190, v190, v191
	v_mul_f32_e32 v191, v113, v194
	v_log_f32_e32 v190, v190
	v_mul_f32_e32 v191, 0xbfb8aa3b, v191
	v_exp_f32_e32 v191, v191
	v_mul_f32_e32 v182, 0x3f317217, v190
	v_fma_f32 v189, v190, s95, -v182
	v_add_f32_e32 v182, 1.0, v191
	v_rcp_f32_e32 v191, v182
	v_fmac_f32_e32 v189, 0x3377d1cf, v190
	v_sub_f32_e32 v182, 1.0, v156
	v_fmac_f32_e32 v189, 0x3f317217, v190
	v_fma_f32 v191, v182, v191, v156
	v_cmp_lt_f32_e64 s[8:9], |v190|, s96
	v_cmp_gt_f32_e64 s[6:7], s90, v191
	s_nop 0
	v_cndmask_b32_e64 v189, v190, v189, s[8:9]
	v_cndmask_b32_e32 v190, 0, v171, vcc
	v_cndmask_b32_e64 v195, 0, 32, s[6:7]
	v_sub_f32_e32 v196, v189, v190
	v_mul_f32_e32 v190, v114, v194
	v_ldexp_f32 v191, v191, v195
	v_mul_f32_e32 v190, 0xbfb8aa3b, v190
	v_log_f32_e32 v191, v191
	v_exp_f32_e32 v190, v190
	v_cndmask_b32_e64 v195, 0, v171, s[6:7]
	v_mul_f32_e32 v189, 0x3f317217, v191
	v_add_f32_e32 v190, 1.0, v190
	v_fma_f32 v189, v191, s95, -v189
	v_rcp_f32_e32 v190, v190
	v_fmac_f32_e32 v189, 0x3377d1cf, v191
	v_fmac_f32_e32 v189, 0x3f317217, v191
	v_cmp_lt_f32_e64 vcc, |v191|, s96
	s_nop 1
	v_cndmask_b32_e32 v191, v191, v189, vcc
	v_sub_f32_e32 v189, 1.0, v155
	v_fma_f32 v190, v189, v190, v155
	v_cmp_gt_f32_e32 vcc, s90, v190
	v_sub_f32_e32 v191, v191, v195
	s_nop 0
	v_cndmask_b32_e64 v197, 0, 32, vcc
	v_ldexp_f32 v190, v190, v197
	v_log_f32_e32 v197, v190
	v_mul_f32_e32 v190, v115, v194
	v_mul_f32_e32 v190, 0xbfb8aa3b, v190
	v_exp_f32_e32 v190, v190
	v_mul_f32_e32 v194, 0x3f317217, v197
	v_fma_f32 v194, v197, s95, -v194
	v_fmac_f32_e32 v194, 0x3377d1cf, v197
	v_add_f32_e32 v190, 1.0, v190
	v_rcp_f32_e32 v195, v190
	v_sub_f32_e32 v190, 1.0, v154
	v_fmac_f32_e32 v194, 0x3f317217, v197
	v_cmp_lt_f32_e64 s[8:9], |v197|, s96
	v_fma_f32 v195, v190, v195, v154
	v_cmp_gt_f32_e64 s[6:7], s90, v195
	v_cndmask_b32_e64 v194, v197, v194, s[8:9]
	v_cndmask_b32_e32 v197, 0, v171, vcc
	v_cndmask_b32_e64 v198, 0, 32, s[6:7]
	v_ldexp_f32 v195, v195, v198
	v_log_f32_e32 v195, v195
	v_sub_f32_e32 v194, v194, v197
	v_mul_f32_e32 v197, 0x3f317217, v195
	v_fma_f32 v197, v195, s95, -v197
	v_fmac_f32_e32 v197, 0x3377d1cf, v195
	v_fmac_f32_e32 v197, 0x3f317217, v195
	v_cmp_lt_f32_e64 vcc, |v195|, s96
	s_nop 1
	v_cndmask_b32_e32 v195, v195, v197, vcc
	v_cndmask_b32_e64 v197, 0, v171, s[6:7]
	v_sub_f32_e32 v195, v195, v197
	v_cvt_pk_f16_f32 v195, v194, v195
	v_cvt_pk_f16_f32 v194, v196, v191
	global_store_dwordx4 v[152:153], v[192:195], off offset:256
	s_nop 1
	v_or_b32_e32 v192, 16, v148
	v_ashrrev_i32_e32 v193, 31, v192
	v_lshl_add_u64 v[194:195], v[192:193], 2, s[30:31]
	v_lshlrev_b64 v[196:197], 10, v[192:193]
	v_lshl_add_u64 v[196:197], s[10:11], 0, v[196:197]
	v_lshl_add_u64 v[196:197], v[196:197], 0, v[136:137]
	v_fmamk_f32 v191, v210, 0x3a800000, v170
	v_rsq_f32_e32 v191, v191
	s_nop 0
	v_mul_f32_e32 v194, v108, v191
	v_mul_f32_e32 v194, 0xbfb8aa3b, v194
	v_exp_f32_e32 v194, v194
	v_mul_f32_e32 v193, v109, v191
	v_mul_f32_e32 v193, 0xbfb8aa3b, v193
	v_exp_f32_e32 v193, v193
	v_add_f32_e32 v194, 1.0, v194
	v_rcp_f32_e32 v194, v194
	v_add_f32_e32 v193, 1.0, v193
	v_rcp_f32_e32 v193, v193
	v_fma_f32 v194, v176, v194, v175
	v_cmp_gt_f32_e32 vcc, s90, v194
	v_fma_f32 v193, v177, v193, v174
	s_nop 0
	v_cndmask_b32_e64 v195, 0, 32, vcc
	v_ldexp_f32 v194, v194, v195
	v_log_f32_e32 v194, v194
	s_nop 0
	v_mul_f32_e32 v192, 0x3f317217, v194
	v_fma_f32 v192, v194, s95, -v192
	v_fmac_f32_e32 v192, 0x3377d1cf, v194
	v_fmac_f32_e32 v192, 0x3f317217, v194
	v_cmp_lt_f32_e64 s[6:7], |v194|, s96
	s_nop 1
	v_cndmask_b32_e64 v192, v194, v192, s[6:7]
	v_cndmask_b32_e32 v194, 0, v171, vcc
	v_cmp_gt_f32_e32 vcc, s90, v193
	v_sub_f32_e32 v192, v192, v194
	s_nop 0
	v_cndmask_b32_e64 v194, 0, 32, vcc
	v_ldexp_f32 v193, v193, v194
	v_mul_f32_e32 v194, v110, v191
	v_mul_f32_e32 v194, 0xbfb8aa3b, v194
	v_exp_f32_e32 v194, v194
	v_log_f32_e32 v193, v193
	v_cndmask_b32_e32 v198, 0, v171, vcc
	v_add_f32_e32 v194, 1.0, v194
	v_rcp_f32_e32 v194, v194
	v_mul_f32_e32 v195, 0x3f317217, v193
	v_fma_f32 v195, v193, s95, -v195
	v_fmac_f32_e32 v195, 0x3377d1cf, v193
	v_fmac_f32_e32 v195, 0x3f317217, v193
	v_cmp_lt_f32_e64 s[6:7], |v193|, s96
	v_fma_f32 v194, v178, v194, v173
	s_nop 0
	v_cndmask_b32_e64 v193, v193, v195, s[6:7]
	v_cmp_gt_f32_e64 s[6:7], s90, v194
	v_sub_f32_e32 v198, v193, v198
	v_cvt_pk_f16_f32 v192, v192, v198
	v_cndmask_b32_e64 v195, 0, 32, s[6:7]
	v_ldexp_f32 v194, v194, v195
	v_mul_f32_e32 v195, v111, v191
	v_mul_f32_e32 v195, 0xbfb8aa3b, v195
	v_exp_f32_e32 v195, v195
	v_log_f32_e32 v194, v194
	v_add_f32_e32 v195, 1.0, v195
	v_rcp_f32_e32 v195, v195
	v_mul_f32_e32 v193, 0x3f317217, v194
	v_fma_f32 v193, v194, s95, -v193
; __device__ __forceinline__ float fsigm(float x) { return __builtin_amdgcn_rcpf(1.f + __expf(-x)); }
; __device__ __forceinline__ float row_rs(const float* ssq, int row) { return ssq ? rsqrtf(ssq[row] * (1.f / 1024.f) + RMS_EPS) : 1.f; }
;     __device__ __forceinline__ void operator()(const f32x4 (&acc)[2][2][4][2], const Unit& u, int wr, int wc, int fr, int fq) const {
;     ...
;                 for (int m = 0; m < 4; ++m) { const int row = row0 + ai * HALF + m * 16; const float rs = row_rs(ssq, row);
; #pragma unroll
;                     for (int bj = 0; bj < 2; ++bj) { f16x4 o[2];
; #pragma unroll
;                         for (int n = 0; n < 2; ++n) { const f32x4 p = acc[ai][bj][m][n] * rs;
; #pragma unroll
;                             for (int j = 0; j < 4; ++j) { const float l = lb[bj][n][j]; const float f = l + (1.f - l) * fsigm(p[j]); o[n][j] = (_Float16)__logf(f); } }
;                         const u32x2 a0 = __builtin_bit_cast(u32x2, o[0]), a1 = __builtin_bit_cast(u32x2, o[1]); u32x4 w; w.x = a0.x; w.y = a0.y; w.z = a1.x; w.w = a1.y;
;                         *(u32x4*)(LF + (size_t)row * 512 + cbase + bj * HALF) = w; } }
	v_fmac_f32_e32 v193, 0x3377d1cf, v194
	v_fma_f32 v195, v183, v195, v172
	v_cmp_gt_f32_e32 vcc, s90, v195
	v_fmac_f32_e32 v193, 0x3f317217, v194
	v_cmp_lt_f32_e64 s[8:9], |v194|, s96
	v_cndmask_b32_e64 v199, 0, 32, vcc
	v_ldexp_f32 v195, v195, v199
	v_mul_f32_e32 v199, v104, v191
	v_mul_f32_e32 v199, 0xbfb8aa3b, v199
	v_log_f32_e32 v195, v195
	v_exp_f32_e32 v199, v199
	v_cndmask_b32_e64 v193, v194, v193, s[8:9]
	v_cndmask_b32_e64 v194, 0, v171, s[6:7]
	v_sub_f32_e32 v193, v193, v194
	v_mul_f32_e32 v194, 0x3f317217, v195
	v_add_f32_e32 v199, 1.0, v199
	v_fma_f32 v194, v195, s95, -v194
	v_rcp_f32_e32 v199, v199
	v_fmac_f32_e32 v194, 0x3377d1cf, v195
	v_fmac_f32_e32 v194, 0x3f317217, v195
	v_cmp_lt_f32_e64 s[6:7], |v195|, s96
	v_fma_f32 v199, v149, v199, v165
	s_nop 0
	v_cndmask_b32_e64 v194, v195, v194, s[6:7]
	v_cndmask_b32_e32 v195, 0, v171, vcc
	v_sub_f32_e32 v194, v194, v195
	v_mul_f32_e32 v195, v105, v191
	v_cmp_gt_f32_e32 vcc, s90, v199
	v_mul_f32_e32 v195, 0xbfb8aa3b, v195
	v_exp_f32_e32 v195, v195
	v_cndmask_b32_e64 v200, 0, 32, vcc
	v_ldexp_f32 v199, v199, v200
	v_log_f32_e32 v199, v199
	v_add_f32_e32 v195, 1.0, v195
	v_rcp_f32_e32 v195, v195
	v_cvt_pk_f16_f32 v193, v193, v194
	v_mul_f32_e32 v194, 0x3f317217, v199
	v_fma_f32 v194, v199, s95, -v194
	v_fmac_f32_e32 v194, 0x3377d1cf, v199
	v_fmac_f32_e32 v194, 0x3f317217, v199
	v_cmp_lt_f32_e64 s[6:7], |v199|, s96
	v_fma_f32 v195, v179, v195, v164
	v_cndmask_b32_e32 v198, 0, v171, vcc
	v_cndmask_b32_e64 v194, v199, v194, s[6:7]
	v_cmp_gt_f32_e32 vcc, s90, v195
	v_sub_f32_e32 v194, v194, v198
	s_nop 0
	v_cndmask_b32_e64 v198, 0, 32, vcc
	v_ldexp_f32 v195, v195, v198
	v_mul_f32_e32 v198, v106, v191
	v_mul_f32_e32 v198, 0xbfb8aa3b, v198
	v_exp_f32_e32 v198, v198
	v_log_f32_e32 v195, v195
	v_cndmask_b32_e32 v200, 0, v171, vcc
	v_add_f32_e32 v198, 1.0, v198
	v_rcp_f32_e32 v198, v198
	v_mul_f32_e32 v199, 0x3f317217, v195
	v_fma_f32 v199, v195, s95, -v199
	v_fmac_f32_e32 v199, 0x3377d1cf, v195
	v_fmac_f32_e32 v199, 0x3f317217, v195
	v_cmp_lt_f32_e64 s[6:7], |v195|, s96
	v_fma_f32 v198, v180, v198, v163
	s_nop 0
	v_cndmask_b32_e64 v195, v195, v199, s[6:7]
	v_cmp_gt_f32_e64 s[6:7], s90, v198
	v_sub_f32_e32 v200, v195, v200
	v_cvt_pk_f16_f32 v194, v194, v200
	v_cndmask_b32_e64 v199, 0, 32, s[6:7]
	v_ldexp_f32 v198, v198, v199
	v_mul_f32_e32 v199, v107, v191
	v_mul_f32_e32 v199, 0xbfb8aa3b, v199
	v_exp_f32_e32 v199, v199
	v_log_f32_e32 v198, v198
	v_add_f32_e32 v199, 1.0, v199
	v_rcp_f32_e32 v199, v199
	v_mul_f32_e32 v195, 0x3f317217, v198
	v_fma_f32 v195, v198, s95, -v195
	v_fmac_f32_e32 v195, 0x3377d1cf, v198
	v_fma_f32 v199, v188, v199, v162
	v_cmp_gt_f32_e32 vcc, s90, v199
	v_fmac_f32_e32 v195, 0x3f317217, v198
	v_cmp_lt_f32_e64 s[8:9], |v198|, s96
	v_cndmask_b32_e64 v201, 0, 32, vcc
	v_ldexp_f32 v199, v199, v201
	v_log_f32_e32 v199, v199
	v_mul_f32_e32 v201, v100, v191
	v_mul_f32_e32 v201, 0xbfb8aa3b, v201
	v_exp_f32_e32 v201, v201
	v_cndmask_b32_e64 v195, v198, v195, s[8:9]
	v_cndmask_b32_e64 v198, 0, v171, s[6:7]
	v_sub_f32_e32 v195, v195, v198
	v_mul_f32_e32 v198, 0x3f317217, v199
	v_fma_f32 v198, v199, s95, -v198
	v_fmac_f32_e32 v198, 0x3377d1cf, v199
	v_add_f32_e32 v201, 1.0, v201
	v_fmac_f32_e32 v198, 0x3f317217, v199
	v_cmp_lt_f32_e64 s[6:7], |v199|, s96
	v_rcp_f32_e32 v201, v201
	s_nop 0
	v_cndmask_b32_e64 v198, v199, v198, s[6:7]
	v_cndmask_b32_e32 v199, 0, v171, vcc
	v_sub_f32_e32 v198, v198, v199
	v_cvt_pk_f16_f32 v195, v195, v198
	v_fma_f32 v198, v184, v201, v161
	global_store_dwordx4 v[196:197], v[192:195], off
	v_cmp_gt_f32_e32 vcc, s90, v198
	s_nop 0
	v_mul_f32_e32 v193, v101, v191
	v_mul_f32_e32 v193, 0xbfb8aa3b, v193
	v_cndmask_b32_e64 v199, 0, 32, vcc
	v_exp_f32_e32 v193, v193
	v_ldexp_f32 v198, v198, v199
	v_log_f32_e32 v198, v198
	v_cndmask_b32_e32 v194, 0, v171, vcc
	v_add_f32_e32 v193, 1.0, v193
	v_rcp_f32_e32 v193, v193
	v_mul_f32_e32 v192, 0x3f317217, v198
	v_fma_f32 v192, v198, s95, -v192
	v_fmac_f32_e32 v192, 0x3377d1cf, v198
	v_fmac_f32_e32 v192, 0x3f317217, v198
	v_cmp_lt_f32_e64 s[6:7], |v198|, s96
	v_fma_f32 v193, v181, v193, v160
	v_cmp_gt_f32_e32 vcc, s90, v193
	v_cndmask_b32_e64 v192, v198, v192, s[6:7]
	v_sub_f32_e32 v192, v192, v194
	v_cndmask_b32_e64 v194, 0, 32, vcc
	v_ldexp_f32 v193, v193, v194
	v_mul_f32_e32 v194, v102, v191
	v_mul_f32_e32 v194, 0xbfb8aa3b, v194
	v_exp_f32_e32 v194, v194
	v_log_f32_e32 v193, v193
	v_cndmask_b32_e32 v198, 0, v171, vcc
	v_add_f32_e32 v194, 1.0, v194
	v_rcp_f32_e32 v194, v194
	v_mul_f32_e32 v195, 0x3f317217, v193
	v_fma_f32 v195, v193, s95, -v195
	v_fmac_f32_e32 v195, 0x3377d1cf, v193
	v_fmac_f32_e32 v195, 0x3f317217, v193
	v_cmp_lt_f32_e64 s[6:7], |v193|, s96
	v_fma_f32 v194, v185, v194, v159
	s_nop 0
	v_cndmask_b32_e64 v193, v193, v195, s[6:7]
	v_cmp_gt_f32_e64 s[6:7], s90, v194
	v_sub_f32_e32 v198, v193, v198
	v_cvt_pk_f16_f32 v192, v192, v198
	v_cndmask_b32_e64 v195, 0, 32, s[6:7]
	v_ldexp_f32 v194, v194, v195
	v_mul_f32_e32 v195, v103, v191
	v_mul_f32_e32 v195, 0xbfb8aa3b, v195
	v_exp_f32_e32 v195, v195
	v_log_f32_e32 v194, v194
	v_add_f32_e32 v195, 1.0, v195
	v_rcp_f32_e32 v195, v195
	v_mul_f32_e32 v193, 0x3f317217, v194
	v_fma_f32 v193, v194, s95, -v193
	v_fmac_f32_e32 v193, 0x3377d1cf, v194
	v_fma_f32 v195, v186, v195, v158
	v_cmp_gt_f32_e32 vcc, s90, v195
	v_fmac_f32_e32 v193, 0x3f317217, v194
	v_cmp_lt_f32_e64 s[8:9], |v194|, s96
	v_cndmask_b32_e64 v199, 0, 32, vcc
	v_ldexp_f32 v195, v195, v199
	v_mul_f32_e32 v199, v96, v191
	v_mul_f32_e32 v199, 0xbfb8aa3b, v199
	v_log_f32_e32 v195, v195
	v_exp_f32_e32 v199, v199
	v_cndmask_b32_e64 v193, v194, v193, s[8:9]
	v_cndmask_b32_e64 v194, 0, v171, s[6:7]
; __device__ __forceinline__ float fsigm(float x) { return __builtin_amdgcn_rcpf(1.f + __expf(-x)); }
; __device__ __forceinline__ float row_rs(const float* ssq, int row) { return ssq ? rsqrtf(ssq[row] * (1.f / 1024.f) + RMS_EPS) : 1.f; }
;     __device__ __forceinline__ void operator()(const f32x4 (&acc)[2][2][4][2], const Unit& u, int wr, int wc, int fr, int fq) const {
;     ...
;                 for (int m = 0; m < 4; ++m) { const int row = row0 + ai * HALF + m * 16; const float rs = row_rs(ssq, row);
; #pragma unroll
;                     for (int bj = 0; bj < 2; ++bj) { f16x4 o[2];
; #pragma unroll
;                         for (int n = 0; n < 2; ++n) { const f32x4 p = acc[ai][bj][m][n] * rs;
; #pragma unroll
;                             for (int j = 0; j < 4; ++j) { const float l = lb[bj][n][j]; const float f = l + (1.f - l) * fsigm(p[j]); o[n][j] = (_Float16)__logf(f); } }
;                         const u32x2 a0 = __builtin_bit_cast(u32x2, o[0]), a1 = __builtin_bit_cast(u32x2, o[1]); u32x4 w; w.x = a0.x; w.y = a0.y; w.z = a1.x; w.w = a1.y;
;                         *(u32x4*)(LF + (size_t)row * 512 + cbase + bj * HALF) = w; } }
	v_sub_f32_e32 v193, v193, v194
	v_mul_f32_e32 v194, 0x3f317217, v195
	v_add_f32_e32 v199, 1.0, v199
	v_fma_f32 v194, v195, s95, -v194
	v_rcp_f32_e32 v199, v199
	v_fmac_f32_e32 v194, 0x3377d1cf, v195
	v_fmac_f32_e32 v194, 0x3f317217, v195
	v_cmp_lt_f32_e64 s[6:7], |v195|, s96
	v_fma_f32 v199, v187, v199, v157
	s_nop 0
	v_cndmask_b32_e64 v194, v195, v194, s[6:7]
	v_cndmask_b32_e32 v195, 0, v171, vcc
	v_sub_f32_e32 v194, v194, v195
	v_mul_f32_e32 v195, v97, v191
	v_cmp_gt_f32_e32 vcc, s90, v199
	v_mul_f32_e32 v195, 0xbfb8aa3b, v195
	v_exp_f32_e32 v195, v195
	v_cndmask_b32_e64 v200, 0, 32, vcc
	v_ldexp_f32 v199, v199, v200
	v_log_f32_e32 v199, v199
	v_add_f32_e32 v195, 1.0, v195
	v_rcp_f32_e32 v195, v195
	v_cvt_pk_f16_f32 v193, v193, v194
	v_mul_f32_e32 v194, 0x3f317217, v199
	v_fma_f32 v194, v199, s95, -v194
	v_fmac_f32_e32 v194, 0x3377d1cf, v199
	v_fmac_f32_e32 v194, 0x3f317217, v199
	v_cmp_lt_f32_e64 s[6:7], |v199|, s96
	v_fma_f32 v195, v182, v195, v156
	v_cndmask_b32_e32 v198, 0, v171, vcc
	v_cndmask_b32_e64 v194, v199, v194, s[6:7]
	v_cmp_gt_f32_e32 vcc, s90, v195
	v_sub_f32_e32 v194, v194, v198
	s_nop 0
	v_cndmask_b32_e64 v198, 0, 32, vcc
	v_ldexp_f32 v195, v195, v198
	v_mul_f32_e32 v198, v98, v191
	v_mul_f32_e32 v198, 0xbfb8aa3b, v198
	v_exp_f32_e32 v198, v198
	v_log_f32_e32 v195, v195
	v_mul_f32_e32 v191, v99, v191
	v_mul_f32_e32 v191, 0xbfb8aa3b, v191
	v_add_f32_e32 v198, 1.0, v198
	v_rcp_f32_e32 v198, v198
	v_exp_f32_e32 v191, v191
	v_mul_f32_e32 v199, 0x3f317217, v195
	v_fma_f32 v199, v195, s95, -v199
	v_fmac_f32_e32 v199, 0x3377d1cf, v195
	v_fmac_f32_e32 v199, 0x3f317217, v195
	v_cmp_lt_f32_e64 s[6:7], |v195|, s96
	v_fma_f32 v198, v189, v198, v155
	v_add_f32_e32 v191, 1.0, v191
	v_cndmask_b32_e64 v195, v195, v199, s[6:7]
	v_cmp_gt_f32_e64 s[6:7], s90, v198
	v_rcp_f32_e32 v191, v191
	s_nop 0
	v_cndmask_b32_e64 v199, 0, 32, s[6:7]
	v_ldexp_f32 v198, v198, v199
	v_log_f32_e32 v198, v198
	v_fma_f32 v191, v190, v191, v154
	v_cndmask_b32_e32 v199, 0, v171, vcc
	v_cmp_gt_f32_e32 vcc, s90, v191
	v_sub_f32_e32 v199, v195, v199
	v_mul_f32_e32 v195, 0x3f317217, v198
	v_cndmask_b32_e64 v200, 0, 32, vcc
	v_ldexp_f32 v191, v191, v200
	v_fma_f32 v195, v198, s95, -v195
	v_log_f32_e32 v191, v191
	v_fmac_f32_e32 v195, 0x3377d1cf, v198
	v_fmac_f32_e32 v195, 0x3f317217, v198
	v_cmp_lt_f32_e64 s[8:9], |v198|, s96
	v_cvt_pk_f16_f32 v194, v194, v199
	s_nop 0
	v_cndmask_b32_e64 v195, v198, v195, s[8:9]
	v_cndmask_b32_e64 v198, 0, v171, s[6:7]
	v_sub_f32_e32 v195, v195, v198
	v_mul_f32_e32 v198, 0x3f317217, v191
	v_fma_f32 v198, v191, s95, -v198
	v_fmac_f32_e32 v198, 0x3377d1cf, v191
	v_fmac_f32_e32 v198, 0x3f317217, v191
	v_cmp_lt_f32_e64 s[6:7], |v191|, s96
	s_nop 1
	v_cndmask_b32_e64 v191, v191, v198, s[6:7]
	v_cndmask_b32_e32 v198, 0, v171, vcc
	v_sub_f32_e32 v191, v191, v198
	v_cvt_pk_f16_f32 v195, v195, v191
	global_store_dwordx4 v[196:197], v[192:195], off offset:256
	s_nop 1
	v_or_b32_e32 v192, 32, v148
	v_ashrrev_i32_e32 v193, 31, v192
	v_lshl_add_u64 v[194:195], v[192:193], 2, s[30:31]
	v_lshlrev_b64 v[196:197], 10, v[192:193]
	v_lshl_add_u64 v[196:197], s[10:11], 0, v[196:197]
	v_lshl_add_u64 v[196:197], v[196:197], 0, v[136:137]
	v_fmamk_f32 v191, v211, 0x3a800000, v170
	v_rsq_f32_e32 v191, v191
	s_nop 0
	v_mul_f32_e32 v194, v92, v191
	v_mul_f32_e32 v194, 0xbfb8aa3b, v194
	v_exp_f32_e32 v194, v194
	v_mul_f32_e32 v193, v93, v191
	v_mul_f32_e32 v193, 0xbfb8aa3b, v193
	v_exp_f32_e32 v193, v193
	v_add_f32_e32 v194, 1.0, v194
	v_rcp_f32_e32 v194, v194
	v_add_f32_e32 v193, 1.0, v193
	v_rcp_f32_e32 v193, v193
	v_fma_f32 v194, v176, v194, v175
	v_cmp_gt_f32_e32 vcc, s90, v194
	v_fma_f32 v193, v177, v193, v174
	s_nop 0
	v_cndmask_b32_e64 v195, 0, 32, vcc
	v_ldexp_f32 v194, v194, v195
	v_log_f32_e32 v194, v194
	s_nop 0
	v_mul_f32_e32 v192, 0x3f317217, v194
	v_fma_f32 v192, v194, s95, -v192
	v_fmac_f32_e32 v192, 0x3377d1cf, v194
	v_fmac_f32_e32 v192, 0x3f317217, v194
	v_cmp_lt_f32_e64 s[6:7], |v194|, s96
	s_nop 1
	v_cndmask_b32_e64 v192, v194, v192, s[6:7]
	v_cndmask_b32_e32 v194, 0, v171, vcc
	v_cmp_gt_f32_e32 vcc, s90, v193
	v_sub_f32_e32 v192, v192, v194
	s_nop 0
	v_cndmask_b32_e64 v194, 0, 32, vcc
	v_ldexp_f32 v193, v193, v194
	v_mul_f32_e32 v194, v94, v191
	v_mul_f32_e32 v194, 0xbfb8aa3b, v194
	v_exp_f32_e32 v194, v194
	v_log_f32_e32 v193, v193
	v_cndmask_b32_e32 v198, 0, v171, vcc
	v_add_f32_e32 v194, 1.0, v194
	v_rcp_f32_e32 v194, v194
	v_mul_f32_e32 v195, 0x3f317217, v193
	v_fma_f32 v195, v193, s95, -v195
	v_fmac_f32_e32 v195, 0x3377d1cf, v193
	v_fmac_f32_e32 v195, 0x3f317217, v193
	v_cmp_lt_f32_e64 s[6:7], |v193|, s96
	v_fma_f32 v194, v178, v194, v173
	s_nop 0
	v_cndmask_b32_e64 v193, v193, v195, s[6:7]
	v_cmp_gt_f32_e64 s[6:7], s90, v194
	v_sub_f32_e32 v198, v193, v198
	v_cvt_pk_f16_f32 v192, v192, v198
	v_cndmask_b32_e64 v195, 0, 32, s[6:7]
	v_ldexp_f32 v194, v194, v195
	v_mul_f32_e32 v195, v95, v191
	v_mul_f32_e32 v195, 0xbfb8aa3b, v195
	v_exp_f32_e32 v195, v195
	v_log_f32_e32 v194, v194
	v_add_f32_e32 v195, 1.0, v195
	v_rcp_f32_e32 v195, v195
	v_mul_f32_e32 v193, 0x3f317217, v194
	v_fma_f32 v193, v194, s95, -v193
	v_fmac_f32_e32 v193, 0x3377d1cf, v194
	v_fma_f32 v195, v183, v195, v172
	v_cmp_gt_f32_e32 vcc, s90, v195
	v_fmac_f32_e32 v193, 0x3f317217, v194
	v_cmp_lt_f32_e64 s[8:9], |v194|, s96
	v_cndmask_b32_e64 v199, 0, 32, vcc
	v_ldexp_f32 v195, v195, v199
	v_mul_f32_e32 v199, v88, v191
	v_mul_f32_e32 v199, 0xbfb8aa3b, v199
	v_log_f32_e32 v195, v195
	v_exp_f32_e32 v199, v199
	v_cndmask_b32_e64 v193, v194, v193, s[8:9]
	v_cndmask_b32_e64 v194, 0, v171, s[6:7]
	v_sub_f32_e32 v193, v193, v194
	v_mul_f32_e32 v194, 0x3f317217, v195
; __device__ __forceinline__ float fsigm(float x) { return __builtin_amdgcn_rcpf(1.f + __expf(-x)); }
; __device__ __forceinline__ float row_rs(const float* ssq, int row) { return ssq ? rsqrtf(ssq[row] * (1.f / 1024.f) + RMS_EPS) : 1.f; }
;     __device__ __forceinline__ void operator()(const f32x4 (&acc)[2][2][4][2], const Unit& u, int wr, int wc, int fr, int fq) const {
;     ...
;                 for (int m = 0; m < 4; ++m) { const int row = row0 + ai * HALF + m * 16; const float rs = row_rs(ssq, row);
; #pragma unroll
;                     for (int bj = 0; bj < 2; ++bj) { f16x4 o[2];
; #pragma unroll
;                         for (int n = 0; n < 2; ++n) { const f32x4 p = acc[ai][bj][m][n] * rs;
; #pragma unroll
;                             for (int j = 0; j < 4; ++j) { const float l = lb[bj][n][j]; const float f = l + (1.f - l) * fsigm(p[j]); o[n][j] = (_Float16)__logf(f); } }
;                         const u32x2 a0 = __builtin_bit_cast(u32x2, o[0]), a1 = __builtin_bit_cast(u32x2, o[1]); u32x4 w; w.x = a0.x; w.y = a0.y; w.z = a1.x; w.w = a1.y;
;                         *(u32x4*)(LF + (size_t)row * 512 + cbase + bj * HALF) = w; } }
	v_add_f32_e32 v199, 1.0, v199
	v_fma_f32 v194, v195, s95, -v194
	v_rcp_f32_e32 v199, v199
	v_fmac_f32_e32 v194, 0x3377d1cf, v195
	v_fmac_f32_e32 v194, 0x3f317217, v195
	v_cmp_lt_f32_e64 s[6:7], |v195|, s96
	v_fma_f32 v199, v149, v199, v165
	s_nop 0
	v_cndmask_b32_e64 v194, v195, v194, s[6:7]
	v_cndmask_b32_e32 v195, 0, v171, vcc
	v_sub_f32_e32 v194, v194, v195
	v_mul_f32_e32 v195, v89, v191
	v_cmp_gt_f32_e32 vcc, s90, v199
	v_mul_f32_e32 v195, 0xbfb8aa3b, v195
	v_exp_f32_e32 v195, v195
	v_cndmask_b32_e64 v200, 0, 32, vcc
	v_ldexp_f32 v199, v199, v200
	v_log_f32_e32 v199, v199
	v_add_f32_e32 v195, 1.0, v195
	v_rcp_f32_e32 v195, v195
	v_cvt_pk_f16_f32 v193, v193, v194
	v_mul_f32_e32 v194, 0x3f317217, v199
	v_fma_f32 v194, v199, s95, -v194
	v_fmac_f32_e32 v194, 0x3377d1cf, v199
	v_fmac_f32_e32 v194, 0x3f317217, v199
	v_cmp_lt_f32_e64 s[6:7], |v199|, s96
	v_fma_f32 v195, v179, v195, v164
	v_cndmask_b32_e32 v198, 0, v171, vcc
	v_cndmask_b32_e64 v194, v199, v194, s[6:7]
	v_cmp_gt_f32_e32 vcc, s90, v195
	v_sub_f32_e32 v194, v194, v198
	s_nop 0
	v_cndmask_b32_e64 v198, 0, 32, vcc
	v_ldexp_f32 v195, v195, v198
	v_mul_f32_e32 v198, v90, v191
	v_mul_f32_e32 v198, 0xbfb8aa3b, v198
	v_exp_f32_e32 v198, v198
	v_log_f32_e32 v195, v195
	v_cndmask_b32_e32 v200, 0, v171, vcc
	v_add_f32_e32 v198, 1.0, v198
	v_rcp_f32_e32 v198, v198
	v_mul_f32_e32 v199, 0x3f317217, v195
	v_fma_f32 v199, v195, s95, -v199
	v_fmac_f32_e32 v199, 0x3377d1cf, v195
	v_fmac_f32_e32 v199, 0x3f317217, v195
	v_cmp_lt_f32_e64 s[6:7], |v195|, s96
	v_fma_f32 v198, v180, v198, v163
	s_nop 0
	v_cndmask_b32_e64 v195, v195, v199, s[6:7]
	v_cmp_gt_f32_e64 s[6:7], s90, v198
	v_sub_f32_e32 v200, v195, v200
	v_cvt_pk_f16_f32 v194, v194, v200
	v_cndmask_b32_e64 v199, 0, 32, s[6:7]
	v_ldexp_f32 v198, v198, v199
	v_mul_f32_e32 v199, v91, v191
	v_mul_f32_e32 v199, 0xbfb8aa3b, v199
	v_exp_f32_e32 v199, v199
	v_log_f32_e32 v198, v198
	v_add_f32_e32 v199, 1.0, v199
	v_rcp_f32_e32 v199, v199
	v_mul_f32_e32 v195, 0x3f317217, v198
	v_fma_f32 v195, v198, s95, -v195
	v_fmac_f32_e32 v195, 0x3377d1cf, v198
	v_fma_f32 v199, v188, v199, v162
	v_cmp_gt_f32_e32 vcc, s90, v199
	v_fmac_f32_e32 v195, 0x3f317217, v198
	v_cmp_lt_f32_e64 s[8:9], |v198|, s96
	v_cndmask_b32_e64 v201, 0, 32, vcc
	v_ldexp_f32 v199, v199, v201
	v_log_f32_e32 v199, v199
	v_mul_f32_e32 v201, v84, v191
	v_mul_f32_e32 v201, 0xbfb8aa3b, v201
	v_exp_f32_e32 v201, v201
	v_cndmask_b32_e64 v195, v198, v195, s[8:9]
	v_cndmask_b32_e64 v198, 0, v171, s[6:7]
	v_sub_f32_e32 v195, v195, v198
	v_mul_f32_e32 v198, 0x3f317217, v199
	v_fma_f32 v198, v199, s95, -v198
	v_fmac_f32_e32 v198, 0x3377d1cf, v199
	v_add_f32_e32 v201, 1.0, v201
	v_fmac_f32_e32 v198, 0x3f317217, v199
	v_cmp_lt_f32_e64 s[6:7], |v199|, s96
	v_rcp_f32_e32 v201, v201
	s_nop 0
	v_cndmask_b32_e64 v198, v199, v198, s[6:7]
	v_cndmask_b32_e32 v199, 0, v171, vcc
	v_sub_f32_e32 v198, v198, v199
	v_cvt_pk_f16_f32 v195, v195, v198
	v_fma_f32 v198, v184, v201, v161
	global_store_dwordx4 v[196:197], v[192:195], off
	v_cmp_gt_f32_e32 vcc, s90, v198
	s_nop 0
	v_mul_f32_e32 v193, v85, v191
	v_mul_f32_e32 v193, 0xbfb8aa3b, v193
	v_cndmask_b32_e64 v199, 0, 32, vcc
	v_exp_f32_e32 v193, v193
	v_ldexp_f32 v198, v198, v199
	v_log_f32_e32 v198, v198
	v_cndmask_b32_e32 v194, 0, v171, vcc
	v_add_f32_e32 v193, 1.0, v193
	v_rcp_f32_e32 v193, v193
	v_mul_f32_e32 v192, 0x3f317217, v198
	v_fma_f32 v192, v198, s95, -v192
	v_fmac_f32_e32 v192, 0x3377d1cf, v198
	v_fmac_f32_e32 v192, 0x3f317217, v198
	v_cmp_lt_f32_e64 s[6:7], |v198|, s96
	v_fma_f32 v193, v181, v193, v160
	v_cmp_gt_f32_e32 vcc, s90, v193
	v_cndmask_b32_e64 v192, v198, v192, s[6:7]
	v_sub_f32_e32 v192, v192, v194
	v_cndmask_b32_e64 v194, 0, 32, vcc
	v_ldexp_f32 v193, v193, v194
	v_mul_f32_e32 v194, v86, v191
	v_mul_f32_e32 v194, 0xbfb8aa3b, v194
	v_exp_f32_e32 v194, v194
	v_log_f32_e32 v193, v193
	v_cndmask_b32_e32 v198, 0, v171, vcc
	v_add_f32_e32 v194, 1.0, v194
	v_rcp_f32_e32 v194, v194
	v_mul_f32_e32 v195, 0x3f317217, v193
	v_fma_f32 v195, v193, s95, -v195
	v_fmac_f32_e32 v195, 0x3377d1cf, v193
	v_fmac_f32_e32 v195, 0x3f317217, v193
	v_cmp_lt_f32_e64 s[6:7], |v193|, s96
	v_fma_f32 v194, v185, v194, v159
	s_nop 0
	v_cndmask_b32_e64 v193, v193, v195, s[6:7]
	v_cmp_gt_f32_e64 s[6:7], s90, v194
	v_sub_f32_e32 v198, v193, v198
	v_cvt_pk_f16_f32 v192, v192, v198
	v_cndmask_b32_e64 v195, 0, 32, s[6:7]
	v_ldexp_f32 v194, v194, v195
	v_mul_f32_e32 v195, v87, v191
	v_mul_f32_e32 v195, 0xbfb8aa3b, v195
	v_exp_f32_e32 v195, v195
	v_log_f32_e32 v194, v194
	v_add_f32_e32 v195, 1.0, v195
	v_rcp_f32_e32 v195, v195
	v_mul_f32_e32 v193, 0x3f317217, v194
	v_fma_f32 v193, v194, s95, -v193
	v_fmac_f32_e32 v193, 0x3377d1cf, v194
	v_fma_f32 v195, v186, v195, v158
	v_cmp_gt_f32_e32 vcc, s90, v195
	v_fmac_f32_e32 v193, 0x3f317217, v194
	v_cmp_lt_f32_e64 s[8:9], |v194|, s96
	v_cndmask_b32_e64 v199, 0, 32, vcc
	v_ldexp_f32 v195, v195, v199
	v_mul_f32_e32 v199, v80, v191
	v_mul_f32_e32 v199, 0xbfb8aa3b, v199
	v_log_f32_e32 v195, v195
	v_exp_f32_e32 v199, v199
	v_cndmask_b32_e64 v193, v194, v193, s[8:9]
	v_cndmask_b32_e64 v194, 0, v171, s[6:7]
	v_sub_f32_e32 v193, v193, v194
	v_mul_f32_e32 v194, 0x3f317217, v195
	v_add_f32_e32 v199, 1.0, v199
	v_fma_f32 v194, v195, s95, -v194
	v_rcp_f32_e32 v199, v199
	v_fmac_f32_e32 v194, 0x3377d1cf, v195
	v_fmac_f32_e32 v194, 0x3f317217, v195
	v_cmp_lt_f32_e64 s[6:7], |v195|, s96
	v_fma_f32 v199, v187, v199, v157
	s_nop 0
	v_cndmask_b32_e64 v194, v195, v194, s[6:7]
	v_cndmask_b32_e32 v195, 0, v171, vcc
	v_sub_f32_e32 v194, v194, v195
	v_mul_f32_e32 v195, v81, v191
	v_cmp_gt_f32_e32 vcc, s90, v199
	v_mul_f32_e32 v195, 0xbfb8aa3b, v195
; __device__ __forceinline__ float fsigm(float x) { return __builtin_amdgcn_rcpf(1.f + __expf(-x)); }
; __device__ __forceinline__ float row_rs(const float* ssq, int row) { return ssq ? rsqrtf(ssq[row] * (1.f / 1024.f) + RMS_EPS) : 1.f; }
;     __device__ __forceinline__ void operator()(const f32x4 (&acc)[2][2][4][2], const Unit& u, int wr, int wc, int fr, int fq) const {
;     ...
;                 for (int m = 0; m < 4; ++m) { const int row = row0 + ai * HALF + m * 16; const float rs = row_rs(ssq, row);
; #pragma unroll
;                     for (int bj = 0; bj < 2; ++bj) { f16x4 o[2];
; #pragma unroll
;                         for (int n = 0; n < 2; ++n) { const f32x4 p = acc[ai][bj][m][n] * rs;
; #pragma unroll
;                             for (int j = 0; j < 4; ++j) { const float l = lb[bj][n][j]; const float f = l + (1.f - l) * fsigm(p[j]); o[n][j] = (_Float16)__logf(f); } }
;                         const u32x2 a0 = __builtin_bit_cast(u32x2, o[0]), a1 = __builtin_bit_cast(u32x2, o[1]); u32x4 w; w.x = a0.x; w.y = a0.y; w.z = a1.x; w.w = a1.y;
;                         *(u32x4*)(LF + (size_t)row * 512 + cbase + bj * HALF) = w; } }
	v_exp_f32_e32 v195, v195
	v_cndmask_b32_e64 v200, 0, 32, vcc
	v_ldexp_f32 v199, v199, v200
	v_log_f32_e32 v199, v199
	v_add_f32_e32 v195, 1.0, v195
	v_rcp_f32_e32 v195, v195
	v_cvt_pk_f16_f32 v193, v193, v194
	v_mul_f32_e32 v194, 0x3f317217, v199
	v_fma_f32 v194, v199, s95, -v194
	v_fmac_f32_e32 v194, 0x3377d1cf, v199
	v_fmac_f32_e32 v194, 0x3f317217, v199
	v_cmp_lt_f32_e64 s[6:7], |v199|, s96
	v_fma_f32 v195, v182, v195, v156
	v_cndmask_b32_e32 v198, 0, v171, vcc
	v_cndmask_b32_e64 v194, v199, v194, s[6:7]
	v_cmp_gt_f32_e32 vcc, s90, v195
	v_sub_f32_e32 v194, v194, v198
	s_nop 0
	v_cndmask_b32_e64 v198, 0, 32, vcc
	v_ldexp_f32 v195, v195, v198
	v_mul_f32_e32 v198, v82, v191
	v_mul_f32_e32 v198, 0xbfb8aa3b, v198
	v_exp_f32_e32 v198, v198
	v_log_f32_e32 v195, v195
	v_mul_f32_e32 v191, v83, v191
	v_mul_f32_e32 v191, 0xbfb8aa3b, v191
	v_add_f32_e32 v198, 1.0, v198
	v_rcp_f32_e32 v198, v198
	v_exp_f32_e32 v191, v191
	v_mul_f32_e32 v199, 0x3f317217, v195
	v_fma_f32 v199, v195, s95, -v199
	v_fmac_f32_e32 v199, 0x3377d1cf, v195
	v_fmac_f32_e32 v199, 0x3f317217, v195
	v_cmp_lt_f32_e64 s[6:7], |v195|, s96
	v_fma_f32 v198, v189, v198, v155
	v_add_f32_e32 v191, 1.0, v191
	v_cndmask_b32_e64 v195, v195, v199, s[6:7]
	v_cmp_gt_f32_e64 s[6:7], s90, v198
	v_rcp_f32_e32 v191, v191
	s_nop 0
	v_cndmask_b32_e64 v199, 0, 32, s[6:7]
	v_ldexp_f32 v198, v198, v199
	v_log_f32_e32 v198, v198
	v_fma_f32 v191, v190, v191, v154
	v_cndmask_b32_e32 v199, 0, v171, vcc
	v_cmp_gt_f32_e32 vcc, s90, v191
	v_sub_f32_e32 v199, v195, v199
	v_mul_f32_e32 v195, 0x3f317217, v198
	v_cndmask_b32_e64 v200, 0, 32, vcc
	v_ldexp_f32 v191, v191, v200
	v_fma_f32 v195, v198, s95, -v195
	v_log_f32_e32 v191, v191
	v_fmac_f32_e32 v195, 0x3377d1cf, v198
	v_fmac_f32_e32 v195, 0x3f317217, v198
	v_cmp_lt_f32_e64 s[8:9], |v198|, s96
	v_cvt_pk_f16_f32 v194, v194, v199
	s_nop 0
	v_cndmask_b32_e64 v195, v198, v195, s[8:9]
	v_cndmask_b32_e64 v198, 0, v171, s[6:7]
	v_sub_f32_e32 v195, v195, v198
	v_mul_f32_e32 v198, 0x3f317217, v191
	v_fma_f32 v198, v191, s95, -v198
	v_fmac_f32_e32 v198, 0x3377d1cf, v191
	v_fmac_f32_e32 v198, 0x3f317217, v191
	v_cmp_lt_f32_e64 s[6:7], |v191|, s96
	s_nop 1
	v_cndmask_b32_e64 v191, v191, v198, s[6:7]
	v_cndmask_b32_e32 v198, 0, v171, vcc
	v_sub_f32_e32 v191, v191, v198
	v_cvt_pk_f16_f32 v195, v195, v191
	global_store_dwordx4 v[196:197], v[192:195], off offset:256
	s_nop 1
	v_or_b32_e32 v192, 48, v148
	v_ashrrev_i32_e32 v193, 31, v192
	v_lshl_add_u64 v[194:195], v[192:193], 2, s[30:31]
	v_lshlrev_b64 v[196:197], 10, v[192:193]
	v_lshl_add_u64 v[196:197], s[10:11], 0, v[196:197]
	v_lshl_add_u64 v[196:197], v[196:197], 0, v[136:137]
	v_fmamk_f32 v191, v212, 0x3a800000, v170
	v_rsq_f32_e32 v191, v191
	s_nop 0
	v_mul_f32_e32 v194, v76, v191
	v_mul_f32_e32 v194, 0xbfb8aa3b, v194
	v_exp_f32_e32 v194, v194
	v_mul_f32_e32 v193, v77, v191
	v_mul_f32_e32 v193, 0xbfb8aa3b, v193
	v_exp_f32_e32 v193, v193
	v_add_f32_e32 v194, 1.0, v194
	v_rcp_f32_e32 v194, v194
	v_add_f32_e32 v193, 1.0, v193
	v_rcp_f32_e32 v193, v193
	v_fma_f32 v194, v176, v194, v175
	v_cmp_gt_f32_e32 vcc, s90, v194
	v_fma_f32 v193, v177, v193, v174
	s_nop 0
	v_cndmask_b32_e64 v195, 0, 32, vcc
	v_ldexp_f32 v194, v194, v195
	v_log_f32_e32 v194, v194
	s_nop 0
	v_mul_f32_e32 v192, 0x3f317217, v194
	v_fma_f32 v192, v194, s95, -v192
	v_fmac_f32_e32 v192, 0x3377d1cf, v194
	v_fmac_f32_e32 v192, 0x3f317217, v194
	v_cmp_lt_f32_e64 s[6:7], |v194|, s96
	s_nop 1
	v_cndmask_b32_e64 v192, v194, v192, s[6:7]
	v_cndmask_b32_e32 v194, 0, v171, vcc
	v_cmp_gt_f32_e32 vcc, s90, v193
	v_sub_f32_e32 v192, v192, v194
	s_nop 0
	v_cndmask_b32_e64 v194, 0, 32, vcc
	v_ldexp_f32 v193, v193, v194
	v_mul_f32_e32 v194, v78, v191
	v_mul_f32_e32 v194, 0xbfb8aa3b, v194
	v_exp_f32_e32 v194, v194
	v_log_f32_e32 v193, v193
	v_cndmask_b32_e32 v198, 0, v171, vcc
	v_add_f32_e32 v194, 1.0, v194
	v_rcp_f32_e32 v194, v194
	v_mul_f32_e32 v195, 0x3f317217, v193
	v_fma_f32 v195, v193, s95, -v195
	v_fmac_f32_e32 v195, 0x3377d1cf, v193
	v_fmac_f32_e32 v195, 0x3f317217, v193
	v_cmp_lt_f32_e64 s[6:7], |v193|, s96
	v_fma_f32 v194, v178, v194, v173
	s_nop 0
	v_cndmask_b32_e64 v193, v193, v195, s[6:7]
	v_cmp_gt_f32_e64 s[6:7], s90, v194
	v_sub_f32_e32 v198, v193, v198
	v_cvt_pk_f16_f32 v192, v192, v198
	v_cndmask_b32_e64 v195, 0, 32, s[6:7]
	v_ldexp_f32 v194, v194, v195
	v_mul_f32_e32 v195, v79, v191
	v_mul_f32_e32 v195, 0xbfb8aa3b, v195
	v_exp_f32_e32 v195, v195
	v_log_f32_e32 v194, v194
	v_add_f32_e32 v195, 1.0, v195
	v_rcp_f32_e32 v195, v195
	v_mul_f32_e32 v193, 0x3f317217, v194
	v_fma_f32 v193, v194, s95, -v193
	v_fmac_f32_e32 v193, 0x3377d1cf, v194
	v_fma_f32 v195, v183, v195, v172
	v_cmp_gt_f32_e32 vcc, s90, v195
	v_fmac_f32_e32 v193, 0x3f317217, v194
	v_cmp_lt_f32_e64 s[8:9], |v194|, s96
	v_cndmask_b32_e64 v199, 0, 32, vcc
	v_ldexp_f32 v195, v195, v199
	v_mul_f32_e32 v199, v72, v191
	v_mul_f32_e32 v199, 0xbfb8aa3b, v199
	v_log_f32_e32 v195, v195
	v_exp_f32_e32 v199, v199
	v_cndmask_b32_e64 v193, v194, v193, s[8:9]
	v_cndmask_b32_e64 v194, 0, v171, s[6:7]
	v_sub_f32_e32 v193, v193, v194
	v_mul_f32_e32 v194, 0x3f317217, v195
	v_add_f32_e32 v199, 1.0, v199
	v_fma_f32 v194, v195, s95, -v194
	v_rcp_f32_e32 v199, v199
	v_fmac_f32_e32 v194, 0x3377d1cf, v195
	v_fmac_f32_e32 v194, 0x3f317217, v195
	v_cmp_lt_f32_e64 s[6:7], |v195|, s96
	v_fma_f32 v199, v149, v199, v165
	s_nop 0
	v_cndmask_b32_e64 v194, v195, v194, s[6:7]
	v_cndmask_b32_e32 v195, 0, v171, vcc
	v_sub_f32_e32 v194, v194, v195
	v_mul_f32_e32 v195, v73, v191
	v_cmp_gt_f32_e32 vcc, s90, v199
	v_mul_f32_e32 v195, 0xbfb8aa3b, v195
	v_exp_f32_e32 v195, v195
	v_cndmask_b32_e64 v200, 0, 32, vcc
	v_ldexp_f32 v199, v199, v200
; __device__ __forceinline__ float fsigm(float x) { return __builtin_amdgcn_rcpf(1.f + __expf(-x)); }
; __device__ __forceinline__ float row_rs(const float* ssq, int row) { return ssq ? rsqrtf(ssq[row] * (1.f / 1024.f) + RMS_EPS) : 1.f; }
;     __device__ __forceinline__ void operator()(const f32x4 (&acc)[2][2][4][2], const Unit& u, int wr, int wc, int fr, int fq) const {
;     ...
;                 for (int m = 0; m < 4; ++m) { const int row = row0 + ai * HALF + m * 16; const float rs = row_rs(ssq, row);
; #pragma unroll
;                     for (int bj = 0; bj < 2; ++bj) { f16x4 o[2];
; #pragma unroll
;                         for (int n = 0; n < 2; ++n) { const f32x4 p = acc[ai][bj][m][n] * rs;
; #pragma unroll
;                             for (int j = 0; j < 4; ++j) { const float l = lb[bj][n][j]; const float f = l + (1.f - l) * fsigm(p[j]); o[n][j] = (_Float16)__logf(f); } }
;                         const u32x2 a0 = __builtin_bit_cast(u32x2, o[0]), a1 = __builtin_bit_cast(u32x2, o[1]); u32x4 w; w.x = a0.x; w.y = a0.y; w.z = a1.x; w.w = a1.y;
;                         *(u32x4*)(LF + (size_t)row * 512 + cbase + bj * HALF) = w; } }
	v_log_f32_e32 v199, v199
	v_add_f32_e32 v195, 1.0, v195
	v_rcp_f32_e32 v195, v195
	v_cvt_pk_f16_f32 v193, v193, v194
	v_mul_f32_e32 v194, 0x3f317217, v199
	v_fma_f32 v194, v199, s95, -v194
	v_fmac_f32_e32 v194, 0x3377d1cf, v199
	v_fmac_f32_e32 v194, 0x3f317217, v199
	v_cmp_lt_f32_e64 s[6:7], |v199|, s96
	v_fma_f32 v195, v179, v195, v164
	v_cndmask_b32_e32 v198, 0, v171, vcc
	v_cndmask_b32_e64 v194, v199, v194, s[6:7]
	v_cmp_gt_f32_e32 vcc, s90, v195
	v_sub_f32_e32 v194, v194, v198
	s_nop 0
	v_cndmask_b32_e64 v198, 0, 32, vcc
	v_ldexp_f32 v195, v195, v198
	v_mul_f32_e32 v198, v74, v191
	v_mul_f32_e32 v198, 0xbfb8aa3b, v198
	v_exp_f32_e32 v198, v198
	v_log_f32_e32 v195, v195
	v_cndmask_b32_e32 v200, 0, v171, vcc
	v_add_f32_e32 v198, 1.0, v198
	v_rcp_f32_e32 v198, v198
	v_mul_f32_e32 v199, 0x3f317217, v195
	v_fma_f32 v199, v195, s95, -v199
	v_fmac_f32_e32 v199, 0x3377d1cf, v195
	v_fmac_f32_e32 v199, 0x3f317217, v195
	v_cmp_lt_f32_e64 s[6:7], |v195|, s96
	v_fma_f32 v198, v180, v198, v163
	s_nop 0
	v_cndmask_b32_e64 v195, v195, v199, s[6:7]
	v_cmp_gt_f32_e64 s[6:7], s90, v198
	v_sub_f32_e32 v200, v195, v200
	v_cvt_pk_f16_f32 v194, v194, v200
	v_cndmask_b32_e64 v199, 0, 32, s[6:7]
	v_ldexp_f32 v198, v198, v199
	v_mul_f32_e32 v199, v75, v191
	v_mul_f32_e32 v199, 0xbfb8aa3b, v199
	v_exp_f32_e32 v199, v199
	v_log_f32_e32 v198, v198
	v_add_f32_e32 v199, 1.0, v199
	v_rcp_f32_e32 v199, v199
	v_mul_f32_e32 v195, 0x3f317217, v198
	v_fma_f32 v195, v198, s95, -v195
	v_fmac_f32_e32 v195, 0x3377d1cf, v198
	v_fma_f32 v199, v188, v199, v162
	v_cmp_gt_f32_e32 vcc, s90, v199
	v_fmac_f32_e32 v195, 0x3f317217, v198
	v_cmp_lt_f32_e64 s[8:9], |v198|, s96
	v_cndmask_b32_e64 v201, 0, 32, vcc
	v_ldexp_f32 v199, v199, v201
	v_log_f32_e32 v199, v199
	v_mul_f32_e32 v201, v68, v191
	v_mul_f32_e32 v201, 0xbfb8aa3b, v201
	v_exp_f32_e32 v201, v201
	v_cndmask_b32_e64 v195, v198, v195, s[8:9]
	v_cndmask_b32_e64 v198, 0, v171, s[6:7]
	v_sub_f32_e32 v195, v195, v198
	v_mul_f32_e32 v198, 0x3f317217, v199
	v_fma_f32 v198, v199, s95, -v198
	v_fmac_f32_e32 v198, 0x3377d1cf, v199
	v_add_f32_e32 v201, 1.0, v201
	v_fmac_f32_e32 v198, 0x3f317217, v199
	v_cmp_lt_f32_e64 s[6:7], |v199|, s96
	v_rcp_f32_e32 v201, v201
	s_nop 0
	v_cndmask_b32_e64 v198, v199, v198, s[6:7]
	v_cndmask_b32_e32 v199, 0, v171, vcc
	v_sub_f32_e32 v198, v198, v199
	v_cvt_pk_f16_f32 v195, v195, v198
	v_fma_f32 v198, v184, v201, v161
	global_store_dwordx4 v[196:197], v[192:195], off
	v_cmp_gt_f32_e32 vcc, s90, v198
	s_nop 0
	v_mul_f32_e32 v192, v69, v191
	v_mul_f32_e32 v192, 0xbfb8aa3b, v192
	v_cndmask_b32_e64 v199, 0, 32, vcc
	v_exp_f32_e32 v192, v192
	v_ldexp_f32 v198, v198, v199
	v_log_f32_e32 v198, v198
	v_cndmask_b32_e32 v193, 0, v171, vcc
	v_add_f32_e32 v192, 1.0, v192
	v_rcp_f32_e32 v192, v192
	v_mul_f32_e32 v136, 0x3f317217, v198
	v_fma_f32 v136, v198, s95, -v136
	v_fmac_f32_e32 v136, 0x3377d1cf, v198
	v_fmac_f32_e32 v136, 0x3f317217, v198
	v_cmp_lt_f32_e64 s[6:7], |v198|, s96
	v_fma_f32 v192, v181, v192, v160
	v_cmp_gt_f32_e32 vcc, s90, v192
	v_cndmask_b32_e64 v136, v198, v136, s[6:7]
	v_sub_f32_e32 v136, v136, v193
	v_cndmask_b32_e64 v193, 0, 32, vcc
	v_ldexp_f32 v192, v192, v193
	v_mul_f32_e32 v193, v70, v191
	v_mul_f32_e32 v193, 0xbfb8aa3b, v193
	v_exp_f32_e32 v193, v193
	v_log_f32_e32 v192, v192
	v_cndmask_b32_e32 v195, 0, v171, vcc
	v_add_f32_e32 v193, 1.0, v193
	v_rcp_f32_e32 v193, v193
	v_mul_f32_e32 v194, 0x3f317217, v192
	v_fma_f32 v194, v192, s95, -v194
	v_fmac_f32_e32 v194, 0x3377d1cf, v192
	v_fmac_f32_e32 v194, 0x3f317217, v192
	v_cmp_lt_f32_e64 s[6:7], |v192|, s96
	v_fma_f32 v193, v185, v193, v159
	s_nop 0
	v_cndmask_b32_e64 v192, v192, v194, s[6:7]
	v_cmp_gt_f32_e64 s[6:7], s90, v193
	v_sub_f32_e32 v192, v192, v195
	v_cvt_pk_f16_f32 v192, v136, v192
	v_cndmask_b32_e64 v194, 0, 32, s[6:7]
	v_ldexp_f32 v193, v193, v194
	v_mul_f32_e32 v194, v71, v191
	v_mul_f32_e32 v194, 0xbfb8aa3b, v194
	v_exp_f32_e32 v194, v194
	v_log_f32_e32 v193, v193
	v_add_f32_e32 v194, 1.0, v194
	v_rcp_f32_e32 v194, v194
	v_mul_f32_e32 v195, 0x3f317217, v193
	v_fma_f32 v195, v193, s95, -v195
	v_fmac_f32_e32 v195, 0x3377d1cf, v193
	v_fma_f32 v194, v186, v194, v158
	v_cmp_gt_f32_e32 vcc, s90, v194
	v_fmac_f32_e32 v195, 0x3f317217, v193
	v_cmp_lt_f32_e64 s[8:9], |v193|, s96
	v_cndmask_b32_e64 v198, 0, 32, vcc
	v_ldexp_f32 v194, v194, v198
	v_mul_f32_e32 v198, v64, v191
	v_log_f32_e32 v194, v194
	v_mul_f32_e32 v198, 0xbfb8aa3b, v198
	v_exp_f32_e32 v198, v198
	v_cndmask_b32_e64 v193, v193, v195, s[8:9]
	v_cndmask_b32_e64 v195, 0, v171, s[6:7]
	v_sub_f32_e32 v193, v193, v195
	v_mul_f32_e32 v195, 0x3f317217, v194
	v_fma_f32 v195, v194, s95, -v195
	v_add_f32_e32 v198, 1.0, v198
	v_fmac_f32_e32 v195, 0x3377d1cf, v194
	v_rcp_f32_e32 v198, v198
	v_fmac_f32_e32 v195, 0x3f317217, v194
	v_cmp_lt_f32_e64 s[6:7], |v194|, s96
	v_fma_f32 v198, v187, v198, v157
	s_nop 0
	v_cndmask_b32_e64 v194, v194, v195, s[6:7]
	v_cndmask_b32_e32 v195, 0, v171, vcc
	v_sub_f32_e32 v194, v194, v195
	v_cvt_pk_f16_f32 v193, v193, v194
	v_mul_f32_e32 v194, v65, v191
	v_cmp_gt_f32_e32 vcc, s90, v198
	v_mul_f32_e32 v194, 0xbfb8aa3b, v194
	v_exp_f32_e32 v194, v194
	v_cndmask_b32_e64 v199, 0, 32, vcc
	v_ldexp_f32 v198, v198, v199
	v_log_f32_e32 v198, v198
	v_add_f32_e32 v194, 1.0, v194
	v_rcp_f32_e32 v194, v194
	v_cndmask_b32_e32 v195, 0, v171, vcc
	v_mul_f32_e32 v136, 0x3f317217, v198
	v_fma_f32 v136, v198, s95, -v136
	v_fmac_f32_e32 v136, 0x3377d1cf, v198
	v_fmac_f32_e32 v136, 0x3f317217, v198
	v_cmp_lt_f32_e64 s[6:7], |v198|, s96
	v_fma_f32 v194, v182, v194, v156
	v_cmp_gt_f32_e32 vcc, s90, v194
	v_cndmask_b32_e64 v136, v198, v136, s[6:7]
	v_sub_f32_e32 v136, v136, v195
; __device__ __forceinline__ float fsigm(float x) { return __builtin_amdgcn_rcpf(1.f + __expf(-x)); }
; __device__ __forceinline__ float row_rs(const float* ssq, int row) { return ssq ? rsqrtf(ssq[row] * (1.f / 1024.f) + RMS_EPS) : 1.f; }
;     __device__ __forceinline__ void operator()(const f32x4 (&acc)[2][2][4][2], const Unit& u, int wr, int wc, int fr, int fq) const {
;     ...
;                 for (int m = 0; m < 4; ++m) { const int row = row0 + ai * HALF + m * 16; const float rs = row_rs(ssq, row);
; #pragma unroll
;                     for (int bj = 0; bj < 2; ++bj) { f16x4 o[2];
; #pragma unroll
;                         for (int n = 0; n < 2; ++n) { const f32x4 p = acc[ai][bj][m][n] * rs;
; #pragma unroll
;                             for (int j = 0; j < 4; ++j) { const float l = lb[bj][n][j]; const float f = l + (1.f - l) * fsigm(p[j]); o[n][j] = (_Float16)__logf(f); } }
;                         const u32x2 a0 = __builtin_bit_cast(u32x2, o[0]), a1 = __builtin_bit_cast(u32x2, o[1]); u32x4 w; w.x = a0.x; w.y = a0.y; w.z = a1.x; w.w = a1.y;
;                         *(u32x4*)(LF + (size_t)row * 512 + cbase + bj * HALF) = w; } }
	v_cndmask_b32_e64 v195, 0, 32, vcc
	v_ldexp_f32 v194, v194, v195
	v_mul_f32_e32 v195, v66, v191
	v_mul_f32_e32 v195, 0xbfb8aa3b, v195
	v_exp_f32_e32 v195, v195
	v_log_f32_e32 v194, v194
	v_mul_f32_e32 v191, v67, v191
	v_mul_f32_e32 v191, 0xbfb8aa3b, v191
	v_add_f32_e32 v195, 1.0, v195
	v_rcp_f32_e32 v195, v195
	v_exp_f32_e32 v191, v191
	v_mul_f32_e32 v198, 0x3f317217, v194
	v_fma_f32 v198, v194, s95, -v198
	v_fmac_f32_e32 v198, 0x3377d1cf, v194
	v_fmac_f32_e32 v198, 0x3f317217, v194
	v_cmp_lt_f32_e64 s[6:7], |v194|, s96
	v_fma_f32 v195, v189, v195, v155
	v_add_f32_e32 v191, 1.0, v191
	v_cndmask_b32_e64 v194, v194, v198, s[6:7]
	v_cmp_gt_f32_e64 s[6:7], s90, v195
	v_rcp_f32_e32 v191, v191
	s_nop 0
	v_cndmask_b32_e64 v198, 0, 32, s[6:7]
	v_ldexp_f32 v195, v195, v198
	v_log_f32_e32 v195, v195
	v_fma_f32 v191, v190, v191, v154
	v_cndmask_b32_e32 v198, 0, v171, vcc
	v_cmp_gt_f32_e32 vcc, s90, v191
	v_sub_f32_e32 v194, v194, v198
	v_mul_f32_e32 v198, 0x3f317217, v195
	v_cndmask_b32_e64 v199, 0, 32, vcc
	v_ldexp_f32 v191, v191, v199
	v_fma_f32 v198, v195, s95, -v198
	v_log_f32_e32 v191, v191
	v_fmac_f32_e32 v198, 0x3377d1cf, v195
	v_fmac_f32_e32 v198, 0x3f317217, v195
	v_cmp_lt_f32_e64 s[8:9], |v195|, s96
	v_cvt_pk_f16_f32 v194, v136, v194
	s_nop 0
	v_cndmask_b32_e64 v195, v195, v198, s[8:9]
	v_cndmask_b32_e64 v198, 0, v171, s[6:7]
	v_sub_f32_e32 v195, v195, v198
	v_mul_f32_e32 v198, 0x3f317217, v191
	v_fma_f32 v198, v191, s95, -v198
	v_fmac_f32_e32 v198, 0x3377d1cf, v191
	v_fmac_f32_e32 v198, 0x3f317217, v191
	v_cmp_lt_f32_e64 s[6:7], |v191|, s96
	s_nop 1
	v_cndmask_b32_e64 v191, v191, v198, s[6:7]
	v_cndmask_b32_e32 v198, 0, v171, vcc
	v_sub_f32_e32 v191, v191, v198
	v_cvt_pk_f16_f32 v195, v195, v191
	global_store_dwordx4 v[196:197], v[192:195], off offset:256
	v_fmamk_f32 v136, v213, 0x3a800000, v170
	v_rsq_f32_e32 v136, v136
	s_nop 0
	v_mul_f32_e32 v191, v60, v136
	v_mul_f32_e32 v191, 0xbfb8aa3b, v191
	v_exp_f32_e32 v191, v191
	v_mul_f32_e32 v193, v61, v136
	v_mul_f32_e32 v193, 0xbfb8aa3b, v193
	v_exp_f32_e32 v193, v193
	v_add_f32_e32 v191, 1.0, v191
	v_rcp_f32_e32 v191, v191
	v_add_f32_e32 v193, 1.0, v193
	v_rcp_f32_e32 v193, v193
	v_fma_f32 v191, v176, v191, v175
	v_cmp_gt_f32_e32 vcc, s90, v191
	s_nop 1
	v_cndmask_b32_e64 v192, 0, 32, vcc
	v_ldexp_f32 v191, v191, v192
	v_log_f32_e32 v191, v191
	s_nop 0
	v_mul_f32_e32 v192, 0x3f317217, v191
	v_fma_f32 v192, v191, s95, -v192
	v_fmac_f32_e32 v192, 0x3377d1cf, v191
	v_fmac_f32_e32 v192, 0x3f317217, v191
	v_cmp_lt_f32_e64 s[6:7], |v191|, s96
	s_nop 1
	v_cndmask_b32_e64 v191, v191, v192, s[6:7]
	v_cndmask_b32_e32 v192, 0, v171, vcc
	v_sub_f32_e32 v191, v191, v192
	v_fma_f32 v192, v177, v193, v174
	v_cmp_gt_f32_e32 vcc, s90, v192
	s_nop 1
	v_cndmask_b32_e64 v193, 0, 32, vcc
	v_ldexp_f32 v192, v192, v193
	v_mul_f32_e32 v193, v62, v136
	v_mul_f32_e32 v193, 0xbfb8aa3b, v193
	v_exp_f32_e32 v193, v193
	v_log_f32_e32 v192, v192
	v_cndmask_b32_e32 v195, 0, v171, vcc
	v_add_f32_e32 v193, 1.0, v193
	v_rcp_f32_e32 v193, v193
	v_mul_f32_e32 v194, 0x3f317217, v192
	v_fma_f32 v194, v192, s95, -v194
	v_fmac_f32_e32 v194, 0x3377d1cf, v192
	v_fmac_f32_e32 v194, 0x3f317217, v192
	v_cmp_lt_f32_e64 s[6:7], |v192|, s96
	v_fma_f32 v193, v178, v193, v173
	s_nop 0
	v_cndmask_b32_e64 v192, v192, v194, s[6:7]
	v_cmp_gt_f32_e64 s[6:7], s90, v193
	v_sub_f32_e32 v192, v192, v195
	v_cvt_pk_f16_f32 v192, v191, v192
	v_cndmask_b32_e64 v194, 0, 32, s[6:7]
	v_ldexp_f32 v193, v193, v194
	v_mul_f32_e32 v194, v63, v136
	v_mul_f32_e32 v194, 0xbfb8aa3b, v194
	v_exp_f32_e32 v194, v194
	v_log_f32_e32 v193, v193
	v_add_f32_e32 v194, 1.0, v194
	v_rcp_f32_e32 v194, v194
	v_mul_f32_e32 v195, 0x3f317217, v193
	v_fma_f32 v195, v193, s95, -v195
	v_fmac_f32_e32 v195, 0x3377d1cf, v193
	v_fma_f32 v194, v183, v194, v172
	v_cmp_gt_f32_e32 vcc, s90, v194
	v_fmac_f32_e32 v195, 0x3f317217, v193
	v_cmp_lt_f32_e64 s[8:9], |v193|, s96
	v_cndmask_b32_e64 v196, 0, 32, vcc
	v_ldexp_f32 v194, v194, v196
	v_mul_f32_e32 v196, v56, v136
	v_log_f32_e32 v194, v194
	v_mul_f32_e32 v196, 0xbfb8aa3b, v196
	v_exp_f32_e32 v196, v196
	v_cndmask_b32_e64 v193, v193, v195, s[8:9]
	v_cndmask_b32_e64 v195, 0, v171, s[6:7]
	v_sub_f32_e32 v193, v193, v195
	v_mul_f32_e32 v195, 0x3f317217, v194
	v_fma_f32 v195, v194, s95, -v195
	v_add_f32_e32 v196, 1.0, v196
	v_fmac_f32_e32 v195, 0x3377d1cf, v194
	v_rcp_f32_e32 v196, v196
	v_fmac_f32_e32 v195, 0x3f317217, v194
	v_cmp_lt_f32_e64 s[6:7], |v194|, s96
	v_fma_f32 v196, v149, v196, v165
	s_nop 0
	v_cndmask_b32_e64 v194, v194, v195, s[6:7]
	v_cndmask_b32_e32 v195, 0, v171, vcc
	v_sub_f32_e32 v194, v194, v195
	v_cvt_pk_f16_f32 v193, v193, v194
	v_mul_f32_e32 v194, v57, v136
	v_cmp_gt_f32_e32 vcc, s90, v196
	v_mul_f32_e32 v194, 0xbfb8aa3b, v194
	v_exp_f32_e32 v194, v194
	v_cndmask_b32_e64 v197, 0, 32, vcc
	v_ldexp_f32 v196, v196, v197
	v_log_f32_e32 v196, v196
	v_add_f32_e32 v194, 1.0, v194
	v_rcp_f32_e32 v194, v194
	v_cndmask_b32_e32 v195, 0, v171, vcc
	v_mul_f32_e32 v191, 0x3f317217, v196
	v_fma_f32 v191, v196, s95, -v191
	v_fmac_f32_e32 v191, 0x3377d1cf, v196
	v_fmac_f32_e32 v191, 0x3f317217, v196
	v_cmp_lt_f32_e64 s[6:7], |v196|, s96
	v_fma_f32 v194, v179, v194, v164
	v_cmp_gt_f32_e32 vcc, s90, v194
	v_cndmask_b32_e64 v191, v196, v191, s[6:7]
	v_sub_f32_e32 v191, v191, v195
	v_cndmask_b32_e64 v195, 0, 32, vcc
	v_ldexp_f32 v194, v194, v195
	v_mul_f32_e32 v195, v58, v136
	v_mul_f32_e32 v195, 0xbfb8aa3b, v195
	v_exp_f32_e32 v195, v195
	v_log_f32_e32 v194, v194
	v_cndmask_b32_e32 v197, 0, v171, vcc
	v_add_f32_e32 v195, 1.0, v195
	v_rcp_f32_e32 v195, v195
	v_mul_f32_e32 v196, 0x3f317217, v194
	v_fma_f32 v196, v194, s95, -v196
; __device__ __forceinline__ float fsigm(float x) { return __builtin_amdgcn_rcpf(1.f + __expf(-x)); }
; __device__ __forceinline__ float row_rs(const float* ssq, int row) { return ssq ? rsqrtf(ssq[row] * (1.f / 1024.f) + RMS_EPS) : 1.f; }
;     __device__ __forceinline__ void operator()(const f32x4 (&acc)[2][2][4][2], const Unit& u, int wr, int wc, int fr, int fq) const {
;     ...
;                 for (int m = 0; m < 4; ++m) { const int row = row0 + ai * HALF + m * 16; const float rs = row_rs(ssq, row);
; #pragma unroll
;                     for (int bj = 0; bj < 2; ++bj) { f16x4 o[2];
; #pragma unroll
;                         for (int n = 0; n < 2; ++n) { const f32x4 p = acc[ai][bj][m][n] * rs;
; #pragma unroll
;                             for (int j = 0; j < 4; ++j) { const float l = lb[bj][n][j]; const float f = l + (1.f - l) * fsigm(p[j]); o[n][j] = (_Float16)__logf(f); } }
;                         const u32x2 a0 = __builtin_bit_cast(u32x2, o[0]), a1 = __builtin_bit_cast(u32x2, o[1]); u32x4 w; w.x = a0.x; w.y = a0.y; w.z = a1.x; w.w = a1.y;
;                         *(u32x4*)(LF + (size_t)row * 512 + cbase + bj * HALF) = w; } }
	v_fmac_f32_e32 v196, 0x3377d1cf, v194
	v_fmac_f32_e32 v196, 0x3f317217, v194
	v_cmp_lt_f32_e64 s[6:7], |v194|, s96
	v_fma_f32 v195, v180, v195, v163
	s_nop 0
	v_cndmask_b32_e64 v194, v194, v196, s[6:7]
	v_cmp_gt_f32_e64 s[6:7], s90, v195
	v_sub_f32_e32 v194, v194, v197
	v_cvt_pk_f16_f32 v194, v191, v194
	v_cndmask_b32_e64 v196, 0, 32, s[6:7]
	v_ldexp_f32 v195, v195, v196
	v_mul_f32_e32 v196, v59, v136
	v_mul_f32_e32 v196, 0xbfb8aa3b, v196
	v_exp_f32_e32 v196, v196
	v_log_f32_e32 v195, v195
	v_add_f32_e32 v196, 1.0, v196
	v_rcp_f32_e32 v196, v196
	v_mul_f32_e32 v197, 0x3f317217, v195
	v_fma_f32 v197, v195, s95, -v197
	v_fmac_f32_e32 v197, 0x3377d1cf, v195
	v_fma_f32 v196, v188, v196, v162
	v_cmp_gt_f32_e32 vcc, s90, v196
	v_fmac_f32_e32 v197, 0x3f317217, v195
	v_cmp_lt_f32_e64 s[8:9], |v195|, s96
	v_cndmask_b32_e64 v198, 0, 32, vcc
	v_ldexp_f32 v196, v196, v198
	v_log_f32_e32 v196, v196
	v_cndmask_b32_e64 v195, v195, v197, s[8:9]
	v_cndmask_b32_e64 v197, 0, v171, s[6:7]
	v_mul_f32_e32 v198, v52, v136
	v_sub_f32_e32 v195, v195, v197
	v_mul_f32_e32 v197, 0x3f317217, v196
	v_mul_f32_e32 v198, 0xbfb8aa3b, v198
	v_fma_f32 v197, v196, s95, -v197
	v_exp_f32_e32 v198, v198
	v_fmac_f32_e32 v197, 0x3377d1cf, v196
	v_fmac_f32_e32 v197, 0x3f317217, v196
	v_cmp_lt_f32_e64 s[6:7], |v196|, s96
	s_nop 1
	v_cndmask_b32_e64 v196, v196, v197, s[6:7]
	v_cndmask_b32_e32 v197, 0, v171, vcc
	v_sub_f32_e32 v196, v196, v197
	v_add_f32_e32 v197, 1.0, v198
	v_rcp_f32_e32 v198, v197
	v_cvt_pk_f16_f32 v195, v195, v196
	v_lshl_add_u64 v[196:197], v[152:153], 0, s[38:39]
	v_fma_f32 v191, v184, v198, v161
	v_cmp_gt_f32_e32 vcc, s90, v191
	s_nop 1
	v_cndmask_b32_e64 v198, 0, 32, vcc
	v_ldexp_f32 v191, v191, v198
	v_add_co_u32_e64 v198, s[6:7], s91, v152
	v_log_f32_e32 v191, v191
	s_nop 0
	v_addc_co_u32_e64 v199, s[6:7], 0, v153, s[6:7]
	global_store_dwordx4 v[198:199], v[192:195], off
	v_cmp_lt_f32_e64 s[6:7], |v191|, s96
	s_nop 0
	v_mul_f32_e32 v193, v53, v136
	v_mul_f32_e32 v193, 0xbfb8aa3b, v193
	v_exp_f32_e32 v193, v193
	v_mul_f32_e32 v192, 0x3f317217, v191
	v_fma_f32 v192, v191, s95, -v192
	v_fmac_f32_e32 v192, 0x3377d1cf, v191
	v_add_f32_e32 v193, 1.0, v193
	v_rcp_f32_e32 v193, v193
	v_fmac_f32_e32 v192, 0x3f317217, v191
	v_cndmask_b32_e64 v191, v191, v192, s[6:7]
	v_cndmask_b32_e32 v192, 0, v171, vcc
	v_sub_f32_e32 v191, v191, v192
	v_fma_f32 v192, v181, v193, v160
	v_cmp_gt_f32_e32 vcc, s90, v192
	s_nop 1
	v_cndmask_b32_e64 v193, 0, 32, vcc
	v_ldexp_f32 v192, v192, v193
	v_mul_f32_e32 v193, v54, v136
	v_mul_f32_e32 v193, 0xbfb8aa3b, v193
	v_exp_f32_e32 v193, v193
	v_log_f32_e32 v192, v192
	v_cndmask_b32_e32 v195, 0, v171, vcc
	v_add_f32_e32 v193, 1.0, v193
	v_rcp_f32_e32 v193, v193
	v_mul_f32_e32 v194, 0x3f317217, v192
	v_fma_f32 v194, v192, s95, -v194
	v_fmac_f32_e32 v194, 0x3377d1cf, v192
	v_fmac_f32_e32 v194, 0x3f317217, v192
	v_cmp_lt_f32_e64 s[6:7], |v192|, s96
	v_fma_f32 v193, v185, v193, v159
	s_nop 0
	v_cndmask_b32_e64 v192, v192, v194, s[6:7]
	v_cmp_gt_f32_e64 s[6:7], s90, v193
	v_sub_f32_e32 v192, v192, v195
	v_cvt_pk_f16_f32 v192, v191, v192
	v_cndmask_b32_e64 v194, 0, 32, s[6:7]
	v_ldexp_f32 v193, v193, v194
	v_mul_f32_e32 v194, v55, v136
	v_mul_f32_e32 v194, 0xbfb8aa3b, v194
	v_exp_f32_e32 v194, v194
	v_log_f32_e32 v193, v193
	v_add_f32_e32 v194, 1.0, v194
	v_rcp_f32_e32 v194, v194
	v_mul_f32_e32 v195, 0x3f317217, v193
	v_fma_f32 v195, v193, s95, -v195
	v_fmac_f32_e32 v195, 0x3377d1cf, v193
	v_fma_f32 v194, v186, v194, v158
	v_cmp_gt_f32_e32 vcc, s90, v194
	v_fmac_f32_e32 v195, 0x3f317217, v193
	v_cmp_lt_f32_e64 s[8:9], |v193|, s96
	v_cndmask_b32_e64 v198, 0, 32, vcc
	v_ldexp_f32 v194, v194, v198
	v_mul_f32_e32 v198, v48, v136
	v_log_f32_e32 v194, v194
	v_mul_f32_e32 v198, 0xbfb8aa3b, v198
	v_exp_f32_e32 v198, v198
	v_cndmask_b32_e64 v193, v193, v195, s[8:9]
	v_cndmask_b32_e64 v195, 0, v171, s[6:7]
	v_sub_f32_e32 v193, v193, v195
	v_mul_f32_e32 v195, 0x3f317217, v194
	v_fma_f32 v195, v194, s95, -v195
	v_add_f32_e32 v198, 1.0, v198
	v_fmac_f32_e32 v195, 0x3377d1cf, v194
	v_rcp_f32_e32 v198, v198
	v_fmac_f32_e32 v195, 0x3f317217, v194
	v_cmp_lt_f32_e64 s[6:7], |v194|, s96
	v_fma_f32 v198, v187, v198, v157
	s_nop 0
	v_cndmask_b32_e64 v194, v194, v195, s[6:7]
	v_cndmask_b32_e32 v195, 0, v171, vcc
	v_sub_f32_e32 v194, v194, v195
	v_cvt_pk_f16_f32 v193, v193, v194
	v_mul_f32_e32 v194, v49, v136
	v_cmp_gt_f32_e32 vcc, s90, v198
	v_mul_f32_e32 v194, 0xbfb8aa3b, v194
	v_exp_f32_e32 v194, v194
	v_cndmask_b32_e64 v199, 0, 32, vcc
	v_ldexp_f32 v198, v198, v199
	v_log_f32_e32 v198, v198
	v_add_f32_e32 v194, 1.0, v194
	v_rcp_f32_e32 v194, v194
	v_cndmask_b32_e32 v195, 0, v171, vcc
	v_mul_f32_e32 v191, 0x3f317217, v198
	v_fma_f32 v191, v198, s95, -v191
	v_fmac_f32_e32 v191, 0x3377d1cf, v198
	v_fmac_f32_e32 v191, 0x3f317217, v198
	v_cmp_lt_f32_e64 s[6:7], |v198|, s96
	v_fma_f32 v194, v182, v194, v156
	v_cmp_gt_f32_e32 vcc, s90, v194
	v_cndmask_b32_e64 v191, v198, v191, s[6:7]
	v_sub_f32_e32 v191, v191, v195
	v_cndmask_b32_e64 v195, 0, 32, vcc
	v_ldexp_f32 v194, v194, v195
	v_mul_f32_e32 v195, v50, v136
	v_mul_f32_e32 v195, 0xbfb8aa3b, v195
	v_exp_f32_e32 v195, v195
	v_log_f32_e32 v194, v194
	v_mul_f32_e32 v136, v51, v136
	v_mul_f32_e32 v136, 0xbfb8aa3b, v136
	v_add_f32_e32 v195, 1.0, v195
	v_rcp_f32_e32 v195, v195
	v_exp_f32_e32 v136, v136
	v_mul_f32_e32 v198, 0x3f317217, v194
	v_fma_f32 v198, v194, s95, -v198
	v_fmac_f32_e32 v198, 0x3377d1cf, v194
	v_fmac_f32_e32 v198, 0x3f317217, v194
	v_cmp_lt_f32_e64 s[6:7], |v194|, s96
	v_fma_f32 v195, v189, v195, v155
	v_add_f32_e32 v136, 1.0, v136
	v_cndmask_b32_e64 v194, v194, v198, s[6:7]
	v_cmp_gt_f32_e64 s[6:7], s90, v195
; __device__ __forceinline__ float fsigm(float x) { return __builtin_amdgcn_rcpf(1.f + __expf(-x)); }
; __device__ __forceinline__ float row_rs(const float* ssq, int row) { return ssq ? rsqrtf(ssq[row] * (1.f / 1024.f) + RMS_EPS) : 1.f; }
;     __device__ __forceinline__ void operator()(const f32x4 (&acc)[2][2][4][2], const Unit& u, int wr, int wc, int fr, int fq) const {
;     ...
;                 for (int m = 0; m < 4; ++m) { const int row = row0 + ai * HALF + m * 16; const float rs = row_rs(ssq, row);
; #pragma unroll
;                     for (int bj = 0; bj < 2; ++bj) { f16x4 o[2];
; #pragma unroll
;                         for (int n = 0; n < 2; ++n) { const f32x4 p = acc[ai][bj][m][n] * rs;
; #pragma unroll
;                             for (int j = 0; j < 4; ++j) { const float l = lb[bj][n][j]; const float f = l + (1.f - l) * fsigm(p[j]); o[n][j] = (_Float16)__logf(f); } }
;                         const u32x2 a0 = __builtin_bit_cast(u32x2, o[0]), a1 = __builtin_bit_cast(u32x2, o[1]); u32x4 w; w.x = a0.x; w.y = a0.y; w.z = a1.x; w.w = a1.y;
;                         *(u32x4*)(LF + (size_t)row * 512 + cbase + bj * HALF) = w; } }
	v_rcp_f32_e32 v136, v136
	s_nop 0
	v_cndmask_b32_e64 v198, 0, 32, s[6:7]
	v_ldexp_f32 v195, v195, v198
	v_log_f32_e32 v195, v195
	v_fma_f32 v136, v190, v136, v154
	v_cndmask_b32_e32 v198, 0, v171, vcc
	v_cmp_gt_f32_e32 vcc, s90, v136
	v_sub_f32_e32 v194, v194, v198
	v_mul_f32_e32 v198, 0x3f317217, v195
	v_cndmask_b32_e64 v199, 0, 32, vcc
	v_ldexp_f32 v136, v136, v199
	v_fma_f32 v198, v195, s95, -v198
	v_log_f32_e32 v136, v136
	v_fmac_f32_e32 v198, 0x3377d1cf, v195
	v_fmac_f32_e32 v198, 0x3f317217, v195
	v_cmp_lt_f32_e64 s[8:9], |v195|, s96
	v_cvt_pk_f16_f32 v194, v191, v194
	s_nop 0
	v_cndmask_b32_e64 v195, v195, v198, s[8:9]
	v_cndmask_b32_e64 v198, 0, v171, s[6:7]
	v_sub_f32_e32 v195, v195, v198
	v_mul_f32_e32 v198, 0x3f317217, v136
	v_fma_f32 v198, v136, s95, -v198
	v_fmac_f32_e32 v198, 0x3377d1cf, v136
	v_fmac_f32_e32 v198, 0x3f317217, v136
	v_cmp_lt_f32_e64 s[6:7], |v136|, s96
	s_nop 1
	v_cndmask_b32_e64 v136, v136, v198, s[6:7]
	v_cndmask_b32_e32 v198, 0, v171, vcc
	v_sub_f32_e32 v136, v136, v198
	v_cvt_pk_f16_f32 v195, v195, v136
	global_store_dwordx4 v[196:197], v[192:195], off offset:256
	v_fmamk_f32 v136, v214, 0x3a800000, v170
	v_rsq_f32_e32 v136, v136
	s_nop 0
	v_mul_f32_e32 v191, v44, v136
	v_mul_f32_e32 v191, 0xbfb8aa3b, v191
	v_exp_f32_e32 v191, v191
	v_mul_f32_e32 v193, v45, v136
	v_mul_f32_e32 v193, 0xbfb8aa3b, v193
	v_exp_f32_e32 v193, v193
	v_add_f32_e32 v191, 1.0, v191
	v_rcp_f32_e32 v191, v191
	v_add_f32_e32 v193, 1.0, v193
	v_rcp_f32_e32 v193, v193
	v_fma_f32 v191, v176, v191, v175
	v_cmp_gt_f32_e32 vcc, s90, v191
	s_nop 1
	v_cndmask_b32_e64 v192, 0, 32, vcc
	v_ldexp_f32 v191, v191, v192
	v_log_f32_e32 v191, v191
	s_nop 0
	v_mul_f32_e32 v192, 0x3f317217, v191
	v_fma_f32 v192, v191, s95, -v192
	v_fmac_f32_e32 v192, 0x3377d1cf, v191
	v_fmac_f32_e32 v192, 0x3f317217, v191
	v_cmp_lt_f32_e64 s[6:7], |v191|, s96
	s_nop 1
	v_cndmask_b32_e64 v191, v191, v192, s[6:7]
	v_cndmask_b32_e32 v192, 0, v171, vcc
	v_sub_f32_e32 v191, v191, v192
	v_fma_f32 v192, v177, v193, v174
	v_cmp_gt_f32_e32 vcc, s90, v192
	s_nop 1
	v_cndmask_b32_e64 v193, 0, 32, vcc
	v_ldexp_f32 v192, v192, v193
	v_mul_f32_e32 v193, v46, v136
	v_mul_f32_e32 v193, 0xbfb8aa3b, v193
	v_exp_f32_e32 v193, v193
	v_log_f32_e32 v192, v192
	v_cndmask_b32_e32 v195, 0, v171, vcc
	v_add_f32_e32 v193, 1.0, v193
	v_rcp_f32_e32 v193, v193
	v_mul_f32_e32 v194, 0x3f317217, v192
	v_fma_f32 v194, v192, s95, -v194
	v_fmac_f32_e32 v194, 0x3377d1cf, v192
	v_fmac_f32_e32 v194, 0x3f317217, v192
	v_cmp_lt_f32_e64 s[6:7], |v192|, s96
	v_fma_f32 v193, v178, v193, v173
	s_nop 0
	v_cndmask_b32_e64 v192, v192, v194, s[6:7]
	v_cmp_gt_f32_e64 s[6:7], s90, v193
	v_sub_f32_e32 v192, v192, v195
	v_cvt_pk_f16_f32 v192, v191, v192
	v_cndmask_b32_e64 v194, 0, 32, s[6:7]
	v_ldexp_f32 v193, v193, v194
	v_mul_f32_e32 v194, v47, v136
	v_mul_f32_e32 v194, 0xbfb8aa3b, v194
	v_exp_f32_e32 v194, v194
	v_log_f32_e32 v193, v193
	v_add_f32_e32 v194, 1.0, v194
	v_rcp_f32_e32 v194, v194
	v_mul_f32_e32 v195, 0x3f317217, v193
	v_fma_f32 v195, v193, s95, -v195
	v_fmac_f32_e32 v195, 0x3377d1cf, v193
	v_fma_f32 v194, v183, v194, v172
	v_cmp_gt_f32_e32 vcc, s90, v194
	v_fmac_f32_e32 v195, 0x3f317217, v193
	v_cmp_lt_f32_e64 s[8:9], |v193|, s96
	v_cndmask_b32_e64 v196, 0, 32, vcc
	v_ldexp_f32 v194, v194, v196
	v_mul_f32_e32 v196, v40, v136
	v_log_f32_e32 v194, v194
	v_mul_f32_e32 v196, 0xbfb8aa3b, v196
	v_exp_f32_e32 v196, v196
	v_cndmask_b32_e64 v193, v193, v195, s[8:9]
	v_cndmask_b32_e64 v195, 0, v171, s[6:7]
	v_sub_f32_e32 v193, v193, v195
	v_mul_f32_e32 v195, 0x3f317217, v194
	v_fma_f32 v195, v194, s95, -v195
	v_add_f32_e32 v196, 1.0, v196
	v_fmac_f32_e32 v195, 0x3377d1cf, v194
	v_rcp_f32_e32 v196, v196
	v_fmac_f32_e32 v195, 0x3f317217, v194
	v_cmp_lt_f32_e64 s[6:7], |v194|, s96
	v_fma_f32 v196, v149, v196, v165
	s_nop 0
	v_cndmask_b32_e64 v194, v194, v195, s[6:7]
	v_cndmask_b32_e32 v195, 0, v171, vcc
	v_sub_f32_e32 v194, v194, v195
	v_cvt_pk_f16_f32 v193, v193, v194
	v_mul_f32_e32 v194, v41, v136
	v_cmp_gt_f32_e32 vcc, s90, v196
	v_mul_f32_e32 v194, 0xbfb8aa3b, v194
	v_exp_f32_e32 v194, v194
	v_cndmask_b32_e64 v197, 0, 32, vcc
	v_ldexp_f32 v196, v196, v197
	v_log_f32_e32 v196, v196
	v_add_f32_e32 v194, 1.0, v194
	v_rcp_f32_e32 v194, v194
	v_cndmask_b32_e32 v195, 0, v171, vcc
	v_mul_f32_e32 v191, 0x3f317217, v196
	v_fma_f32 v191, v196, s95, -v191
	v_fmac_f32_e32 v191, 0x3377d1cf, v196
	v_fmac_f32_e32 v191, 0x3f317217, v196
	v_cmp_lt_f32_e64 s[6:7], |v196|, s96
	v_fma_f32 v194, v179, v194, v164
	v_cmp_gt_f32_e32 vcc, s90, v194
	v_cndmask_b32_e64 v191, v196, v191, s[6:7]
	v_sub_f32_e32 v191, v191, v195
	v_cndmask_b32_e64 v195, 0, 32, vcc
	v_ldexp_f32 v194, v194, v195
	v_mul_f32_e32 v195, v42, v136
	v_mul_f32_e32 v195, 0xbfb8aa3b, v195
	v_exp_f32_e32 v195, v195
	v_log_f32_e32 v194, v194
	v_cndmask_b32_e32 v197, 0, v171, vcc
	v_add_f32_e32 v195, 1.0, v195
	v_rcp_f32_e32 v195, v195
	v_mul_f32_e32 v196, 0x3f317217, v194
	v_fma_f32 v196, v194, s95, -v196
	v_fmac_f32_e32 v196, 0x3377d1cf, v194
	v_fmac_f32_e32 v196, 0x3f317217, v194
	v_cmp_lt_f32_e64 s[6:7], |v194|, s96
	v_fma_f32 v195, v180, v195, v163
	s_nop 0
	v_cndmask_b32_e64 v194, v194, v196, s[6:7]
	v_cmp_gt_f32_e64 s[6:7], s90, v195
	v_sub_f32_e32 v194, v194, v197
	v_cvt_pk_f16_f32 v194, v191, v194
	v_cndmask_b32_e64 v196, 0, 32, s[6:7]
	v_ldexp_f32 v195, v195, v196
	v_mul_f32_e32 v196, v43, v136
	v_mul_f32_e32 v196, 0xbfb8aa3b, v196
	v_exp_f32_e32 v196, v196
	v_log_f32_e32 v195, v195
	v_add_f32_e32 v196, 1.0, v196
	v_rcp_f32_e32 v196, v196
	v_mul_f32_e32 v197, 0x3f317217, v195
	v_fma_f32 v197, v195, s95, -v197
	v_fmac_f32_e32 v197, 0x3377d1cf, v195
; __device__ __forceinline__ float fsigm(float x) { return __builtin_amdgcn_rcpf(1.f + __expf(-x)); }
; __device__ __forceinline__ float row_rs(const float* ssq, int row) { return ssq ? rsqrtf(ssq[row] * (1.f / 1024.f) + RMS_EPS) : 1.f; }
;     __device__ __forceinline__ void operator()(const f32x4 (&acc)[2][2][4][2], const Unit& u, int wr, int wc, int fr, int fq) const {
;     ...
;                 for (int m = 0; m < 4; ++m) { const int row = row0 + ai * HALF + m * 16; const float rs = row_rs(ssq, row);
; #pragma unroll
;                     for (int bj = 0; bj < 2; ++bj) { f16x4 o[2];
; #pragma unroll
;                         for (int n = 0; n < 2; ++n) { const f32x4 p = acc[ai][bj][m][n] * rs;
; #pragma unroll
;                             for (int j = 0; j < 4; ++j) { const float l = lb[bj][n][j]; const float f = l + (1.f - l) * fsigm(p[j]); o[n][j] = (_Float16)__logf(f); } }
;                         const u32x2 a0 = __builtin_bit_cast(u32x2, o[0]), a1 = __builtin_bit_cast(u32x2, o[1]); u32x4 w; w.x = a0.x; w.y = a0.y; w.z = a1.x; w.w = a1.y;
;                         *(u32x4*)(LF + (size_t)row * 512 + cbase + bj * HALF) = w; } }
	v_fma_f32 v196, v188, v196, v162
	v_cmp_gt_f32_e32 vcc, s90, v196
	v_fmac_f32_e32 v197, 0x3f317217, v195
	v_cmp_lt_f32_e64 s[8:9], |v195|, s96
	v_cndmask_b32_e64 v198, 0, 32, vcc
	v_ldexp_f32 v196, v196, v198
	v_log_f32_e32 v196, v196
	v_cndmask_b32_e64 v195, v195, v197, s[8:9]
	v_cndmask_b32_e64 v197, 0, v171, s[6:7]
	v_mul_f32_e32 v198, v36, v136
	v_sub_f32_e32 v195, v195, v197
	v_mul_f32_e32 v197, 0x3f317217, v196
	v_mul_f32_e32 v198, 0xbfb8aa3b, v198
	v_fma_f32 v197, v196, s95, -v197
	v_exp_f32_e32 v198, v198
	v_fmac_f32_e32 v197, 0x3377d1cf, v196
	v_fmac_f32_e32 v197, 0x3f317217, v196
	v_cmp_lt_f32_e64 s[6:7], |v196|, s96
	s_nop 1
	v_cndmask_b32_e64 v196, v196, v197, s[6:7]
	v_cndmask_b32_e32 v197, 0, v171, vcc
	v_sub_f32_e32 v196, v196, v197
	v_add_f32_e32 v197, 1.0, v198
	v_rcp_f32_e32 v198, v197
	v_cvt_pk_f16_f32 v195, v195, v196
	v_lshl_add_u64 v[196:197], v[152:153], 0, s[40:41]
	v_fma_f32 v191, v184, v198, v161
	v_cmp_gt_f32_e32 vcc, s90, v191
	s_nop 1
	v_cndmask_b32_e64 v198, 0, 32, vcc
	v_ldexp_f32 v191, v191, v198
	v_add_co_u32_e64 v198, s[6:7], s92, v152
	v_log_f32_e32 v191, v191
	s_nop 0
	v_addc_co_u32_e64 v199, s[6:7], 0, v153, s[6:7]
	global_store_dwordx4 v[198:199], v[192:195], off
	v_cmp_lt_f32_e64 s[6:7], |v191|, s96
	s_nop 0
	v_mul_f32_e32 v193, v37, v136
	v_mul_f32_e32 v193, 0xbfb8aa3b, v193
	v_exp_f32_e32 v193, v193
	v_mul_f32_e32 v192, 0x3f317217, v191
	v_fma_f32 v192, v191, s95, -v192
	v_fmac_f32_e32 v192, 0x3377d1cf, v191
	v_add_f32_e32 v193, 1.0, v193
	v_rcp_f32_e32 v193, v193
	v_fmac_f32_e32 v192, 0x3f317217, v191
	v_cndmask_b32_e64 v191, v191, v192, s[6:7]
	v_cndmask_b32_e32 v192, 0, v171, vcc
	v_sub_f32_e32 v191, v191, v192
	v_fma_f32 v192, v181, v193, v160
	v_cmp_gt_f32_e32 vcc, s90, v192
	s_nop 1
	v_cndmask_b32_e64 v193, 0, 32, vcc
	v_ldexp_f32 v192, v192, v193
	v_mul_f32_e32 v193, v38, v136
	v_mul_f32_e32 v193, 0xbfb8aa3b, v193
	v_exp_f32_e32 v193, v193
	v_log_f32_e32 v192, v192
	v_cndmask_b32_e32 v195, 0, v171, vcc
	v_add_f32_e32 v193, 1.0, v193
	v_rcp_f32_e32 v193, v193
	v_mul_f32_e32 v194, 0x3f317217, v192
	v_fma_f32 v194, v192, s95, -v194
	v_fmac_f32_e32 v194, 0x3377d1cf, v192
	v_fmac_f32_e32 v194, 0x3f317217, v192
	v_cmp_lt_f32_e64 s[6:7], |v192|, s96
	v_fma_f32 v193, v185, v193, v159
	s_nop 0
	v_cndmask_b32_e64 v192, v192, v194, s[6:7]
	v_cmp_gt_f32_e64 s[6:7], s90, v193
	v_sub_f32_e32 v192, v192, v195
	v_cvt_pk_f16_f32 v192, v191, v192
	v_cndmask_b32_e64 v194, 0, 32, s[6:7]
	v_ldexp_f32 v193, v193, v194
	v_mul_f32_e32 v194, v39, v136
	v_mul_f32_e32 v194, 0xbfb8aa3b, v194
	v_exp_f32_e32 v194, v194
	v_log_f32_e32 v193, v193
	v_add_f32_e32 v194, 1.0, v194
	v_rcp_f32_e32 v194, v194
	v_mul_f32_e32 v195, 0x3f317217, v193
	v_fma_f32 v195, v193, s95, -v195
	v_fmac_f32_e32 v195, 0x3377d1cf, v193
	v_fma_f32 v194, v186, v194, v158
	v_cmp_gt_f32_e32 vcc, s90, v194
	v_fmac_f32_e32 v195, 0x3f317217, v193
	v_cmp_lt_f32_e64 s[8:9], |v193|, s96
	v_cndmask_b32_e64 v198, 0, 32, vcc
	v_ldexp_f32 v194, v194, v198
	v_mul_f32_e32 v198, v32, v136
	v_log_f32_e32 v194, v194
	v_mul_f32_e32 v198, 0xbfb8aa3b, v198
	v_exp_f32_e32 v198, v198
	v_cndmask_b32_e64 v193, v193, v195, s[8:9]
	v_cndmask_b32_e64 v195, 0, v171, s[6:7]
	v_sub_f32_e32 v193, v193, v195
	v_mul_f32_e32 v195, 0x3f317217, v194
	v_fma_f32 v195, v194, s95, -v195
	v_add_f32_e32 v198, 1.0, v198
	v_fmac_f32_e32 v195, 0x3377d1cf, v194
	v_rcp_f32_e32 v198, v198
	v_fmac_f32_e32 v195, 0x3f317217, v194
	v_cmp_lt_f32_e64 s[6:7], |v194|, s96
	v_fma_f32 v198, v187, v198, v157
	s_nop 0
	v_cndmask_b32_e64 v194, v194, v195, s[6:7]
	v_cndmask_b32_e32 v195, 0, v171, vcc
	v_sub_f32_e32 v194, v194, v195
	v_cvt_pk_f16_f32 v193, v193, v194
	v_mul_f32_e32 v194, v33, v136
	v_cmp_gt_f32_e32 vcc, s90, v198
	v_mul_f32_e32 v194, 0xbfb8aa3b, v194
	v_exp_f32_e32 v194, v194
	v_cndmask_b32_e64 v199, 0, 32, vcc
	v_ldexp_f32 v198, v198, v199
	v_log_f32_e32 v198, v198
	v_add_f32_e32 v194, 1.0, v194
	v_rcp_f32_e32 v194, v194
	v_cndmask_b32_e32 v195, 0, v171, vcc
	v_mul_f32_e32 v191, 0x3f317217, v198
	v_fma_f32 v191, v198, s95, -v191
	v_fmac_f32_e32 v191, 0x3377d1cf, v198
	v_fmac_f32_e32 v191, 0x3f317217, v198
	v_cmp_lt_f32_e64 s[6:7], |v198|, s96
	v_fma_f32 v194, v182, v194, v156
	v_cmp_gt_f32_e32 vcc, s90, v194
	v_cndmask_b32_e64 v191, v198, v191, s[6:7]
	v_sub_f32_e32 v191, v191, v195
	v_cndmask_b32_e64 v195, 0, 32, vcc
	v_ldexp_f32 v194, v194, v195
	v_mul_f32_e32 v195, v34, v136
	v_mul_f32_e32 v195, 0xbfb8aa3b, v195
	v_exp_f32_e32 v195, v195
	v_log_f32_e32 v194, v194
	v_mul_f32_e32 v136, v35, v136
	v_mul_f32_e32 v136, 0xbfb8aa3b, v136
	v_add_f32_e32 v195, 1.0, v195
	v_rcp_f32_e32 v195, v195
	v_exp_f32_e32 v136, v136
	v_mul_f32_e32 v198, 0x3f317217, v194
	v_fma_f32 v198, v194, s95, -v198
	v_fmac_f32_e32 v198, 0x3377d1cf, v194
	v_fmac_f32_e32 v198, 0x3f317217, v194
	v_cmp_lt_f32_e64 s[6:7], |v194|, s96
	v_fma_f32 v195, v189, v195, v155
	v_add_f32_e32 v136, 1.0, v136
	v_cndmask_b32_e64 v194, v194, v198, s[6:7]
	v_cmp_gt_f32_e64 s[6:7], s90, v195
	v_rcp_f32_e32 v136, v136
	s_nop 0
	v_cndmask_b32_e64 v198, 0, 32, s[6:7]
	v_ldexp_f32 v195, v195, v198
	v_log_f32_e32 v195, v195
	v_fma_f32 v136, v190, v136, v154
	v_cndmask_b32_e32 v198, 0, v171, vcc
	v_cmp_gt_f32_e32 vcc, s90, v136
	v_sub_f32_e32 v194, v194, v198
	v_mul_f32_e32 v198, 0x3f317217, v195
	v_cndmask_b32_e64 v199, 0, 32, vcc
	v_ldexp_f32 v136, v136, v199
	v_fma_f32 v198, v195, s95, -v198
	v_log_f32_e32 v136, v136
	v_fmac_f32_e32 v198, 0x3377d1cf, v195
	v_fmac_f32_e32 v198, 0x3f317217, v195
	v_cmp_lt_f32_e64 s[8:9], |v195|, s96
	v_cvt_pk_f16_f32 v194, v191, v194
	s_nop 0
	v_cndmask_b32_e64 v195, v195, v198, s[8:9]
	v_cndmask_b32_e64 v198, 0, v171, s[6:7]
; __device__ __forceinline__ float fsigm(float x) { return __builtin_amdgcn_rcpf(1.f + __expf(-x)); }
; __device__ __forceinline__ float row_rs(const float* ssq, int row) { return ssq ? rsqrtf(ssq[row] * (1.f / 1024.f) + RMS_EPS) : 1.f; }
;     __device__ __forceinline__ void operator()(const f32x4 (&acc)[2][2][4][2], const Unit& u, int wr, int wc, int fr, int fq) const {
;     ...
;                 for (int m = 0; m < 4; ++m) { const int row = row0 + ai * HALF + m * 16; const float rs = row_rs(ssq, row);
; #pragma unroll
;                     for (int bj = 0; bj < 2; ++bj) { f16x4 o[2];
; #pragma unroll
;                         for (int n = 0; n < 2; ++n) { const f32x4 p = acc[ai][bj][m][n] * rs;
; #pragma unroll
;                             for (int j = 0; j < 4; ++j) { const float l = lb[bj][n][j]; const float f = l + (1.f - l) * fsigm(p[j]); o[n][j] = (_Float16)__logf(f); } }
;                         const u32x2 a0 = __builtin_bit_cast(u32x2, o[0]), a1 = __builtin_bit_cast(u32x2, o[1]); u32x4 w; w.x = a0.x; w.y = a0.y; w.z = a1.x; w.w = a1.y;
;                         *(u32x4*)(LF + (size_t)row * 512 + cbase + bj * HALF) = w; } }
	v_sub_f32_e32 v195, v195, v198
	v_mul_f32_e32 v198, 0x3f317217, v136
	v_fma_f32 v198, v136, s95, -v198
	v_fmac_f32_e32 v198, 0x3377d1cf, v136
	v_fmac_f32_e32 v198, 0x3f317217, v136
	v_cmp_lt_f32_e64 s[6:7], |v136|, s96
	s_nop 1
	v_cndmask_b32_e64 v136, v136, v198, s[6:7]
	v_cndmask_b32_e32 v198, 0, v171, vcc
	v_sub_f32_e32 v136, v136, v198
	v_cvt_pk_f16_f32 v195, v195, v136
	global_store_dwordx4 v[196:197], v[192:195], off offset:256
	v_fmamk_f32 v136, v215, 0x3a800000, v170
	v_rsq_f32_e32 v136, v136
	s_nop 0
	v_mul_f32_e32 v191, v28, v136
	v_mul_f32_e32 v191, 0xbfb8aa3b, v191
	v_exp_f32_e32 v191, v191
	v_mul_f32_e32 v193, v29, v136
	v_mul_f32_e32 v193, 0xbfb8aa3b, v193
	v_exp_f32_e32 v193, v193
	v_add_f32_e32 v191, 1.0, v191
	v_rcp_f32_e32 v191, v191
	v_add_f32_e32 v193, 1.0, v193
	v_rcp_f32_e32 v193, v193
	v_fma_f32 v191, v176, v191, v175
	v_cmp_gt_f32_e32 vcc, s90, v191
	s_nop 1
	v_cndmask_b32_e64 v192, 0, 32, vcc
	v_ldexp_f32 v191, v191, v192
	v_log_f32_e32 v191, v191
	s_nop 0
	v_mul_f32_e32 v192, 0x3f317217, v191
	v_fma_f32 v192, v191, s95, -v192
	v_fmac_f32_e32 v192, 0x3377d1cf, v191
	v_fmac_f32_e32 v192, 0x3f317217, v191
	v_cmp_lt_f32_e64 s[6:7], |v191|, s96
	s_nop 1
	v_cndmask_b32_e64 v191, v191, v192, s[6:7]
	v_cndmask_b32_e32 v192, 0, v171, vcc
	v_sub_f32_e32 v191, v191, v192
	v_fma_f32 v192, v177, v193, v174
	v_cmp_gt_f32_e32 vcc, s90, v192
	s_nop 1
	v_cndmask_b32_e64 v193, 0, 32, vcc
	v_ldexp_f32 v192, v192, v193
	v_mul_f32_e32 v193, v30, v136
	v_mul_f32_e32 v193, 0xbfb8aa3b, v193
	v_exp_f32_e32 v193, v193
	v_log_f32_e32 v192, v192
	v_cndmask_b32_e32 v195, 0, v171, vcc
	v_add_f32_e32 v193, 1.0, v193
	v_rcp_f32_e32 v193, v193
	v_mul_f32_e32 v194, 0x3f317217, v192
	v_fma_f32 v194, v192, s95, -v194
	v_fmac_f32_e32 v194, 0x3377d1cf, v192
	v_fmac_f32_e32 v194, 0x3f317217, v192
	v_cmp_lt_f32_e64 s[6:7], |v192|, s96
	v_fma_f32 v193, v178, v193, v173
	s_nop 0
	v_cndmask_b32_e64 v192, v192, v194, s[6:7]
	v_cmp_gt_f32_e64 s[6:7], s90, v193
	v_sub_f32_e32 v192, v192, v195
	v_cvt_pk_f16_f32 v192, v191, v192
	v_cndmask_b32_e64 v194, 0, 32, s[6:7]
	v_ldexp_f32 v193, v193, v194
	v_mul_f32_e32 v194, v31, v136
	v_mul_f32_e32 v194, 0xbfb8aa3b, v194
	v_exp_f32_e32 v194, v194
	v_log_f32_e32 v193, v193
	v_add_f32_e32 v194, 1.0, v194
	v_rcp_f32_e32 v194, v194
	v_mul_f32_e32 v195, 0x3f317217, v193
	v_fma_f32 v195, v193, s95, -v195
	v_fmac_f32_e32 v195, 0x3377d1cf, v193
	v_fma_f32 v194, v183, v194, v172
	v_cmp_gt_f32_e32 vcc, s90, v194
	v_fmac_f32_e32 v195, 0x3f317217, v193
	v_cmp_lt_f32_e64 s[8:9], |v193|, s96
	v_cndmask_b32_e64 v196, 0, 32, vcc
	v_ldexp_f32 v194, v194, v196
	v_mul_f32_e32 v196, v24, v136
	v_log_f32_e32 v194, v194
	v_mul_f32_e32 v196, 0xbfb8aa3b, v196
	v_exp_f32_e32 v196, v196
	v_cndmask_b32_e64 v193, v193, v195, s[8:9]
	v_cndmask_b32_e64 v195, 0, v171, s[6:7]
	v_sub_f32_e32 v193, v193, v195
	v_mul_f32_e32 v195, 0x3f317217, v194
	v_fma_f32 v195, v194, s95, -v195
	v_add_f32_e32 v196, 1.0, v196
	v_fmac_f32_e32 v195, 0x3377d1cf, v194
	v_rcp_f32_e32 v196, v196
	v_fmac_f32_e32 v195, 0x3f317217, v194
	v_cmp_lt_f32_e64 s[6:7], |v194|, s96
	v_fma_f32 v196, v149, v196, v165
	s_nop 0
	v_cndmask_b32_e64 v194, v194, v195, s[6:7]
	v_cndmask_b32_e32 v195, 0, v171, vcc
	v_sub_f32_e32 v194, v194, v195
	v_cvt_pk_f16_f32 v193, v193, v194
	v_mul_f32_e32 v194, v25, v136
	v_cmp_gt_f32_e32 vcc, s90, v196
	v_mul_f32_e32 v194, 0xbfb8aa3b, v194
	v_exp_f32_e32 v194, v194
	v_cndmask_b32_e64 v197, 0, 32, vcc
	v_ldexp_f32 v196, v196, v197
	v_log_f32_e32 v196, v196
	v_add_f32_e32 v194, 1.0, v194
	v_rcp_f32_e32 v194, v194
	v_cndmask_b32_e32 v195, 0, v171, vcc
	v_mul_f32_e32 v191, 0x3f317217, v196
	v_fma_f32 v191, v196, s95, -v191
	v_fmac_f32_e32 v191, 0x3377d1cf, v196
	v_fmac_f32_e32 v191, 0x3f317217, v196
	v_cmp_lt_f32_e64 s[6:7], |v196|, s96
	v_fma_f32 v194, v179, v194, v164
	v_cmp_gt_f32_e32 vcc, s90, v194
	v_cndmask_b32_e64 v191, v196, v191, s[6:7]
	v_sub_f32_e32 v191, v191, v195
	v_cndmask_b32_e64 v195, 0, 32, vcc
	v_ldexp_f32 v194, v194, v195
	v_mul_f32_e32 v195, v26, v136
	v_mul_f32_e32 v195, 0xbfb8aa3b, v195
	v_exp_f32_e32 v195, v195
	v_log_f32_e32 v194, v194
	v_cndmask_b32_e32 v197, 0, v171, vcc
	v_add_f32_e32 v195, 1.0, v195
	v_rcp_f32_e32 v195, v195
	v_mul_f32_e32 v196, 0x3f317217, v194
	v_fma_f32 v196, v194, s95, -v196
	v_fmac_f32_e32 v196, 0x3377d1cf, v194
	v_fmac_f32_e32 v196, 0x3f317217, v194
	v_cmp_lt_f32_e64 s[6:7], |v194|, s96
	v_fma_f32 v195, v180, v195, v163
	s_nop 0
	v_cndmask_b32_e64 v194, v194, v196, s[6:7]
	v_cmp_gt_f32_e64 s[6:7], s90, v195
	v_sub_f32_e32 v194, v194, v197
	v_cvt_pk_f16_f32 v194, v191, v194
	v_cndmask_b32_e64 v196, 0, 32, s[6:7]
	v_ldexp_f32 v195, v195, v196
	v_mul_f32_e32 v196, v27, v136
	v_mul_f32_e32 v196, 0xbfb8aa3b, v196
	v_exp_f32_e32 v196, v196
	v_log_f32_e32 v195, v195
	v_add_f32_e32 v196, 1.0, v196
	v_rcp_f32_e32 v196, v196
	v_mul_f32_e32 v197, 0x3f317217, v195
	v_fma_f32 v197, v195, s95, -v197
	v_fmac_f32_e32 v197, 0x3377d1cf, v195
	v_fma_f32 v196, v188, v196, v162
	v_cmp_gt_f32_e32 vcc, s90, v196
	v_fmac_f32_e32 v197, 0x3f317217, v195
	v_cmp_lt_f32_e64 s[8:9], |v195|, s96
	v_cndmask_b32_e64 v198, 0, 32, vcc
	v_ldexp_f32 v196, v196, v198
	v_log_f32_e32 v196, v196
	v_cndmask_b32_e64 v195, v195, v197, s[8:9]
	v_cndmask_b32_e64 v197, 0, v171, s[6:7]
	v_mul_f32_e32 v198, v20, v136
	v_sub_f32_e32 v195, v195, v197
	v_mul_f32_e32 v197, 0x3f317217, v196
	v_mul_f32_e32 v198, 0xbfb8aa3b, v198
	v_fma_f32 v197, v196, s95, -v197
	v_exp_f32_e32 v198, v198
	v_fmac_f32_e32 v197, 0x3377d1cf, v196
	v_fmac_f32_e32 v197, 0x3f317217, v196
	v_cmp_lt_f32_e64 s[6:7], |v196|, s96
	s_nop 1
	v_cndmask_b32_e64 v196, v196, v197, s[6:7]
; __device__ __forceinline__ float fsigm(float x) { return __builtin_amdgcn_rcpf(1.f + __expf(-x)); }
; __device__ __forceinline__ float row_rs(const float* ssq, int row) { return ssq ? rsqrtf(ssq[row] * (1.f / 1024.f) + RMS_EPS) : 1.f; }
;     __device__ __forceinline__ void operator()(const f32x4 (&acc)[2][2][4][2], const Unit& u, int wr, int wc, int fr, int fq) const {
;     ...
;                 for (int m = 0; m < 4; ++m) { const int row = row0 + ai * HALF + m * 16; const float rs = row_rs(ssq, row);
; #pragma unroll
;                     for (int bj = 0; bj < 2; ++bj) { f16x4 o[2];
; #pragma unroll
;                         for (int n = 0; n < 2; ++n) { const f32x4 p = acc[ai][bj][m][n] * rs;
; #pragma unroll
;                             for (int j = 0; j < 4; ++j) { const float l = lb[bj][n][j]; const float f = l + (1.f - l) * fsigm(p[j]); o[n][j] = (_Float16)__logf(f); } }
;                         const u32x2 a0 = __builtin_bit_cast(u32x2, o[0]), a1 = __builtin_bit_cast(u32x2, o[1]); u32x4 w; w.x = a0.x; w.y = a0.y; w.z = a1.x; w.w = a1.y;
;                         *(u32x4*)(LF + (size_t)row * 512 + cbase + bj * HALF) = w; } }
	v_cndmask_b32_e32 v197, 0, v171, vcc
	v_sub_f32_e32 v196, v196, v197
	v_add_f32_e32 v197, 1.0, v198
	v_rcp_f32_e32 v198, v197
	v_cvt_pk_f16_f32 v195, v195, v196
	v_lshl_add_u64 v[196:197], v[152:153], 0, s[42:43]
	v_fma_f32 v191, v184, v198, v161
	v_cmp_gt_f32_e32 vcc, s90, v191
	s_nop 1
	v_cndmask_b32_e64 v198, 0, 32, vcc
	v_ldexp_f32 v191, v191, v198
	v_add_co_u32_e64 v198, s[6:7], s93, v152
	v_log_f32_e32 v191, v191
	s_nop 0
	v_addc_co_u32_e64 v199, s[6:7], 0, v153, s[6:7]
	global_store_dwordx4 v[198:199], v[192:195], off
	v_cmp_lt_f32_e64 s[6:7], |v191|, s96
	s_nop 0
	v_mul_f32_e32 v193, v21, v136
	v_mul_f32_e32 v193, 0xbfb8aa3b, v193
	v_exp_f32_e32 v193, v193
	v_mul_f32_e32 v192, 0x3f317217, v191
	v_fma_f32 v192, v191, s95, -v192
	v_fmac_f32_e32 v192, 0x3377d1cf, v191
	v_add_f32_e32 v193, 1.0, v193
	v_rcp_f32_e32 v193, v193
	v_fmac_f32_e32 v192, 0x3f317217, v191
	v_cndmask_b32_e64 v191, v191, v192, s[6:7]
	v_cndmask_b32_e32 v192, 0, v171, vcc
	v_sub_f32_e32 v191, v191, v192
	v_fma_f32 v192, v181, v193, v160
	v_cmp_gt_f32_e32 vcc, s90, v192
	s_nop 1
	v_cndmask_b32_e64 v193, 0, 32, vcc
	v_ldexp_f32 v192, v192, v193
	v_mul_f32_e32 v193, v22, v136
	v_mul_f32_e32 v193, 0xbfb8aa3b, v193
	v_exp_f32_e32 v193, v193
	v_log_f32_e32 v192, v192
	v_cndmask_b32_e32 v195, 0, v171, vcc
	v_add_f32_e32 v193, 1.0, v193
	v_rcp_f32_e32 v193, v193
	v_mul_f32_e32 v194, 0x3f317217, v192
	v_fma_f32 v194, v192, s95, -v194
	v_fmac_f32_e32 v194, 0x3377d1cf, v192
	v_fmac_f32_e32 v194, 0x3f317217, v192
	v_cmp_lt_f32_e64 s[6:7], |v192|, s96
	v_fma_f32 v193, v185, v193, v159
	s_nop 0
	v_cndmask_b32_e64 v192, v192, v194, s[6:7]
	v_cmp_gt_f32_e64 s[6:7], s90, v193
	v_sub_f32_e32 v192, v192, v195
	v_cvt_pk_f16_f32 v192, v191, v192
	v_cndmask_b32_e64 v194, 0, 32, s[6:7]
	v_ldexp_f32 v193, v193, v194
	v_mul_f32_e32 v194, v23, v136
	v_mul_f32_e32 v194, 0xbfb8aa3b, v194
	v_exp_f32_e32 v194, v194
	v_log_f32_e32 v193, v193
	v_add_f32_e32 v194, 1.0, v194
	v_rcp_f32_e32 v194, v194
	v_mul_f32_e32 v195, 0x3f317217, v193
	v_fma_f32 v195, v193, s95, -v195
	v_fmac_f32_e32 v195, 0x3377d1cf, v193
	v_fma_f32 v194, v186, v194, v158
	v_cmp_gt_f32_e32 vcc, s90, v194
	v_fmac_f32_e32 v195, 0x3f317217, v193
	v_cmp_lt_f32_e64 s[8:9], |v193|, s96
	v_cndmask_b32_e64 v198, 0, 32, vcc
	v_ldexp_f32 v194, v194, v198
	v_mul_f32_e32 v198, v16, v136
	v_log_f32_e32 v194, v194
	v_mul_f32_e32 v198, 0xbfb8aa3b, v198
	v_exp_f32_e32 v198, v198
	v_cndmask_b32_e64 v193, v193, v195, s[8:9]
	v_cndmask_b32_e64 v195, 0, v171, s[6:7]
	v_sub_f32_e32 v193, v193, v195
	v_mul_f32_e32 v195, 0x3f317217, v194
	v_fma_f32 v195, v194, s95, -v195
	v_add_f32_e32 v198, 1.0, v198
	v_fmac_f32_e32 v195, 0x3377d1cf, v194
	v_rcp_f32_e32 v198, v198
	v_fmac_f32_e32 v195, 0x3f317217, v194
	v_cmp_lt_f32_e64 s[6:7], |v194|, s96
	v_fma_f32 v198, v187, v198, v157
	s_nop 0
	v_cndmask_b32_e64 v194, v194, v195, s[6:7]
	v_cndmask_b32_e32 v195, 0, v171, vcc
	v_sub_f32_e32 v194, v194, v195
	v_cvt_pk_f16_f32 v193, v193, v194
	v_mul_f32_e32 v194, v17, v136
	v_cmp_gt_f32_e32 vcc, s90, v198
	v_mul_f32_e32 v194, 0xbfb8aa3b, v194
	v_exp_f32_e32 v194, v194
	v_cndmask_b32_e64 v199, 0, 32, vcc
	v_ldexp_f32 v198, v198, v199
	v_log_f32_e32 v198, v198
	v_add_f32_e32 v194, 1.0, v194
	v_rcp_f32_e32 v194, v194
	v_cndmask_b32_e32 v195, 0, v171, vcc
	v_mul_f32_e32 v191, 0x3f317217, v198
	v_fma_f32 v191, v198, s95, -v191
	v_fmac_f32_e32 v191, 0x3377d1cf, v198
	v_fmac_f32_e32 v191, 0x3f317217, v198
	v_cmp_lt_f32_e64 s[6:7], |v198|, s96
	v_fma_f32 v194, v182, v194, v156
	v_cmp_gt_f32_e32 vcc, s90, v194
	v_cndmask_b32_e64 v191, v198, v191, s[6:7]
	v_sub_f32_e32 v191, v191, v195
	v_cndmask_b32_e64 v195, 0, 32, vcc
	v_ldexp_f32 v194, v194, v195
	v_mul_f32_e32 v195, v18, v136
	v_mul_f32_e32 v195, 0xbfb8aa3b, v195
	v_exp_f32_e32 v195, v195
	v_log_f32_e32 v194, v194
	v_mul_f32_e32 v136, v19, v136
	v_mul_f32_e32 v136, 0xbfb8aa3b, v136
	v_add_f32_e32 v195, 1.0, v195
	v_rcp_f32_e32 v195, v195
	v_exp_f32_e32 v136, v136
	v_mul_f32_e32 v198, 0x3f317217, v194
	v_fma_f32 v198, v194, s95, -v198
	v_fmac_f32_e32 v198, 0x3377d1cf, v194
	v_fmac_f32_e32 v198, 0x3f317217, v194
	v_cmp_lt_f32_e64 s[6:7], |v194|, s96
	v_fma_f32 v195, v189, v195, v155
	v_add_f32_e32 v136, 1.0, v136
	v_cndmask_b32_e64 v194, v194, v198, s[6:7]
	v_cmp_gt_f32_e64 s[6:7], s90, v195
	v_rcp_f32_e32 v136, v136
	s_nop 0
	v_cndmask_b32_e64 v198, 0, 32, s[6:7]
	v_ldexp_f32 v195, v195, v198
	v_log_f32_e32 v195, v195
	v_fma_f32 v136, v190, v136, v154
	v_cndmask_b32_e32 v198, 0, v171, vcc
	v_cmp_gt_f32_e32 vcc, s90, v136
	v_sub_f32_e32 v194, v194, v198
	v_mul_f32_e32 v198, 0x3f317217, v195
	v_cndmask_b32_e64 v199, 0, 32, vcc
	v_ldexp_f32 v136, v136, v199
	v_fma_f32 v198, v195, s95, -v198
	v_log_f32_e32 v136, v136
	v_fmac_f32_e32 v198, 0x3377d1cf, v195
	v_fmac_f32_e32 v198, 0x3f317217, v195
	v_cmp_lt_f32_e64 s[8:9], |v195|, s96
	v_cvt_pk_f16_f32 v194, v191, v194
	s_nop 0
	v_cndmask_b32_e64 v195, v195, v198, s[8:9]
	v_cndmask_b32_e64 v198, 0, v171, s[6:7]
	v_sub_f32_e32 v195, v195, v198
	v_mul_f32_e32 v198, 0x3f317217, v136
	v_fma_f32 v198, v136, s95, -v198
	v_fmac_f32_e32 v198, 0x3377d1cf, v136
	v_fmac_f32_e32 v198, 0x3f317217, v136
	v_cmp_lt_f32_e64 s[6:7], |v136|, s96
	s_nop 1
	v_cndmask_b32_e64 v136, v136, v198, s[6:7]
	v_cndmask_b32_e32 v198, 0, v171, vcc
	v_sub_f32_e32 v136, v136, v198
	v_cvt_pk_f16_f32 v195, v195, v136
	global_store_dwordx4 v[196:197], v[192:195], off offset:256
	v_fmamk_f32 v136, v216, 0x3a800000, v170
	v_rsq_f32_e32 v136, v136
	s_nop 0
	v_mul_f32_e32 v150, v12, v136
	v_mul_f32_e32 v150, 0xbfb8aa3b, v150
	v_exp_f32_e32 v150, v150
	s_nop 0
	v_add_f32_e32 v150, 1.0, v150
	v_rcp_f32_e32 v150, v150
; __device__ __forceinline__ float fsigm(float x) { return __builtin_amdgcn_rcpf(1.f + __expf(-x)); }
; __device__ __forceinline__ float row_rs(const float* ssq, int row) { return ssq ? rsqrtf(ssq[row] * (1.f / 1024.f) + RMS_EPS) : 1.f; }
;     __device__ __forceinline__ void operator()(const f32x4 (&acc)[2][2][4][2], const Unit& u, int wr, int wc, int fr, int fq) const {
;     ...
;                 for (int m = 0; m < 4; ++m) { const int row = row0 + ai * HALF + m * 16; const float rs = row_rs(ssq, row);
; #pragma unroll
;                     for (int bj = 0; bj < 2; ++bj) { f16x4 o[2];
; #pragma unroll
;                         for (int n = 0; n < 2; ++n) { const f32x4 p = acc[ai][bj][m][n] * rs;
; #pragma unroll
;                             for (int j = 0; j < 4; ++j) { const float l = lb[bj][n][j]; const float f = l + (1.f - l) * fsigm(p[j]); o[n][j] = (_Float16)__logf(f); } }
;                         const u32x2 a0 = __builtin_bit_cast(u32x2, o[0]), a1 = __builtin_bit_cast(u32x2, o[1]); u32x4 w; w.x = a0.x; w.y = a0.y; w.z = a1.x; w.w = a1.y;
;                         *(u32x4*)(LF + (size_t)row * 512 + cbase + bj * HALF) = w; } }
	s_nop 0
	v_fmac_f32_e32 v175, v176, v150
	v_cmp_gt_f32_e32 vcc, s90, v175
	s_nop 1
	v_cndmask_b32_e64 v150, 0, 32, vcc
	v_ldexp_f32 v150, v175, v150
	v_mul_f32_e32 v175, v13, v136
	v_mul_f32_e32 v175, 0xbfb8aa3b, v175
	v_exp_f32_e32 v175, v175
	v_log_f32_e32 v150, v150
	v_add_f32_e32 v175, 1.0, v175
	v_rcp_f32_e32 v175, v175
	v_mul_f32_e32 v151, 0x3f317217, v150
	v_fma_f32 v151, v150, s95, -v151
	v_fmac_f32_e32 v151, 0x3377d1cf, v150
	v_fmac_f32_e32 v151, 0x3f317217, v150
	v_cmp_lt_f32_e64 s[6:7], |v150|, s96
	v_fmac_f32_e32 v174, v177, v175
	s_nop 0
	v_cndmask_b32_e64 v150, v150, v151, s[6:7]
	v_cndmask_b32_e32 v151, 0, v171, vcc
	v_cmp_gt_f32_e32 vcc, s90, v174
	v_sub_f32_e32 v150, v150, v151
	s_nop 0
	v_cndmask_b32_e64 v151, 0, 32, vcc
	v_ldexp_f32 v151, v174, v151
	v_mul_f32_e32 v174, v14, v136
	v_mul_f32_e32 v174, 0xbfb8aa3b, v174
	v_exp_f32_e32 v174, v174
	v_log_f32_e32 v151, v151
	v_add_f32_e32 v174, 1.0, v174
	v_rcp_f32_e32 v174, v174
	v_mul_f32_e32 v175, 0x3f317217, v151
	v_fma_f32 v175, v151, s95, -v175
	v_fmac_f32_e32 v175, 0x3377d1cf, v151
	v_fmac_f32_e32 v175, 0x3f317217, v151
	v_cmp_lt_f32_e64 s[6:7], |v151|, s96
	v_fmac_f32_e32 v173, v178, v174
	s_nop 0
	v_cndmask_b32_e64 v151, v151, v175, s[6:7]
	v_cmp_gt_f32_e64 s[6:7], s90, v173
	v_cndmask_b32_e32 v175, 0, v171, vcc
	v_sub_f32_e32 v151, v151, v175
	v_cndmask_b32_e64 v174, 0, 32, s[6:7]
	v_ldexp_f32 v173, v173, v174
	v_mul_f32_e32 v174, v15, v136
	v_mul_f32_e32 v174, 0xbfb8aa3b, v174
	v_exp_f32_e32 v174, v174
	v_log_f32_e32 v173, v173
	v_add_f32_e32 v174, 1.0, v174
	v_mul_f32_e32 v175, 0x3f317217, v173
	v_rcp_f32_e32 v174, v174
	v_fma_f32 v175, v173, s95, -v175
	v_fmac_f32_e32 v175, 0x3377d1cf, v173
	v_fmac_f32_e32 v175, 0x3f317217, v173
	v_cmp_lt_f32_e64 s[8:9], |v173|, s96
	v_fmac_f32_e32 v172, v183, v174
	v_cmp_gt_f32_e32 vcc, s90, v172
	v_cndmask_b32_e64 v173, v173, v175, s[8:9]
	v_mul_f32_e32 v175, v8, v136
	v_mul_f32_e32 v175, 0xbfb8aa3b, v175
	v_cndmask_b32_e64 v174, 0, 32, vcc
	v_exp_f32_e32 v175, v175
	v_ldexp_f32 v172, v172, v174
	v_log_f32_e32 v172, v172
	v_cndmask_b32_e64 v174, 0, v171, s[6:7]
	v_add_f32_e32 v175, 1.0, v175
	v_rcp_f32_e32 v175, v175
	v_sub_f32_e32 v173, v173, v174
	v_mul_f32_e32 v174, 0x3f317217, v172
	v_fma_f32 v174, v172, s95, -v174
	v_fmac_f32_e32 v174, 0x3377d1cf, v172
	v_fmac_f32_e32 v174, 0x3f317217, v172
	v_cmp_lt_f32_e64 s[6:7], |v172|, s96
	v_fmac_f32_e32 v165, v149, v175
	s_nop 0
	v_cndmask_b32_e64 v172, v172, v174, s[6:7]
	v_cndmask_b32_e32 v174, 0, v171, vcc
	v_cmp_gt_f32_e32 vcc, s90, v165
	s_nop 1
	v_cndmask_b32_e64 v149, 0, 32, vcc
	v_ldexp_f32 v149, v165, v149
	v_sub_f32_e32 v165, v172, v174
	v_cvt_pk_f16_f32 v172, v150, v151
	v_mul_f32_e32 v151, v9, v136
	v_mul_f32_e32 v151, 0xbfb8aa3b, v151
	v_exp_f32_e32 v151, v151
	v_log_f32_e32 v149, v149
	v_cvt_pk_f16_f32 v173, v173, v165
	v_add_f32_e32 v151, 1.0, v151
	v_rcp_f32_e32 v151, v151
	v_mul_f32_e32 v150, 0x3f317217, v149
	v_fma_f32 v150, v149, s95, -v150
	v_fmac_f32_e32 v150, 0x3377d1cf, v149
	v_fmac_f32_e32 v150, 0x3f317217, v149
	v_cmp_lt_f32_e64 s[6:7], |v149|, s96
	v_fmac_f32_e32 v164, v179, v151
	v_mul_f32_e32 v151, v10, v136
	v_cndmask_b32_e64 v149, v149, v150, s[6:7]
	v_cndmask_b32_e32 v150, 0, v171, vcc
	v_cmp_gt_f32_e32 vcc, s90, v164
	v_mul_f32_e32 v151, 0xbfb8aa3b, v151
	v_sub_f32_e32 v149, v149, v150
	v_cndmask_b32_e64 v150, 0, 32, vcc
	v_exp_f32_e32 v151, v151
	v_ldexp_f32 v150, v164, v150
	v_log_f32_e32 v150, v150
	v_add_f32_e32 v151, 1.0, v151
	v_rcp_f32_e32 v151, v151
	v_mul_f32_e32 v164, 0x3f317217, v150
	v_fma_f32 v164, v150, s95, -v164
	v_fmac_f32_e32 v164, 0x3377d1cf, v150
	v_fmac_f32_e32 v164, 0x3f317217, v150
	v_cmp_lt_f32_e64 s[6:7], |v150|, s96
	v_fmac_f32_e32 v163, v180, v151
	s_nop 0
	v_cndmask_b32_e64 v150, v150, v164, s[6:7]
	v_cmp_gt_f32_e64 s[6:7], s90, v163
	v_cndmask_b32_e32 v164, 0, v171, vcc
	v_sub_f32_e32 v150, v150, v164
	v_cndmask_b32_e64 v151, 0, 32, s[6:7]
	v_ldexp_f32 v151, v163, v151
	v_mul_f32_e32 v163, v11, v136
	v_mul_f32_e32 v163, 0xbfb8aa3b, v163
	v_exp_f32_e32 v163, v163
	v_log_f32_e32 v151, v151
	v_cvt_pk_f16_f32 v174, v149, v150
	v_add_f32_e32 v163, 1.0, v163
	v_rcp_f32_e32 v163, v163
	v_mul_f32_e32 v164, 0x3f317217, v151
	v_fma_f32 v164, v151, s95, -v164
	v_fmac_f32_e32 v164, 0x3377d1cf, v151
	v_fmac_f32_e32 v162, v188, v163
	v_cmp_gt_f32_e32 vcc, s90, v162
	v_fmac_f32_e32 v164, 0x3f317217, v151
	v_cmp_lt_f32_e64 s[8:9], |v151|, s96
	v_cndmask_b32_e64 v163, 0, 32, vcc
	v_ldexp_f32 v162, v162, v163
	v_log_f32_e32 v162, v162
	v_cndmask_b32_e64 v151, v151, v164, s[8:9]
	v_cndmask_b32_e64 v163, 0, v171, s[6:7]
	v_mul_f32_e32 v164, v4, v136
	v_sub_f32_e32 v151, v151, v163
	v_mul_f32_e32 v163, 0x3f317217, v162
	v_mul_f32_e32 v164, 0xbfb8aa3b, v164
	v_fma_f32 v163, v162, s95, -v163
	v_exp_f32_e32 v164, v164
	v_fmac_f32_e32 v163, 0x3377d1cf, v162
	v_fmac_f32_e32 v163, 0x3f317217, v162
	v_cmp_lt_f32_e64 s[6:7], |v162|, s96
	s_nop 1
	v_cndmask_b32_e64 v162, v162, v163, s[6:7]
	v_cndmask_b32_e32 v163, 0, v171, vcc
	v_sub_f32_e32 v162, v162, v163
	v_add_f32_e32 v163, 1.0, v164
	v_rcp_f32_e32 v164, v163
	v_add_co_u32_e64 v150, s[6:7], s94, v152
; __device__ __forceinline__ float fsigm(float x) { return __builtin_amdgcn_rcpf(1.f + __expf(-x)); }
; __device__ __forceinline__ float row_rs(const float* ssq, int row) { return ssq ? rsqrtf(ssq[row] * (1.f / 1024.f) + RMS_EPS) : 1.f; }
;     __device__ __forceinline__ void operator()(const f32x4 (&acc)[2][2][4][2], const Unit& u, int wr, int wc, int fr, int fq) const {
;     ...
;                 for (int m = 0; m < 4; ++m) { const int row = row0 + ai * HALF + m * 16; const float rs = row_rs(ssq, row);
; #pragma unroll
;                     for (int bj = 0; bj < 2; ++bj) { f16x4 o[2];
; #pragma unroll
;                         for (int n = 0; n < 2; ++n) { const f32x4 p = acc[ai][bj][m][n] * rs;
; #pragma unroll
;                             for (int j = 0; j < 4; ++j) { const float l = lb[bj][n][j]; const float f = l + (1.f - l) * fsigm(p[j]); o[n][j] = (_Float16)__logf(f); } }
;                         const u32x2 a0 = __builtin_bit_cast(u32x2, o[0]), a1 = __builtin_bit_cast(u32x2, o[1]); u32x4 w; w.x = a0.x; w.y = a0.y; w.z = a1.x; w.w = a1.y;
;                         *(u32x4*)(LF + (size_t)row * 512 + cbase + bj * HALF) = w; } }
	v_cvt_pk_f16_f32 v175, v151, v162
	s_nop 0
	v_addc_co_u32_e64 v151, s[6:7], 0, v153, s[6:7]
	v_fmac_f32_e32 v161, v184, v164
	global_store_dwordx4 v[150:151], v[172:175], off
	v_mul_f32_e32 v151, v5, v136
	v_cmp_gt_f32_e32 vcc, s90, v161
	v_mul_f32_e32 v151, 0xbfb8aa3b, v151
	v_exp_f32_e32 v151, v151
	v_cndmask_b32_e64 v149, 0, 32, vcc
	v_ldexp_f32 v149, v161, v149
	v_log_f32_e32 v149, v149
	v_add_f32_e32 v151, 1.0, v151
	v_rcp_f32_e32 v151, v151
	v_lshl_add_u64 v[162:163], v[152:153], 0, s[62:63]
	v_mul_f32_e32 v150, 0x3f317217, v149
	v_fma_f32 v150, v149, s95, -v150
	v_fmac_f32_e32 v150, 0x3377d1cf, v149
	v_fmac_f32_e32 v150, 0x3f317217, v149
	v_cmp_lt_f32_e64 s[6:7], |v149|, s96
	v_fmac_f32_e32 v160, v181, v151
	v_mul_f32_e32 v151, v6, v136
	v_cndmask_b32_e64 v149, v149, v150, s[6:7]
	v_cndmask_b32_e32 v150, 0, v171, vcc
	v_cmp_gt_f32_e32 vcc, s90, v160
	v_sub_f32_e32 v149, v149, v150
	v_mul_f32_e32 v151, 0xbfb8aa3b, v151
	v_cndmask_b32_e64 v150, 0, 32, vcc
	v_ldexp_f32 v150, v160, v150
	v_log_f32_e32 v150, v150
	v_exp_f32_e32 v151, v151
	v_cndmask_b32_e32 v153, 0, v171, vcc
	v_mul_f32_e32 v152, 0x3f317217, v150
	v_fma_f32 v152, v150, s95, -v152
	v_fmac_f32_e32 v152, 0x3377d1cf, v150
	v_fmac_f32_e32 v152, 0x3f317217, v150
	v_cmp_lt_f32_e64 s[6:7], |v150|, s96
	v_add_f32_e32 v151, 1.0, v151
	v_rcp_f32_e32 v151, v151
	v_cndmask_b32_e64 v150, v150, v152, s[6:7]
	v_mul_f32_e32 v152, v7, v136
	v_mul_f32_e32 v152, 0xbfb8aa3b, v152
	v_exp_f32_e32 v152, v152
	v_fmac_f32_e32 v159, v185, v151
	v_cmp_gt_f32_e64 s[6:7], s90, v159
	v_sub_f32_e32 v150, v150, v153
	v_add_f32_e32 v152, 1.0, v152
	v_rcp_f32_e32 v152, v152
	v_cndmask_b32_e64 v151, 0, 32, s[6:7]
	v_ldexp_f32 v151, v159, v151
	v_log_f32_e32 v151, v151
	v_fmac_f32_e32 v158, v186, v152
	v_cmp_gt_f32_e32 vcc, s90, v158
	v_cvt_pk_f16_f32 v150, v149, v150
	v_mul_f32_e32 v153, 0x3f317217, v151
	v_cndmask_b32_e64 v152, 0, 32, vcc
	v_ldexp_f32 v152, v158, v152
	v_mul_f32_e32 v158, v0, v136
	v_mul_f32_e32 v158, 0xbfb8aa3b, v158
	v_exp_f32_e32 v158, v158
	v_fma_f32 v153, v151, s95, -v153
	v_log_f32_e32 v152, v152
	v_fmac_f32_e32 v153, 0x3377d1cf, v151
	v_fmac_f32_e32 v153, 0x3f317217, v151
	v_cmp_lt_f32_e64 s[8:9], |v151|, s96
	v_add_f32_e32 v158, 1.0, v158
	v_rcp_f32_e32 v158, v158
	v_cndmask_b32_e64 v151, v151, v153, s[8:9]
	v_cndmask_b32_e64 v153, 0, v171, s[6:7]
	v_sub_f32_e32 v151, v151, v153
	v_mul_f32_e32 v153, 0x3f317217, v152
	v_fma_f32 v153, v152, s95, -v153
	v_fmac_f32_e32 v153, 0x3377d1cf, v152
	v_fmac_f32_e32 v153, 0x3f317217, v152
	v_cmp_lt_f32_e64 s[6:7], |v152|, s96
	v_fmac_f32_e32 v157, v187, v158
	s_nop 0
	v_cndmask_b32_e64 v152, v152, v153, s[6:7]
	v_cndmask_b32_e32 v153, 0, v171, vcc
	v_cmp_gt_f32_e32 vcc, s90, v157
	v_sub_f32_e32 v152, v152, v153
	v_cvt_pk_f16_f32 v151, v151, v152
	v_cndmask_b32_e64 v158, 0, 32, vcc
	v_mul_f32_e32 v152, v1, v136
	v_ldexp_f32 v157, v157, v158
	v_mul_f32_e32 v152, 0xbfb8aa3b, v152
	v_log_f32_e32 v157, v157
	v_exp_f32_e32 v152, v152
	v_cndmask_b32_e32 v153, 0, v171, vcc
	v_mul_f32_e32 v149, 0x3f317217, v157
	v_add_f32_e32 v152, 1.0, v152
	v_fma_f32 v149, v157, s95, -v149
	v_rcp_f32_e32 v152, v152
	v_fmac_f32_e32 v149, 0x3377d1cf, v157
	v_fmac_f32_e32 v149, 0x3f317217, v157
	v_cmp_lt_f32_e64 s[6:7], |v157|, s96
	v_fmac_f32_e32 v156, v182, v152
	v_cmp_gt_f32_e32 vcc, s90, v156
	v_cndmask_b32_e64 v149, v157, v149, s[6:7]
	v_sub_f32_e32 v149, v149, v153
	v_mul_f32_e32 v153, v2, v136
	v_mul_f32_e32 v153, 0xbfb8aa3b, v153
	v_cndmask_b32_e64 v152, 0, 32, vcc
	v_exp_f32_e32 v153, v153
	v_ldexp_f32 v152, v156, v152
	v_log_f32_e32 v152, v152
	v_mul_f32_e32 v136, v3, v136
	v_add_f32_e32 v153, 1.0, v153
	v_mul_f32_e32 v136, 0xbfb8aa3b, v136
	v_rcp_f32_e32 v153, v153
	v_exp_f32_e32 v136, v136
	v_mul_f32_e32 v156, 0x3f317217, v152
	v_fma_f32 v156, v152, s95, -v156
	v_fmac_f32_e32 v156, 0x3377d1cf, v152
	v_fmac_f32_e32 v156, 0x3f317217, v152
	v_cmp_lt_f32_e64 s[6:7], |v152|, s96
	v_fmac_f32_e32 v155, v189, v153
	v_add_f32_e32 v136, 1.0, v136
	v_cndmask_b32_e64 v152, v152, v156, s[6:7]
	v_cmp_gt_f32_e64 s[6:7], s90, v155
	v_rcp_f32_e32 v136, v136
	s_nop 0
	v_cndmask_b32_e64 v153, 0, 32, s[6:7]
	v_ldexp_f32 v153, v155, v153
	v_log_f32_e32 v153, v153
	v_fmac_f32_e32 v154, v190, v136
	v_cndmask_b32_e32 v155, 0, v171, vcc
	v_cmp_gt_f32_e32 vcc, s90, v154
	v_sub_f32_e32 v152, v152, v155
	v_mul_f32_e32 v155, 0x3f317217, v153
	v_cndmask_b32_e64 v136, 0, 32, vcc
	v_ldexp_f32 v136, v154, v136
	v_fma_f32 v155, v153, s95, -v155
	v_log_f32_e32 v136, v136
	v_fmac_f32_e32 v155, 0x3377d1cf, v153
	v_fmac_f32_e32 v155, 0x3f317217, v153
	v_cmp_lt_f32_e64 s[8:9], |v153|, s96
	v_cndmask_b32_e64 v154, 0, v171, s[6:7]
	v_cmp_lt_f32_e64 s[6:7], |v136|, s96
	v_cndmask_b32_e64 v153, v153, v155, s[8:9]
	v_sub_f32_e32 v153, v153, v154
	v_mul_f32_e32 v154, 0x3f317217, v136
	v_fma_f32 v154, v136, s95, -v154
	v_fmac_f32_e32 v154, 0x3377d1cf, v136
	v_fmac_f32_e32 v154, 0x3f317217, v136
	v_cndmask_b32_e64 v136, v136, v154, s[6:7]
	v_cndmask_b32_e32 v154, 0, v171, vcc
	v_sub_f32_e32 v136, v136, v154
	v_cvt_pk_f16_f32 v153, v153, v136
	v_cvt_pk_f16_f32 v152, v149, v152
	global_store_dwordx4 v[162:163], v[150:153], off offset:256

; __device__ __forceinline__ unsigned cvt_pk_bf16(float lo, float hi) { cvf32x2_t v = {lo, hi}; cvbf16x2_t b = __builtin_convertvector(v, cvbf16x2_t); return __builtin_bit_cast(unsigned, b); }
; __device__ __forceinline__ float row_rs(const float* ssq, int row) { return ssq ? rsqrtf(ssq[row] * (1.f / 1024.f) + RMS_EPS) : 1.f; }
;     __device__ __forceinline__ void operator()(const f32x4 (&acc)[2][2][4][2], const Unit& u, int wr, int wc, int fr, int fq) const {
;     ...
;         if (pn >= 10) {
; #pragma unroll
;             for (int ai = 0; ai < 2; ++ai)
; #pragma unroll
;                 for (int m = 0; m < 4; ++m) { const int row = row0 + ai * HALF + m * 16; const float rs = row_rs(ssq, row); const float rs2 = rs * rs;
;                     const f32x4 v0 = acc[ai][0][m][0] * acc[ai][1][m][0] * rs2, v1 = acc[ai][0][m][1] * acc[ai][1][m][1] * rs2; u32x4 w;
;                     w.x = cvt_pk_bf16(v0[0], v0[1]); w.y = cvt_pk_bf16(v0[2], v0[3]); w.z = cvt_pk_bf16(v1[0], v1[1]); w.w = cvt_pk_bf16(v1[2], v1[3]);
.LBB0_648:
	v_ashrrev_i32_e32 v149, 31, v148
	v_lshl_add_u64 v[150:151], v[148:149], 2, s[30:31]
	global_load_dword v152, v[150:151], off
	global_load_dword v210, v[150:151], off offset:64
	global_load_dword v211, v[150:151], off offset:128
	global_load_dword v212, v[150:151], off offset:192
	global_load_dword v213, v[150:151], off offset:512
	global_load_dword v214, v[150:151], off offset:576
	global_load_dword v215, v[150:151], off offset:640
	global_load_dword v216, v[150:151], off offset:704
	v_pk_mul_f32 v[116:117], v[124:125], v[116:117]
	v_pk_mul_f32 v[118:119], v[126:127], v[118:119]
	s_lshl_b32 s6, s18, 7
	v_pk_mul_f32 v[120:121], v[120:121], v[112:113]
	s_add_i32 s18, s6, 0xfffffb00
	v_lshlrev_b64 v[112:113], 10, v[148:149]
	v_pk_mul_f32 v[114:115], v[122:123], v[114:115]
	v_lshl_add_u64 v[112:113], s[28:29], 0, v[112:113]
	s_lshl_b64 s[6:7], s[18:19], 1
	v_lshlrev_b32_e32 v136, 1, v138
	v_or_b32_e32 v122, 16, v148
	v_lshl_add_u64 v[112:113], v[112:113], 0, s[6:7]
	v_ashrrev_i32_e32 v123, 31, v122
	v_lshl_add_u64 v[112:113], v[112:113], 0, v[136:137]
	v_pk_mul_f32 v[102:103], v[110:111], v[102:103]
	v_pk_mul_f32 v[98:99], v[106:107], v[98:99]
	v_lshlrev_b64 v[106:107], 10, v[122:123]
	v_pk_mul_f32 v[100:101], v[108:109], v[100:101]
	v_pk_mul_f32 v[96:97], v[104:105], v[96:97]
	v_lshl_add_u64 v[106:107], s[28:29], 0, v[106:107]
	v_or_b32_e32 v104, 32, v148
	v_lshl_add_u64 v[106:107], v[106:107], 0, s[6:7]
	v_ashrrev_i32_e32 v105, 31, v104
	v_lshl_add_u64 v[106:107], v[106:107], 0, v[136:137]
	v_lshl_add_u64 v[108:109], v[104:105], 2, s[30:31]
	v_pk_mul_f32 v[86:87], v[94:95], v[86:87]
	v_pk_mul_f32 v[82:83], v[90:91], v[82:83]
	v_lshlrev_b64 v[90:91], 10, v[104:105]
	v_pk_mul_f32 v[84:85], v[92:93], v[84:85]
	v_pk_mul_f32 v[80:81], v[88:89], v[80:81]
	v_lshl_add_u64 v[90:91], s[28:29], 0, v[90:91]
	v_or_b32_e32 v88, 48, v148
	v_lshl_add_u64 v[90:91], v[90:91], 0, s[6:7]
	v_ashrrev_i32_e32 v89, 31, v88
	v_lshl_add_u64 v[90:91], v[90:91], 0, v[136:137]
	v_lshl_add_u64 v[92:93], v[88:89], 2, s[30:31]
	v_pk_mul_f32 v[66:67], v[74:75], v[66:67]
	v_pk_mul_f32 v[64:65], v[72:73], v[64:65]
	v_lshlrev_b64 v[72:73], 10, v[88:89]
	v_pk_mul_f32 v[70:71], v[78:79], v[70:71]
	v_pk_mul_f32 v[68:69], v[76:77], v[68:69]
	v_lshl_add_u64 v[72:73], s[28:29], 0, v[72:73]
	v_lshl_add_u64 v[72:73], v[72:73], 0, s[6:7]
	v_lshl_add_u64 v[72:73], v[72:73], 0, v[136:137]
	v_pk_mul_f32 v[48:49], v[56:57], v[48:49]
	v_pk_mul_f32 v[50:51], v[58:59], v[50:51]
	v_pk_mul_f32 v[54:55], v[62:63], v[54:55]
	v_pk_mul_f32 v[52:53], v[60:61], v[52:53]
	v_pk_mul_f32 v[32:33], v[40:41], v[32:33]
	v_pk_mul_f32 v[34:35], v[42:43], v[34:35]
	v_pk_mul_f32 v[38:39], v[46:47], v[38:39]
	v_pk_mul_f32 v[36:37], v[44:45], v[36:37]
	v_pk_mul_f32 v[16:17], v[24:25], v[16:17]
	v_pk_mul_f32 v[18:19], v[26:27], v[18:19]
	v_pk_mul_f32 v[22:23], v[30:31], v[22:23]
	v_pk_mul_f32 v[20:21], v[28:29], v[20:21]
	v_pk_mul_f32 v[2:3], v[10:11], v[2:3]
	v_pk_mul_f32 v[0:1], v[8:9], v[0:1]
	v_pk_mul_f32 v[6:7], v[14:15], v[6:7]
	v_pk_mul_f32 v[4:5], v[12:13], v[4:5]
	s_waitcnt vmcnt(0)
; __device__ __forceinline__ unsigned cvt_pk_bf16(float lo, float hi) { cvf32x2_t v = {lo, hi}; cvbf16x2_t b = __builtin_convertvector(v, cvbf16x2_t); return __builtin_bit_cast(unsigned, b); }
; __device__ __forceinline__ float row_rs(const float* ssq, int row) { return ssq ? rsqrtf(ssq[row] * (1.f / 1024.f) + RMS_EPS) : 1.f; }
;     __device__ __forceinline__ void operator()(const f32x4 (&acc)[2][2][4][2], const Unit& u, int wr, int wc, int fr, int fq) const {
;     ...
;                 for (int m = 0; m < 4; ++m) { const int row = row0 + ai * HALF + m * 16; const float rs = row_rs(ssq, row); const float rs2 = rs * rs;
;                     const f32x4 v0 = acc[ai][0][m][0] * acc[ai][1][m][0] * rs2, v1 = acc[ai][0][m][1] * acc[ai][1][m][1] * rs2; u32x4 w;
;                     w.x = cvt_pk_bf16(v0[0], v0[1]); w.y = cvt_pk_bf16(v0[2], v0[3]); w.z = cvt_pk_bf16(v1[0], v1[1]); w.w = cvt_pk_bf16(v1[2], v1[3]);
;                     *(u32x4*)(CU + (size_t)row * 512 + (pn - 10) * HALF + cw) = w; }
	v_fmamk_f32 v124, v152, 0x3a800000, v170
	v_rsq_f32_e32 v126, v124
	v_lshl_add_u64 v[124:125], v[122:123], 2, s[30:31]
	v_mul_f32_e32 v126, v126, v126
	v_pk_mul_f32 v[118:119], v[118:119], v[126:127] op_sel_hi:[1,0]
	v_pk_mul_f32 v[116:117], v[116:117], v[126:127] op_sel_hi:[1,0]
	v_pk_mul_f32 v[152:153], v[114:115], v[126:127] op_sel_hi:[1,0]
	v_pk_mul_f32 v[120:121], v[120:121], v[126:127] op_sel_hi:[1,0]
	v_cvt_pk_bf16_f32 v114, v116, v117
	v_cvt_pk_bf16_f32 v115, v118, v119
	v_cvt_pk_bf16_f32 v116, v120, v121
	v_cvt_pk_bf16_f32 v117, v152, v153
	global_store_dwordx4 v[112:113], v[114:117], off
	v_fmamk_f32 v110, v210, 0x3a800000, v170
	v_rsq_f32_e32 v110, v110
	s_nop 0
	v_mul_f32_e32 v110, v110, v110
	v_pk_mul_f32 v[102:103], v[102:103], v[110:111] op_sel_hi:[1,0]
	v_pk_mul_f32 v[100:101], v[100:101], v[110:111] op_sel_hi:[1,0]
	v_pk_mul_f32 v[114:115], v[98:99], v[110:111] op_sel_hi:[1,0]
	v_pk_mul_f32 v[98:99], v[96:97], v[110:111] op_sel_hi:[1,0]
	v_cvt_pk_bf16_f32 v96, v100, v101
	v_cvt_pk_bf16_f32 v97, v102, v103
	v_cvt_pk_bf16_f32 v98, v98, v99
	v_cvt_pk_bf16_f32 v99, v114, v115
	global_store_dwordx4 v[106:107], v[96:99], off
	v_fmamk_f32 v94, v211, 0x3a800000, v170
	v_rsq_f32_e32 v94, v94
	s_nop 0
	v_mul_f32_e32 v94, v94, v94
	v_pk_mul_f32 v[86:87], v[86:87], v[94:95] op_sel_hi:[1,0]
	v_pk_mul_f32 v[84:85], v[84:85], v[94:95] op_sel_hi:[1,0]
	v_pk_mul_f32 v[96:97], v[82:83], v[94:95] op_sel_hi:[1,0]
	v_pk_mul_f32 v[82:83], v[80:81], v[94:95] op_sel_hi:[1,0]
	v_cvt_pk_bf16_f32 v80, v84, v85
	v_cvt_pk_bf16_f32 v81, v86, v87
	v_cvt_pk_bf16_f32 v82, v82, v83
	v_cvt_pk_bf16_f32 v83, v96, v97
	global_store_dwordx4 v[90:91], v[80:83], off
	v_fmamk_f32 v74, v212, 0x3a800000, v170
	v_rsq_f32_e32 v74, v74
	s_nop 0
	v_mul_f32_e32 v74, v74, v74
	v_pk_mul_f32 v[70:71], v[70:71], v[74:75] op_sel_hi:[1,0]
	v_pk_mul_f32 v[68:69], v[68:69], v[74:75] op_sel_hi:[1,0]
	v_pk_mul_f32 v[76:77], v[66:67], v[74:75] op_sel_hi:[1,0]
	v_pk_mul_f32 v[66:67], v[64:65], v[74:75] op_sel_hi:[1,0]
	v_cvt_pk_bf16_f32 v64, v68, v69
	v_cvt_pk_bf16_f32 v65, v70, v71
	v_cvt_pk_bf16_f32 v66, v66, v67
	v_cvt_pk_bf16_f32 v67, v76, v77
	global_store_dwordx4 v[72:73], v[64:67], off
	v_fmamk_f32 v56, v213, 0x3a800000, v170
	v_rsq_f32_e32 v58, v56
	v_add_co_u32_e64 v56, s[6:7], s91, v112
	v_mul_f32_e32 v58, v58, v58
	v_pk_mul_f32 v[54:55], v[54:55], v[58:59] op_sel_hi:[1,0]
	v_pk_mul_f32 v[52:53], v[52:53], v[58:59] op_sel_hi:[1,0]
	v_pk_mul_f32 v[60:61], v[50:51], v[58:59] op_sel_hi:[1,0]
	v_pk_mul_f32 v[50:51], v[48:49], v[58:59] op_sel_hi:[1,0]
	v_addc_co_u32_e64 v57, s[6:7], 0, v113, s[6:7]
	v_cvt_pk_bf16_f32 v48, v52, v53
	v_cvt_pk_bf16_f32 v49, v54, v55
	v_cvt_pk_bf16_f32 v50, v50, v51
	v_cvt_pk_bf16_f32 v51, v60, v61
	global_store_dwordx4 v[56:57], v[48:51], off
	v_fmamk_f32 v40, v214, 0x3a800000, v170
	v_rsq_f32_e32 v42, v40
	v_add_co_u32_e64 v40, s[6:7], s92, v112
	v_mul_f32_e32 v42, v42, v42
	v_pk_mul_f32 v[38:39], v[38:39], v[42:43] op_sel_hi:[1,0]
	v_pk_mul_f32 v[36:37], v[36:37], v[42:43] op_sel_hi:[1,0]
	v_pk_mul_f32 v[44:45], v[34:35], v[42:43] op_sel_hi:[1,0]
	v_pk_mul_f32 v[34:35], v[32:33], v[42:43] op_sel_hi:[1,0]
	v_addc_co_u32_e64 v41, s[6:7], 0, v113, s[6:7]
	v_cvt_pk_bf16_f32 v32, v36, v37
	v_cvt_pk_bf16_f32 v33, v38, v39
	v_cvt_pk_bf16_f32 v34, v34, v35
	v_cvt_pk_bf16_f32 v35, v44, v45
	global_store_dwordx4 v[40:41], v[32:35], off
	v_fmamk_f32 v24, v215, 0x3a800000, v170
	v_rsq_f32_e32 v26, v24
	v_add_co_u32_e64 v24, s[6:7], s93, v112
	v_mul_f32_e32 v26, v26, v26
	v_pk_mul_f32 v[22:23], v[22:23], v[26:27] op_sel_hi:[1,0]
	v_pk_mul_f32 v[20:21], v[20:21], v[26:27] op_sel_hi:[1,0]
	v_pk_mul_f32 v[28:29], v[18:19], v[26:27] op_sel_hi:[1,0]
	v_pk_mul_f32 v[18:19], v[16:17], v[26:27] op_sel_hi:[1,0]
	v_addc_co_u32_e64 v25, s[6:7], 0, v113, s[6:7]
	v_cvt_pk_bf16_f32 v16, v20, v21
	v_cvt_pk_bf16_f32 v17, v22, v23
	v_cvt_pk_bf16_f32 v18, v18, v19
	v_cvt_pk_bf16_f32 v19, v28, v29
	global_store_dwordx4 v[24:25], v[16:19], off
	v_add_co_u32_e32 v8, vcc, 0x2c000, v112
	v_fmamk_f32 v10, v216, 0x3a800000, v170
	v_rsq_f32_e32 v10, v10
	s_nop 0
	v_mov_b32_e32 v9, v10
	v_mul_f32_e32 v10, v9, v9
	v_pk_mul_f32 v[6:7], v[6:7], v[10:11] op_sel_hi:[1,0]
	v_pk_mul_f32 v[4:5], v[4:5], v[10:11] op_sel_hi:[1,0]
	v_pk_mul_f32 v[12:13], v[2:3], v[10:11] op_sel_hi:[1,0]
	v_pk_mul_f32 v[2:3], v[0:1], v[10:11] op_sel_hi:[1,0]
	v_cvt_pk_bf16_f32 v0, v4, v5
	v_cvt_pk_bf16_f32 v1, v6, v7
	v_cvt_pk_bf16_f32 v2, v2, v3
	v_cvt_pk_bf16_f32 v3, v12, v13
	v_addc_co_u32_e32 v9, vcc, 0, v113, vcc
	global_store_dwordx4 v[8:9], v[0:3], off
	s_andn2_b64 vcc, exec, s[4:5]
	s_mov_b64 s[4:5], -1
	s_cbranch_vccnz .LBB0_592

; __device__ __forceinline__ unsigned pk2(float lo, float hi) { return pg8::cvt_pk_bf16(lo, hi); }
; template <int NR>
; __device__ __forceinline__ void conv_rows(const Args& a, int r0, int rstride, int lane) {
;     ...
;     for (int i = 0; i < NR; ++i) { const int row = r0 + i * rstride, t = row & (SEQ - 1);
;         bq[i] = *(const v4u*)(BCp + (size_t)row * 512 + c0); u0[i] = *(const v4u*)(CUp + (size_t)row * 512 + c0);
;         u1[i] = (v4u){0, 0, 0, 0}; u2[i] = (v4u){0, 0, 0, 0};
;         if (t >= 1) u1[i] = *(const v4u*)(CUp + (size_t)(row - 1) * 512 + c0);
;         if (t >= 2) u2[i] = *(const v4u*)(CUp + (size_t)(row - 2) * 512 + c0); }
;     const float* cw = a.in[I_CONVW] + c0; const float* gn = a.in[I_CONVN] + c0;
;     const f32x4 w0a = *(const f32x4*)(cw), w0b = *(const f32x4*)(cw + 4), w1a = *(const f32x4*)(cw + 512), w1b = *(const f32x4*)(cw + 516), w2a = *(const f32x4*)(cw + 1024), w2b = *(const f32x4*)(cw + 1028);
;     const f32x4 ga = *(const f32x4*)(gn), gb = *(const f32x4*)(gn + 4);
; #pragma unroll
;     for (int i = 0; i < NR; ++i) { const int row = r0 + i * rstride; float y[8]; float s = 0.f;
; #pragma unroll
;         for (int j = 0; j < 8; ++j) { const int sh = (j & 1) * 16; const unsigned ub = bq[i][j >> 1], x0 = u0[i][j >> 1], x1 = u1[i][j >> 1], x2 = u2[i][j >> 1];
;             const float B = __uint_as_float(((ub >> sh) & 0xffffu) << 16), c_0 = __uint_as_float(((x0 >> sh) & 0xffffu) << 16), c_1 = __uint_as_float(((x1 >> sh) & 0xffffu) << 16), c_2 = __uint_as_float(((x2 >> sh) & 0xffffu) << 16);
;             const float k0 = j < 4 ? w0a[j & 3] : w0b[j & 3], k1 = j < 4 ? w1a[j & 3] : w1b[j & 3], k2 = j < 4 ? w2a[j & 3] : w2b[j & 3];
;             y[j] = B * (k0 * c_2 + k1 * c_1 + k2 * c_0); s += y[j] * y[j]; }
;         s = wave_sum(s); const float rs = rsqrtf(s * (1.f / 512.f) + EPS);
;         v4u o; o.x = pk2(y[0] * rs * ga[0], y[1] * rs * ga[1]); o.y = pk2(y[2] * rs * ga[2], y[3] * rs * ga[3]); o.z = pk2(y[4] * rs * gb[0], y[5] * rs * gb[1]); o.w = pk2(y[6] * rs * gb[2], y[7] * rs * gb[3]);
;         pg8::st_wt16((bf16*)(ws + WS_MIX) + (size_t)row * 1024 + 512 + c0, o); }
.LBB0_747:
	global_load_dwordx4 v[20:23], v[10:11], off
	global_load_dwordx4 v[24:27], v[100:101], off offset:2064
	global_load_dwordx4 v[28:31], v[100:101], off offset:2048
	v_add_co_u32_e32 v60, vcc, 0x1000000, v10
	global_load_dwordx4 v[32:35], v[100:101], off
	global_load_dwordx4 v[36:39], v[100:101], off offset:16
	v_addc_co_u32_e32 v61, vcc, 0, v11, vcc
	global_load_dwordx4 v[40:43], v[60:61], off
	global_load_dwordx4 v[44:47], v[104:105], off offset:16
	global_load_dwordx4 v[48:51], v[104:105], off
	global_load_dwordx4 v[52:55], v[102:103], off offset:16
	global_load_dwordx4 v[56:59], v[102:103], off
	s_waitcnt vmcnt(10)
	v_lshlrev_b32_e32 v60, 16, v7
	v_and_b32_e32 v61, 0xffff0000, v7
	v_lshlrev_b32_e32 v62, 16, v3
	v_and_b32_e32 v63, 0xffff0000, v3
	v_lshlrev_b32_e32 v64, 16, v6
	v_and_b32_e32 v65, 0xffff0000, v6
	v_lshlrev_b32_e32 v6, 16, v2
	v_and_b32_e32 v7, 0xffff0000, v2
	v_lshlrev_b32_e32 v2, 16, v5
	v_and_b32_e32 v3, 0xffff0000, v5
	v_lshlrev_b32_e32 v66, 16, v1
	v_and_b32_e32 v67, 0xffff0000, v1
	v_lshlrev_b32_e32 v68, 16, v4
	v_and_b32_e32 v69, 0xffff0000, v4
	v_lshlrev_b32_e32 v4, 16, v0
	v_and_b32_e32 v5, 0xffff0000, v0
	s_add_i32 s11, s11, s58
	s_cmpk_lt_i32 s11, 0x4000
	v_lshl_add_u64 v[10:11], v[10:11], 0, s[8:9]
	s_waitcnt vmcnt(9)
	v_lshlrev_b32_e32 v0, 16, v23
	v_and_b32_e32 v1, 0xffff0000, v23
	s_waitcnt vmcnt(8)
	v_pk_mul_f32 v[6:7], v[24:25], v[6:7]
	v_lshlrev_b32_e32 v24, 16, v22
	v_and_b32_e32 v25, 0xffff0000, v22
	s_waitcnt vmcnt(7)
	v_pk_mul_f32 v[22:23], v[30:31], v[66:67]
	v_pk_mul_f32 v[4:5], v[28:29], v[4:5]
	s_waitcnt vmcnt(6)
	v_pk_fma_f32 v[2:3], v[34:35], v[2:3], v[22:23]
	v_pk_fma_f32 v[4:5], v[32:33], v[68:69], v[4:5]
	s_waitcnt vmcnt(4)
	v_lshlrev_b32_e32 v34, 16, v40
	v_and_b32_e32 v35, 0xffff0000, v40
	v_pk_mul_f32 v[26:27], v[26:27], v[62:63]
	v_lshlrev_b32_e32 v28, 16, v20
	v_and_b32_e32 v29, 0xffff0000, v20
	v_lshlrev_b32_e32 v32, 16, v41
	v_and_b32_e32 v33, 0xffff0000, v41
	s_waitcnt vmcnt(2)
	v_pk_fma_f32 v[4:5], v[48:49], v[34:35], v[4:5]
	v_lshlrev_b32_e32 v30, 16, v21
	v_and_b32_e32 v31, 0xffff0000, v21
	v_pk_fma_f32 v[20:21], v[38:39], v[60:61], v[26:27]
	v_pk_fma_f32 v[6:7], v[36:37], v[64:65], v[6:7]
	v_lshlrev_b32_e32 v26, 16, v42
	v_and_b32_e32 v27, 0xffff0000, v42
	v_pk_fma_f32 v[2:3], v[50:51], v[32:33], v[2:3]
	v_pk_mul_f32 v[4:5], v[4:5], v[28:29]
	v_pk_fma_f32 v[6:7], v[44:45], v[26:27], v[6:7]
	v_pk_mul_f32 v[2:3], v[2:3], v[30:31]
	v_pk_mul_f32 v[26:27], v[4:5], v[4:5]
	v_pk_mul_f32 v[6:7], v[6:7], v[24:25]
	v_pk_mul_f32 v[24:25], v[2:3], v[2:3]
	v_add_f32_e32 v19, v26, v27
	v_lshlrev_b32_e32 v22, 16, v43
	v_and_b32_e32 v23, 0xffff0000, v43
	v_add_f32_e32 v19, v24, v19
	v_pk_fma_f32 v[20:21], v[46:47], v[22:23], v[20:21]
	v_pk_mul_f32 v[22:23], v[6:7], v[6:7]
	v_add_f32_e32 v19, v25, v19
	v_pk_mul_f32 v[0:1], v[20:21], v[0:1]
	v_add_f32_e32 v19, v22, v19
	v_pk_mul_f32 v[20:21], v[0:1], v[0:1]
	v_add_f32_e32 v19, v23, v19
	v_add_f32_e32 v19, v20, v19
	v_add_f32_e32 v19, v21, v19
	ds_bpermute_b32 v20, v17, v19
	s_waitcnt lgkmcnt(0)
	v_add_f32_e32 v19, v19, v20
	ds_bpermute_b32 v20, v16, v19
	s_waitcnt lgkmcnt(0)
	v_add_f32_e32 v19, v19, v20
	ds_bpermute_b32 v20, v15, v19
	s_waitcnt lgkmcnt(0)
	v_add_f32_e32 v19, v19, v20
	ds_bpermute_b32 v20, v14, v19
	s_waitcnt lgkmcnt(0)
	v_add_f32_e32 v19, v19, v20
	ds_bpermute_b32 v20, v13, v19
	s_waitcnt lgkmcnt(0)
	v_add_f32_e32 v19, v19, v20
	ds_bpermute_b32 v20, v12, v19
	s_waitcnt lgkmcnt(0)
	v_add_f32_e32 v19, v19, v20
	v_fmamk_f32 v19, v19, 0x3b000000, v18
	v_rsq_f32_e32 v19, v19
	s_nop 0
	v_mov_b32_e32 v20, v19
	v_pk_mul_f32 v[4:5], v[4:5], v[20:21] op_sel_hi:[1,0]
	v_pk_mul_f32 v[2:3], v[2:3], v[20:21] op_sel_hi:[1,0]
	v_pk_mul_f32 v[6:7], v[6:7], v[20:21] op_sel_hi:[1,0]
	v_pk_mul_f32 v[0:1], v[0:1], v[20:21] op_sel_hi:[1,0]
	s_waitcnt vmcnt(0)
	v_pk_mul_f32 v[4:5], v[56:57], v[4:5]
	v_pk_mul_f32 v[2:3], v[58:59], v[2:3]
	v_pk_mul_f32 v[6:7], v[52:53], v[6:7]
	v_pk_mul_f32 v[20:21], v[54:55], v[0:1]
	v_cvt_pk_bf16_f32 v0, v4, v5
	v_cvt_pk_bf16_f32 v1, v2, v3
	v_cvt_pk_bf16_f32 v2, v6, v7
	v_cvt_pk_bf16_f32 v3, v20, v21
	global_store_dwordx4 v[8:9], v[0:3], off
	v_lshl_add_u64 v[8:9], v[8:9], 0, s[6:7]
	s_cbranch_scc0 .LBB0_753

; template <int NR>
; __device__ __forceinline__ void conv_rows(const Args& a, int r0, int rstride, int lane) {
;     ...
;     const float* cw = a.in[I_CONVW] + c0; const float* gn = a.in[I_CONVN] + c0;
;     const f32x4 w0a = *(const f32x4*)(cw), w0b = *(const f32x4*)(cw + 4), w1a = *(const f32x4*)(cw + 512), w1b = *(const f32x4*)(cw + 516), w2a = *(const f32x4*)(cw + 1024), w2b = *(const f32x4*)(cw + 1028);
;     const f32x4 ga = *(const f32x4*)(gn), gb = *(const f32x4*)(gn + 4);
; #pragma unroll
;     for (int i = 0; i < NR; ++i) { const int row = r0 + i * rstride; float y[8]; float s = 0.f;
; #pragma unroll
;         for (int j = 0; j < 8; ++j) { const int sh = (j & 1) * 16; const unsigned ub = bq[i][j >> 1], x0 = u0[i][j >> 1], x1 = u1[i][j >> 1], x2 = u2[i][j >> 1];
;             const float B = __uint_as_float(((ub >> sh) & 0xffffu) << 16), c_0 = __uint_as_float(((x0 >> sh) & 0xffffu) << 16), c_1 = __uint_as_float(((x1 >> sh) & 0xffffu) << 16), c_2 = __uint_as_float(((x2 >> sh) & 0xffffu) << 16);
;             const float k0 = j < 4 ? w0a[j & 3] : w0b[j & 3], k1 = j < 4 ? w1a[j & 3] : w1b[j & 3], k2 = j < 4 ? w2a[j & 3] : w2b[j & 3];
;             y[j] = B * (k0 * c_2 + k1 * c_1 + k2 * c_0); s += y[j] * y[j]; }
;         s = wave_sum(s); const float rs = rsqrtf(s * (1.f / 512.f) + EPS);
.LBB0_757:
	global_load_dwordx4 v[72:75], v[100:101], off offset:2064
	global_load_dwordx4 v[40:43], v[100:101], off offset:2048
	global_load_dwordx4 v[76:79], v[100:101], off offset:16
	global_load_dwordx4 v[44:47], v[100:101], off
	global_load_dwordx4 v[68:71], v[104:105], off offset:16
	global_load_dwordx4 v[36:39], v[104:105], off
	global_load_dwordx4 v[16:19], v[102:103], off offset:16
	global_load_dwordx4 v[20:23], v[102:103], off
	v_lshlrev_b32_e32 v120, 16, v3
	v_and_b32_e32 v121, 0xffff0000, v3
	v_lshlrev_b32_e32 v116, 16, v87
	v_and_b32_e32 v117, 0xffff0000, v87
	v_lshlrev_b32_e32 v118, 16, v83
	v_and_b32_e32 v119, 0xffff0000, v83
	v_lshlrev_b32_e32 v122, 16, v91
	v_and_b32_e32 v123, 0xffff0000, v91
	v_lshlrev_b32_e32 v124, 16, v86
	v_and_b32_e32 v125, 0xffff0000, v86
	v_lshlrev_b32_e32 v86, 16, v82
	v_and_b32_e32 v87, 0xffff0000, v82
	v_lshlrev_b32_e32 v82, 16, v2
	v_and_b32_e32 v83, 0xffff0000, v2
	v_lshlrev_b32_e32 v2, 16, v90
	v_and_b32_e32 v3, 0xffff0000, v90
	v_lshlrev_b32_e32 v90, 16, v85
	v_and_b32_e32 v91, 0xffff0000, v85
	v_lshlrev_b32_e32 v126, 16, v81
	v_and_b32_e32 v127, 0xffff0000, v81
	v_lshlrev_b32_e32 v128, 16, v1
	v_and_b32_e32 v129, 0xffff0000, v1
	v_lshlrev_b32_e32 v130, 16, v89
	v_and_b32_e32 v131, 0xffff0000, v89
	v_lshlrev_b32_e32 v132, 16, v84
	v_and_b32_e32 v133, 0xffff0000, v84
	v_lshlrev_b32_e32 v84, 16, v80
	v_and_b32_e32 v85, 0xffff0000, v80
	v_lshlrev_b32_e32 v80, 16, v0
	v_and_b32_e32 v81, 0xffff0000, v0
	v_lshlrev_b32_e32 v0, 16, v88
	v_and_b32_e32 v1, 0xffff0000, v88
	s_waitcnt vmcnt(13)
	v_lshlrev_b32_e32 v88, 16, v67
	v_and_b32_e32 v89, 0xffff0000, v67
	s_waitcnt vmcnt(12)
	v_lshlrev_b32_e32 v134, 16, v63
	v_and_b32_e32 v135, 0xffff0000, v63
	v_lshlrev_b32_e32 v140, 16, v66
	v_and_b32_e32 v141, 0xffff0000, v66
	v_lshlrev_b32_e32 v66, 16, v62
	v_and_b32_e32 v67, 0xffff0000, v62
	v_lshlrev_b32_e32 v62, 16, v6
	v_and_b32_e32 v63, 0xffff0000, v6
	v_lshlrev_b32_e32 v136, 16, v7
	v_and_b32_e32 v137, 0xffff0000, v7
	v_lshlrev_b32_e32 v6, 16, v94
	v_and_b32_e32 v7, 0xffff0000, v94
	v_lshlrev_b32_e32 v138, 16, v95
	v_and_b32_e32 v139, 0xffff0000, v95
	v_lshlrev_b32_e32 v94, 16, v65
	v_and_b32_e32 v95, 0xffff0000, v65
	v_and_b32_e32 v65, 0xffff0000, v60
	s_add_i32 s26, s10, s58
	s_add_i32 s26, s26, s58
	s_lshl_b64 s[4:5], s[24:25], 11
	s_add_u32 s4, s18, s4
	s_addc_u32 s5, s19, s5
	s_waitcnt vmcnt(7)
	v_pk_mul_f32 v[120:121], v[74:75], v[120:121]
	s_waitcnt vmcnt(6)
	v_pk_mul_f32 v[80:81], v[40:41], v[80:81]
	v_pk_mul_f32 v[62:63], v[72:73], v[62:63]
	s_waitcnt vmcnt(5)
	v_pk_fma_f32 v[120:121], v[78:79], v[122:123], v[120:121]
	s_waitcnt vmcnt(4)
	v_pk_fma_f32 v[0:1], v[44:45], v[0:1], v[80:81]
	v_pk_fma_f32 v[6:7], v[76:77], v[6:7], v[62:63]
	s_waitcnt vmcnt(3)
	v_pk_fma_f32 v[62:63], v[70:71], v[118:119], v[120:121]
	s_waitcnt vmcnt(2)
	v_pk_fma_f32 v[0:1], v[36:37], v[84:85], v[0:1]
	v_pk_mul_f32 v[84:85], v[62:63], v[116:117]
	v_lshlrev_b32_e32 v116, 16, v5
	v_and_b32_e32 v117, 0xffff0000, v5
	v_pk_fma_f32 v[66:67], v[68:69], v[66:67], v[6:7]
	v_lshlrev_b32_e32 v118, 16, v93
	v_and_b32_e32 v119, 0xffff0000, v93
	v_pk_mul_f32 v[116:117], v[42:43], v[116:117]
	v_pk_mul_f32 v[62:63], v[66:67], v[140:141]
	v_lshlrev_b32_e32 v66, 16, v61
	v_and_b32_e32 v67, 0xffff0000, v61
	v_pk_fma_f32 v[116:117], v[46:47], v[118:119], v[116:117]
	v_and_b32_e32 v61, 0xffff0000, v4
	v_pk_fma_f32 v[66:67], v[38:39], v[66:67], v[116:117]
	v_and_b32_e32 v5, 0xffff0000, v92
	v_pk_mul_f32 v[66:67], v[66:67], v[94:95]
	v_lshlrev_b32_e32 v94, 16, v64
	v_and_b32_e32 v95, 0xffff0000, v64
	v_lshlrev_b32_e32 v64, 16, v60
	v_lshlrev_b32_e32 v60, 16, v4
	v_lshlrev_b32_e32 v4, 16, v92
	v_pk_mul_f32 v[60:61], v[40:41], v[60:61]
	v_pk_mul_f32 v[82:83], v[72:73], v[82:83]
	v_pk_fma_f32 v[4:5], v[44:45], v[4:5], v[60:61]
	v_pk_mul_f32 v[128:129], v[42:43], v[128:129]
	v_pk_fma_f32 v[4:5], v[36:37], v[64:65], v[4:5]
	v_pk_fma_f32 v[2:3], v[76:77], v[2:3], v[82:83]
	v_pk_fma_f32 v[82:83], v[46:47], v[130:131], v[128:129]
	v_pk_mul_f32 v[0:1], v[0:1], v[132:133]
	v_pk_mul_f32 v[4:5], v[4:5], v[94:95]
	v_pk_fma_f32 v[82:83], v[38:39], v[126:127], v[82:83]
	v_mov_b32_e32 v94, v5
	v_mov_b32_e32 v95, v1
	v_pk_mul_f32 v[136:137], v[74:75], v[136:137]
	v_pk_fma_f32 v[2:3], v[68:69], v[86:87], v[2:3]
	v_pk_mul_f32 v[82:83], v[82:83], v[90:91]
	v_mov_b32_e32 v92, v4
	v_mov_b32_e32 v93, v0
	v_pk_mul_f32 v[94:95], v[94:95], v[94:95]
	v_pk_fma_f32 v[80:81], v[78:79], v[138:139], v[136:137]
	v_pk_mul_f32 v[2:3], v[2:3], v[124:125]
	v_mov_b32_e32 v60, v66
	v_mov_b32_e32 v61, v82
	v_pk_fma_f32 v[92:93], v[92:93], v[92:93], v[94:95]
	v_pk_fma_f32 v[80:81], v[70:71], v[134:135], v[80:81]
	v_pk_mul_f32 v[86:87], v[2:3], v[2:3]
	v_pk_mul_f32 v[90:91], v[62:63], v[62:63]
	v_mov_b32_e32 v64, v67
	v_mov_b32_e32 v65, v83
	v_pk_fma_f32 v[60:61], v[60:61], v[60:61], v[92:93]
	v_pk_mul_f32 v[6:7], v[80:81], v[88:89]
	v_pk_fma_f32 v[60:61], v[64:65], v[64:65], v[60:61]
	v_mov_b32_e32 v64, v90
	v_mov_b32_e32 v65, v86
	v_pk_mul_f32 v[80:81], v[84:85], v[84:85]
	v_pk_mul_f32 v[88:89], v[6:7], v[6:7]
	v_pk_add_f32 v[60:61], v[64:65], v[60:61]
	v_mov_b32_e32 v86, v91
	v_pk_add_f32 v[60:61], v[86:87], v[60:61]
	v_mov_b32_e32 v64, v88
	v_mov_b32_e32 v65, v80
	v_pk_add_f32 v[60:61], v[64:65], v[60:61]
	v_mov_b32_e32 v80, v89
	v_pk_add_f32 v[60:61], v[80:81], v[60:61]
	ds_bpermute_b32 v65, v97, v61
	ds_bpermute_b32 v64, v97, v60
	s_waitcnt lgkmcnt(0)
	v_pk_add_f32 v[60:61], v[60:61], v[64:65]
	ds_bpermute_b32 v65, v110, v61
	ds_bpermute_b32 v64, v110, v60
	s_waitcnt lgkmcnt(0)
	v_pk_add_f32 v[60:61], v[60:61], v[64:65]
	ds_bpermute_b32 v65, v111, v61
	ds_bpermute_b32 v64, v111, v60
	s_waitcnt lgkmcnt(0)
; __device__ __forceinline__ unsigned pk2(float lo, float hi) { return pg8::cvt_pk_bf16(lo, hi); }
; template <int NR>
; __device__ __forceinline__ void conv_rows(const Args& a, int r0, int rstride, int lane) {
;     ...
;     for (int i = 0; i < NR; ++i) { const int row = r0 + i * rstride; float y[8]; float s = 0.f;
; #pragma unroll
;         for (int j = 0; j < 8; ++j) { const int sh = (j & 1) * 16; const unsigned ub = bq[i][j >> 1], x0 = u0[i][j >> 1], x1 = u1[i][j >> 1], x2 = u2[i][j >> 1];
;             const float B = __uint_as_float(((ub >> sh) & 0xffffu) << 16), c_0 = __uint_as_float(((x0 >> sh) & 0xffffu) << 16), c_1 = __uint_as_float(((x1 >> sh) & 0xffffu) << 16), c_2 = __uint_as_float(((x2 >> sh) & 0xffffu) << 16);
;             const float k0 = j < 4 ? w0a[j & 3] : w0b[j & 3], k1 = j < 4 ? w1a[j & 3] : w1b[j & 3], k2 = j < 4 ? w2a[j & 3] : w2b[j & 3];
;             y[j] = B * (k0 * c_2 + k1 * c_1 + k2 * c_0); s += y[j] * y[j]; }
;         s = wave_sum(s); const float rs = rsqrtf(s * (1.f / 512.f) + EPS);
;         v4u o; o.x = pk2(y[0] * rs * ga[0], y[1] * rs * ga[1]); o.y = pk2(y[2] * rs * ga[2], y[3] * rs * ga[3]); o.z = pk2(y[4] * rs * gb[0], y[5] * rs * gb[1]); o.w = pk2(y[6] * rs * gb[2], y[7] * rs * gb[3]);
;         pg8::st_wt16((bf16*)(ws + WS_MIX) + (size_t)row * 1024 + 512 + c0, o); }
	v_pk_add_f32 v[60:61], v[60:61], v[64:65]
	ds_bpermute_b32 v65, v112, v61
	ds_bpermute_b32 v64, v112, v60
	s_waitcnt lgkmcnt(0)
	v_pk_add_f32 v[60:61], v[60:61], v[64:65]
	ds_bpermute_b32 v65, v113, v61
	ds_bpermute_b32 v64, v113, v60
	s_waitcnt lgkmcnt(0)
	v_pk_add_f32 v[60:61], v[60:61], v[64:65]
	ds_bpermute_b32 v65, v114, v61
	ds_bpermute_b32 v64, v114, v60
	s_waitcnt lgkmcnt(0)
	v_pk_add_f32 v[64:65], v[60:61], v[64:65]
	v_mov_b64_e32 v[60:61], s[8:9]
	v_pk_fma_f32 v[80:81], v[64:65], s[6:7], v[60:61] op_sel_hi:[1,0,0]
	s_nop 0
	v_rsq_f32_e32 v81, v81
	v_lshl_add_u64 v[64:65], s[4:5], 0, v[106:107]
	v_mov_b32_e32 v86, v81
	v_pk_mul_f32 v[0:1], v[0:1], v[86:87] op_sel_hi:[1,0]
	v_pk_mul_f32 v[82:83], v[82:83], v[86:87] op_sel_hi:[1,0]
	s_waitcnt vmcnt(0)
	v_pk_mul_f32 v[0:1], v[20:21], v[0:1]
	v_pk_mul_f32 v[82:83], v[22:23], v[82:83]
	v_cvt_pk_bf16_f32 v0, v0, v1
	v_cvt_pk_bf16_f32 v1, v82, v83
	v_pk_mul_f32 v[2:3], v[2:3], v[86:87] op_sel_hi:[1,0]
	v_pk_mul_f32 v[82:83], v[84:85], v[86:87] op_sel_hi:[1,0]
	v_lshlrev_b32_e32 v84, 16, v11
	v_and_b32_e32 v85, 0xffff0000, v11
	v_pk_mul_f32 v[2:3], v[16:17], v[2:3]
	v_pk_mul_f32 v[82:83], v[18:19], v[82:83]
	v_mul_f32_e32 v81, 0x4b800000, v80
	v_cmp_gt_f32_e32 vcc, s22, v80
	v_lshlrev_b32_e32 v86, 16, v59
	v_and_b32_e32 v87, 0xffff0000, v59
	v_pk_mul_f32 v[84:85], v[74:75], v[84:85]
	v_cvt_pk_bf16_f32 v2, v2, v3
	v_cvt_pk_bf16_f32 v3, v82, v83
	v_cndmask_b32_e32 v80, v80, v81, vcc
	v_lshlrev_b32_e32 v82, 16, v51
	v_and_b32_e32 v83, 0xffff0000, v51
	v_pk_fma_f32 v[84:85], v[78:79], v[86:87], v[84:85]
	v_rsq_f32_e32 v88, v80
	v_lshlrev_b32_e32 v80, 16, v55
	v_and_b32_e32 v81, 0xffff0000, v55
	v_pk_fma_f32 v[82:83], v[70:71], v[82:83], v[84:85]
	v_lshlrev_b32_e32 v84, 16, v54
	v_and_b32_e32 v85, 0xffff0000, v54
	v_lshlrev_b32_e32 v54, 16, v50
	v_and_b32_e32 v55, 0xffff0000, v50
	v_lshlrev_b32_e32 v50, 16, v10
	v_and_b32_e32 v51, 0xffff0000, v10
	v_lshlrev_b32_e32 v10, 16, v58
	v_and_b32_e32 v11, 0xffff0000, v58
	v_pk_mul_f32 v[50:51], v[72:73], v[50:51]
	v_lshlrev_b32_e32 v86, 16, v57
	v_pk_fma_f32 v[10:11], v[76:77], v[10:11], v[50:51]
	v_and_b32_e32 v87, 0xffff0000, v57
	v_pk_fma_f32 v[10:11], v[68:69], v[54:55], v[10:11]
	v_lshlrev_b32_e32 v58, 16, v49
	v_pk_mul_f32 v[10:11], v[10:11], v[84:85]
	v_lshlrev_b32_e32 v84, 16, v9
	v_and_b32_e32 v85, 0xffff0000, v9
	v_pk_mul_f32 v[84:85], v[42:43], v[84:85]
	v_and_b32_e32 v59, 0xffff0000, v49
	v_pk_fma_f32 v[84:85], v[46:47], v[86:87], v[84:85]
	v_lshlrev_b32_e32 v54, 16, v53
	v_and_b32_e32 v55, 0xffff0000, v53
	v_pk_fma_f32 v[58:59], v[38:39], v[58:59], v[84:85]
	v_and_b32_e32 v53, 0xffff0000, v48
	v_pk_mul_f32 v[54:55], v[58:59], v[54:55]
	v_lshlrev_b32_e32 v58, 16, v52
	v_and_b32_e32 v59, 0xffff0000, v52
	v_lshlrev_b32_e32 v52, 16, v48
	v_lshlrev_b32_e32 v48, 16, v8
	v_and_b32_e32 v49, 0xffff0000, v8
	v_lshlrev_b32_e32 v8, 16, v56
	v_and_b32_e32 v9, 0xffff0000, v56
	v_pk_mul_f32 v[48:49], v[40:41], v[48:49]
	v_lshlrev_b32_e32 v56, 16, v31
	v_pk_fma_f32 v[8:9], v[44:45], v[8:9], v[48:49]
	v_lshlrev_b32_e32 v48, 16, v35
	v_pk_fma_f32 v[8:9], v[36:37], v[52:53], v[8:9]
	v_lshlrev_b32_e32 v52, 16, v15
	v_and_b32_e32 v53, 0xffff0000, v15
	v_and_b32_e32 v49, 0xffff0000, v35
	v_pk_mul_f32 v[52:53], v[74:75], v[52:53]
	v_and_b32_e32 v57, 0xffff0000, v31
	v_pk_fma_f32 v[48:49], v[78:79], v[48:49], v[52:53]
	v_and_b32_e32 v35, 0xffff0000, v14
	v_pk_fma_f32 v[48:49], v[70:71], v[56:57], v[48:49]
	v_lshlrev_b32_e32 v56, 16, v34
	v_and_b32_e32 v57, 0xffff0000, v34
	v_lshlrev_b32_e32 v34, 16, v14
	v_pk_mul_f32 v[14:15], v[72:73], v[34:35]
	v_lshlrev_b32_e32 v34, 16, v30
	v_pk_fma_f32 v[14:15], v[76:77], v[56:57], v[14:15]
	v_and_b32_e32 v35, 0xffff0000, v30
	v_pk_fma_f32 v[14:15], v[68:69], v[34:35], v[14:15]
	v_lshlrev_b32_e32 v30, 16, v26
	v_and_b32_e32 v31, 0xffff0000, v26
	v_lshlrev_b32_e32 v34, 16, v13
	v_and_b32_e32 v35, 0xffff0000, v13
	v_pk_mul_f32 v[14:15], v[14:15], v[30:31]
	v_lshlrev_b32_e32 v30, 16, v33
	v_and_b32_e32 v31, 0xffff0000, v33
	v_pk_mul_f32 v[34:35], v[42:43], v[34:35]
	v_and_b32_e32 v33, 0xffff0000, v12
	v_pk_fma_f32 v[30:31], v[46:47], v[30:31], v[34:35]
	v_lshlrev_b32_e32 v34, 16, v29
	v_and_b32_e32 v35, 0xffff0000, v29
	v_pk_fma_f32 v[30:31], v[38:39], v[34:35], v[30:31]
	v_lshlrev_b32_e32 v34, 16, v25
	v_and_b32_e32 v35, 0xffff0000, v25
	v_pk_mul_f32 v[30:31], v[30:31], v[34:35]
	v_lshlrev_b32_e32 v34, 16, v32
	v_and_b32_e32 v35, 0xffff0000, v32
	v_lshlrev_b32_e32 v32, 16, v12
	v_pk_mul_f32 v[12:13], v[40:41], v[32:33]
	v_lshlrev_b32_e32 v32, 16, v28
	v_pk_fma_f32 v[12:13], v[44:45], v[34:35], v[12:13]
	v_and_b32_e32 v33, 0xffff0000, v28
	v_pk_fma_f32 v[12:13], v[36:37], v[32:33], v[12:13]
	v_lshlrev_b32_e32 v28, 16, v24
	v_and_b32_e32 v29, 0xffff0000, v24
	v_pk_mul_f32 v[8:9], v[8:9], v[58:59]
	v_pk_mul_f32 v[12:13], v[12:13], v[28:29]
	v_mov_b32_e32 v35, v9
	v_mov_b32_e32 v34, v13
	v_mov_b32_e32 v32, v12
	v_mov_b32_e32 v33, v8
	v_pk_mul_f32 v[34:35], v[34:35], v[34:35]
	v_mov_b32_e32 v24, v30
	v_mov_b32_e32 v25, v54
	v_pk_fma_f32 v[32:33], v[32:33], v[32:33], v[34:35]
	v_pk_mul_f32 v[50:51], v[10:11], v[10:11]
	v_lshlrev_b32_e32 v58, 16, v27
	v_and_b32_e32 v59, 0xffff0000, v27
	v_pk_mul_f32 v[26:27], v[14:15], v[14:15]
	v_mov_b32_e32 v28, v31
	v_mov_b32_e32 v29, v55
	v_pk_fma_f32 v[24:25], v[24:25], v[24:25], v[32:33]
	v_pk_mul_f32 v[80:81], v[82:83], v[80:81]
	v_pk_mul_f32 v[48:49], v[48:49], v[58:59]
	v_pk_fma_f32 v[24:25], v[28:29], v[28:29], v[24:25]
	v_mov_b32_e32 v28, v26
	v_mov_b32_e32 v29, v50
	v_pk_mul_f32 v[82:83], v[80:81], v[80:81]
	v_pk_mul_f32 v[52:53], v[48:49], v[48:49]
	v_pk_add_f32 v[24:25], v[28:29], v[24:25]
	v_mov_b32_e32 v50, v27
	v_pk_add_f32 v[24:25], v[50:51], v[24:25]
	v_mov_b32_e32 v26, v52
	v_mov_b32_e32 v27, v82
	v_pk_add_f32 v[24:25], v[26:27], v[24:25]
	v_mov_b32_e32 v82, v53
	v_pk_add_f32 v[24:25], v[82:83], v[24:25]
	ds_bpermute_b32 v27, v97, v25
	ds_bpermute_b32 v26, v97, v24
	v_add_co_u32_e64 v28, s[4:5], s23, v64
	s_nop 1
	v_addc_co_u32_e64 v29, s[4:5], 0, v65, s[4:5]
	global_store_dwordx4 v[28:29], v[0:3], off offset:1024
	s_lshl_b64 s[4:5], s[10:11], 11
	s_add_u32 s4, s18, s4
	s_waitcnt lgkmcnt(0)
; __device__ __forceinline__ unsigned pk2(float lo, float hi) { return pg8::cvt_pk_bf16(lo, hi); }
; template <int NR>
; __device__ __forceinline__ void conv_rows(const Args& a, int r0, int rstride, int lane) {
;     ...
;     for (int i = 0; i < NR; ++i) { const int row = r0 + i * rstride; float y[8]; float s = 0.f;
; #pragma unroll
;         for (int j = 0; j < 8; ++j) { const int sh = (j & 1) * 16; const unsigned ub = bq[i][j >> 1], x0 = u0[i][j >> 1], x1 = u1[i][j >> 1], x2 = u2[i][j >> 1];
;             const float B = __uint_as_float(((ub >> sh) & 0xffffu) << 16), c_0 = __uint_as_float(((x0 >> sh) & 0xffffu) << 16), c_1 = __uint_as_float(((x1 >> sh) & 0xffffu) << 16), c_2 = __uint_as_float(((x2 >> sh) & 0xffffu) << 16);
;             const float k0 = j < 4 ? w0a[j & 3] : w0b[j & 3], k1 = j < 4 ? w1a[j & 3] : w1b[j & 3], k2 = j < 4 ? w2a[j & 3] : w2b[j & 3];
;             y[j] = B * (k0 * c_2 + k1 * c_1 + k2 * c_0); s += y[j] * y[j]; }
;         s = wave_sum(s); const float rs = rsqrtf(s * (1.f / 512.f) + EPS);
;         v4u o; o.x = pk2(y[0] * rs * ga[0], y[1] * rs * ga[1]); o.y = pk2(y[2] * rs * ga[2], y[3] * rs * ga[3]); o.z = pk2(y[4] * rs * gb[0], y[5] * rs * gb[1]); o.w = pk2(y[6] * rs * gb[2], y[7] * rs * gb[3]);
;         pg8::st_wt16((bf16*)(ws + WS_MIX) + (size_t)row * 1024 + 512 + c0, o); }
	v_pk_add_f32 v[2:3], v[24:25], v[26:27]
	ds_bpermute_b32 v25, v110, v3
	ds_bpermute_b32 v24, v110, v2
	v_mul_f32_e32 v0, 0x45800000, v88
	v_cndmask_b32_e32 v28, v88, v0, vcc
	v_pk_mul_f32 v[0:1], v[4:5], v[28:29] op_sel_hi:[1,0]
	v_pk_mul_f32 v[4:5], v[66:67], v[28:29] op_sel_hi:[1,0]
	s_waitcnt lgkmcnt(0)
	v_pk_add_f32 v[2:3], v[2:3], v[24:25]
	ds_bpermute_b32 v25, v111, v3
	ds_bpermute_b32 v24, v111, v2
	v_pk_mul_f32 v[0:1], v[20:21], v[0:1]
	v_pk_mul_f32 v[4:5], v[22:23], v[4:5]
	v_cvt_pk_bf16_f32 v0, v0, v1
	v_cvt_pk_bf16_f32 v1, v4, v5
	s_waitcnt lgkmcnt(0)
	v_pk_add_f32 v[24:25], v[2:3], v[24:25]
	ds_bpermute_b32 v27, v112, v25
	ds_bpermute_b32 v26, v112, v24
	v_pk_mul_f32 v[4:5], v[62:63], v[28:29] op_sel_hi:[1,0]
	s_addc_u32 s5, s19, s5
	v_pk_mul_f32 v[4:5], v[16:17], v[4:5]
	s_nop 0
	v_cvt_pk_bf16_f32 v2, v4, v5
	v_pk_mul_f32 v[4:5], v[6:7], v[28:29] op_sel_hi:[1,0]
	s_nop 0
	v_pk_mul_f32 v[4:5], v[18:19], v[4:5]
	s_nop 0
	v_cvt_pk_bf16_f32 v3, v4, v5
	s_waitcnt lgkmcnt(0)
	v_pk_add_f32 v[4:5], v[24:25], v[26:27]
	ds_bpermute_b32 v7, v113, v5
	ds_bpermute_b32 v6, v113, v4
	v_lshl_add_u64 v[24:25], s[4:5], 0, v[106:107]
	v_add_co_u32_e32 v24, vcc, s23, v24
	s_lshl_b64 s[4:5], s[14:15], 11
	s_waitcnt lgkmcnt(0)
	v_pk_add_f32 v[4:5], v[4:5], v[6:7]
	ds_bpermute_b32 v7, v114, v5
	ds_bpermute_b32 v6, v114, v4
	v_addc_co_u32_e32 v25, vcc, 0, v25, vcc
	global_store_dwordx4 v[24:25], v[0:3], off offset:1024
	s_add_u32 s4, s18, s4
	s_addc_u32 s5, s19, s5
	s_waitcnt lgkmcnt(0)
	v_pk_add_f32 v[0:1], v[4:5], v[6:7]
	v_lshl_add_u64 v[6:7], s[4:5], 0, v[106:107]
	v_pk_fma_f32 v[4:5], v[0:1], s[6:7], v[60:61] op_sel_hi:[1,0,0]
	s_nop 0
	v_rsq_f32_e32 v0, v5
	v_mul_f32_e32 v5, 0x4b800000, v4
	v_mov_b32_e32 v24, v0
	v_pk_mul_f32 v[0:1], v[8:9], v[24:25] op_sel_hi:[1,0]
	v_pk_mul_f32 v[2:3], v[54:55], v[24:25] op_sel_hi:[1,0]
	v_pk_mul_f32 v[0:1], v[20:21], v[0:1]
	v_pk_mul_f32 v[2:3], v[22:23], v[2:3]
	v_cvt_pk_bf16_f32 v0, v0, v1
	v_cvt_pk_bf16_f32 v1, v2, v3
	v_pk_mul_f32 v[2:3], v[10:11], v[24:25] op_sel_hi:[1,0]
	v_pk_mul_f32 v[8:9], v[80:81], v[24:25] op_sel_hi:[1,0]
	v_cmp_gt_f32_e32 vcc, s22, v4
	v_pk_mul_f32 v[2:3], v[16:17], v[2:3]
	v_pk_mul_f32 v[8:9], v[18:19], v[8:9]
	v_cndmask_b32_e32 v4, v4, v5, vcc
	v_cvt_pk_bf16_f32 v2, v2, v3
	v_cvt_pk_bf16_f32 v3, v8, v9
	v_rsq_f32_e32 v8, v4
	v_add_co_u32_e64 v4, s[4:5], s23, v6
	s_nop 1
	v_addc_co_u32_e64 v5, s[4:5], 0, v7, s[4:5]
	global_store_dwordx4 v[4:5], v[0:3], off offset:1024
	s_lshl_b64 s[4:5], s[20:21], 11
	s_add_u32 s4, s18, s4
	v_mul_f32_e32 v0, 0x45800000, v8
	v_cndmask_b32_e32 v4, v8, v0, vcc
	v_pk_mul_f32 v[0:1], v[12:13], v[4:5] op_sel_hi:[1,0]
	v_pk_mul_f32 v[2:3], v[30:31], v[4:5] op_sel_hi:[1,0]
	v_pk_mul_f32 v[0:1], v[20:21], v[0:1]
	v_pk_mul_f32 v[2:3], v[22:23], v[2:3]
	v_cvt_pk_bf16_f32 v0, v0, v1
	v_cvt_pk_bf16_f32 v1, v2, v3
	v_pk_mul_f32 v[2:3], v[14:15], v[4:5] op_sel_hi:[1,0]
	v_pk_mul_f32 v[4:5], v[48:49], v[4:5] op_sel_hi:[1,0]
	v_pk_mul_f32 v[2:3], v[16:17], v[2:3]
	v_pk_mul_f32 v[4:5], v[18:19], v[4:5]
	s_addc_u32 s5, s19, s5
	v_cvt_pk_bf16_f32 v2, v2, v3
	v_cvt_pk_bf16_f32 v3, v4, v5
	v_lshl_add_u64 v[4:5], s[4:5], 0, v[106:107]
	v_add_co_u32_e32 v4, vcc, 0xe000000, v4
	s_add_i32 s24, s26, s58
	s_nop 0
	v_addc_co_u32_e32 v5, vcc, 0, v5, vcc
	s_cmpk_gt_i32 s24, 0x3fff
	global_store_dwordx4 v[4:5], v[0:3], off offset:1024
	s_cbranch_scc1 .LBB0_776

; #define LAS __attribute__((address_space(3)))
; __device__ __forceinline__ unsigned pk2(float lo, float hi) { return pg8::cvt_pk_bf16(lo, hi); }
; #define LBAR() do { asm volatile("s_waitcnt lgkmcnt(0)" ::: "memory"); __builtin_amdgcn_s_barrier(); asm volatile("" ::: "memory"); } while (0)
; __device__ __forceinline__ void hg_c2_unit(const Args& a, const float* Gp, LAS unsigned char* lds, int unit, int tid) {
;     ...
;         for (int kt = 0; kt < 8; ++kt) { const f32x4 d = *(const LAS f32x4*)(dl + 16 * kt + 4 * lq); S[kt] = S[kt] * d;
; #pragma unroll
;             for (int ss = 0; ss < 2; ++ss) { const bf16x8 x = *(const LAS bf16x8*)(KPt + (16 * kt + l15) * 72 + 32 * ss + 8 * lq), y = *(const LAS bf16x8*)(Vt + (16 * wave + l15) * 72 + 32 * ss + 8 * lq);
;                 S[kt] = __builtin_amdgcn_mfma_f32_16x16x32_bf16(x, y, S[kt], 0, 0, 0); } }
;         LBAR();
;         const float rs = rsqrtf((part[t] + part[64 + t]) * (1.f / 128.f) + EPS);
;         const size_t orow = (size_t)(row0 + t);
; #pragma unroll
;         for (int n = 0; n < 4; ++n) { const int v0 = 64 * vh + 16 * n + 4 * lq; const v2u gsw = gsw4[n]; const f32x4 gn = gn4[n];
;             const float o0 = acc[n][0] * rs * gn[0] * __uint_as_float(gsw.x << 16), o1 = acc[n][1] * rs * gn[1] * __uint_as_float(gsw.x & 0xffff0000u);
;             const float o2 = acc[n][2] * rs * gn[2] * __uint_as_float(gsw.y << 16), o3 = acc[n][3] * rs * gn[3] * __uint_as_float(gsw.y & 0xffff0000u);
;             v2u w; w.x = pk2(o0, o1); w.y = pk2(o2, o3); pg8::st_wt8((bf16*)(ws + WS_MIX) + orow * 1024 + h * 128 + v0, w); }
;         LBAR();
.LBB0_919:
	s_or_b64 exec, exec, s[34:35]
	ds_read_b128 v[96:99], v206
	ds_read_b128 v[104:107], v205
	ds_read_b128 v[108:111], v206 offset:64
	ds_read_b128 v[116:119], v194 offset:56320
	ds_read_b128 v[228:231], v194 offset:56384
	ds_read_b128 v[232:235], v205 offset:64
	s_waitcnt lgkmcnt(4)
	v_pk_mul_f32 v[10:11], v[10:11], v[106:107]
	v_pk_mul_f32 v[8:9], v[8:9], v[104:105]
	ds_read_b128 v[104:107], v206 offset:2368
	v_lshlrev_b64 v[82:83], 11, v[82:83]
	s_waitcnt lgkmcnt(3)
	v_mfma_f32_16x16x32_bf16 v[8:11], v[96:99], v[116:119], v[8:11]
	ds_read_b128 v[96:99], v206 offset:2304
	s_waitcnt lgkmcnt(2)
	v_pk_mul_f32 v[18:19], v[18:19], v[234:235]
	v_pk_mul_f32 v[16:17], v[16:17], v[232:233]
	v_mfma_f32_16x16x32_bf16 v[8:11], v[108:111], v[228:231], v[8:11]
	s_add_i32 s36, s36, 64
	s_cmpk_lg_i32 s36, 0x100
	s_waitcnt lgkmcnt(0)
	v_mfma_f32_16x16x32_bf16 v[16:19], v[96:99], v[116:119], v[16:19]
	ds_read_b128 v[96:99], v206 offset:4608
	ds_read_b128 v[108:111], v205 offset:128
	s_waitcnt lgkmcnt(0)
	v_pk_mul_f32 v[26:27], v[26:27], v[110:111]
	v_pk_mul_f32 v[24:25], v[24:25], v[108:109]
	v_mfma_f32_16x16x32_bf16 v[16:19], v[104:107], v[228:231], v[16:19]
	ds_read_b128 v[104:107], v206 offset:4672
	ds_read_b128 v[232:235], v205 offset:192
	s_waitcnt lgkmcnt(0)
	v_pk_mul_f32 v[34:35], v[34:35], v[234:235]
	v_mfma_f32_16x16x32_bf16 v[24:27], v[96:99], v[116:119], v[24:27]
	ds_read_b128 v[96:99], v206 offset:6912
	v_pk_mul_f32 v[32:33], v[32:33], v[232:233]
	v_mfma_f32_16x16x32_bf16 v[24:27], v[104:107], v[228:231], v[24:27]
	ds_read_b128 v[104:107], v206 offset:6976
	s_waitcnt lgkmcnt(1)
	v_mfma_f32_16x16x32_bf16 v[32:35], v[96:99], v[116:119], v[32:35]
	ds_read_b128 v[96:99], v206 offset:9216
	ds_read_b128 v[108:111], v205 offset:256
	s_waitcnt lgkmcnt(0)
	v_pk_mul_f32 v[42:43], v[42:43], v[110:111]
	v_pk_mul_f32 v[40:41], v[40:41], v[108:109]
	v_mfma_f32_16x16x32_bf16 v[32:35], v[104:107], v[228:231], v[32:35]
	ds_read_b128 v[104:107], v206 offset:9280
	ds_read_b128 v[232:235], v205 offset:320
	s_waitcnt lgkmcnt(0)
	v_pk_mul_f32 v[50:51], v[50:51], v[234:235]
	v_mfma_f32_16x16x32_bf16 v[40:43], v[96:99], v[116:119], v[40:43]
	ds_read_b128 v[96:99], v206 offset:11520
	ds_read_b128 v[108:111], v206 offset:11584
	v_pk_mul_f32 v[48:49], v[48:49], v[232:233]
	v_mfma_f32_16x16x32_bf16 v[40:43], v[104:107], v[228:231], v[40:43]
	ds_read_b128 v[104:107], v206 offset:13824
	s_waitcnt lgkmcnt(2)
	v_mfma_f32_16x16x32_bf16 v[48:51], v[96:99], v[116:119], v[48:51]
	ds_read_b128 v[96:99], v205 offset:384
	ds_read_b128 v[232:235], v206 offset:13888
	s_waitcnt lgkmcnt(1)
	v_pk_mul_f32 v[58:59], v[58:59], v[98:99]
	v_pk_mul_f32 v[56:57], v[56:57], v[96:97]
	v_mfma_f32_16x16x32_bf16 v[48:51], v[108:111], v[228:231], v[48:51]
	ds_read_b128 v[108:111], v205 offset:448
	s_waitcnt lgkmcnt(0)
	v_pk_mul_f32 v[14:15], v[14:15], v[110:111]
	v_mfma_f32_16x16x32_bf16 v[56:59], v[104:107], v[116:119], v[56:59]
	ds_read_b128 v[96:99], v206 offset:16128
	ds_read_b128 v[104:107], v206 offset:16192
	s_waitcnt lgkmcnt(0)
	s_barrier
	ds_read2st64_b32 v[90:91], v207 offset0:10 offset1:11
	v_pk_mul_f32 v[12:13], v[12:13], v[108:109]
	v_mfma_f32_16x16x32_bf16 v[56:59], v[232:235], v[228:231], v[56:59]
	s_waitcnt lgkmcnt(0)
	v_add_f32_e32 v90, v90, v91
	v_fmamk_f32 v90, v90, 0x3c000000, v210
	v_mfma_f32_16x16x32_bf16 v[12:15], v[96:99], v[116:119], v[12:15]
	s_nop 0
	v_rsq_f32_e32 v90, v90
	v_mfma_f32_16x16x32_bf16 v[12:15], v[104:107], v[228:231], v[12:15]
	v_pk_mul_f32 v[68:69], v[68:69], v[90:91] op_sel_hi:[1,0]
	s_waitcnt vmcnt(7)
	v_pk_mul_f32 v[44:45], v[44:45], v[68:69]
	s_waitcnt vmcnt(5)
	v_lshlrev_b32_e32 v68, 16, v80
	v_and_b32_e32 v69, 0xffff0000, v80
	v_pk_mul_f32 v[44:45], v[44:45], v[68:69]
	v_pk_mul_f32 v[68:69], v[70:71], v[90:91] op_sel_hi:[1,0]
	v_cvt_pk_bf16_f32 v44, v44, v45
	v_pk_mul_f32 v[46:47], v[46:47], v[68:69]
	v_lshlrev_b32_e32 v68, 16, v81
	v_and_b32_e32 v69, 0xffff0000, v81
	v_pk_mul_f32 v[46:47], v[46:47], v[68:69]
	s_nop 0
	v_cvt_pk_bf16_f32 v45, v46, v47
	v_lshl_add_u64 v[46:47], v[6:7], 0, v[82:83]
	global_store_dwordx2 v[46:47], v[44:45], off
	v_pk_mul_f32 v[44:45], v[64:65], v[90:91] op_sel_hi:[1,0]
	s_nop 0
	v_pk_mul_f32 v[36:37], v[36:37], v[44:45]
	s_waitcnt vmcnt(5)
	v_lshlrev_b32_e32 v44, 16, v78
	v_and_b32_e32 v45, 0xffff0000, v78
	v_pk_mul_f32 v[36:37], v[36:37], v[44:45]
	v_pk_mul_f32 v[44:45], v[66:67], v[90:91] op_sel_hi:[1,0]
	v_cvt_pk_bf16_f32 v36, v36, v37
	v_pk_mul_f32 v[38:39], v[38:39], v[44:45]
	v_lshlrev_b32_e32 v44, 16, v79
	v_and_b32_e32 v45, 0xffff0000, v79
	v_pk_mul_f32 v[38:39], v[38:39], v[44:45]
	s_nop 0
	v_cvt_pk_bf16_f32 v37, v38, v39
	global_store_dwordx2 v[46:47], v[36:37], off offset:32
	v_pk_mul_f32 v[36:37], v[60:61], v[90:91] op_sel_hi:[1,0]
	s_waitcnt vmcnt(3)
	v_pk_mul_f32 v[28:29], v[28:29], v[36:37]
	v_lshlrev_b32_e32 v36, 16, v76
	v_and_b32_e32 v37, 0xffff0000, v76
	v_pk_mul_f32 v[28:29], v[28:29], v[36:37]
	v_pk_mul_f32 v[36:37], v[62:63], v[90:91] op_sel_hi:[1,0]
	v_cvt_pk_bf16_f32 v28, v28, v29
	v_pk_mul_f32 v[30:31], v[30:31], v[36:37]
	v_lshlrev_b32_e32 v36, 16, v77
	v_and_b32_e32 v37, 0xffff0000, v77
	v_pk_mul_f32 v[30:31], v[30:31], v[36:37]
	s_nop 0
	v_cvt_pk_bf16_f32 v29, v30, v31
	global_store_dwordx2 v[46:47], v[28:29], off offset:64
	v_pk_mul_f32 v[28:29], v[52:53], v[90:91] op_sel_hi:[1,0]
	s_waitcnt vmcnt(3)
	v_pk_mul_f32 v[20:21], v[20:21], v[28:29]
	v_lshlrev_b32_e32 v28, 16, v74
	v_and_b32_e32 v29, 0xffff0000, v74
	v_pk_mul_f32 v[20:21], v[20:21], v[28:29]
	v_pk_mul_f32 v[28:29], v[54:55], v[90:91] op_sel_hi:[1,0]
	v_cvt_pk_bf16_f32 v20, v20, v21
	v_pk_mul_f32 v[22:23], v[22:23], v[28:29]
	v_lshlrev_b32_e32 v28, 16, v75
	v_and_b32_e32 v29, 0xffff0000, v75
	v_pk_mul_f32 v[22:23], v[22:23], v[28:29]
	s_nop 0
	v_cvt_pk_bf16_f32 v21, v22, v23
	global_store_dwordx2 v[46:47], v[20:21], off offset:96
	s_waitcnt lgkmcnt(0)
	s_barrier
	s_cbranch_scc0 .LBB0_778

; __device__ __forceinline__ float row_rs(const float* ssq, int row) { return ssq ? rsqrtf(ssq[row] * (1.f / 1024.f) + RMS_EPS) : 1.f; }
; #define LAS __attribute__((address_space(3)))
; __device__ __forceinline__ unsigned pk2(float lo, float hi) { return pg8::cvt_pk_bf16(lo, hi); }
;     __device__ __forceinline__ void fused(f32x4 (&acc)[2][2][4][2], const pg8::Unit& u, int wr, int wc, int fr, int fq, LAS unsigned char* lds, int wid, int lane) const {
;     ...
;             for (int m = 0; m < 4; ++m) { const int rl = ai * 128 + wr * 64 + m * 16 + fr; const float rs = pg8::row_rs(ssq, u.pm * 256 + rl);
; #pragma unroll
;                 for (int bj = 0; bj < 2; ++bj)
; #pragma unroll
;                     for (int n = 0; n < 2; ++n) { const f32x4 v = acc[ai][bj][m][n] * rs; v2u w; w.x = pk2(v[0], v[1]); w.y = pk2(v[2], v[3]);
;                         *(LAS v2u*)(QI + rl * XP + bj * 128 + wc * 32 + n * 16 + 4 * fq) = w; } }
.LBB0_1108:
	s_add_u32 s4, s48, 0x20000
	s_addc_u32 s5, s49, 0
	v_lshrrev_b32_e32 v128, 5, v208
	s_lshl_b32 s13, s10, 8
	v_lshlrev_b32_e32 v189, 4, v128
	v_lshlrev_b32_e32 v211, 2, v128
	v_add_u32_e32 v128, s13, v146
	v_ashrrev_i32_e32 v129, 31, v128
	v_lshl_add_u64 v[132:133], v[128:129], 2, s[4:5]
	s_barrier
	global_load_dword v131, v[132:133], off
	global_load_dword v136, v[132:133], off offset:64
	global_load_dword v137, v[132:133], off offset:128
	global_load_dword v138, v[132:133], off offset:192
	global_load_dword v139, v[132:133], off offset:512
	global_load_dword v140, v[132:133], off offset:576
	global_load_dword v141, v[132:133], off offset:640
	global_load_dword v142, v[132:133], off offset:704
	s_lshl_b32 s6, s39, 6
	v_mov_b32_e32 v129, 0x358637bd
	s_add_i32 s7, s6, 0
	s_mov_b32 s6, 0x800000
	s_movk_i32 s14, 0x210
	s_ashr_i32 s15, s10, 4
	s_add_i32 s12, 0, 0x10800
	s_andn2_b32 s30, s30, 63
	v_and_b32_e32 v210, 31, v209
	v_and_b32_e32 v188, 8, v147
	v_and_b32_e32 v190, 0x1f0, v144
	v_lshl_or_b32 v214, s31, 5, v210
	v_mov_b32_e32 v191, 0
	v_lshlrev_b32_e32 v130, 1, v188
	v_add_u32_e32 v216, 0, v190
	v_add_u32_e32 v215, s12, v190
	v_mul_u32_u24_e32 v212, 0x210, v210
	v_add3_u32 v213, 0, v212, v189
	s_mov_b32 s11, 0
	s_waitcnt vmcnt(0)
	v_fmamk_f32 v131, v131, 0x3a800000, v129
	s_nop 0
	v_rsq_f32_e32 v131, v131
	s_nop 0
	v_mov_b32_e32 v132, v131
	v_mul_lo_u32 v131, v146, s14
	v_pk_mul_f32 v[118:119], v[118:119], v[132:133] op_sel_hi:[1,0]
	v_pk_mul_f32 v[116:117], v[116:117], v[132:133] op_sel_hi:[1,0]
	v_pk_mul_f32 v[114:115], v[114:115], v[132:133] op_sel_hi:[1,0]
	v_pk_mul_f32 v[112:113], v[112:113], v[132:133] op_sel_hi:[1,0]
	v_add3_u32 v131, s7, v145, v131
	v_cvt_pk_bf16_f32 v116, v116, v117
	v_cvt_pk_bf16_f32 v117, v118, v119
	v_cvt_pk_bf16_f32 v112, v112, v113
	v_cvt_pk_bf16_f32 v113, v114, v115
	ds_write2_b64 v131, v[116:117], v[112:113] offset0:32 offset1:36
	v_pk_mul_f32 v[126:127], v[126:127], v[132:133] op_sel_hi:[1,0]
	v_pk_mul_f32 v[124:125], v[124:125], v[132:133] op_sel_hi:[1,0]
	v_pk_mul_f32 v[122:123], v[122:123], v[132:133] op_sel_hi:[1,0]
	v_pk_mul_f32 v[120:121], v[120:121], v[132:133] op_sel_hi:[1,0]
	v_cvt_pk_bf16_f32 v124, v124, v125
	v_cvt_pk_bf16_f32 v125, v126, v127
	v_cvt_pk_bf16_f32 v120, v120, v121
	v_cvt_pk_bf16_f32 v121, v122, v123
	ds_write2_b64 v131, v[124:125], v[120:121] offset1:4
	s_waitcnt vmcnt(0)
	v_fmamk_f32 v112, v136, 0x3a800000, v129
	s_nop 0
	v_rsq_f32_e32 v112, v112
	s_nop 0
	v_add_u32_e32 v113, 0x2100, v131
	v_pk_mul_f32 v[106:107], v[106:107], v[112:113] op_sel_hi:[1,0]
	v_pk_mul_f32 v[104:105], v[104:105], v[112:113] op_sel_hi:[1,0]
	v_pk_mul_f32 v[102:103], v[102:103], v[112:113] op_sel_hi:[1,0]
	v_pk_mul_f32 v[100:101], v[100:101], v[112:113] op_sel_hi:[1,0]
	v_pk_mul_f32 v[98:99], v[98:99], v[112:113] op_sel_hi:[1,0]
	v_pk_mul_f32 v[96:97], v[96:97], v[112:113] op_sel_hi:[1,0]
	v_cvt_pk_bf16_f32 v104, v104, v105
	v_cvt_pk_bf16_f32 v105, v106, v107
	v_add_u32_e32 v106, 0x2000, v131
	v_cvt_pk_bf16_f32 v100, v100, v101
	v_cvt_pk_bf16_f32 v101, v102, v103
	v_cvt_pk_bf16_f32 v96, v96, v97
	v_cvt_pk_bf16_f32 v97, v98, v99
	ds_write2_b64 v106, v[100:101], v[96:97] offset0:64 offset1:68
	v_pk_mul_f32 v[110:111], v[110:111], v[112:113] op_sel_hi:[1,0]
	v_pk_mul_f32 v[108:109], v[108:109], v[112:113] op_sel_hi:[1,0]
	s_waitcnt vmcnt(0)
	v_fmamk_f32 v96, v137, 0x3a800000, v129
	v_cvt_pk_bf16_f32 v108, v108, v109
	v_rsq_f32_e32 v96, v96
	v_cvt_pk_bf16_f32 v109, v110, v111
	ds_write2_b64 v106, v[108:109], v[104:105] offset0:32 offset1:36
	v_add_u32_e32 v97, 0x4200, v131
	v_pk_mul_f32 v[90:91], v[90:91], v[96:97] op_sel_hi:[1,0]
	v_pk_mul_f32 v[88:89], v[88:89], v[96:97] op_sel_hi:[1,0]
	v_pk_mul_f32 v[86:87], v[86:87], v[96:97] op_sel_hi:[1,0]
	v_pk_mul_f32 v[84:85], v[84:85], v[96:97] op_sel_hi:[1,0]
	v_pk_mul_f32 v[82:83], v[82:83], v[96:97] op_sel_hi:[1,0]
	v_pk_mul_f32 v[80:81], v[80:81], v[96:97] op_sel_hi:[1,0]
	v_cvt_pk_bf16_f32 v88, v88, v89
	v_cvt_pk_bf16_f32 v89, v90, v91
	v_add_u32_e32 v90, 0x4000, v131
	v_cvt_pk_bf16_f32 v84, v84, v85
	v_cvt_pk_bf16_f32 v85, v86, v87
	v_cvt_pk_bf16_f32 v80, v80, v81
	v_cvt_pk_bf16_f32 v81, v82, v83
	ds_write2_b64 v90, v[84:85], v[80:81] offset0:96 offset1:100
	v_pk_mul_f32 v[94:95], v[94:95], v[96:97] op_sel_hi:[1,0]
	v_pk_mul_f32 v[92:93], v[92:93], v[96:97] op_sel_hi:[1,0]
	s_waitcnt vmcnt(0)
	v_fmamk_f32 v80, v138, 0x3a800000, v129
	v_cvt_pk_bf16_f32 v92, v92, v93
	v_rsq_f32_e32 v80, v80
	v_cvt_pk_bf16_f32 v93, v94, v95
	ds_write2_b64 v90, v[92:93], v[88:89] offset0:64 offset1:68
	v_mov_b32_e32 v82, v80
	v_pk_mul_f32 v[74:75], v[74:75], v[82:83] op_sel_hi:[1,0]
	v_pk_mul_f32 v[72:73], v[72:73], v[82:83] op_sel_hi:[1,0]
	v_pk_mul_f32 v[70:71], v[70:71], v[82:83] op_sel_hi:[1,0]
	v_pk_mul_f32 v[68:69], v[68:69], v[82:83] op_sel_hi:[1,0]
	v_pk_mul_f32 v[66:67], v[66:67], v[82:83] op_sel_hi:[1,0]
	v_pk_mul_f32 v[64:65], v[64:65], v[82:83] op_sel_hi:[1,0]
	v_cvt_pk_bf16_f32 v72, v72, v73
	v_cvt_pk_bf16_f32 v73, v74, v75
	v_add_u32_e32 v74, 0x6000, v131
	v_cvt_pk_bf16_f32 v68, v68, v69
	v_cvt_pk_bf16_f32 v69, v70, v71
	v_cvt_pk_bf16_f32 v64, v64, v65
	v_cvt_pk_bf16_f32 v65, v66, v67
	ds_write2_b64 v74, v[68:69], v[64:65] offset0:128 offset1:132
	v_add_u32_e32 v80, 0x6300, v131
	v_pk_mul_f32 v[78:79], v[78:79], v[82:83] op_sel_hi:[1,0]
	v_pk_mul_f32 v[76:77], v[76:77], v[82:83] op_sel_hi:[1,0]
	v_add3_u32 v68, s12, v212, v189
	v_cvt_pk_bf16_f32 v76, v76, v77
	v_cvt_pk_bf16_f32 v77, v78, v79
	ds_write2_b64 v74, v[76:77], v[72:73] offset0:96 offset1:100
	v_add3_u32 v189, s12, v189, v212
	s_waitcnt vmcnt(0)
; __device__ __forceinline__ float row_rs(const float* ssq, int row) { return ssq ? rsqrtf(ssq[row] * (1.f / 1024.f) + RMS_EPS) : 1.f; }
; #define LAS __attribute__((address_space(3)))
; __device__ __forceinline__ unsigned pk2(float lo, float hi) { return pg8::cvt_pk_bf16(lo, hi); }
; __device__ __forceinline__ void stage_half(const bf16* g, LAS bf16* dst, int tid) {
;     ...
;     for (int i = 0; i < 8; ++i) { const int ch = tid + i * NT, r = ch >> 5, cc = ch & 31; t[i] = *(const v4u*)(g + (size_t)r * 1024 + cc * 8); }
; #pragma unroll
;     for (int i = 0; i < 8; ++i) { const int ch = tid + i * NT, r = ch >> 5, cc = ch & 31; *(LAS v4u*)(dst + r * XP + cc * 8) = t[i]; }
;     __device__ __forceinline__ void fused(f32x4 (&acc)[2][2][4][2], const pg8::Unit& u, int wr, int wc, int fr, int fq, LAS unsigned char* lds, int wid, int lane) const {
;     ...
;             for (int m = 0; m < 4; ++m) { const int rl = ai * 128 + wr * 64 + m * 16 + fr; const float rs = pg8::row_rs(ssq, u.pm * 256 + rl);
; #pragma unroll
;                 for (int bj = 0; bj < 2; ++bj)
; #pragma unroll
;                     for (int n = 0; n < 2; ++n) { const f32x4 v = acc[ai][bj][m][n] * rs; v2u w; w.x = pk2(v[0], v[1]); w.y = pk2(v[2], v[3]);
;                         *(LAS v2u*)(QI + rl * XP + bj * 128 + wc * 32 + n * 16 + 4 * fq) = w; } }
	v_fmamk_f32 v64, v139, 0x3a800000, v129
	s_nop 0
	v_rsq_f32_e32 v64, v64
	s_nop 0
	v_mov_b32_e32 v66, v64
	v_pk_mul_f32 v[54:55], v[54:55], v[66:67] op_sel_hi:[1,0]
	v_pk_mul_f32 v[52:53], v[52:53], v[66:67] op_sel_hi:[1,0]
	v_pk_mul_f32 v[50:51], v[50:51], v[66:67] op_sel_hi:[1,0]
	v_pk_mul_f32 v[48:49], v[48:49], v[66:67] op_sel_hi:[1,0]
	v_cvt_pk_bf16_f32 v52, v52, v53
	v_cvt_pk_bf16_f32 v53, v54, v55
	v_cvt_pk_bf16_f32 v48, v48, v49
	v_cvt_pk_bf16_f32 v49, v50, v51
	v_add_u32_e32 v50, 0xe800, v113
	ds_write2_b64 v50, v[52:53], v[48:49] offset1:4
	v_pk_mul_f32 v[62:63], v[62:63], v[66:67] op_sel_hi:[1,0]
	v_pk_mul_f32 v[60:61], v[60:61], v[66:67] op_sel_hi:[1,0]
	v_pk_mul_f32 v[58:59], v[58:59], v[66:67] op_sel_hi:[1,0]
	v_pk_mul_f32 v[56:57], v[56:57], v[66:67] op_sel_hi:[1,0]
	v_cvt_pk_bf16_f32 v60, v60, v61
	v_cvt_pk_bf16_f32 v61, v62, v63
	v_cvt_pk_bf16_f32 v56, v56, v57
	v_cvt_pk_bf16_f32 v57, v58, v59
	v_add_u32_e32 v58, 0xe000, v113
	ds_write2_b64 v58, v[60:61], v[56:57] offset0:224 offset1:228
	v_add_u32_e32 v64, 0xe700, v113
	s_waitcnt vmcnt(0)
	v_fmamk_f32 v48, v140, 0x3a800000, v129
	s_nop 0
	v_rsq_f32_e32 v48, v48
	s_nop 0
	v_pk_mul_f32 v[38:39], v[38:39], v[48:49] op_sel_hi:[1,0]
	v_pk_mul_f32 v[36:37], v[36:37], v[48:49] op_sel_hi:[1,0]
	v_pk_mul_f32 v[34:35], v[34:35], v[48:49] op_sel_hi:[1,0]
	v_pk_mul_f32 v[32:33], v[32:33], v[48:49] op_sel_hi:[1,0]
	v_cvt_pk_bf16_f32 v36, v36, v37
	v_cvt_pk_bf16_f32 v37, v38, v39
	v_cvt_pk_bf16_f32 v32, v32, v33
	v_cvt_pk_bf16_f32 v33, v34, v35
	v_add_u32_e32 v34, 0xe800, v97
	ds_write2_b64 v34, v[36:37], v[32:33] offset1:4
	v_pk_mul_f32 v[46:47], v[46:47], v[48:49] op_sel_hi:[1,0]
	v_pk_mul_f32 v[44:45], v[44:45], v[48:49] op_sel_hi:[1,0]
	v_pk_mul_f32 v[42:43], v[42:43], v[48:49] op_sel_hi:[1,0]
	v_pk_mul_f32 v[40:41], v[40:41], v[48:49] op_sel_hi:[1,0]
	v_cvt_pk_bf16_f32 v44, v44, v45
	v_cvt_pk_bf16_f32 v45, v46, v47
	v_cvt_pk_bf16_f32 v40, v40, v41
	v_cvt_pk_bf16_f32 v41, v42, v43
	v_add_u32_e32 v42, 0xe000, v97
	ds_write2_b64 v42, v[44:45], v[40:41] offset0:224 offset1:228
	s_waitcnt vmcnt(0)
	v_fmamk_f32 v32, v141, 0x3a800000, v129
	s_nop 0
	v_rsq_f32_e32 v32, v32
	s_nop 0
	v_pk_mul_f32 v[22:23], v[22:23], v[32:33] op_sel_hi:[1,0]
	v_pk_mul_f32 v[20:21], v[20:21], v[32:33] op_sel_hi:[1,0]
	v_pk_mul_f32 v[18:19], v[18:19], v[32:33] op_sel_hi:[1,0]
	v_pk_mul_f32 v[16:17], v[16:17], v[32:33] op_sel_hi:[1,0]
	v_cvt_pk_bf16_f32 v20, v20, v21
	v_cvt_pk_bf16_f32 v21, v22, v23
	v_cvt_pk_bf16_f32 v16, v16, v17
	v_cvt_pk_bf16_f32 v17, v18, v19
	v_add_u32_e32 v18, 0xe800, v80
	ds_write2_b64 v18, v[20:21], v[16:17] offset1:4
	v_pk_mul_f32 v[30:31], v[30:31], v[32:33] op_sel_hi:[1,0]
	v_pk_mul_f32 v[28:29], v[28:29], v[32:33] op_sel_hi:[1,0]
	v_pk_mul_f32 v[26:27], v[26:27], v[32:33] op_sel_hi:[1,0]
	v_pk_mul_f32 v[24:25], v[24:25], v[32:33] op_sel_hi:[1,0]
	v_cvt_pk_bf16_f32 v28, v28, v29
	v_cvt_pk_bf16_f32 v29, v30, v31
	v_cvt_pk_bf16_f32 v24, v24, v25
	v_cvt_pk_bf16_f32 v25, v26, v27
	v_add_u32_e32 v26, 0xe000, v80
	v_or_b32_e32 v30, s30, v208
	ds_write2_b64 v26, v[28:29], v[24:25] offset0:224 offset1:228
	v_ashrrev_i32_e32 v34, 5, v30
	v_add_u32_e32 v20, 0xa00, v30
	v_add_u32_e32 v24, 0xc00, v30
	v_ashrrev_i32_e32 v44, 5, v20
	v_ashrrev_i32_e32 v46, 5, v24
	v_ashrrev_i32_e32 v35, 31, v34
	v_ashrrev_i32_e32 v45, 31, v44
	v_ashrrev_i32_e32 v47, 31, v46
	v_lshlrev_b64 v[192:193], 11, v[34:35]
	v_lshlrev_b64 v[202:203], 11, v[44:45]
	v_lshlrev_b64 v[204:205], 11, v[46:47]
	v_mul_lo_u32 v34, v34, s14
	v_add_u32_e32 v223, v216, v34
	v_add_u32_e32 v230, v215, v34
	s_waitcnt vmcnt(0)
	v_fmac_f32_e32 v129, 0x3a800000, v142
	s_lshl_b32 s6, s15, 8
	v_rsq_f32_e32 v16, v129
	s_ashr_i32 s7, s6, 31
	s_lshl_b64 s[4:5], s[6:7], 11
	s_add_u32 s10, s48, s4
	s_addc_u32 s19, s49, s5
	s_lshl_b32 s16, s34, 8
	v_pk_mul_f32 v[14:15], v[14:15], v[16:17] op_sel_hi:[1,0]
	v_pk_mul_f32 v[12:13], v[12:13], v[16:17] op_sel_hi:[1,0]
	v_pk_mul_f32 v[10:11], v[10:11], v[16:17] op_sel_hi:[1,0]
	v_pk_mul_f32 v[8:9], v[8:9], v[16:17] op_sel_hi:[1,0]
	v_pk_mul_f32 v[6:7], v[6:7], v[16:17] op_sel_hi:[1,0]
	v_pk_mul_f32 v[4:5], v[4:5], v[16:17] op_sel_hi:[1,0]
	v_pk_mul_f32 v[2:3], v[2:3], v[16:17] op_sel_hi:[1,0]
	v_pk_mul_f32 v[0:1], v[0:1], v[16:17] op_sel_hi:[1,0]
	s_ashr_i32 s17, s16, 31
	v_cvt_pk_bf16_f32 v12, v12, v13
	v_cvt_pk_bf16_f32 v13, v14, v15
	v_cvt_pk_bf16_f32 v8, v8, v9
	v_cvt_pk_bf16_f32 v9, v10, v11
	v_add_u32_e32 v10, 0x6000, v64
	v_cvt_pk_bf16_f32 v4, v4, v5
	v_cvt_pk_bf16_f32 v5, v6, v7
	v_cvt_pk_bf16_f32 v0, v0, v1
	v_cvt_pk_bf16_f32 v1, v2, v3
	s_lshl_b64 s[4:5], s[16:17], 1
	ds_write2_b64 v10, v[12:13], v[8:9] offset0:96 offset1:100
	ds_write2_b64 v10, v[4:5], v[0:1] offset0:128 offset1:132
	s_add_u32 s18, s10, s4
	v_add_u32_e32 v4, 0x200, v30
	v_add_u32_e32 v8, 0x400, v30
	v_add_u32_e32 v12, 0x600, v30
	v_add_u32_e32 v16, 0x800, v30
	v_add_u32_e32 v30, 0xe00, v30
	s_addc_u32 s19, s19, s5
	v_ashrrev_i32_e32 v36, 5, v4
	v_ashrrev_i32_e32 v38, 5, v8
	v_ashrrev_i32_e32 v40, 5, v12
	v_ashrrev_i32_e32 v42, 5, v16
	v_ashrrev_i32_e32 v48, 5, v30
	v_mul_lo_u32 v0, v214, s14
	v_lshl_add_u64 v[32:33], s[18:19], 0, v[190:191]
	s_mov_b64 s[18:19], 0x5600000
	v_ashrrev_i32_e32 v37, 31, v36
	v_ashrrev_i32_e32 v39, 31, v38
	v_ashrrev_i32_e32 v41, 31, v40
	v_ashrrev_i32_e32 v43, 31, v42
	v_ashrrev_i32_e32 v49, 31, v48
	v_add3_u32 v0, 0, v130, v0
	v_lshl_add_u64 v[28:29], v[32:33], 0, s[18:19]
	v_lshlrev_b64 v[194:195], 11, v[36:37]
	v_lshlrev_b64 v[196:197], 11, v[38:39]
	v_lshlrev_b64 v[198:199], 11, v[40:41]
	v_lshlrev_b64 v[200:201], 11, v[42:43]
	v_lshlrev_b64 v[206:207], 11, v[48:49]
	s_waitcnt lgkmcnt(0)
	s_barrier
; #define LAS __attribute__((address_space(3)))
; __device__ __forceinline__ void stage_half(const bf16* g, LAS bf16* dst, int tid) {
;     ...
;     for (int i = 0; i < 8; ++i) { const int ch = tid + i * NT, r = ch >> 5, cc = ch & 31; t[i] = *(const v4u*)(g + (size_t)r * 1024 + cc * 8); }
; #pragma unroll
;     for (int i = 0; i < 8; ++i) { const int ch = tid + i * NT, r = ch >> 5, cc = ch & 31; *(LAS v4u*)(dst + r * XP + cc * 8) = t[i]; }
; }
; __device__ __forceinline__ void xattn_core(unsigned char* ws, LAS unsigned char* lds, int b, int hd, int qb, int tid, const bf16x8 (&qf)[16]) {
;     const int lane = tid & 63, wave = tid >> 6, r32 = lane & 31, hh = lane >> 5;
;     LAS bf16* L0 = (LAS bf16*)lds; LAS bf16* L1 = L0 + 128 * XP;
;     const bf16* Kg = (const bf16*)(ws + WS_KB) + (size_t)(b * 256) * 1024 + hd * 256;
;     const bf16* Vg = (const bf16*)(ws + WS_VT) + (size_t)(hd * 256) * 1024 + b * 256;
;     stage_half(Kg, L0, tid); stage_half(Kg + (size_t)128 * 1024, L1, tid);
;     const int q0 = b * SEQ + qb * 256 + 32 * wave;
;     __syncthreads();
;     f32x16 sacc[8];
; #pragma unroll
;     for (int mt = 0; mt < 8; ++mt) {
; #pragma unroll
;         for (int r = 0; r < 16; ++r) sacc[mt][r] = 0.f;
;         const LAS bf16* kp = (mt < 4 ? L0 : L1) + ((mt & 3) * 32 + r32) * XP + 8 * hh;
; #pragma unroll
;         for (int ds = 0; ds < 16; ++ds) { const bf16x8 kf = *(const LAS bf16x8*)(kp + 16 * ds); sacc[mt] = __builtin_amdgcn_mfma_f32_32x32x16_bf16(kf, qf[ds], sacc[mt], 0, 0, 0); } }
;     __device__ __forceinline__ void fused(f32x4 (&acc)[2][2][4][2], const pg8::Unit& u, int wr, int wc, int fr, int fq, LAS unsigned char* lds, int wid, int lane) const {
;     ...
;         const int r32 = lane & 31, hh = lane >> 5; bf16x8 qf[16];
; #pragma unroll
;         for (int ds = 0; ds < 16; ++ds) qf[ds] = *(const LAS bf16x8*)(QI + (32 * wid + r32) * XP + 16 * ds + 8 * hh);
	ds_read_b128 v[112:115], v0
	ds_read_b128 v[184:187], v0 offset:32
	ds_read_b128 v[180:183], v0 offset:64
	ds_read_b128 v[176:179], v0 offset:96
	ds_read_b128 v[172:175], v0 offset:128
	ds_read_b128 v[168:171], v0 offset:160
	ds_read_b128 v[164:167], v0 offset:192
	ds_read_b128 v[160:163], v0 offset:224
	ds_read_b128 v[156:159], v0 offset:256
	ds_read_b128 v[152:155], v0 offset:288
	ds_read_b128 v[148:151], v0 offset:320
	ds_read_b128 v[144:147], v0 offset:352
	ds_read_b128 v[140:143], v0 offset:384
	ds_read_b128 v[136:139], v0 offset:416
	ds_read_b128 v[132:135], v0 offset:448
	ds_read_b128 v[128:131], v0 offset:480
	v_lshl_add_u64 v[0:1], v[28:29], 0, v[192:193]
	v_lshl_add_u64 v[4:5], v[28:29], 0, v[194:195]
	v_lshl_add_u64 v[8:9], v[28:29], 0, v[196:197]
	v_lshl_add_u64 v[12:13], v[28:29], 0, v[198:199]
	v_lshl_add_u64 v[16:17], v[28:29], 0, v[200:201]
	v_lshl_add_u64 v[20:21], v[28:29], 0, v[202:203]
	v_lshl_add_u64 v[24:25], v[28:29], 0, v[204:205]
	v_lshl_add_u64 v[28:29], v[28:29], 0, v[206:207]
	s_waitcnt lgkmcnt(0)
	s_barrier
	s_mov_b64 s[18:19], 0x5640000
	v_lshl_add_u64 v[100:101], v[32:33], 0, s[18:19]
	v_lshl_add_u64 v[72:73], v[100:101], 0, v[192:193]
	v_lshl_add_u64 v[76:77], v[100:101], 0, v[194:195]
	v_lshl_add_u64 v[80:81], v[100:101], 0, v[196:197]
	v_lshl_add_u64 v[84:85], v[100:101], 0, v[198:199]
	v_lshl_add_u64 v[88:89], v[100:101], 0, v[200:201]
	v_lshl_add_u64 v[92:93], v[100:101], 0, v[202:203]
	v_lshl_add_u64 v[96:97], v[100:101], 0, v[204:205]
	v_lshl_add_u64 v[100:101], v[100:101], 0, v[206:207]
	global_load_dwordx4 v[0:3], v[0:1], off
	v_mul_lo_u32 v35, v36, s14
	global_load_dwordx4 v[4:7], v[4:5], off
	v_mul_lo_u32 v36, v38, s14
	global_load_dwordx4 v[8:11], v[8:9], off
	v_mul_lo_u32 v37, v40, s14
	global_load_dwordx4 v[12:15], v[12:13], off
	v_mul_lo_u32 v38, v42, s14
	global_load_dwordx4 v[16:19], v[16:17], off
	v_mul_lo_u32 v39, v44, s14
	global_load_dwordx4 v[20:23], v[20:21], off
	v_mul_lo_u32 v40, v46, s14
	global_load_dwordx4 v[24:27], v[24:25], off
	v_mul_lo_u32 v41, v48, s14
	global_load_dwordx4 v[28:31], v[28:29], off
	global_load_dwordx4 v[72:75], v[72:73], off
	global_load_dwordx4 v[76:79], v[76:77], off
	global_load_dwordx4 v[80:83], v[80:81], off
	global_load_dwordx4 v[84:87], v[84:85], off
	global_load_dwordx4 v[88:91], v[88:89], off
	global_load_dwordx4 v[92:95], v[92:93], off
	global_load_dwordx4 v[96:99], v[96:97], off
	global_load_dwordx4 v[100:103], v[100:101], off
	v_add_u32_e32 v222, v216, v35
	v_add_u32_e32 v221, v216, v36
	v_add_u32_e32 v220, v216, v37
	v_add_u32_e32 v219, v216, v38
	v_add_u32_e32 v218, v216, v39
	v_add_u32_e32 v217, v216, v40
	v_add_u32_e32 v216, v216, v41
	s_mov_b64 s[18:19], 0x5640000
	v_add_u32_e32 v224, v215, v35
	v_add_u32_e32 v225, v215, v36
	v_add_u32_e32 v226, v215, v37
	v_add_u32_e32 v227, v215, v38
	v_add_u32_e32 v228, v215, v39
	v_add_u32_e32 v229, v215, v40
	v_add_u32_e32 v215, v215, v41
	s_lshl_b64 s[16:17], s[16:17], 11
	s_add_u32 s16, s48, s16
	s_addc_u32 s17, s49, s17
	s_and_b32 s10, s13, 0xf00
	s_lshl_b64 s[6:7], s[6:7], 1
	s_add_u32 s16, s16, s6
	s_addc_u32 s17, s17, s7
	s_lshl_b32 s6, s15, 12
	s_mov_b64 s[14:15], 0x5800000
	s_mov_b32 s7, 0xff61b1e6
	s_or_b32 s6, s10, s6
	s_waitcnt vmcnt(15)
	ds_write_b128 v223, v[0:3]
	s_waitcnt vmcnt(14)
	ds_write_b128 v222, v[4:7]
	s_waitcnt vmcnt(13)
	ds_write_b128 v221, v[8:11]
	s_waitcnt vmcnt(12)
	ds_write_b128 v220, v[12:15]
	s_waitcnt vmcnt(11)
	ds_write_b128 v219, v[16:19]
	s_waitcnt vmcnt(10)
	ds_write_b128 v218, v[20:23]
	s_waitcnt vmcnt(9)
	ds_write_b128 v217, v[24:27]
	s_waitcnt vmcnt(8)
	ds_write_b128 v216, v[28:31]
	s_waitcnt vmcnt(7)
	ds_write_b128 v230, v[72:75]
	s_waitcnt vmcnt(6)
	ds_write_b128 v224, v[76:79]
	s_waitcnt vmcnt(5)
	ds_write_b128 v225, v[80:83]
	s_waitcnt vmcnt(4)
	ds_write_b128 v226, v[84:87]
	s_waitcnt vmcnt(3)
	ds_write_b128 v227, v[88:91]
	s_waitcnt vmcnt(2)
	ds_write_b128 v228, v[92:95]
	s_waitcnt vmcnt(1)
	ds_write_b128 v229, v[96:99]
	s_waitcnt vmcnt(0)
	ds_write_b128 v215, v[100:103]
	s_waitcnt lgkmcnt(0)
	s_barrier
	ds_read_b128 v[0:3], v213
	ds_read_b128 v[4:7], v213 offset:32
	s_waitcnt lgkmcnt(1)
	v_mfma_f32_32x32x16_bf16 v[96:111], v[0:3], v[112:115], 0
	ds_read_b128 v[0:3], v213 offset:64
	ds_read_b128 v[48:51], v213 offset:50720
	s_waitcnt lgkmcnt(2)
	v_mfma_f32_32x32x16_bf16 v[96:111], v[4:7], v[184:187], v[96:111]
	s_waitcnt lgkmcnt(1)
	v_mfma_f32_32x32x16_bf16 v[96:111], v[0:3], v[180:183], v[96:111]
	ds_read_b128 v[0:3], v213 offset:96
	s_waitcnt lgkmcnt(0)
	v_mfma_f32_32x32x16_bf16 v[96:111], v[0:3], v[176:179], v[96:111]
	ds_read_b128 v[0:3], v213 offset:128
	s_waitcnt lgkmcnt(0)
	v_mfma_f32_32x32x16_bf16 v[96:111], v[0:3], v[172:175], v[96:111]
	ds_read_b128 v[0:3], v213 offset:160
	s_waitcnt lgkmcnt(0)
	v_mfma_f32_32x32x16_bf16 v[96:111], v[0:3], v[168:171], v[96:111]
	ds_read_b128 v[0:3], v213 offset:192
	s_waitcnt lgkmcnt(0)
	v_mfma_f32_32x32x16_bf16 v[96:111], v[0:3], v[164:167], v[96:111]
	ds_read_b128 v[0:3], v213 offset:224
	s_waitcnt lgkmcnt(0)
	v_mfma_f32_32x32x16_bf16 v[96:111], v[0:3], v[160:163], v[96:111]
	ds_read_b128 v[0:3], v213 offset:256
	s_waitcnt lgkmcnt(0)
	v_mfma_f32_32x32x16_bf16 v[96:111], v[0:3], v[156:159], v[96:111]
	ds_read_b128 v[0:3], v213 offset:288
	s_waitcnt lgkmcnt(0)
	v_mfma_f32_32x32x16_bf16 v[96:111], v[0:3], v[152:155], v[96:111]
	ds_read_b128 v[0:3], v213 offset:320
	s_waitcnt lgkmcnt(0)
	v_mfma_f32_32x32x16_bf16 v[96:111], v[0:3], v[148:151], v[96:111]
	ds_read_b128 v[0:3], v213 offset:352
	s_waitcnt lgkmcnt(0)
	v_mfma_f32_32x32x16_bf16 v[96:111], v[0:3], v[144:147], v[96:111]
	ds_read_b128 v[0:3], v213 offset:384
	s_waitcnt lgkmcnt(0)
; #define LAS __attribute__((address_space(3)))
; __device__ __forceinline__ void xattn_core(unsigned char* ws, LAS unsigned char* lds, int b, int hd, int qb, int tid, const bf16x8 (&qf)[16]) {
;     ...
;     for (int mt = 0; mt < 8; ++mt) {
; #pragma unroll
;         for (int r = 0; r < 16; ++r) sacc[mt][r] = 0.f;
;         const LAS bf16* kp = (mt < 4 ? L0 : L1) + ((mt & 3) * 32 + r32) * XP + 8 * hh;
; #pragma unroll
;         for (int ds = 0; ds < 16; ++ds) { const bf16x8 kf = *(const LAS bf16x8*)(kp + 16 * ds); sacc[mt] = __builtin_amdgcn_mfma_f32_32x32x16_bf16(kf, qf[ds], sacc[mt], 0, 0, 0); } }
	v_mfma_f32_32x32x16_bf16 v[96:111], v[0:3], v[140:143], v[96:111]
	ds_read_b128 v[0:3], v213 offset:416
	s_waitcnt lgkmcnt(0)
	v_mfma_f32_32x32x16_bf16 v[96:111], v[0:3], v[136:139], v[96:111]
	ds_read_b128 v[0:3], v213 offset:448
	s_waitcnt lgkmcnt(0)
	v_mfma_f32_32x32x16_bf16 v[96:111], v[0:3], v[132:135], v[96:111]
	ds_read_b128 v[0:3], v213 offset:480
	s_waitcnt lgkmcnt(0)
	v_mfma_f32_32x32x16_bf16 v[96:111], v[0:3], v[128:131], v[96:111]
	ds_read_b128 v[0:3], v213 offset:16896
	s_waitcnt lgkmcnt(0)
	v_mfma_f32_32x32x16_bf16 v[32:47], v[0:3], v[112:115], 0
	ds_read_b128 v[0:3], v213 offset:16928
	s_waitcnt lgkmcnt(0)
	v_mfma_f32_32x32x16_bf16 v[32:47], v[0:3], v[184:187], v[32:47]
	ds_read_b128 v[0:3], v213 offset:16960
	s_waitcnt lgkmcnt(0)
	v_mfma_f32_32x32x16_bf16 v[32:47], v[0:3], v[180:183], v[32:47]
	ds_read_b128 v[0:3], v213 offset:16992
	s_waitcnt lgkmcnt(0)
	v_mfma_f32_32x32x16_bf16 v[32:47], v[0:3], v[176:179], v[32:47]
	ds_read_b128 v[0:3], v213 offset:17024
	s_waitcnt lgkmcnt(0)
	v_mfma_f32_32x32x16_bf16 v[32:47], v[0:3], v[172:175], v[32:47]
	ds_read_b128 v[0:3], v213 offset:17056
	s_waitcnt lgkmcnt(0)
	v_mfma_f32_32x32x16_bf16 v[32:47], v[0:3], v[168:171], v[32:47]
	ds_read_b128 v[0:3], v213 offset:17088
	s_waitcnt lgkmcnt(0)
	v_mfma_f32_32x32x16_bf16 v[32:47], v[0:3], v[164:167], v[32:47]
	ds_read_b128 v[0:3], v213 offset:17120
	s_waitcnt lgkmcnt(0)
	v_mfma_f32_32x32x16_bf16 v[32:47], v[0:3], v[160:163], v[32:47]
	ds_read_b128 v[0:3], v213 offset:17152
	s_waitcnt lgkmcnt(0)
	v_mfma_f32_32x32x16_bf16 v[32:47], v[0:3], v[156:159], v[32:47]
	ds_read_b128 v[0:3], v213 offset:17184
	s_waitcnt lgkmcnt(0)
	v_mfma_f32_32x32x16_bf16 v[32:47], v[0:3], v[152:155], v[32:47]
	ds_read_b128 v[0:3], v213 offset:17216
	s_waitcnt lgkmcnt(0)
	v_mfma_f32_32x32x16_bf16 v[32:47], v[0:3], v[148:151], v[32:47]
	ds_read_b128 v[0:3], v213 offset:17248
	s_waitcnt lgkmcnt(0)
	v_mfma_f32_32x32x16_bf16 v[32:47], v[0:3], v[144:147], v[32:47]
	ds_read_b128 v[0:3], v213 offset:17280
	s_waitcnt lgkmcnt(0)
	v_mfma_f32_32x32x16_bf16 v[32:47], v[0:3], v[140:143], v[32:47]
	ds_read_b128 v[0:3], v213 offset:17312
	s_waitcnt lgkmcnt(0)
	v_mfma_f32_32x32x16_bf16 v[32:47], v[0:3], v[136:139], v[32:47]
	ds_read_b128 v[0:3], v213 offset:17344
	s_waitcnt lgkmcnt(0)
	v_mfma_f32_32x32x16_bf16 v[32:47], v[0:3], v[132:135], v[32:47]
	ds_read_b128 v[0:3], v213 offset:17376
	s_waitcnt lgkmcnt(0)
	v_mfma_f32_32x32x16_bf16 v[32:47], v[0:3], v[128:131], v[32:47]
	ds_read_b128 v[0:3], v213 offset:33792
	s_waitcnt lgkmcnt(0)
	v_mfma_f32_32x32x16_bf16 v[16:31], v[0:3], v[112:115], 0
	ds_read_b128 v[0:3], v213 offset:33824
	s_waitcnt lgkmcnt(0)
	v_mfma_f32_32x32x16_bf16 v[16:31], v[0:3], v[184:187], v[16:31]
	ds_read_b128 v[0:3], v213 offset:33856
	s_waitcnt lgkmcnt(0)
	v_mfma_f32_32x32x16_bf16 v[16:31], v[0:3], v[180:183], v[16:31]
	ds_read_b128 v[0:3], v213 offset:33888
	s_waitcnt lgkmcnt(0)
	v_mfma_f32_32x32x16_bf16 v[16:31], v[0:3], v[176:179], v[16:31]
	ds_read_b128 v[0:3], v213 offset:33920
	s_waitcnt lgkmcnt(0)
	v_mfma_f32_32x32x16_bf16 v[16:31], v[0:3], v[172:175], v[16:31]
	ds_read_b128 v[0:3], v213 offset:33952
	s_waitcnt lgkmcnt(0)
	v_mfma_f32_32x32x16_bf16 v[16:31], v[0:3], v[168:171], v[16:31]
	ds_read_b128 v[0:3], v213 offset:33984
	s_waitcnt lgkmcnt(0)
	v_mfma_f32_32x32x16_bf16 v[16:31], v[0:3], v[164:167], v[16:31]
	ds_read_b128 v[0:3], v213 offset:34016
	s_waitcnt lgkmcnt(0)
	v_mfma_f32_32x32x16_bf16 v[16:31], v[0:3], v[160:163], v[16:31]
	ds_read_b128 v[0:3], v213 offset:34048
	s_waitcnt lgkmcnt(0)
	v_mfma_f32_32x32x16_bf16 v[16:31], v[0:3], v[156:159], v[16:31]
	ds_read_b128 v[0:3], v213 offset:34080
	s_waitcnt lgkmcnt(0)
	v_mfma_f32_32x32x16_bf16 v[16:31], v[0:3], v[152:155], v[16:31]
	ds_read_b128 v[0:3], v213 offset:34112
	s_waitcnt lgkmcnt(0)
	v_mfma_f32_32x32x16_bf16 v[16:31], v[0:3], v[148:151], v[16:31]
	ds_read_b128 v[0:3], v213 offset:34144
	s_waitcnt lgkmcnt(0)
	v_mfma_f32_32x32x16_bf16 v[16:31], v[0:3], v[144:147], v[16:31]
	ds_read_b128 v[0:3], v213 offset:34176
	s_waitcnt lgkmcnt(0)
	v_mfma_f32_32x32x16_bf16 v[16:31], v[0:3], v[140:143], v[16:31]
	ds_read_b128 v[0:3], v213 offset:34208
	s_waitcnt lgkmcnt(0)
	v_mfma_f32_32x32x16_bf16 v[16:31], v[0:3], v[136:139], v[16:31]
	ds_read_b128 v[0:3], v213 offset:34240
	s_waitcnt lgkmcnt(0)
	v_mfma_f32_32x32x16_bf16 v[16:31], v[0:3], v[132:135], v[16:31]
	ds_read_b128 v[0:3], v213 offset:34272
	s_waitcnt lgkmcnt(0)
	v_mfma_f32_32x32x16_bf16 v[16:31], v[0:3], v[128:131], v[16:31]
	ds_read_b128 v[0:3], v213 offset:50688
	s_waitcnt lgkmcnt(0)
	v_mfma_f32_32x32x16_bf16 v[0:15], v[0:3], v[112:115], 0
	v_mfma_f32_32x32x16_bf16 v[0:15], v[48:51], v[184:187], v[0:15]
	ds_read_b128 v[48:51], v213 offset:50752
	s_waitcnt lgkmcnt(0)
	v_mfma_f32_32x32x16_bf16 v[0:15], v[48:51], v[180:183], v[0:15]
	ds_read_b128 v[48:51], v213 offset:50784
	s_waitcnt lgkmcnt(0)
	v_mfma_f32_32x32x16_bf16 v[0:15], v[48:51], v[176:179], v[0:15]
	ds_read_b128 v[48:51], v213 offset:50816
	s_waitcnt lgkmcnt(0)
	v_mfma_f32_32x32x16_bf16 v[0:15], v[48:51], v[172:175], v[0:15]
	ds_read_b128 v[48:51], v213 offset:50848
	s_waitcnt lgkmcnt(0)
	v_mfma_f32_32x32x16_bf16 v[0:15], v[48:51], v[168:171], v[0:15]
	ds_read_b128 v[48:51], v213 offset:50880
	s_waitcnt lgkmcnt(0)
	v_mfma_f32_32x32x16_bf16 v[0:15], v[48:51], v[164:167], v[0:15]
	ds_read_b128 v[48:51], v213 offset:50912
	s_waitcnt lgkmcnt(0)
	v_mfma_f32_32x32x16_bf16 v[0:15], v[48:51], v[160:163], v[0:15]
	ds_read_b128 v[48:51], v213 offset:50944
	s_waitcnt lgkmcnt(0)
	v_mfma_f32_32x32x16_bf16 v[0:15], v[48:51], v[156:159], v[0:15]
	ds_read_b128 v[48:51], v213 offset:50976
	s_waitcnt lgkmcnt(0)
; #define LAS __attribute__((address_space(3)))
; __device__ __forceinline__ void xattn_core(unsigned char* ws, LAS unsigned char* lds, int b, int hd, int qb, int tid, const bf16x8 (&qf)[16]) {
;     ...
;     for (int mt = 0; mt < 8; ++mt) {
; #pragma unroll
;         for (int r = 0; r < 16; ++r) sacc[mt][r] = 0.f;
;         const LAS bf16* kp = (mt < 4 ? L0 : L1) + ((mt & 3) * 32 + r32) * XP + 8 * hh;
; #pragma unroll
;         for (int ds = 0; ds < 16; ++ds) { const bf16x8 kf = *(const LAS bf16x8*)(kp + 16 * ds); sacc[mt] = __builtin_amdgcn_mfma_f32_32x32x16_bf16(kf, qf[ds], sacc[mt], 0, 0, 0); } }
	v_mfma_f32_32x32x16_bf16 v[0:15], v[48:51], v[152:155], v[0:15]
	ds_read_b128 v[48:51], v213 offset:51008
	s_waitcnt lgkmcnt(0)
	v_mfma_f32_32x32x16_bf16 v[0:15], v[48:51], v[148:151], v[0:15]
	ds_read_b128 v[48:51], v213 offset:51040
	s_waitcnt lgkmcnt(0)
	v_mfma_f32_32x32x16_bf16 v[0:15], v[48:51], v[144:147], v[0:15]
	ds_read_b128 v[48:51], v213 offset:51072
	s_waitcnt lgkmcnt(0)
	v_mfma_f32_32x32x16_bf16 v[0:15], v[48:51], v[140:143], v[0:15]
	ds_read_b128 v[48:51], v213 offset:51104
	s_waitcnt lgkmcnt(0)
	v_mfma_f32_32x32x16_bf16 v[0:15], v[48:51], v[136:139], v[0:15]
	ds_read_b128 v[48:51], v213 offset:51136
	s_waitcnt lgkmcnt(0)
	v_mfma_f32_32x32x16_bf16 v[0:15], v[48:51], v[132:135], v[0:15]
	ds_read_b128 v[48:51], v213 offset:51168
	s_waitcnt lgkmcnt(0)
	v_mfma_f32_32x32x16_bf16 v[0:15], v[48:51], v[128:131], v[0:15]
	ds_read_b128 v[48:51], v68
	ds_read_b128 v[64:67], v68 offset:32
	s_waitcnt lgkmcnt(1)
	v_mfma_f32_32x32x16_bf16 v[48:63], v[48:51], v[112:115], 0
	s_waitcnt lgkmcnt(0)
	v_mfma_f32_32x32x16_bf16 v[48:63], v[64:67], v[184:187], v[48:63]
	ds_read_b128 v[64:67], v68 offset:64
	s_waitcnt lgkmcnt(0)
	v_mfma_f32_32x32x16_bf16 v[48:63], v[64:67], v[180:183], v[48:63]
	ds_read_b128 v[64:67], v68 offset:96
	s_waitcnt lgkmcnt(0)
	v_mfma_f32_32x32x16_bf16 v[48:63], v[64:67], v[176:179], v[48:63]
	ds_read_b128 v[64:67], v68 offset:128
	s_waitcnt lgkmcnt(0)
	v_mfma_f32_32x32x16_bf16 v[48:63], v[64:67], v[172:175], v[48:63]
	ds_read_b128 v[64:67], v68 offset:160
	s_waitcnt lgkmcnt(0)
	v_mfma_f32_32x32x16_bf16 v[48:63], v[64:67], v[168:171], v[48:63]
	ds_read_b128 v[64:67], v68 offset:192
	s_waitcnt lgkmcnt(0)
	v_mfma_f32_32x32x16_bf16 v[48:63], v[64:67], v[164:167], v[48:63]
	ds_read_b128 v[64:67], v68 offset:224
	s_waitcnt lgkmcnt(0)
	v_mfma_f32_32x32x16_bf16 v[48:63], v[64:67], v[160:163], v[48:63]
	ds_read_b128 v[64:67], v68 offset:256
	s_waitcnt lgkmcnt(0)
	v_mfma_f32_32x32x16_bf16 v[48:63], v[64:67], v[156:159], v[48:63]
	ds_read_b128 v[64:67], v68 offset:288
	s_waitcnt lgkmcnt(0)
	v_mfma_f32_32x32x16_bf16 v[48:63], v[64:67], v[152:155], v[48:63]
	ds_read_b128 v[64:67], v68 offset:320
	s_waitcnt lgkmcnt(0)
	v_mfma_f32_32x32x16_bf16 v[48:63], v[64:67], v[148:151], v[48:63]
	ds_read_b128 v[64:67], v68 offset:352
	s_waitcnt lgkmcnt(0)
	v_mfma_f32_32x32x16_bf16 v[48:63], v[64:67], v[144:147], v[48:63]
	ds_read_b128 v[64:67], v68 offset:384
	s_waitcnt lgkmcnt(0)
	v_mfma_f32_32x32x16_bf16 v[48:63], v[64:67], v[140:143], v[48:63]
	ds_read_b128 v[64:67], v68 offset:416
	s_waitcnt lgkmcnt(0)
	v_mfma_f32_32x32x16_bf16 v[48:63], v[64:67], v[136:139], v[48:63]
	ds_read_b128 v[64:67], v68 offset:448
	s_waitcnt lgkmcnt(0)
	v_mfma_f32_32x32x16_bf16 v[48:63], v[64:67], v[132:135], v[48:63]
	ds_read_b128 v[64:67], v68 offset:480
	s_waitcnt lgkmcnt(0)
	v_mfma_f32_32x32x16_bf16 v[48:63], v[64:67], v[128:131], v[48:63]
	ds_read_b128 v[64:67], v189 offset:16896
	ds_read_b128 v[68:71], v189 offset:16928
	ds_read_b128 v[116:119], v189 offset:33824
	ds_read_b128 v[232:235], v189 offset:50720
	s_waitcnt lgkmcnt(3)
	v_mfma_f32_32x32x16_bf16 v[80:95], v[64:67], v[112:115], 0
	ds_read_b128 v[64:67], v189 offset:16960
	s_waitcnt lgkmcnt(3)
	v_mfma_f32_32x32x16_bf16 v[80:95], v[68:71], v[184:187], v[80:95]
	s_waitcnt lgkmcnt(0)
	v_mfma_f32_32x32x16_bf16 v[80:95], v[64:67], v[180:183], v[80:95]
	ds_read_b128 v[64:67], v189 offset:16992
	s_waitcnt lgkmcnt(0)
	v_mfma_f32_32x32x16_bf16 v[80:95], v[64:67], v[176:179], v[80:95]
	ds_read_b128 v[64:67], v189 offset:17024
	s_waitcnt lgkmcnt(0)
	v_mfma_f32_32x32x16_bf16 v[80:95], v[64:67], v[172:175], v[80:95]
	ds_read_b128 v[64:67], v189 offset:17056
	s_waitcnt lgkmcnt(0)
	v_mfma_f32_32x32x16_bf16 v[80:95], v[64:67], v[168:171], v[80:95]
	ds_read_b128 v[64:67], v189 offset:17088
	s_waitcnt lgkmcnt(0)
	v_mfma_f32_32x32x16_bf16 v[80:95], v[64:67], v[164:167], v[80:95]
	ds_read_b128 v[64:67], v189 offset:17120
	s_waitcnt lgkmcnt(0)
	v_mfma_f32_32x32x16_bf16 v[80:95], v[64:67], v[160:163], v[80:95]
	ds_read_b128 v[64:67], v189 offset:17152
	s_waitcnt lgkmcnt(0)
	v_mfma_f32_32x32x16_bf16 v[80:95], v[64:67], v[156:159], v[80:95]
	ds_read_b128 v[64:67], v189 offset:17184
	s_waitcnt lgkmcnt(0)
	v_mfma_f32_32x32x16_bf16 v[80:95], v[64:67], v[152:155], v[80:95]
	ds_read_b128 v[64:67], v189 offset:17216
	s_waitcnt lgkmcnt(0)
	v_mfma_f32_32x32x16_bf16 v[80:95], v[64:67], v[148:151], v[80:95]
	ds_read_b128 v[64:67], v189 offset:17248
	s_waitcnt lgkmcnt(0)
	v_mfma_f32_32x32x16_bf16 v[80:95], v[64:67], v[144:147], v[80:95]
	ds_read_b128 v[64:67], v189 offset:17280
	s_waitcnt lgkmcnt(0)
	v_mfma_f32_32x32x16_bf16 v[80:95], v[64:67], v[140:143], v[80:95]
	ds_read_b128 v[64:67], v189 offset:17312
	s_waitcnt lgkmcnt(0)
	v_mfma_f32_32x32x16_bf16 v[80:95], v[64:67], v[136:139], v[80:95]
	ds_read_b128 v[64:67], v189 offset:17344
	s_waitcnt lgkmcnt(0)
	v_mfma_f32_32x32x16_bf16 v[80:95], v[64:67], v[132:135], v[80:95]
	ds_read_b128 v[64:67], v189 offset:17376
	s_waitcnt lgkmcnt(0)
	v_mfma_f32_32x32x16_bf16 v[80:95], v[64:67], v[128:131], v[80:95]
	ds_read_b128 v[64:67], v189 offset:33792
	s_waitcnt lgkmcnt(0)
	v_mfma_f32_32x32x16_bf16 v[64:79], v[64:67], v[112:115], 0
	v_mfma_f32_32x32x16_bf16 v[64:79], v[116:119], v[184:187], v[64:79]
	ds_read_b128 v[116:119], v189 offset:33856
	s_waitcnt lgkmcnt(0)
	v_mfma_f32_32x32x16_bf16 v[64:79], v[116:119], v[180:183], v[64:79]
	ds_read_b128 v[116:119], v189 offset:33888
	s_waitcnt lgkmcnt(0)
	v_mfma_f32_32x32x16_bf16 v[64:79], v[116:119], v[176:179], v[64:79]
	ds_read_b128 v[116:119], v189 offset:33920
	s_waitcnt lgkmcnt(0)
	v_mfma_f32_32x32x16_bf16 v[64:79], v[116:119], v[172:175], v[64:79]
	ds_read_b128 v[116:119], v189 offset:33952
	s_waitcnt lgkmcnt(0)
; #define LAS __attribute__((address_space(3)))
; __device__ __forceinline__ void stage_half(const bf16* g, LAS bf16* dst, int tid) {
;     v4u t[8];
; #pragma unroll
;     for (int i = 0; i < 8; ++i) { const int ch = tid + i * NT, r = ch >> 5, cc = ch & 31; t[i] = *(const v4u*)(g + (size_t)r * 1024 + cc * 8); }
; #pragma unroll
;     for (int i = 0; i < 8; ++i) { const int ch = tid + i * NT, r = ch >> 5, cc = ch & 31; *(LAS v4u*)(dst + r * XP + cc * 8) = t[i]; }
; }
; __device__ __forceinline__ void xattn_core(unsigned char* ws, LAS unsigned char* lds, int b, int hd, int qb, int tid, const bf16x8 (&qf)[16]) {
;     ...
;     for (int mt = 0; mt < 8; ++mt) {
; #pragma unroll
;         for (int r = 0; r < 16; ++r) sacc[mt][r] = 0.f;
;         const LAS bf16* kp = (mt < 4 ? L0 : L1) + ((mt & 3) * 32 + r32) * XP + 8 * hh;
; #pragma unroll
;         for (int ds = 0; ds < 16; ++ds) { const bf16x8 kf = *(const LAS bf16x8*)(kp + 16 * ds); sacc[mt] = __builtin_amdgcn_mfma_f32_32x32x16_bf16(kf, qf[ds], sacc[mt], 0, 0, 0); } }
;     __syncthreads();
;     stage_half(Vg, L0, tid); stage_half(Vg + (size_t)128 * 1024, L1, tid);
	v_mfma_f32_32x32x16_bf16 v[64:79], v[116:119], v[168:171], v[64:79]
	ds_read_b128 v[116:119], v189 offset:33984
	s_waitcnt lgkmcnt(0)
	v_mfma_f32_32x32x16_bf16 v[64:79], v[116:119], v[164:167], v[64:79]
	ds_read_b128 v[116:119], v189 offset:34016
	s_waitcnt lgkmcnt(0)
	v_mfma_f32_32x32x16_bf16 v[64:79], v[116:119], v[160:163], v[64:79]
	ds_read_b128 v[116:119], v189 offset:34048
	s_waitcnt lgkmcnt(0)
	v_mfma_f32_32x32x16_bf16 v[64:79], v[116:119], v[156:159], v[64:79]
	ds_read_b128 v[116:119], v189 offset:34080
	s_waitcnt lgkmcnt(0)
	v_mfma_f32_32x32x16_bf16 v[64:79], v[116:119], v[152:155], v[64:79]
	ds_read_b128 v[116:119], v189 offset:34112
	s_waitcnt lgkmcnt(0)
	v_mfma_f32_32x32x16_bf16 v[64:79], v[116:119], v[148:151], v[64:79]
	ds_read_b128 v[116:119], v189 offset:34144
	s_waitcnt lgkmcnt(0)
	v_mfma_f32_32x32x16_bf16 v[64:79], v[116:119], v[144:147], v[64:79]
	ds_read_b128 v[116:119], v189 offset:34176
	s_waitcnt lgkmcnt(0)
	v_mfma_f32_32x32x16_bf16 v[64:79], v[116:119], v[140:143], v[64:79]
	ds_read_b128 v[116:119], v189 offset:34208
	s_waitcnt lgkmcnt(0)
	v_mfma_f32_32x32x16_bf16 v[64:79], v[116:119], v[136:139], v[64:79]
	ds_read_b128 v[116:119], v189 offset:34240
	s_waitcnt lgkmcnt(0)
	v_mfma_f32_32x32x16_bf16 v[64:79], v[116:119], v[132:135], v[64:79]
	ds_read_b128 v[116:119], v189 offset:34272
	s_waitcnt lgkmcnt(0)
	v_mfma_f32_32x32x16_bf16 v[64:79], v[116:119], v[128:131], v[64:79]
	ds_read_b128 v[116:119], v189 offset:50688
	s_waitcnt lgkmcnt(0)
	v_mfma_f32_32x32x16_bf16 v[112:127], v[116:119], v[112:115], 0
	v_mfma_f32_32x32x16_bf16 v[112:127], v[232:235], v[184:187], v[112:127]
	ds_read_b128 v[184:187], v189 offset:50752
	s_waitcnt lgkmcnt(0)
	v_mfma_f32_32x32x16_bf16 v[112:127], v[184:187], v[180:183], v[112:127]
	ds_read_b128 v[180:183], v189 offset:50784
	s_waitcnt lgkmcnt(0)
	v_mfma_f32_32x32x16_bf16 v[112:127], v[180:183], v[176:179], v[112:127]
	ds_read_b128 v[176:179], v189 offset:50816
	s_waitcnt lgkmcnt(0)
	v_mfma_f32_32x32x16_bf16 v[112:127], v[176:179], v[172:175], v[112:127]
	ds_read_b128 v[172:175], v189 offset:50848
	s_waitcnt lgkmcnt(0)
	v_mfma_f32_32x32x16_bf16 v[112:127], v[172:175], v[168:171], v[112:127]
	ds_read_b128 v[168:171], v189 offset:50880
	s_waitcnt lgkmcnt(0)
	v_mfma_f32_32x32x16_bf16 v[112:127], v[168:171], v[164:167], v[112:127]
	ds_read_b128 v[164:167], v189 offset:50912
	s_waitcnt lgkmcnt(0)
	v_mfma_f32_32x32x16_bf16 v[112:127], v[164:167], v[160:163], v[112:127]
	ds_read_b128 v[160:163], v189 offset:50944
	s_waitcnt lgkmcnt(0)
	v_mfma_f32_32x32x16_bf16 v[112:127], v[160:163], v[156:159], v[112:127]
	ds_read_b128 v[156:159], v189 offset:50976
	v_lshl_add_u64 v[160:161], s[16:17], 0, v[190:191]
	s_waitcnt lgkmcnt(0)
	v_mfma_f32_32x32x16_bf16 v[112:127], v[156:159], v[152:155], v[112:127]
	ds_read_b128 v[152:155], v189 offset:51008
	v_lshl_add_u64 v[156:157], v[160:161], 0, s[14:15]
	s_mov_b64 s[14:15], 0x5840000
	s_waitcnt lgkmcnt(0)
	v_mfma_f32_32x32x16_bf16 v[112:127], v[152:155], v[148:151], v[112:127]
	ds_read_b128 v[148:151], v189 offset:51040
	v_lshl_add_u64 v[152:153], v[156:157], 0, v[204:205]
	s_waitcnt lgkmcnt(0)
	v_mfma_f32_32x32x16_bf16 v[112:127], v[148:151], v[144:147], v[112:127]
	ds_read_b128 v[144:147], v189 offset:51072
	v_lshl_add_u64 v[148:149], v[156:157], 0, v[202:203]
	s_waitcnt lgkmcnt(0)
	v_mfma_f32_32x32x16_bf16 v[112:127], v[144:147], v[140:143], v[112:127]
	ds_read_b128 v[140:143], v189 offset:51104
	v_lshl_add_u64 v[144:145], v[156:157], 0, v[200:201]
	s_waitcnt lgkmcnt(0)
	v_mfma_f32_32x32x16_bf16 v[112:127], v[140:143], v[136:139], v[112:127]
	ds_read_b128 v[136:139], v189 offset:51136
	v_lshl_add_u64 v[140:141], v[156:157], 0, v[198:199]
	s_waitcnt lgkmcnt(0)
	v_mfma_f32_32x32x16_bf16 v[112:127], v[136:139], v[132:135], v[112:127]
	ds_read_b128 v[132:135], v189 offset:51168
	s_waitcnt lgkmcnt(0)
	s_barrier
	v_lshl_add_u64 v[136:137], v[156:157], 0, v[196:197]
	global_load_dwordx4 v[136:139], v[136:137], off
	v_mov_b32_e32 v189, v191
	v_mfma_f32_32x32x16_bf16 v[112:127], v[132:135], v[128:131], v[112:127]
	v_lshl_add_u64 v[128:129], v[156:157], 0, v[192:193]
	global_load_dwordx4 v[128:131], v[128:129], off
	v_lshl_add_u64 v[132:133], v[156:157], 0, v[194:195]
	global_load_dwordx4 v[132:135], v[132:133], off
	v_lshl_add_u64 v[156:157], v[156:157], 0, v[206:207]
	global_load_dwordx4 v[140:143], v[140:141], off
	s_nop 0
	global_load_dwordx4 v[144:147], v[144:145], off
	s_nop 0
	global_load_dwordx4 v[148:151], v[148:149], off
	s_nop 0
	global_load_dwordx4 v[152:155], v[152:153], off
	s_nop 0
	global_load_dwordx4 v[156:159], v[156:157], off
	s_waitcnt vmcnt(6)
	ds_write_b128 v223, v[128:131]
	s_waitcnt vmcnt(5)
	ds_write_b128 v222, v[132:135]
	ds_write_b128 v221, v[136:139]
	s_waitcnt vmcnt(4)
	ds_write_b128 v220, v[140:143]
	s_waitcnt vmcnt(3)
	ds_write_b128 v219, v[144:147]
	s_waitcnt vmcnt(2)
	ds_write_b128 v218, v[148:151]
	s_waitcnt vmcnt(1)
	ds_write_b128 v217, v[152:155]
	s_waitcnt vmcnt(0)
	ds_write_b128 v216, v[156:159]
	v_lshl_add_u64 v[156:157], v[160:161], 0, s[14:15]
	v_lshl_add_u64 v[128:129], v[156:157], 0, v[192:193]
	global_load_dwordx4 v[128:131], v[128:129], off
	v_lshl_add_u64 v[132:133], v[156:157], 0, v[194:195]
	global_load_dwordx4 v[132:135], v[132:133], off
	v_lshl_add_u64 v[136:137], v[156:157], 0, v[196:197]
	global_load_dwordx4 v[136:139], v[136:137], off
	v_lshl_add_u64 v[140:141], v[156:157], 0, v[198:199]
	global_load_dwordx4 v[140:143], v[140:141], off
	v_lshl_add_u64 v[144:145], v[156:157], 0, v[200:201]
	global_load_dwordx4 v[144:147], v[144:145], off
	v_lshl_add_u64 v[148:149], v[156:157], 0, v[202:203]
	global_load_dwordx4 v[148:151], v[148:149], off
	v_lshl_add_u64 v[152:153], v[156:157], 0, v[204:205]
	global_load_dwordx4 v[152:155], v[152:153], off
	v_lshl_add_u64 v[156:157], v[156:157], 0, v[206:207]
	global_load_dwordx4 v[156:159], v[156:157], off
	s_waitcnt vmcnt(7)
; #define LAS __attribute__((address_space(3)))
; __device__ __forceinline__ void stage_half(const bf16* g, LAS bf16* dst, int tid) {
;     ...
;     for (int i = 0; i < 8; ++i) { const int ch = tid + i * NT, r = ch >> 5, cc = ch & 31; t[i] = *(const v4u*)(g + (size_t)r * 1024 + cc * 8); }
; #pragma unroll
;     for (int i = 0; i < 8; ++i) { const int ch = tid + i * NT, r = ch >> 5, cc = ch & 31; *(LAS v4u*)(dst + r * XP + cc * 8) = t[i]; }
; __device__ __forceinline__ void xattn_core(unsigned char* ws, LAS unsigned char* lds, int b, int hd, int qb, int tid, const bf16x8 (&qf)[16]) {
;     ...
;     float mx = -3.0e38f;
; #pragma unroll
;     for (int mt = 0; mt < 8; ++mt)
; #pragma unroll
;         for (int r = 0; r < 16; ++r) mx = fmaxf(mx, sacc[mt][r]);
;     mx = fmaxf(mx, __shfl_xor(mx, 32));
;     float sum = 0.f; bf16x8 pf[8][2];
; #pragma unroll
;     for (int mt = 0; mt < 8; ++mt) {
;         float e[16];
; #pragma unroll
;         for (int r = 0; r < 16; ++r) { e[r] = __expf(sacc[mt][r] - mx); sum += e[r]; }
	ds_write_b128 v230, v[128:131]
	s_waitcnt vmcnt(6)
	ds_write_b128 v224, v[132:135]
	s_waitcnt vmcnt(5)
	ds_write_b128 v225, v[136:139]
	s_waitcnt vmcnt(4)
	ds_write_b128 v226, v[140:143]
	s_waitcnt vmcnt(3)
	ds_write_b128 v227, v[144:147]
	s_waitcnt vmcnt(2)
	ds_write_b128 v228, v[148:151]
	s_waitcnt vmcnt(1)
	ds_write_b128 v229, v[152:155]
	s_waitcnt vmcnt(0)
	ds_write_b128 v215, v[156:159]
	v_max3_f32 v128, v96, s7, v97
	v_max3_f32 v128, v128, v98, v99
	v_max3_f32 v128, v128, v100, v101
	v_max3_f32 v128, v128, v102, v103
	v_max3_f32 v128, v128, v104, v105
	v_max3_f32 v128, v128, v106, v107
	v_max3_f32 v128, v128, v108, v109
	v_max3_f32 v128, v128, v110, v111
	v_max3_f32 v128, v128, v32, v33
	v_max3_f32 v128, v128, v34, v35
	v_max3_f32 v128, v128, v36, v37
	v_max3_f32 v128, v128, v38, v39
	v_max3_f32 v128, v128, v40, v41
	v_max3_f32 v128, v128, v42, v43
	v_max3_f32 v128, v128, v44, v45
	v_max3_f32 v128, v128, v46, v47
	v_max3_f32 v128, v128, v16, v17
	v_max3_f32 v128, v128, v18, v19
	v_max3_f32 v128, v128, v20, v21
	v_max3_f32 v128, v128, v22, v23
	v_max3_f32 v128, v128, v24, v25
	v_max3_f32 v128, v128, v26, v27
	v_max3_f32 v128, v128, v28, v29
	v_max3_f32 v128, v128, v30, v31
	v_max3_f32 v128, v128, v0, v1
	v_max3_f32 v128, v128, v2, v3
	v_max3_f32 v128, v128, v4, v5
	v_max3_f32 v128, v128, v6, v7
	v_max3_f32 v128, v128, v8, v9
	v_max3_f32 v128, v128, v10, v11
	v_max3_f32 v128, v128, v12, v13
	v_max3_f32 v128, v128, v14, v15
	v_max3_f32 v128, v128, v48, v49
	v_max3_f32 v128, v128, v50, v51
	v_max3_f32 v128, v128, v52, v53
	v_max3_f32 v128, v128, v54, v55
	v_max3_f32 v128, v128, v56, v57
	v_max3_f32 v128, v128, v58, v59
	v_max3_f32 v128, v128, v60, v61
	v_max3_f32 v128, v128, v62, v63
	v_max3_f32 v128, v128, v80, v81
	v_max3_f32 v128, v128, v82, v83
	v_max3_f32 v128, v128, v84, v85
	v_max3_f32 v128, v128, v86, v87
	v_max3_f32 v128, v128, v88, v89
	v_max3_f32 v128, v128, v90, v91
	v_max3_f32 v128, v128, v92, v93
	v_max3_f32 v128, v128, v94, v95
	v_max3_f32 v128, v128, v64, v65
	v_max3_f32 v128, v128, v66, v67
	v_max3_f32 v128, v128, v68, v69
	v_max3_f32 v128, v128, v70, v71
	v_max3_f32 v128, v128, v72, v73
	v_max3_f32 v128, v128, v74, v75
	v_max3_f32 v128, v128, v76, v77
	v_max3_f32 v128, v128, v78, v79
	v_max3_f32 v128, v128, v112, v113
	v_max3_f32 v128, v128, v114, v115
	v_max3_f32 v128, v128, v116, v117
	v_max3_f32 v128, v128, v118, v119
	v_max3_f32 v128, v128, v120, v121
	v_max3_f32 v128, v128, v122, v123
	v_max3_f32 v128, v128, v124, v125
	v_max3_f32 v129, v128, v126, v127
	v_mbcnt_lo_u32_b32 v128, -1, 0
	v_mbcnt_hi_u32_b32 v128, -1, v128
	v_and_b32_e32 v131, 64, v128
	v_xor_b32_e32 v130, 32, v128
	v_add_u32_e32 v131, 64, v131
	v_cmp_lt_i32_e32 vcc, v130, v131
	s_waitcnt lgkmcnt(0)
	s_barrier
	v_cndmask_b32_e32 v128, v128, v130, vcc
	v_lshlrev_b32_e32 v128, 2, v128
	ds_bpermute_b32 v130, v128, v129
	s_waitcnt lgkmcnt(0)
	v_max_f32_e32 v130, v130, v130
	v_max_f32_e32 v129, v129, v130
	v_sub_f32_e32 v96, v96, v129
	v_mul_f32_e32 v96, 0x3fb8aa3b, v96
	v_exp_f32_e32 v130, v96
	v_sub_f32_e32 v96, v97, v129
	v_mul_f32_e32 v96, 0x3fb8aa3b, v96
	v_exp_f32_e32 v131, v96
	v_sub_f32_e32 v96, v98, v129
	v_mul_f32_e32 v96, 0x3fb8aa3b, v96
	v_exp_f32_e32 v132, v96
	v_sub_f32_e32 v96, v99, v129
	v_mul_f32_e32 v96, 0x3fb8aa3b, v96
	v_exp_f32_e32 v133, v96
	v_sub_f32_e32 v96, v100, v129
	v_mul_f32_e32 v96, 0x3fb8aa3b, v96
	v_exp_f32_e32 v134, v96
	v_sub_f32_e32 v96, v101, v129
	v_mul_f32_e32 v96, 0x3fb8aa3b, v96
	v_exp_f32_e32 v135, v96
	v_sub_f32_e32 v96, v102, v129
	v_mul_f32_e32 v96, 0x3fb8aa3b, v96
	v_exp_f32_e32 v136, v96
	v_sub_f32_e32 v96, v103, v129
	v_mul_f32_e32 v96, 0x3fb8aa3b, v96
	v_exp_f32_e32 v137, v96
	v_sub_f32_e32 v96, v104, v129
	v_mul_f32_e32 v96, 0x3fb8aa3b, v96
	v_exp_f32_e32 v104, v96
	v_sub_f32_e32 v96, v105, v129
	v_mul_f32_e32 v96, 0x3fb8aa3b, v96
	v_exp_f32_e32 v105, v96
	v_sub_f32_e32 v96, v106, v129
	v_mul_f32_e32 v96, 0x3fb8aa3b, v96
	v_exp_f32_e32 v106, v96
	v_sub_f32_e32 v96, v107, v129
	v_mul_f32_e32 v96, 0x3fb8aa3b, v96
	v_exp_f32_e32 v107, v96
	v_sub_f32_e32 v96, v108, v129
	v_mul_f32_e32 v96, 0x3fb8aa3b, v96
	v_exp_f32_e32 v108, v96
	v_sub_f32_e32 v96, v109, v129
	v_mul_f32_e32 v96, 0x3fb8aa3b, v96
	v_exp_f32_e32 v109, v96
	v_sub_f32_e32 v96, v110, v129
	v_mul_f32_e32 v96, 0x3fb8aa3b, v96
	v_exp_f32_e32 v110, v96
	v_sub_f32_e32 v96, v111, v129
	v_mul_f32_e32 v96, 0x3fb8aa3b, v96
	v_exp_f32_e32 v111, v96
	v_cvt_pk_bf16_f32 v96, v130, v131
	v_add_f32_e32 v130, 0, v130
	v_add_f32_e32 v130, v131, v130
	v_add_f32_e32 v130, v132, v130
	v_add_f32_e32 v130, v133, v130
	v_add_f32_e32 v130, v134, v130
	v_add_f32_e32 v130, v135, v130
	v_add_f32_e32 v130, v136, v130
	v_add_f32_e32 v130, v137, v130
	v_sub_f32_e32 v32, v32, v129
	v_cvt_pk_bf16_f32 v100, v104, v105
	v_add_f32_e32 v104, v104, v130
	v_mul_f32_e32 v32, 0x3fb8aa3b, v32
	v_add_f32_e32 v104, v105, v104
	v_exp_f32_e32 v105, v32
	v_sub_f32_e32 v32, v33, v129
	v_mul_f32_e32 v32, 0x3fb8aa3b, v32
	v_cvt_pk_bf16_f32 v101, v106, v107
	v_add_f32_e32 v104, v106, v104
	v_exp_f32_e32 v106, v32
	v_sub_f32_e32 v32, v34, v129
	v_mul_f32_e32 v32, 0x3fb8aa3b, v32
	v_add_f32_e32 v104, v107, v104
	v_exp_f32_e32 v107, v32
	v_sub_f32_e32 v32, v35, v129
	v_mul_f32_e32 v32, 0x3fb8aa3b, v32
	v_cvt_pk_bf16_f32 v102, v108, v109
	v_add_f32_e32 v104, v108, v104
	v_exp_f32_e32 v108, v32
	v_sub_f32_e32 v32, v36, v129
	v_mul_f32_e32 v32, 0x3fb8aa3b, v32
	v_add_f32_e32 v104, v109, v104
	v_exp_f32_e32 v109, v32
	v_sub_f32_e32 v32, v37, v129
	v_mul_f32_e32 v32, 0x3fb8aa3b, v32
	v_cvt_pk_bf16_f32 v103, v110, v111
	v_add_f32_e32 v104, v110, v104
	v_exp_f32_e32 v110, v32
	v_sub_f32_e32 v32, v38, v129
; __device__ __forceinline__ unsigned pk2(float lo, float hi) { return pg8::cvt_pk_bf16(lo, hi); }
; __device__ __forceinline__ void xattn_core(unsigned char* ws, LAS unsigned char* lds, int b, int hd, int qb, int tid, const bf16x8 (&qf)[16]) {
;     ...
;     for (int mt = 0; mt < 8; ++mt) {
;         float e[16];
; #pragma unroll
;         for (int r = 0; r < 16; ++r) { e[r] = __expf(sacc[mt][r] - mx); sum += e[r]; }
; #pragma unroll
;         for (int s = 0; s < 2; ++s) { v4u w; w.x = pk2(e[8 * s], e[8 * s + 1]); w.y = pk2(e[8 * s + 2], e[8 * s + 3]); w.z = pk2(e[8 * s + 4], e[8 * s + 5]); w.w = pk2(e[8 * s + 6], e[8 * s + 7]); pf[mt][s] = __builtin_bit_cast(bf16x8, w); }
;     }
	v_mul_f32_e32 v32, 0x3fb8aa3b, v32
	v_add_f32_e32 v104, v111, v104
	v_exp_f32_e32 v111, v32
	v_sub_f32_e32 v32, v39, v129
	v_mul_f32_e32 v32, 0x3fb8aa3b, v32
	v_exp_f32_e32 v130, v32
	v_sub_f32_e32 v32, v40, v129
	v_mul_f32_e32 v32, 0x3fb8aa3b, v32
	v_add_f32_e32 v104, v105, v104
	v_exp_f32_e32 v40, v32
	v_sub_f32_e32 v32, v41, v129
	v_add_f32_e32 v104, v106, v104
	v_mul_f32_e32 v32, 0x3fb8aa3b, v32
	v_add_f32_e32 v104, v107, v104
	v_exp_f32_e32 v41, v32
	v_sub_f32_e32 v32, v42, v129
	v_add_f32_e32 v104, v108, v104
	v_mul_f32_e32 v32, 0x3fb8aa3b, v32
	v_add_f32_e32 v104, v109, v104
	v_exp_f32_e32 v42, v32
	v_sub_f32_e32 v32, v43, v129
	v_add_f32_e32 v104, v110, v104
	v_mul_f32_e32 v32, 0x3fb8aa3b, v32
	v_add_f32_e32 v104, v111, v104
	v_exp_f32_e32 v43, v32
	v_sub_f32_e32 v32, v44, v129
	v_add_f32_e32 v104, v130, v104
	v_sub_f32_e32 v16, v16, v129
	v_mul_f32_e32 v32, 0x3fb8aa3b, v32
	v_cvt_pk_bf16_f32 v36, v40, v41
	v_add_f32_e32 v40, v40, v104
	v_mul_f32_e32 v16, 0x3fb8aa3b, v16
	v_exp_f32_e32 v44, v32
	v_sub_f32_e32 v32, v45, v129
	v_add_f32_e32 v40, v41, v40
	v_exp_f32_e32 v41, v16
	v_sub_f32_e32 v16, v17, v129
	v_mul_f32_e32 v32, 0x3fb8aa3b, v32
	v_mul_f32_e32 v16, 0x3fb8aa3b, v16
	v_exp_f32_e32 v45, v32
	v_sub_f32_e32 v32, v46, v129
	v_cvt_pk_bf16_f32 v37, v42, v43
	v_add_f32_e32 v40, v42, v40
	v_exp_f32_e32 v42, v16
	v_sub_f32_e32 v16, v18, v129
	v_mul_f32_e32 v32, 0x3fb8aa3b, v32
	v_mul_f32_e32 v16, 0x3fb8aa3b, v16
	v_exp_f32_e32 v46, v32
	v_sub_f32_e32 v32, v47, v129
	v_add_f32_e32 v40, v43, v40
	v_exp_f32_e32 v43, v16
	v_sub_f32_e32 v16, v19, v129
	v_mul_f32_e32 v32, 0x3fb8aa3b, v32
	v_mul_f32_e32 v16, 0x3fb8aa3b, v16
	v_exp_f32_e32 v47, v32
	v_cvt_pk_bf16_f32 v38, v44, v45
	v_add_f32_e32 v40, v44, v40
	v_exp_f32_e32 v44, v16
	v_sub_f32_e32 v16, v20, v129
	v_mul_f32_e32 v16, 0x3fb8aa3b, v16
	v_add_f32_e32 v40, v45, v40
	v_exp_f32_e32 v45, v16
	v_sub_f32_e32 v16, v21, v129
	v_mul_f32_e32 v16, 0x3fb8aa3b, v16
	v_cvt_pk_bf16_f32 v39, v46, v47
	v_add_f32_e32 v40, v46, v40
	v_exp_f32_e32 v46, v16
	v_sub_f32_e32 v16, v22, v129
	v_mul_f32_e32 v16, 0x3fb8aa3b, v16
	v_add_f32_e32 v40, v47, v40
	v_exp_f32_e32 v47, v16
	v_sub_f32_e32 v16, v23, v129
	v_mul_f32_e32 v16, 0x3fb8aa3b, v16
	v_exp_f32_e32 v104, v16
	v_sub_f32_e32 v16, v24, v129
	v_mul_f32_e32 v16, 0x3fb8aa3b, v16
	v_exp_f32_e32 v24, v16
	v_sub_f32_e32 v16, v25, v129
	v_mul_f32_e32 v16, 0x3fb8aa3b, v16
	v_exp_f32_e32 v25, v16
	v_sub_f32_e32 v16, v26, v129
	v_mul_f32_e32 v16, 0x3fb8aa3b, v16
	v_add_f32_e32 v40, v41, v40
	v_exp_f32_e32 v26, v16
	v_sub_f32_e32 v16, v27, v129
	v_add_f32_e32 v40, v42, v40
	v_mul_f32_e32 v16, 0x3fb8aa3b, v16
	v_add_f32_e32 v40, v43, v40
	v_exp_f32_e32 v27, v16
	v_sub_f32_e32 v16, v28, v129
	v_add_f32_e32 v40, v44, v40
	v_mul_f32_e32 v16, 0x3fb8aa3b, v16
	v_add_f32_e32 v40, v45, v40
	v_exp_f32_e32 v28, v16
	v_sub_f32_e32 v16, v29, v129
	v_add_f32_e32 v40, v46, v40
	v_mul_f32_e32 v16, 0x3fb8aa3b, v16
	v_add_f32_e32 v40, v47, v40
	v_exp_f32_e32 v29, v16
	v_sub_f32_e32 v16, v30, v129
	v_add_f32_e32 v40, v104, v40
	v_mul_f32_e32 v16, 0x3fb8aa3b, v16
	v_cvt_pk_bf16_f32 v20, v24, v25
	v_add_f32_e32 v24, v24, v40
	v_exp_f32_e32 v30, v16
	v_sub_f32_e32 v16, v31, v129
	v_add_f32_e32 v24, v25, v24
	v_mul_f32_e32 v16, 0x3fb8aa3b, v16
	v_add_f32_e32 v24, v26, v24
	v_sub_f32_e32 v0, v0, v129
	v_sub_f32_e32 v1, v1, v129
	v_exp_f32_e32 v31, v16
	v_add_f32_e32 v24, v27, v24
	v_mul_f32_e32 v0, 0x3fb8aa3b, v0
	v_mul_f32_e32 v1, 0x3fb8aa3b, v1
	v_add_f32_e32 v24, v28, v24
	v_exp_f32_e32 v0, v0
	v_exp_f32_e32 v1, v1
	v_sub_f32_e32 v2, v2, v129
	v_add_f32_e32 v24, v29, v24
	v_mul_f32_e32 v2, 0x3fb8aa3b, v2
	v_sub_f32_e32 v3, v3, v129
	v_add_f32_e32 v24, v30, v24
	v_exp_f32_e32 v2, v2
	v_mul_f32_e32 v3, 0x3fb8aa3b, v3
	v_sub_f32_e32 v4, v4, v129
	v_add_f32_e32 v40, v31, v24
	v_exp_f32_e32 v3, v3
	v_mul_f32_e32 v4, 0x3fb8aa3b, v4
	v_sub_f32_e32 v5, v5, v129
	v_exp_f32_e32 v4, v4
	v_mul_f32_e32 v5, 0x3fb8aa3b, v5
	v_sub_f32_e32 v6, v6, v129
	v_cvt_pk_bf16_f32 v24, v0, v1
	v_add_f32_e32 v0, v0, v40
	v_exp_f32_e32 v5, v5
	v_mul_f32_e32 v6, 0x3fb8aa3b, v6
	v_sub_f32_e32 v7, v7, v129
	v_add_f32_e32 v0, v1, v0
	v_exp_f32_e32 v6, v6
	v_mul_f32_e32 v7, 0x3fb8aa3b, v7
	v_sub_f32_e32 v8, v8, v129
	v_add_f32_e32 v0, v2, v0
	v_exp_f32_e32 v7, v7
	v_mul_f32_e32 v8, 0x3fb8aa3b, v8
	v_sub_f32_e32 v9, v9, v129
	v_add_f32_e32 v0, v3, v0
	v_exp_f32_e32 v8, v8
	v_mul_f32_e32 v9, 0x3fb8aa3b, v9
	v_sub_f32_e32 v10, v10, v129
	v_add_f32_e32 v0, v4, v0
	v_exp_f32_e32 v9, v9
	v_mul_f32_e32 v10, 0x3fb8aa3b, v10
	v_sub_f32_e32 v11, v11, v129
	v_add_f32_e32 v0, v5, v0
	v_exp_f32_e32 v10, v10
	v_mul_f32_e32 v11, 0x3fb8aa3b, v11
	v_sub_f32_e32 v12, v12, v129
	v_add_f32_e32 v0, v6, v0
	v_exp_f32_e32 v11, v11
	v_mul_f32_e32 v12, 0x3fb8aa3b, v12
	v_sub_f32_e32 v13, v13, v129
	v_add_f32_e32 v0, v7, v0
	v_exp_f32_e32 v12, v12
	v_mul_f32_e32 v13, 0x3fb8aa3b, v13
	v_sub_f32_e32 v14, v14, v129
	v_add_f32_e32 v0, v8, v0
	v_exp_f32_e32 v13, v13
	v_mul_f32_e32 v14, 0x3fb8aa3b, v14
	v_sub_f32_e32 v15, v15, v129
	v_add_f32_e32 v0, v9, v0
	v_exp_f32_e32 v14, v14
	v_mul_f32_e32 v15, 0x3fb8aa3b, v15
	v_add_f32_e32 v0, v10, v0
	v_sub_f32_e32 v1, v48, v129
	v_exp_f32_e32 v15, v15
	v_cvt_pk_bf16_f32 v25, v2, v3
	v_add_f32_e32 v0, v11, v0
	v_mul_f32_e32 v1, 0x3fb8aa3b, v1
	v_sub_f32_e32 v2, v49, v129
	v_add_f32_e32 v0, v12, v0
	v_exp_f32_e32 v1, v1
	v_mul_f32_e32 v2, 0x3fb8aa3b, v2
	v_sub_f32_e32 v3, v50, v129
	v_cvt_pk_bf16_f32 v21, v26, v27
	v_cvt_pk_bf16_f32 v26, v4, v5
	v_add_f32_e32 v0, v13, v0
	v_exp_f32_e32 v2, v2
	v_mul_f32_e32 v3, 0x3fb8aa3b, v3
	v_sub_f32_e32 v4, v51, v129
	v_add_f32_e32 v0, v14, v0
	v_exp_f32_e32 v3, v3
; __device__ __forceinline__ unsigned pk2(float lo, float hi) { return pg8::cvt_pk_bf16(lo, hi); }
; __device__ __forceinline__ void xattn_core(unsigned char* ws, LAS unsigned char* lds, int b, int hd, int qb, int tid, const bf16x8 (&qf)[16]) {
;     ...
;     for (int mt = 0; mt < 8; ++mt) {
;         float e[16];
; #pragma unroll
;         for (int r = 0; r < 16; ++r) { e[r] = __expf(sacc[mt][r] - mx); sum += e[r]; }
; #pragma unroll
;         for (int s = 0; s < 2; ++s) { v4u w; w.x = pk2(e[8 * s], e[8 * s + 1]); w.y = pk2(e[8 * s + 2], e[8 * s + 3]); w.z = pk2(e[8 * s + 4], e[8 * s + 5]); w.w = pk2(e[8 * s + 6], e[8 * s + 7]); pf[mt][s] = __builtin_bit_cast(bf16x8, w); }
;     }
	v_mul_f32_e32 v4, 0x3fb8aa3b, v4
	v_sub_f32_e32 v5, v52, v129
	v_cvt_pk_bf16_f32 v27, v6, v7
	v_add_f32_e32 v0, v15, v0
	v_exp_f32_e32 v4, v4
	v_mul_f32_e32 v5, 0x3fb8aa3b, v5
	v_sub_f32_e32 v6, v53, v129
	v_exp_f32_e32 v5, v5
	v_mul_f32_e32 v6, 0x3fb8aa3b, v6
	v_sub_f32_e32 v7, v54, v129
	v_add_f32_e32 v0, v1, v0
	v_cvt_pk_bf16_f32 v22, v28, v29
	v_cvt_pk_bf16_f32 v28, v8, v9
	v_exp_f32_e32 v6, v6
	v_mul_f32_e32 v7, 0x3fb8aa3b, v7
	v_sub_f32_e32 v8, v55, v129
	v_add_f32_e32 v0, v2, v0
	v_exp_f32_e32 v7, v7
	v_mul_f32_e32 v8, 0x3fb8aa3b, v8
	v_sub_f32_e32 v9, v56, v129
	v_add_f32_e32 v0, v3, v0
	v_cvt_pk_bf16_f32 v29, v10, v11
	v_exp_f32_e32 v8, v8
	v_mul_f32_e32 v9, 0x3fb8aa3b, v9
	v_sub_f32_e32 v10, v57, v129
	v_add_f32_e32 v0, v4, v0
	v_exp_f32_e32 v9, v9
	v_mul_f32_e32 v10, 0x3fb8aa3b, v10
	v_sub_f32_e32 v11, v58, v129
	v_add_f32_e32 v0, v5, v0
	v_cvt_pk_bf16_f32 v23, v30, v31
	v_cvt_pk_bf16_f32 v30, v12, v13
	v_exp_f32_e32 v10, v10
	v_mul_f32_e32 v11, 0x3fb8aa3b, v11
	v_sub_f32_e32 v12, v59, v129
	v_add_f32_e32 v0, v6, v0
	v_exp_f32_e32 v11, v11
	v_mul_f32_e32 v12, 0x3fb8aa3b, v12
	v_sub_f32_e32 v13, v60, v129
	v_add_f32_e32 v0, v7, v0
	v_cvt_pk_bf16_f32 v31, v14, v15
	v_exp_f32_e32 v12, v12
	v_mul_f32_e32 v13, 0x3fb8aa3b, v13
	v_sub_f32_e32 v14, v61, v129
	v_add_f32_e32 v0, v8, v0
	v_exp_f32_e32 v13, v13
	v_mul_f32_e32 v14, 0x3fb8aa3b, v14
	v_sub_f32_e32 v15, v62, v129
	v_sub_f32_e32 v40, v63, v129
	v_add_f32_e32 v0, v9, v0
	v_exp_f32_e32 v14, v14
	v_mul_f32_e32 v15, 0x3fb8aa3b, v15
	v_mul_f32_e32 v40, 0x3fb8aa3b, v40
	v_add_f32_e32 v0, v10, v0
	v_exp_f32_e32 v15, v15
	v_exp_f32_e32 v48, v40
	v_cvt_pk_bf16_f32 v40, v1, v2
	v_add_f32_e32 v0, v11, v0
	v_sub_f32_e32 v1, v80, v129
	v_add_f32_e32 v0, v12, v0
	v_mul_f32_e32 v1, 0x3fb8aa3b, v1
	v_sub_f32_e32 v2, v81, v129
	v_cvt_pk_bf16_f32 v16, v41, v42
	v_cvt_pk_bf16_f32 v41, v3, v4
	v_add_f32_e32 v0, v13, v0
	v_exp_f32_e32 v1, v1
	v_mul_f32_e32 v2, 0x3fb8aa3b, v2
	v_sub_f32_e32 v3, v82, v129
	v_add_f32_e32 v0, v14, v0
	v_exp_f32_e32 v2, v2
	v_mul_f32_e32 v3, 0x3fb8aa3b, v3
	v_sub_f32_e32 v4, v83, v129
	v_cvt_pk_bf16_f32 v42, v5, v6
	v_add_f32_e32 v0, v15, v0
	v_exp_f32_e32 v3, v3
	v_mul_f32_e32 v4, 0x3fb8aa3b, v4
	v_sub_f32_e32 v5, v84, v129
	v_add_f32_e32 v0, v48, v0
	v_exp_f32_e32 v4, v4
	v_mul_f32_e32 v5, 0x3fb8aa3b, v5
	v_sub_f32_e32 v6, v85, v129
	v_cvt_pk_bf16_f32 v17, v43, v44
	v_cvt_pk_bf16_f32 v43, v7, v8
	v_exp_f32_e32 v5, v5
	v_mul_f32_e32 v6, 0x3fb8aa3b, v6
	v_sub_f32_e32 v7, v86, v129
	v_add_f32_e32 v0, v1, v0
	v_exp_f32_e32 v6, v6
	v_mul_f32_e32 v7, 0x3fb8aa3b, v7
	v_sub_f32_e32 v8, v87, v129
	v_add_f32_e32 v0, v2, v0
	v_cvt_pk_bf16_f32 v44, v9, v10
	v_exp_f32_e32 v7, v7
	v_mul_f32_e32 v8, 0x3fb8aa3b, v8
	v_sub_f32_e32 v9, v88, v129
	v_add_f32_e32 v0, v3, v0
	v_exp_f32_e32 v8, v8
	v_mul_f32_e32 v9, 0x3fb8aa3b, v9
	v_sub_f32_e32 v10, v89, v129
	v_add_f32_e32 v0, v4, v0
	v_cvt_pk_bf16_f32 v18, v45, v46
	v_cvt_pk_bf16_f32 v45, v11, v12
	v_exp_f32_e32 v9, v9
	v_mul_f32_e32 v10, 0x3fb8aa3b, v10
	v_sub_f32_e32 v11, v90, v129
	v_add_f32_e32 v0, v5, v0
	v_exp_f32_e32 v10, v10
	v_mul_f32_e32 v11, 0x3fb8aa3b, v11
	v_sub_f32_e32 v12, v91, v129
	v_add_f32_e32 v0, v6, v0
	v_cvt_pk_bf16_f32 v46, v13, v14
	v_exp_f32_e32 v11, v11
	v_mul_f32_e32 v12, 0x3fb8aa3b, v12
	v_sub_f32_e32 v13, v92, v129
	v_add_f32_e32 v0, v7, v0
	v_exp_f32_e32 v12, v12
	v_mul_f32_e32 v13, 0x3fb8aa3b, v13
	v_sub_f32_e32 v14, v93, v129
	v_add_f32_e32 v0, v8, v0
	v_cvt_pk_bf16_f32 v19, v47, v104
	v_cvt_pk_bf16_f32 v47, v15, v48
	v_exp_f32_e32 v13, v13
	v_mul_f32_e32 v14, 0x3fb8aa3b, v14
	v_sub_f32_e32 v15, v94, v129
	v_sub_f32_e32 v48, v95, v129
	v_add_f32_e32 v0, v9, v0
	v_exp_f32_e32 v14, v14
	v_mul_f32_e32 v15, 0x3fb8aa3b, v15
	v_mul_f32_e32 v48, 0x3fb8aa3b, v48
	v_add_f32_e32 v0, v10, v0
	v_exp_f32_e32 v15, v15
	v_exp_f32_e32 v56, v48
	v_cvt_pk_bf16_f32 v48, v1, v2
	v_add_f32_e32 v0, v11, v0
	v_sub_f32_e32 v1, v64, v129
	v_add_f32_e32 v0, v12, v0
	v_mul_f32_e32 v1, 0x3fb8aa3b, v1
	v_sub_f32_e32 v2, v65, v129
	v_cvt_pk_bf16_f32 v49, v3, v4
	v_add_f32_e32 v0, v13, v0
	v_exp_f32_e32 v1, v1
	v_mul_f32_e32 v2, 0x3fb8aa3b, v2
	v_sub_f32_e32 v3, v66, v129
	v_add_f32_e32 v0, v14, v0
	v_exp_f32_e32 v2, v2
	v_mul_f32_e32 v3, 0x3fb8aa3b, v3
	v_sub_f32_e32 v4, v67, v129
	v_cvt_pk_bf16_f32 v50, v5, v6
	v_add_f32_e32 v0, v15, v0
	v_exp_f32_e32 v3, v3
	v_mul_f32_e32 v4, 0x3fb8aa3b, v4
	v_sub_f32_e32 v5, v68, v129
	v_add_f32_e32 v0, v56, v0
	v_exp_f32_e32 v4, v4
	v_mul_f32_e32 v5, 0x3fb8aa3b, v5
	v_sub_f32_e32 v6, v69, v129
	v_cvt_pk_bf16_f32 v51, v7, v8
	v_exp_f32_e32 v5, v5
	v_mul_f32_e32 v6, 0x3fb8aa3b, v6
	v_sub_f32_e32 v7, v70, v129
	v_add_f32_e32 v0, v1, v0
	v_exp_f32_e32 v6, v6
	v_mul_f32_e32 v7, 0x3fb8aa3b, v7
; __device__ __forceinline__ unsigned pk2(float lo, float hi) { return pg8::cvt_pk_bf16(lo, hi); }
; __device__ __forceinline__ void xattn_core(unsigned char* ws, LAS unsigned char* lds, int b, int hd, int qb, int tid, const bf16x8 (&qf)[16]) {
;     ...
;     float sum = 0.f; bf16x8 pf[8][2];
; #pragma unroll
;     for (int mt = 0; mt < 8; ++mt) {
;         float e[16];
; #pragma unroll
;         for (int r = 0; r < 16; ++r) { e[r] = __expf(sacc[mt][r] - mx); sum += e[r]; }
; #pragma unroll
;         for (int s = 0; s < 2; ++s) { v4u w; w.x = pk2(e[8 * s], e[8 * s + 1]); w.y = pk2(e[8 * s + 2], e[8 * s + 3]); w.z = pk2(e[8 * s + 4], e[8 * s + 5]); w.w = pk2(e[8 * s + 6], e[8 * s + 7]); pf[mt][s] = __builtin_bit_cast(bf16x8, w); }
;     }
;     sum += __shfl_xor(sum, 32);
;     const float inv = 1.f / sum;
;     __syncthreads();
;     bf16* op = (bf16*)(ws + WS_O) + (size_t)(q0 + r32) * 1024 + hd * 256 + 4 * hh;
	v_sub_f32_e32 v8, v71, v129
	v_add_f32_e32 v0, v2, v0
	v_cvt_pk_bf16_f32 v52, v9, v10
	v_exp_f32_e32 v7, v7
	v_mul_f32_e32 v8, 0x3fb8aa3b, v8
	v_sub_f32_e32 v9, v72, v129
	v_add_f32_e32 v0, v3, v0
	v_exp_f32_e32 v8, v8
	v_mul_f32_e32 v9, 0x3fb8aa3b, v9
	v_sub_f32_e32 v10, v73, v129
	v_add_f32_e32 v0, v4, v0
	v_cvt_pk_bf16_f32 v53, v11, v12
	v_exp_f32_e32 v9, v9
	v_mul_f32_e32 v10, 0x3fb8aa3b, v10
	v_sub_f32_e32 v11, v74, v129
	v_add_f32_e32 v0, v5, v0
	v_exp_f32_e32 v10, v10
	v_mul_f32_e32 v11, 0x3fb8aa3b, v11
	v_sub_f32_e32 v12, v75, v129
	v_add_f32_e32 v0, v6, v0
	v_cvt_pk_bf16_f32 v54, v13, v14
	v_exp_f32_e32 v11, v11
	v_mul_f32_e32 v12, 0x3fb8aa3b, v12
	v_sub_f32_e32 v13, v76, v129
	v_add_f32_e32 v0, v7, v0
	v_exp_f32_e32 v12, v12
	v_mul_f32_e32 v13, 0x3fb8aa3b, v13
	v_sub_f32_e32 v14, v77, v129
	v_add_f32_e32 v0, v8, v0
	v_cvt_pk_bf16_f32 v55, v15, v56
	v_exp_f32_e32 v13, v13
	v_mul_f32_e32 v14, 0x3fb8aa3b, v14
	v_sub_f32_e32 v15, v78, v129
	v_sub_f32_e32 v56, v79, v129
	v_add_f32_e32 v0, v9, v0
	v_exp_f32_e32 v14, v14
	v_mul_f32_e32 v15, 0x3fb8aa3b, v15
	v_mul_f32_e32 v56, 0x3fb8aa3b, v56
	v_add_f32_e32 v0, v10, v0
	v_exp_f32_e32 v15, v15
	v_exp_f32_e32 v64, v56
	v_cvt_pk_bf16_f32 v56, v1, v2
	v_add_f32_e32 v0, v11, v0
	v_sub_f32_e32 v1, v112, v129
	v_add_f32_e32 v0, v12, v0
	v_mul_f32_e32 v1, 0x3fb8aa3b, v1
	v_sub_f32_e32 v2, v113, v129
	v_cvt_pk_bf16_f32 v57, v3, v4
	v_add_f32_e32 v0, v13, v0
	v_exp_f32_e32 v1, v1
	v_mul_f32_e32 v2, 0x3fb8aa3b, v2
	v_sub_f32_e32 v3, v114, v129
	v_add_f32_e32 v0, v14, v0
	v_exp_f32_e32 v2, v2
	v_mul_f32_e32 v3, 0x3fb8aa3b, v3
	v_sub_f32_e32 v4, v115, v129
	v_cvt_pk_bf16_f32 v58, v5, v6
	v_add_f32_e32 v0, v15, v0
	v_exp_f32_e32 v3, v3
	v_mul_f32_e32 v4, 0x3fb8aa3b, v4
	v_sub_f32_e32 v5, v116, v129
	v_add_f32_e32 v0, v64, v0
	v_exp_f32_e32 v4, v4
	v_mul_f32_e32 v5, 0x3fb8aa3b, v5
	v_sub_f32_e32 v6, v117, v129
	v_cvt_pk_bf16_f32 v59, v7, v8
	v_exp_f32_e32 v5, v5
	v_mul_f32_e32 v6, 0x3fb8aa3b, v6
	v_sub_f32_e32 v7, v118, v129
	v_add_f32_e32 v0, v1, v0
	v_exp_f32_e32 v6, v6
	v_mul_f32_e32 v7, 0x3fb8aa3b, v7
	v_sub_f32_e32 v8, v119, v129
	v_add_f32_e32 v0, v2, v0
	v_cvt_pk_bf16_f32 v60, v9, v10
	v_exp_f32_e32 v7, v7
	v_mul_f32_e32 v8, 0x3fb8aa3b, v8
	v_sub_f32_e32 v9, v120, v129
	v_add_f32_e32 v0, v3, v0
	v_exp_f32_e32 v8, v8
	v_mul_f32_e32 v9, 0x3fb8aa3b, v9
	v_sub_f32_e32 v10, v121, v129
	v_add_f32_e32 v0, v4, v0
	v_cvt_pk_bf16_f32 v61, v11, v12
	v_exp_f32_e32 v9, v9
	v_mul_f32_e32 v10, 0x3fb8aa3b, v10
	v_sub_f32_e32 v11, v122, v129
	v_add_f32_e32 v0, v5, v0
	v_exp_f32_e32 v10, v10
	v_mul_f32_e32 v11, 0x3fb8aa3b, v11
	v_sub_f32_e32 v12, v123, v129
	v_add_f32_e32 v0, v6, v0
	v_cvt_pk_bf16_f32 v62, v13, v14
	v_exp_f32_e32 v11, v11
	v_mul_f32_e32 v12, 0x3fb8aa3b, v12
	v_sub_f32_e32 v13, v124, v129
	v_add_f32_e32 v0, v7, v0
	v_exp_f32_e32 v12, v12
	v_mul_f32_e32 v13, 0x3fb8aa3b, v13
	v_sub_f32_e32 v14, v125, v129
	v_add_f32_e32 v0, v8, v0
	v_cvt_pk_bf16_f32 v63, v15, v64
	v_exp_f32_e32 v13, v13
	v_mul_f32_e32 v14, 0x3fb8aa3b, v14
	v_sub_f32_e32 v15, v126, v129
	v_add_f32_e32 v0, v9, v0
	v_exp_f32_e32 v14, v14
	v_mul_f32_e32 v15, 0x3fb8aa3b, v15
	v_sub_f32_e32 v64, v127, v129
	v_add_f32_e32 v0, v10, v0
	v_exp_f32_e32 v15, v15
	v_mul_f32_e32 v64, 0x3fb8aa3b, v64
	v_add_f32_e32 v0, v11, v0
	v_exp_f32_e32 v72, v64
	v_add_f32_e32 v0, v12, v0
	v_add_f32_e32 v0, v13, v0
	v_add_f32_e32 v0, v14, v0
	v_add_f32_e32 v0, v15, v0
	v_add_f32_e32 v0, v72, v0
	v_cvt_pk_bf16_f32 v64, v1, v2
	ds_bpermute_b32 v1, v128, v0
	v_cvt_pk_bf16_f32 v65, v3, v4
	v_cvt_pk_bf16_f32 v66, v5, v6
	v_cvt_pk_bf16_f32 v71, v15, v72
	v_cvt_pk_bf16_f32 v97, v132, v133
	s_waitcnt lgkmcnt(0)
	v_add_f32_e32 v0, v0, v1
	v_div_scale_f32 v1, s[14:15], v0, v0, 1.0
	v_rcp_f32_e32 v2, v1
	v_cvt_pk_bf16_f32 v98, v134, v135
	v_cvt_pk_bf16_f32 v99, v136, v137
	v_cvt_pk_bf16_f32 v32, v105, v106
	v_fma_f32 v3, -v1, v2, 1.0
	v_fmac_f32_e32 v2, v3, v2
	v_div_scale_f32 v3, vcc, 1.0, v0, 1.0
	v_mul_f32_e32 v4, v3, v2
	v_fma_f32 v5, -v1, v4, v3
	v_fmac_f32_e32 v4, v5, v2
	v_fma_f32 v1, -v1, v4, v3
	v_div_fmas_f32 v1, v1, v2, v4
	v_div_fixup_f32 v72, v1, v0, 1.0
	v_add_u32_e32 v0, s6, v214
	v_ashrrev_i32_e32 v1, 31, v0
	v_lshlrev_b64 v[0:1], 11, v[0:1]
	v_lshl_add_u64 v[2:3], s[48:49], 0, v[188:189]
	v_lshl_add_u64 v[0:1], v[0:1], 0, s[4:5]
	v_lshl_add_u64 v[0:1], v[2:3], 0, v[0:1]
	s_mov_b64 s[4:5], 0xc000020
	v_cvt_pk_bf16_f32 v33, v107, v108
	v_cvt_pk_bf16_f32 v34, v109, v110
	v_cvt_pk_bf16_f32 v35, v111, v130
	v_cvt_pk_bf16_f32 v67, v7, v8
	v_cvt_pk_bf16_f32 v68, v9, v10
	v_cvt_pk_bf16_f32 v69, v11, v12
	v_cvt_pk_bf16_f32 v70, v13, v14
	v_mov_b32_e32 v73, v72
	v_lshl_add_u64 v[74:75], v[0:1], 0, s[4:5]
	v_lshlrev_b32_e32 v76, 1, v211
	s_mov_b32 s4, 0

; __device__ __forceinline__ unsigned cvt_pk_bf16(float lo, float hi) { cvf32x2_t v = {lo, hi}; cvbf16x2_t b = __builtin_convertvector(v, cvbf16x2_t); return __builtin_bit_cast(unsigned, b); }
; __device__ __forceinline__ float fsigm(float x) { return __builtin_amdgcn_rcpf(1.f + __expf(-x)); }
; __device__ __forceinline__ float fsilu(float x) { return x * fsigm(x); }
; __device__ __forceinline__ float row_rs(const float* ssq, int row) { return ssq ? rsqrtf(ssq[row] * (1.f / 1024.f) + RMS_EPS) : 1.f; }
;     __device__ __forceinline__ void operator()(const f32x4 (&acc)[2][2][4][2], const Unit& u, int wr, int wc, int fr, int fq) const {
;         const int row0 = u.pm * BM + wr * 64 + fr, col0 = u.pn * HALF + wc * 32 + 8 * fq;
; #pragma unroll
;         for (int ai = 0; ai < 2; ++ai)
; #pragma unroll
;             for (int m = 0; m < 4; ++m) { const int row = row0 + ai * HALF + m * 16; const float rs = row_rs(ssq, row);
;                 u32x4 w; unsigned pk[4];
; #pragma unroll
;                 for (int n = 0; n < 2; ++n) { const f32x4 g = acc[ai][0][m][n] * rs, up = acc[ai][1][m][n] * rs;
;                     pk[2 * n] = cvt_pk_bf16(fsilu(g[0]) * up[0], fsilu(g[1]) * up[1]); pk[2 * n + 1] = cvt_pk_bf16(fsilu(g[2]) * up[2], fsilu(g[3]) * up[3]); }
;                 w.x = pk[0]; w.y = pk[1]; w.z = pk[2]; w.w = pk[3];
;                 st_wt16(H + (size_t)row * ldh + col0, w); }
.LBB0_1274:
	v_lshl_add_u32 v144, s6, 8, v152
	v_ashrrev_i32_e32 v145, 31, v144
	v_lshl_add_u64 v[150:151], v[144:145], 2, s[12:13]
	global_load_dword v145, v[150:151], off
	global_load_dword v176, v[150:151], off offset:64
	global_load_dword v177, v[150:151], off offset:128
	global_load_dword v178, v[150:151], off offset:192
	global_load_dword v179, v[150:151], off offset:512
	global_load_dword v180, v[150:151], off offset:576
	global_load_dword v181, v[150:151], off offset:640
	global_load_dword v182, v[150:151], off offset:704
	v_or_b32_e32 v162, 16, v144
	v_ashrrev_i32_e32 v163, 31, v162
	v_lshl_add_u64 v[164:165], v[162:163], 2, s[12:13]
	v_lshl_or_b32 v148, s7, 7, v154
	v_mov_b64_e32 v[146:147], s[56:57]
	v_ashrrev_i32_e32 v149, 31, v148
	v_mad_i64_i32 v[160:161], s[6:7], v144, s79, v[146:147]
	v_lshlrev_b64 v[148:149], 1, v[148:149]
	v_lshl_add_u64 v[160:161], v[160:161], 0, v[148:149]
	s_waitcnt vmcnt(0)
	v_fmamk_f32 v145, v145, 0x3a800000, v158
	v_rsq_f32_e32 v145, v145
	s_nop 0
	v_mov_b32_e32 v166, v145
	v_mov_b32_e32 v192, 1.0
	v_mul_f32_e32 v188, 0xbfb8aa3b, v166
	v_mul_f32_e32 v190, v166, v166
	v_pk_mul_f32 v[184:185], v[124:125], v[188:189] op_sel_hi:[1,0]
	v_pk_mul_f32 v[186:187], v[126:127], v[188:189] op_sel_hi:[1,0]
	v_pk_mul_f32 v[124:125], v[124:125], v[116:117]
	v_exp_f32_e32 v184, v184
	v_exp_f32_e32 v185, v185
	v_exp_f32_e32 v186, v186
	v_exp_f32_e32 v187, v187
	v_pk_mul_f32 v[126:127], v[126:127], v[118:119]
	v_pk_add_f32 v[184:185], v[184:185], v[192:193] op_sel_hi:[1,0]
	v_pk_add_f32 v[186:187], v[186:187], v[192:193] op_sel_hi:[1,0]
	v_rcp_f32_e32 v184, v184
	v_rcp_f32_e32 v185, v185
	v_rcp_f32_e32 v186, v186
	v_rcp_f32_e32 v187, v187
	v_pk_mul_f32 v[124:125], v[124:125], v[190:191] op_sel_hi:[1,0]
	v_pk_mul_f32 v[126:127], v[126:127], v[190:191] op_sel_hi:[1,0]
	v_pk_mul_f32 v[124:125], v[124:125], v[184:185]
	v_pk_mul_f32 v[126:127], v[126:127], v[186:187]
	v_pk_mul_f32 v[184:185], v[120:121], v[188:189] op_sel_hi:[1,0]
	v_pk_mul_f32 v[186:187], v[122:123], v[188:189] op_sel_hi:[1,0]
	v_pk_mul_f32 v[120:121], v[120:121], v[112:113]
	v_exp_f32_e32 v184, v184
	v_exp_f32_e32 v185, v185
	v_exp_f32_e32 v186, v186
	v_exp_f32_e32 v187, v187
	v_pk_mul_f32 v[122:123], v[122:123], v[114:115]
	v_pk_add_f32 v[184:185], v[184:185], v[192:193] op_sel_hi:[1,0]
	v_pk_add_f32 v[186:187], v[186:187], v[192:193] op_sel_hi:[1,0]
	v_rcp_f32_e32 v184, v184
	v_rcp_f32_e32 v185, v185
	v_rcp_f32_e32 v186, v186
	v_rcp_f32_e32 v187, v187
	v_pk_mul_f32 v[120:121], v[120:121], v[190:191] op_sel_hi:[1,0]
	v_pk_mul_f32 v[122:123], v[122:123], v[190:191] op_sel_hi:[1,0]
	v_pk_mul_f32 v[120:121], v[120:121], v[184:185]
	v_pk_mul_f32 v[122:123], v[122:123], v[186:187]
	v_cvt_pk_bf16_f32 v112, v124, v125
	v_cvt_pk_bf16_f32 v113, v126, v127
	v_cvt_pk_bf16_f32 v114, v120, v121
	v_cvt_pk_bf16_f32 v115, v122, v123
	s_nop 0
	global_store_dwordx4 v[160:161], v[112:115], off
	s_nop 1
	s_nop 0
	v_or_b32_e32 v112, 32, v144
	v_mad_i64_i32 v[114:115], s[6:7], v162, s79, v[146:147]
	v_lshl_add_u64 v[114:115], v[114:115], 0, v[148:149]
	v_fmamk_f32 v113, v176, 0x3a800000, v158
	v_rsq_f32_e32 v118, v113
	v_ashrrev_i32_e32 v113, 31, v112
	v_lshl_add_u64 v[116:117], v[112:113], 2, s[12:13]
	v_mul_f32_e32 v188, 0xbfb8aa3b, v118
	v_mul_f32_e32 v190, v118, v118
	v_pk_mul_f32 v[184:185], v[108:109], v[188:189] op_sel_hi:[1,0]
	v_pk_mul_f32 v[186:187], v[110:111], v[188:189] op_sel_hi:[1,0]
	v_pk_mul_f32 v[108:109], v[108:109], v[100:101]
	v_exp_f32_e32 v184, v184
	v_exp_f32_e32 v185, v185
	v_exp_f32_e32 v186, v186
	v_exp_f32_e32 v187, v187
	v_pk_mul_f32 v[110:111], v[110:111], v[102:103]
	v_pk_add_f32 v[184:185], v[184:185], v[192:193] op_sel_hi:[1,0]
	v_pk_add_f32 v[186:187], v[186:187], v[192:193] op_sel_hi:[1,0]
	v_rcp_f32_e32 v184, v184
	v_rcp_f32_e32 v185, v185
	v_rcp_f32_e32 v186, v186
	v_rcp_f32_e32 v187, v187
	v_pk_mul_f32 v[108:109], v[108:109], v[190:191] op_sel_hi:[1,0]
	v_pk_mul_f32 v[110:111], v[110:111], v[190:191] op_sel_hi:[1,0]
	v_pk_mul_f32 v[108:109], v[108:109], v[184:185]
	v_pk_mul_f32 v[110:111], v[110:111], v[186:187]
	v_pk_mul_f32 v[184:185], v[104:105], v[188:189] op_sel_hi:[1,0]
	v_pk_mul_f32 v[186:187], v[106:107], v[188:189] op_sel_hi:[1,0]
	v_pk_mul_f32 v[104:105], v[104:105], v[96:97]
	v_exp_f32_e32 v184, v184
	v_exp_f32_e32 v185, v185
	v_exp_f32_e32 v186, v186
	v_exp_f32_e32 v187, v187
	v_pk_mul_f32 v[106:107], v[106:107], v[98:99]
	v_pk_add_f32 v[184:185], v[184:185], v[192:193] op_sel_hi:[1,0]
	v_pk_add_f32 v[186:187], v[186:187], v[192:193] op_sel_hi:[1,0]
	v_rcp_f32_e32 v184, v184
	v_rcp_f32_e32 v185, v185
	v_rcp_f32_e32 v186, v186
	v_rcp_f32_e32 v187, v187
	v_pk_mul_f32 v[104:105], v[104:105], v[190:191] op_sel_hi:[1,0]
	v_pk_mul_f32 v[106:107], v[106:107], v[190:191] op_sel_hi:[1,0]
	v_pk_mul_f32 v[104:105], v[104:105], v[184:185]
	v_pk_mul_f32 v[106:107], v[106:107], v[186:187]
	v_cvt_pk_bf16_f32 v96, v108, v109
	v_cvt_pk_bf16_f32 v97, v110, v111
	v_cvt_pk_bf16_f32 v98, v104, v105
	v_cvt_pk_bf16_f32 v99, v106, v107
	s_nop 0
	global_store_dwordx4 v[114:115], v[96:99], off
	s_nop 1
	s_nop 0
	v_or_b32_e32 v96, 48, v144
	v_mad_i64_i32 v[98:99], s[6:7], v112, s79, v[146:147]
	v_lshl_add_u64 v[98:99], v[98:99], 0, v[148:149]
	v_fmamk_f32 v97, v177, 0x3a800000, v158
	v_rsq_f32_e32 v102, v97
	v_ashrrev_i32_e32 v97, 31, v96
	v_lshl_add_u64 v[100:101], v[96:97], 2, s[12:13]
	v_mul_f32_e32 v188, 0xbfb8aa3b, v102
	v_mul_f32_e32 v190, v102, v102
	v_pk_mul_f32 v[184:185], v[92:93], v[188:189] op_sel_hi:[1,0]
	v_pk_mul_f32 v[186:187], v[94:95], v[188:189] op_sel_hi:[1,0]
	v_pk_mul_f32 v[92:93], v[92:93], v[84:85]
	v_exp_f32_e32 v184, v184
; __device__ __forceinline__ unsigned cvt_pk_bf16(float lo, float hi) { cvf32x2_t v = {lo, hi}; cvbf16x2_t b = __builtin_convertvector(v, cvbf16x2_t); return __builtin_bit_cast(unsigned, b); }
; __device__ __forceinline__ float row_rs(const float* ssq, int row) { return ssq ? rsqrtf(ssq[row] * (1.f / 1024.f) + RMS_EPS) : 1.f; }
; __device__ __forceinline__ float fsigm(float x) { return __builtin_amdgcn_rcpf(1.f + __expf(-x)); }
; __device__ __forceinline__ float fsilu(float x) { return x * fsigm(x); }
;     __device__ __forceinline__ void operator()(const f32x4 (&acc)[2][2][4][2], const Unit& u, int wr, int wc, int fr, int fq) const {
;     ...
;             for (int m = 0; m < 4; ++m) { const int row = row0 + ai * HALF + m * 16; const float rs = row_rs(ssq, row);
;                 u32x4 w; unsigned pk[4];
; #pragma unroll
;                 for (int n = 0; n < 2; ++n) { const f32x4 g = acc[ai][0][m][n] * rs, up = acc[ai][1][m][n] * rs;
;                     pk[2 * n] = cvt_pk_bf16(fsilu(g[0]) * up[0], fsilu(g[1]) * up[1]); pk[2 * n + 1] = cvt_pk_bf16(fsilu(g[2]) * up[2], fsilu(g[3]) * up[3]); }
;                 w.x = pk[0]; w.y = pk[1]; w.z = pk[2]; w.w = pk[3];
;                 st_wt16(H + (size_t)row * ldh + col0, w); }
	v_exp_f32_e32 v185, v185
	v_exp_f32_e32 v186, v186
	v_exp_f32_e32 v187, v187
	v_pk_mul_f32 v[94:95], v[94:95], v[86:87]
	v_pk_add_f32 v[184:185], v[184:185], v[192:193] op_sel_hi:[1,0]
	v_pk_add_f32 v[186:187], v[186:187], v[192:193] op_sel_hi:[1,0]
	v_rcp_f32_e32 v184, v184
	v_rcp_f32_e32 v185, v185
	v_rcp_f32_e32 v186, v186
	v_rcp_f32_e32 v187, v187
	v_pk_mul_f32 v[92:93], v[92:93], v[190:191] op_sel_hi:[1,0]
	v_pk_mul_f32 v[94:95], v[94:95], v[190:191] op_sel_hi:[1,0]
	v_pk_mul_f32 v[92:93], v[92:93], v[184:185]
	v_pk_mul_f32 v[94:95], v[94:95], v[186:187]
	v_pk_mul_f32 v[184:185], v[88:89], v[188:189] op_sel_hi:[1,0]
	v_pk_mul_f32 v[186:187], v[90:91], v[188:189] op_sel_hi:[1,0]
	v_pk_mul_f32 v[88:89], v[88:89], v[80:81]
	v_exp_f32_e32 v184, v184
	v_exp_f32_e32 v185, v185
	v_exp_f32_e32 v186, v186
	v_exp_f32_e32 v187, v187
	v_pk_mul_f32 v[90:91], v[90:91], v[82:83]
	v_pk_add_f32 v[184:185], v[184:185], v[192:193] op_sel_hi:[1,0]
	v_pk_add_f32 v[186:187], v[186:187], v[192:193] op_sel_hi:[1,0]
	v_rcp_f32_e32 v184, v184
	v_rcp_f32_e32 v185, v185
	v_rcp_f32_e32 v186, v186
	v_rcp_f32_e32 v187, v187
	v_pk_mul_f32 v[88:89], v[88:89], v[190:191] op_sel_hi:[1,0]
	v_pk_mul_f32 v[90:91], v[90:91], v[190:191] op_sel_hi:[1,0]
	v_pk_mul_f32 v[88:89], v[88:89], v[184:185]
	v_pk_mul_f32 v[90:91], v[90:91], v[186:187]
	v_cvt_pk_bf16_f32 v80, v92, v93
	v_cvt_pk_bf16_f32 v81, v94, v95
	v_cvt_pk_bf16_f32 v82, v88, v89
	v_cvt_pk_bf16_f32 v83, v90, v91
	s_nop 0
	global_store_dwordx4 v[98:99], v[80:83], off
	s_nop 1
	v_fmamk_f32 v80, v178, 0x3a800000, v158
	v_rsq_f32_e32 v82, v80
	v_mad_i64_i32 v[80:81], s[6:7], v96, s79, v[146:147]
	v_lshl_add_u64 v[80:81], v[80:81], 0, v[148:149]
	v_mul_f32_e32 v188, 0xbfb8aa3b, v82
	v_mul_f32_e32 v190, v82, v82
	v_pk_mul_f32 v[184:185], v[76:77], v[188:189] op_sel_hi:[1,0]
	v_pk_mul_f32 v[186:187], v[78:79], v[188:189] op_sel_hi:[1,0]
	v_pk_mul_f32 v[76:77], v[76:77], v[68:69]
	v_exp_f32_e32 v184, v184
	v_exp_f32_e32 v185, v185
	v_exp_f32_e32 v186, v186
	v_exp_f32_e32 v187, v187
	v_pk_mul_f32 v[78:79], v[78:79], v[70:71]
	v_pk_add_f32 v[184:185], v[184:185], v[192:193] op_sel_hi:[1,0]
	v_pk_add_f32 v[186:187], v[186:187], v[192:193] op_sel_hi:[1,0]
	v_rcp_f32_e32 v184, v184
	v_rcp_f32_e32 v185, v185
	v_rcp_f32_e32 v186, v186
	v_rcp_f32_e32 v187, v187
	v_pk_mul_f32 v[76:77], v[76:77], v[190:191] op_sel_hi:[1,0]
	v_pk_mul_f32 v[78:79], v[78:79], v[190:191] op_sel_hi:[1,0]
	v_pk_mul_f32 v[76:77], v[76:77], v[184:185]
	v_pk_mul_f32 v[78:79], v[78:79], v[186:187]
	v_pk_mul_f32 v[184:185], v[72:73], v[188:189] op_sel_hi:[1,0]
	v_pk_mul_f32 v[186:187], v[74:75], v[188:189] op_sel_hi:[1,0]
	v_pk_mul_f32 v[72:73], v[72:73], v[64:65]
	v_exp_f32_e32 v184, v184
	v_exp_f32_e32 v185, v185
	v_exp_f32_e32 v186, v186
	v_exp_f32_e32 v187, v187
	v_pk_mul_f32 v[74:75], v[74:75], v[66:67]
	v_pk_add_f32 v[184:185], v[184:185], v[192:193] op_sel_hi:[1,0]
	v_pk_add_f32 v[186:187], v[186:187], v[192:193] op_sel_hi:[1,0]
	v_rcp_f32_e32 v184, v184
	v_rcp_f32_e32 v185, v185
	v_rcp_f32_e32 v186, v186
	v_rcp_f32_e32 v187, v187
	v_pk_mul_f32 v[72:73], v[72:73], v[190:191] op_sel_hi:[1,0]
	v_pk_mul_f32 v[74:75], v[74:75], v[190:191] op_sel_hi:[1,0]
	v_pk_mul_f32 v[72:73], v[72:73], v[184:185]
	v_pk_mul_f32 v[74:75], v[74:75], v[186:187]
	v_cvt_pk_bf16_f32 v64, v76, v77
	v_cvt_pk_bf16_f32 v65, v78, v79
	v_cvt_pk_bf16_f32 v66, v72, v73
	v_cvt_pk_bf16_f32 v67, v74, v75
	s_nop 0
	global_store_dwordx4 v[80:81], v[64:67], off
	s_nop 1
	s_nop 0
	v_add_u32_e32 v65, 0x80, v144
	v_fmamk_f32 v64, v179, 0x3a800000, v158
	v_rsq_f32_e32 v66, v64
	v_mad_i64_i32 v[64:65], s[6:7], v65, s79, v[146:147]
	v_lshl_add_u64 v[64:65], v[64:65], 0, v[148:149]
	v_mul_f32_e32 v188, 0xbfb8aa3b, v66
	v_mul_f32_e32 v190, v66, v66
	v_pk_mul_f32 v[184:185], v[60:61], v[188:189] op_sel_hi:[1,0]
	v_pk_mul_f32 v[186:187], v[62:63], v[188:189] op_sel_hi:[1,0]
	v_pk_mul_f32 v[60:61], v[60:61], v[52:53]
	v_exp_f32_e32 v184, v184
	v_exp_f32_e32 v185, v185
	v_exp_f32_e32 v186, v186
	v_exp_f32_e32 v187, v187
	v_pk_mul_f32 v[62:63], v[62:63], v[54:55]
	v_pk_add_f32 v[184:185], v[184:185], v[192:193] op_sel_hi:[1,0]
	v_pk_add_f32 v[186:187], v[186:187], v[192:193] op_sel_hi:[1,0]
	v_rcp_f32_e32 v184, v184
	v_rcp_f32_e32 v185, v185
	v_rcp_f32_e32 v186, v186
	v_rcp_f32_e32 v187, v187
	v_pk_mul_f32 v[60:61], v[60:61], v[190:191] op_sel_hi:[1,0]
	v_pk_mul_f32 v[62:63], v[62:63], v[190:191] op_sel_hi:[1,0]
	v_pk_mul_f32 v[60:61], v[60:61], v[184:185]
	v_pk_mul_f32 v[62:63], v[62:63], v[186:187]
	v_pk_mul_f32 v[184:185], v[56:57], v[188:189] op_sel_hi:[1,0]
	v_pk_mul_f32 v[186:187], v[58:59], v[188:189] op_sel_hi:[1,0]
	v_pk_mul_f32 v[56:57], v[56:57], v[48:49]
	v_exp_f32_e32 v184, v184
	v_exp_f32_e32 v185, v185
	v_exp_f32_e32 v186, v186
	v_exp_f32_e32 v187, v187
	v_pk_mul_f32 v[58:59], v[58:59], v[50:51]
	v_pk_add_f32 v[184:185], v[184:185], v[192:193] op_sel_hi:[1,0]
	v_pk_add_f32 v[186:187], v[186:187], v[192:193] op_sel_hi:[1,0]
	v_rcp_f32_e32 v184, v184
	v_rcp_f32_e32 v185, v185
	v_rcp_f32_e32 v186, v186
	v_rcp_f32_e32 v187, v187
	v_pk_mul_f32 v[56:57], v[56:57], v[190:191] op_sel_hi:[1,0]
	v_pk_mul_f32 v[58:59], v[58:59], v[190:191] op_sel_hi:[1,0]
	v_pk_mul_f32 v[56:57], v[56:57], v[184:185]
	v_pk_mul_f32 v[58:59], v[58:59], v[186:187]
	v_cvt_pk_bf16_f32 v48, v60, v61
	v_cvt_pk_bf16_f32 v49, v62, v63
	v_cvt_pk_bf16_f32 v50, v56, v57
	v_cvt_pk_bf16_f32 v51, v58, v59
	s_nop 0
	global_store_dwordx4 v[64:65], v[48:51], off
	s_nop 1
	s_nop 0
	v_add_u32_e32 v49, 0x90, v144
	v_fmamk_f32 v48, v180, 0x3a800000, v158
	v_rsq_f32_e32 v50, v48
	v_mad_i64_i32 v[48:49], s[6:7], v49, s79, v[146:147]
; __device__ __forceinline__ unsigned cvt_pk_bf16(float lo, float hi) { cvf32x2_t v = {lo, hi}; cvbf16x2_t b = __builtin_convertvector(v, cvbf16x2_t); return __builtin_bit_cast(unsigned, b); }
; __device__ __forceinline__ float row_rs(const float* ssq, int row) { return ssq ? rsqrtf(ssq[row] * (1.f / 1024.f) + RMS_EPS) : 1.f; }
; __device__ __forceinline__ float fsigm(float x) { return __builtin_amdgcn_rcpf(1.f + __expf(-x)); }
; __device__ __forceinline__ float fsilu(float x) { return x * fsigm(x); }
;     __device__ __forceinline__ void operator()(const f32x4 (&acc)[2][2][4][2], const Unit& u, int wr, int wc, int fr, int fq) const {
;     ...
;             for (int m = 0; m < 4; ++m) { const int row = row0 + ai * HALF + m * 16; const float rs = row_rs(ssq, row);
;                 u32x4 w; unsigned pk[4];
; #pragma unroll
;                 for (int n = 0; n < 2; ++n) { const f32x4 g = acc[ai][0][m][n] * rs, up = acc[ai][1][m][n] * rs;
;                     pk[2 * n] = cvt_pk_bf16(fsilu(g[0]) * up[0], fsilu(g[1]) * up[1]); pk[2 * n + 1] = cvt_pk_bf16(fsilu(g[2]) * up[2], fsilu(g[3]) * up[3]); }
;                 w.x = pk[0]; w.y = pk[1]; w.z = pk[2]; w.w = pk[3];
;                 st_wt16(H + (size_t)row * ldh + col0, w); }
	v_lshl_add_u64 v[48:49], v[48:49], 0, v[148:149]
	v_mul_f32_e32 v188, 0xbfb8aa3b, v50
	v_mul_f32_e32 v190, v50, v50
	v_pk_mul_f32 v[184:185], v[44:45], v[188:189] op_sel_hi:[1,0]
	v_pk_mul_f32 v[186:187], v[46:47], v[188:189] op_sel_hi:[1,0]
	v_pk_mul_f32 v[44:45], v[44:45], v[36:37]
	v_exp_f32_e32 v184, v184
	v_exp_f32_e32 v185, v185
	v_exp_f32_e32 v186, v186
	v_exp_f32_e32 v187, v187
	v_pk_mul_f32 v[46:47], v[46:47], v[38:39]
	v_pk_add_f32 v[184:185], v[184:185], v[192:193] op_sel_hi:[1,0]
	v_pk_add_f32 v[186:187], v[186:187], v[192:193] op_sel_hi:[1,0]
	v_rcp_f32_e32 v184, v184
	v_rcp_f32_e32 v185, v185
	v_rcp_f32_e32 v186, v186
	v_rcp_f32_e32 v187, v187
	v_pk_mul_f32 v[44:45], v[44:45], v[190:191] op_sel_hi:[1,0]
	v_pk_mul_f32 v[46:47], v[46:47], v[190:191] op_sel_hi:[1,0]
	v_pk_mul_f32 v[44:45], v[44:45], v[184:185]
	v_pk_mul_f32 v[46:47], v[46:47], v[186:187]
	v_pk_mul_f32 v[184:185], v[40:41], v[188:189] op_sel_hi:[1,0]
	v_pk_mul_f32 v[186:187], v[42:43], v[188:189] op_sel_hi:[1,0]
	v_pk_mul_f32 v[40:41], v[40:41], v[32:33]
	v_exp_f32_e32 v184, v184
	v_exp_f32_e32 v185, v185
	v_exp_f32_e32 v186, v186
	v_exp_f32_e32 v187, v187
	v_pk_mul_f32 v[42:43], v[42:43], v[34:35]
	v_pk_add_f32 v[184:185], v[184:185], v[192:193] op_sel_hi:[1,0]
	v_pk_add_f32 v[186:187], v[186:187], v[192:193] op_sel_hi:[1,0]
	v_rcp_f32_e32 v184, v184
	v_rcp_f32_e32 v185, v185
	v_rcp_f32_e32 v186, v186
	v_rcp_f32_e32 v187, v187
	v_pk_mul_f32 v[40:41], v[40:41], v[190:191] op_sel_hi:[1,0]
	v_pk_mul_f32 v[42:43], v[42:43], v[190:191] op_sel_hi:[1,0]
	v_pk_mul_f32 v[40:41], v[40:41], v[184:185]
	v_pk_mul_f32 v[42:43], v[42:43], v[186:187]
	v_cvt_pk_bf16_f32 v32, v44, v45
	v_cvt_pk_bf16_f32 v33, v46, v47
	v_cvt_pk_bf16_f32 v34, v40, v41
	v_cvt_pk_bf16_f32 v35, v42, v43
	s_nop 0
	global_store_dwordx4 v[48:49], v[32:35], off
	s_nop 1
	s_nop 0
	v_add_u32_e32 v33, 0xa0, v144
	v_fmamk_f32 v32, v181, 0x3a800000, v158
	v_rsq_f32_e32 v34, v32
	v_mad_i64_i32 v[32:33], s[6:7], v33, s79, v[146:147]
	v_lshl_add_u64 v[32:33], v[32:33], 0, v[148:149]
	v_mul_f32_e32 v188, 0xbfb8aa3b, v34
	v_mul_f32_e32 v190, v34, v34
	v_pk_mul_f32 v[184:185], v[28:29], v[188:189] op_sel_hi:[1,0]
	v_pk_mul_f32 v[186:187], v[30:31], v[188:189] op_sel_hi:[1,0]
	v_pk_mul_f32 v[28:29], v[28:29], v[20:21]
	v_exp_f32_e32 v184, v184
	v_exp_f32_e32 v185, v185
	v_exp_f32_e32 v186, v186
	v_exp_f32_e32 v187, v187
	v_pk_mul_f32 v[30:31], v[30:31], v[22:23]
	v_pk_add_f32 v[184:185], v[184:185], v[192:193] op_sel_hi:[1,0]
	v_pk_add_f32 v[186:187], v[186:187], v[192:193] op_sel_hi:[1,0]
	v_rcp_f32_e32 v184, v184
	v_rcp_f32_e32 v185, v185
	v_rcp_f32_e32 v186, v186
	v_rcp_f32_e32 v187, v187
	v_pk_mul_f32 v[28:29], v[28:29], v[190:191] op_sel_hi:[1,0]
	v_pk_mul_f32 v[30:31], v[30:31], v[190:191] op_sel_hi:[1,0]
	v_pk_mul_f32 v[28:29], v[28:29], v[184:185]
	v_pk_mul_f32 v[30:31], v[30:31], v[186:187]
	v_pk_mul_f32 v[184:185], v[24:25], v[188:189] op_sel_hi:[1,0]
	v_pk_mul_f32 v[186:187], v[26:27], v[188:189] op_sel_hi:[1,0]
	v_pk_mul_f32 v[24:25], v[24:25], v[16:17]
	v_exp_f32_e32 v184, v184
	v_exp_f32_e32 v185, v185
	v_exp_f32_e32 v186, v186
	v_exp_f32_e32 v187, v187
	v_pk_mul_f32 v[26:27], v[26:27], v[18:19]
	v_pk_add_f32 v[184:185], v[184:185], v[192:193] op_sel_hi:[1,0]
	v_pk_add_f32 v[186:187], v[186:187], v[192:193] op_sel_hi:[1,0]
	v_rcp_f32_e32 v184, v184
	v_rcp_f32_e32 v185, v185
	v_rcp_f32_e32 v186, v186
	v_rcp_f32_e32 v187, v187
	v_pk_mul_f32 v[24:25], v[24:25], v[190:191] op_sel_hi:[1,0]
	v_pk_mul_f32 v[26:27], v[26:27], v[190:191] op_sel_hi:[1,0]
	v_pk_mul_f32 v[24:25], v[24:25], v[184:185]
	v_pk_mul_f32 v[26:27], v[26:27], v[186:187]
	v_cvt_pk_bf16_f32 v16, v28, v29
	v_cvt_pk_bf16_f32 v17, v30, v31
	v_cvt_pk_bf16_f32 v18, v24, v25
	v_cvt_pk_bf16_f32 v19, v26, v27
	s_nop 0
	global_store_dwordx4 v[32:33], v[16:19], off
	s_nop 1
	s_andn2_b64 vcc, exec, s[4:5]
	v_add_u32_e32 v17, 0xb0, v144
	s_mov_b64 s[4:5], -1
	v_fmamk_f32 v16, v182, 0x3a800000, v158
	v_rsq_f32_e32 v18, v16
	v_mad_i64_i32 v[16:17], s[34:35], v17, s79, v[146:147]
	v_lshl_add_u64 v[16:17], v[16:17], 0, v[148:149]
	v_mul_f32_e32 v188, 0xbfb8aa3b, v18
	v_mul_f32_e32 v190, v18, v18
	v_pk_mul_f32 v[184:185], v[12:13], v[188:189] op_sel_hi:[1,0]
	v_pk_mul_f32 v[186:187], v[14:15], v[188:189] op_sel_hi:[1,0]
	v_pk_mul_f32 v[12:13], v[12:13], v[4:5]
	v_exp_f32_e32 v184, v184
	v_exp_f32_e32 v185, v185
	v_exp_f32_e32 v186, v186
	v_exp_f32_e32 v187, v187
	v_pk_mul_f32 v[14:15], v[14:15], v[6:7]
	v_pk_add_f32 v[184:185], v[184:185], v[192:193] op_sel_hi:[1,0]
	v_pk_add_f32 v[186:187], v[186:187], v[192:193] op_sel_hi:[1,0]
	v_rcp_f32_e32 v184, v184
	v_rcp_f32_e32 v185, v185
	v_rcp_f32_e32 v186, v186
	v_rcp_f32_e32 v187, v187
	v_pk_mul_f32 v[12:13], v[12:13], v[190:191] op_sel_hi:[1,0]
	v_pk_mul_f32 v[14:15], v[14:15], v[190:191] op_sel_hi:[1,0]
	v_pk_mul_f32 v[12:13], v[12:13], v[184:185]
	v_pk_mul_f32 v[14:15], v[14:15], v[186:187]
	v_pk_mul_f32 v[184:185], v[8:9], v[188:189] op_sel_hi:[1,0]
	v_pk_mul_f32 v[186:187], v[10:11], v[188:189] op_sel_hi:[1,0]
	v_pk_mul_f32 v[8:9], v[8:9], v[0:1]
	v_exp_f32_e32 v184, v184
	v_exp_f32_e32 v185, v185
	v_exp_f32_e32 v186, v186
	v_exp_f32_e32 v187, v187
	v_pk_mul_f32 v[10:11], v[10:11], v[2:3]
	v_pk_add_f32 v[184:185], v[184:185], v[192:193] op_sel_hi:[1,0]
	v_pk_add_f32 v[186:187], v[186:187], v[192:193] op_sel_hi:[1,0]
	v_rcp_f32_e32 v184, v184
	v_rcp_f32_e32 v185, v185
	v_rcp_f32_e32 v186, v186
	v_rcp_f32_e32 v187, v187
	v_pk_mul_f32 v[8:9], v[8:9], v[190:191] op_sel_hi:[1,0]
	v_pk_mul_f32 v[10:11], v[10:11], v[190:191] op_sel_hi:[1,0]
	v_pk_mul_f32 v[8:9], v[8:9], v[184:185]
	v_pk_mul_f32 v[10:11], v[10:11], v[186:187]
	v_cvt_pk_bf16_f32 v0, v12, v13
	v_cvt_pk_bf16_f32 v1, v14, v15
	v_cvt_pk_bf16_f32 v2, v8, v9
	v_cvt_pk_bf16_f32 v3, v10, v11
	s_nop 0
	global_store_dwordx4 v[16:17], v[0:3], off
	s_cbranch_vccnz .LBB0_1267
	s_andn2_b64 vcc, exec, s[10:11]
	s_cbranch_vccnz .LBB0_1266
	s_barrier
	s_branch .LBB0_1266

;     __device__ __forceinline__ void fused(f32x4 (&acc)[2][2][4][2], const Unit& u, int wr, int wc, int fr, int fq, PG8_LAS unsigned char* lds, int wid, int lane) const {
;     ...
;         asm volatile("s_waitcnt vmcnt(0) lgkmcnt(0)" ::: "memory"); __builtin_amdgcn_s_barrier(); asm volatile("" ::: "memory");
; #pragma unroll
;         for (int ai = 0; ai < 2; ++ai)
; #pragma unroll
;             for (int m = 0; m < 4; ++m) { const int row = row0 + ai * HALF + m * 16; const size_t off = (size_t)row * 1024 + col0;
;                 const float rs = rsqrtf(__hip_atomic_load(ssq + row, __ATOMIC_RELAXED, __HIP_MEMORY_SCOPE_AGENT) * (1.f / 1024.f) + RMS_EPS);
; #pragma unroll
;                 for (int bj = 0; bj < 2; ++bj)
; #pragma unroll
;                     for (int n = 0; n < 2; ++n) { const f32x4 g = *(const f32x4*)(gain + col0 + bj * HALF + n * 4); *(f32x4*)(out + off + bj * HALF + n * 4) = acc[ai][bj][m][n] * rs * g; } }
.LBB0_1467:
	s_waitcnt vmcnt(0) lgkmcnt(0)
	s_barrier
	s_waitcnt lgkmcnt(0)
	v_lshl_add_u64 v[148:149], v[128:129], 2, s[2:3]
	global_load_dword v160, v[148:149], off sc1
	global_load_dword v161, v[148:149], off offset:64 sc1
	global_load_dword v162, v[148:149], off offset:128 sc1
	global_load_dword v163, v[148:149], off offset:192 sc1
	global_load_dword v164, v[148:149], off offset:512 sc1
	global_load_dword v165, v[148:149], off offset:576 sc1
	global_load_dword v166, v[148:149], off offset:640 sc1
	global_load_dword v167, v[148:149], off offset:704 sc1
	v_lshlrev_b64 v[146:147], 2, v[130:131]
	v_lshl_add_u64 v[130:131], s[8:9], 0, v[146:147]
	global_load_dwordx4 v[168:171], v[130:131], off
	global_load_dwordx4 v[172:175], v[130:131], off offset:16
	global_load_dwordx4 v[176:179], v[130:131], off offset:512
	global_load_dwordx4 v[180:183], v[130:131], off offset:528
	v_mov_b32_e32 v150, 0x358637bd
	s_mov_b32 s0, 0x800000
	v_lshlrev_b64 v[128:129], 12, v[128:129]
	v_lshl_add_u64 v[128:129], s[10:11], 0, v[128:129]
	s_waitcnt vmcnt(0)
	v_fmamk_f32 v151, v160, 0x3a800000, v150
	v_rsq_f32_e32 v151, v151
	v_lshl_add_u64 v[156:157], v[128:129], 0, v[146:147]
	v_mov_b32_e32 v158, v151
	v_pk_mul_f32 v[132:133], v[132:133], v[158:159] op_sel_hi:[1,0]
	v_pk_mul_f32 v[126:127], v[126:127], v[158:159] op_sel_hi:[1,0]
	v_pk_mul_f32 v[122:123], v[122:123], v[158:159] op_sel_hi:[1,0]
	v_pk_mul_f32 v[128:129], v[170:171], v[126:127]
	v_pk_mul_f32 v[126:127], v[168:169], v[132:133]
	global_store_dwordx4 v[156:157], v[126:129], off
	v_pk_mul_f32 v[120:121], v[120:121], v[158:159] op_sel_hi:[1,0]
	v_pk_mul_f32 v[118:119], v[118:119], v[158:159] op_sel_hi:[1,0]
	v_pk_mul_f32 v[116:117], v[116:117], v[158:159] op_sel_hi:[1,0]
	v_pk_mul_f32 v[114:115], v[114:115], v[158:159] op_sel_hi:[1,0]
	v_pk_mul_f32 v[112:113], v[112:113], v[158:159] op_sel_hi:[1,0]
	v_pk_mul_f32 v[120:121], v[172:173], v[120:121]
	v_pk_mul_f32 v[122:123], v[174:175], v[122:123]
	global_store_dwordx4 v[156:157], v[120:123], off offset:16
	v_pk_mul_f32 v[116:117], v[176:177], v[116:117]
	v_pk_mul_f32 v[118:119], v[178:179], v[118:119]
	global_store_dwordx4 v[156:157], v[116:119], off offset:512
	v_lshl_add_u64 v[120:121], v[124:125], 2, s[2:3]
	v_pk_mul_f32 v[112:113], v[180:181], v[112:113]
	v_pk_mul_f32 v[114:115], v[182:183], v[114:115]
	global_store_dwordx4 v[156:157], v[112:115], off offset:528
	s_nop 0
	v_fmamk_f32 v116, v161, 0x3a800000, v150
	v_rsq_f32_e32 v118, v116
	v_lshlrev_b64 v[116:117], 12, v[124:125]
	v_lshl_add_u64 v[116:117], s[10:11], 0, v[116:117]
	v_lshl_add_u64 v[116:117], v[116:117], 0, v[146:147]
	v_pk_mul_f32 v[120:121], v[134:135], v[118:119] op_sel_hi:[1,0]
	v_pk_mul_f32 v[110:111], v[110:111], v[118:119] op_sel_hi:[1,0]
	v_pk_mul_f32 v[112:113], v[168:169], v[120:121]
	v_pk_mul_f32 v[114:115], v[170:171], v[110:111]
	global_store_dwordx4 v[116:117], v[112:115], off
	v_pk_mul_f32 v[106:107], v[106:107], v[118:119] op_sel_hi:[1,0]
	v_pk_mul_f32 v[104:105], v[104:105], v[118:119] op_sel_hi:[1,0]
	v_pk_mul_f32 v[102:103], v[102:103], v[118:119] op_sel_hi:[1,0]
	v_pk_mul_f32 v[100:101], v[100:101], v[118:119] op_sel_hi:[1,0]
	v_pk_mul_f32 v[98:99], v[98:99], v[118:119] op_sel_hi:[1,0]
	v_pk_mul_f32 v[96:97], v[96:97], v[118:119] op_sel_hi:[1,0]
	v_pk_mul_f32 v[104:105], v[172:173], v[104:105]
	v_pk_mul_f32 v[106:107], v[174:175], v[106:107]
	global_store_dwordx4 v[116:117], v[104:107], off offset:16
	v_pk_mul_f32 v[100:101], v[176:177], v[100:101]
	v_pk_mul_f32 v[102:103], v[178:179], v[102:103]
	global_store_dwordx4 v[116:117], v[100:103], off offset:512
	v_lshl_add_u64 v[104:105], v[108:109], 2, s[2:3]
	v_pk_mul_f32 v[96:97], v[180:181], v[96:97]
	v_pk_mul_f32 v[98:99], v[182:183], v[98:99]
	global_store_dwordx4 v[116:117], v[96:99], off offset:528
	s_nop 0
	v_fmamk_f32 v100, v162, 0x3a800000, v150
	v_rsq_f32_e32 v102, v100
	v_lshlrev_b64 v[100:101], 12, v[108:109]
	v_lshl_add_u64 v[100:101], s[10:11], 0, v[100:101]
	v_lshl_add_u64 v[100:101], v[100:101], 0, v[146:147]
	v_pk_mul_f32 v[104:105], v[136:137], v[102:103] op_sel_hi:[1,0]
	v_pk_mul_f32 v[94:95], v[94:95], v[102:103] op_sel_hi:[1,0]
	v_pk_mul_f32 v[96:97], v[168:169], v[104:105]
	v_pk_mul_f32 v[98:99], v[170:171], v[94:95]
	global_store_dwordx4 v[100:101], v[96:99], off
	v_pk_mul_f32 v[90:91], v[90:91], v[102:103] op_sel_hi:[1,0]
	v_pk_mul_f32 v[88:89], v[88:89], v[102:103] op_sel_hi:[1,0]
	v_pk_mul_f32 v[86:87], v[86:87], v[102:103] op_sel_hi:[1,0]
	v_pk_mul_f32 v[84:85], v[84:85], v[102:103] op_sel_hi:[1,0]
	v_pk_mul_f32 v[82:83], v[82:83], v[102:103] op_sel_hi:[1,0]
	v_pk_mul_f32 v[80:81], v[80:81], v[102:103] op_sel_hi:[1,0]
	v_pk_mul_f32 v[88:89], v[172:173], v[88:89]
	v_pk_mul_f32 v[90:91], v[174:175], v[90:91]
	global_store_dwordx4 v[100:101], v[88:91], off offset:16
	v_pk_mul_f32 v[84:85], v[176:177], v[84:85]
	v_pk_mul_f32 v[86:87], v[178:179], v[86:87]
	global_store_dwordx4 v[100:101], v[84:87], off offset:512
	v_lshl_add_u64 v[88:89], v[92:93], 2, s[2:3]
	v_pk_mul_f32 v[80:81], v[180:181], v[80:81]
	v_pk_mul_f32 v[82:83], v[182:183], v[82:83]
	global_store_dwordx4 v[100:101], v[80:83], off offset:528
	s_nop 0
	v_fmamk_f32 v84, v163, 0x3a800000, v150
	v_rsq_f32_e32 v86, v84
	v_lshlrev_b64 v[84:85], 12, v[92:93]
	v_lshl_add_u64 v[84:85], s[10:11], 0, v[84:85]
	v_lshl_add_u64 v[84:85], v[84:85], 0, v[146:147]
	v_pk_mul_f32 v[88:89], v[138:139], v[86:87] op_sel_hi:[1,0]
	v_pk_mul_f32 v[78:79], v[78:79], v[86:87] op_sel_hi:[1,0]
	v_pk_mul_f32 v[80:81], v[168:169], v[88:89]
	v_pk_mul_f32 v[82:83], v[170:171], v[78:79]
	global_store_dwordx4 v[84:85], v[80:83], off
	v_pk_mul_f32 v[74:75], v[74:75], v[86:87] op_sel_hi:[1,0]
;     __device__ __forceinline__ void fused(f32x4 (&acc)[2][2][4][2], const Unit& u, int wr, int wc, int fr, int fq, PG8_LAS unsigned char* lds, int wid, int lane) const {
;     ...
;         for (int ai = 0; ai < 2; ++ai)
; #pragma unroll
;             for (int m = 0; m < 4; ++m) { const int row = row0 + ai * HALF + m * 16; const size_t off = (size_t)row * 1024 + col0;
;                 const float rs = rsqrtf(__hip_atomic_load(ssq + row, __ATOMIC_RELAXED, __HIP_MEMORY_SCOPE_AGENT) * (1.f / 1024.f) + RMS_EPS);
; #pragma unroll
;                 for (int bj = 0; bj < 2; ++bj)
; #pragma unroll
;                     for (int n = 0; n < 2; ++n) { const f32x4 g = *(const f32x4*)(gain + col0 + bj * HALF + n * 4); *(f32x4*)(out + off + bj * HALF + n * 4) = acc[ai][bj][m][n] * rs * g; } }
	v_pk_mul_f32 v[72:73], v[72:73], v[86:87] op_sel_hi:[1,0]
	v_pk_mul_f32 v[70:71], v[70:71], v[86:87] op_sel_hi:[1,0]
	v_pk_mul_f32 v[68:69], v[68:69], v[86:87] op_sel_hi:[1,0]
	v_pk_mul_f32 v[66:67], v[66:67], v[86:87] op_sel_hi:[1,0]
	v_pk_mul_f32 v[64:65], v[64:65], v[86:87] op_sel_hi:[1,0]
	v_pk_mul_f32 v[72:73], v[172:173], v[72:73]
	v_pk_mul_f32 v[74:75], v[174:175], v[74:75]
	global_store_dwordx4 v[84:85], v[72:75], off offset:16
	v_pk_mul_f32 v[68:69], v[176:177], v[68:69]
	v_pk_mul_f32 v[70:71], v[178:179], v[70:71]
	global_store_dwordx4 v[84:85], v[68:71], off offset:512
	v_pk_mul_f32 v[64:65], v[180:181], v[64:65]
	v_pk_mul_f32 v[66:67], v[182:183], v[66:67]
	global_store_dwordx4 v[84:85], v[64:67], off offset:528
	s_nop 0
	v_fmamk_f32 v68, v164, 0x3a800000, v150
	v_rsq_f32_e32 v70, v68
	v_lshlrev_b64 v[68:69], 12, v[76:77]
	v_lshl_add_u64 v[68:69], s[10:11], 0, v[68:69]
	v_lshl_add_u64 v[68:69], v[68:69], 0, v[146:147]
	v_pk_mul_f32 v[72:73], v[140:141], v[70:71] op_sel_hi:[1,0]
	v_pk_mul_f32 v[62:63], v[62:63], v[70:71] op_sel_hi:[1,0]
	v_pk_mul_f32 v[64:65], v[168:169], v[72:73]
	v_pk_mul_f32 v[66:67], v[170:171], v[62:63]
	global_store_dwordx4 v[68:69], v[64:67], off
	v_pk_mul_f32 v[58:59], v[58:59], v[70:71] op_sel_hi:[1,0]
	v_pk_mul_f32 v[56:57], v[56:57], v[70:71] op_sel_hi:[1,0]
	v_pk_mul_f32 v[54:55], v[54:55], v[70:71] op_sel_hi:[1,0]
	v_pk_mul_f32 v[52:53], v[52:53], v[70:71] op_sel_hi:[1,0]
	v_pk_mul_f32 v[50:51], v[50:51], v[70:71] op_sel_hi:[1,0]
	v_pk_mul_f32 v[48:49], v[48:49], v[70:71] op_sel_hi:[1,0]
	v_pk_mul_f32 v[56:57], v[172:173], v[56:57]
	v_pk_mul_f32 v[58:59], v[174:175], v[58:59]
	global_store_dwordx4 v[68:69], v[56:59], off offset:16
	v_pk_mul_f32 v[52:53], v[176:177], v[52:53]
	v_pk_mul_f32 v[54:55], v[178:179], v[54:55]
	global_store_dwordx4 v[68:69], v[52:55], off offset:512
	v_pk_mul_f32 v[48:49], v[180:181], v[48:49]
	v_pk_mul_f32 v[50:51], v[182:183], v[50:51]
	global_store_dwordx4 v[68:69], v[48:51], off offset:528
	s_nop 0
	v_fmamk_f32 v52, v165, 0x3a800000, v150
	v_rsq_f32_e32 v54, v52
	v_lshlrev_b64 v[52:53], 12, v[60:61]
	v_lshl_add_u64 v[52:53], s[10:11], 0, v[52:53]
	v_lshl_add_u64 v[52:53], v[52:53], 0, v[146:147]
	v_pk_mul_f32 v[56:57], v[142:143], v[54:55] op_sel_hi:[1,0]
	v_pk_mul_f32 v[46:47], v[46:47], v[54:55] op_sel_hi:[1,0]
	v_pk_mul_f32 v[48:49], v[168:169], v[56:57]
	v_pk_mul_f32 v[50:51], v[170:171], v[46:47]
	global_store_dwordx4 v[52:53], v[48:51], off
	v_pk_mul_f32 v[42:43], v[42:43], v[54:55] op_sel_hi:[1,0]
	v_pk_mul_f32 v[40:41], v[40:41], v[54:55] op_sel_hi:[1,0]
	v_pk_mul_f32 v[38:39], v[38:39], v[54:55] op_sel_hi:[1,0]
	v_pk_mul_f32 v[36:37], v[36:37], v[54:55] op_sel_hi:[1,0]
	v_pk_mul_f32 v[34:35], v[34:35], v[54:55] op_sel_hi:[1,0]
	v_pk_mul_f32 v[32:33], v[32:33], v[54:55] op_sel_hi:[1,0]
	v_pk_mul_f32 v[40:41], v[172:173], v[40:41]
	v_pk_mul_f32 v[42:43], v[174:175], v[42:43]
	global_store_dwordx4 v[52:53], v[40:43], off offset:16
	v_pk_mul_f32 v[36:37], v[176:177], v[36:37]
	v_pk_mul_f32 v[38:39], v[178:179], v[38:39]
	global_store_dwordx4 v[52:53], v[36:39], off offset:512
	v_pk_mul_f32 v[32:33], v[180:181], v[32:33]
	v_pk_mul_f32 v[34:35], v[182:183], v[34:35]
	global_store_dwordx4 v[52:53], v[32:35], off offset:528
	s_nop 0
	v_fmamk_f32 v36, v166, 0x3a800000, v150
	v_rsq_f32_e32 v38, v36
	v_lshlrev_b64 v[36:37], 12, v[44:45]
	v_lshl_add_u64 v[36:37], s[10:11], 0, v[36:37]
	v_lshl_add_u64 v[36:37], v[36:37], 0, v[146:147]
	v_pk_mul_f32 v[40:41], v[144:145], v[38:39] op_sel_hi:[1,0]
	v_pk_mul_f32 v[30:31], v[30:31], v[38:39] op_sel_hi:[1,0]
	v_pk_mul_f32 v[32:33], v[168:169], v[40:41]
	v_pk_mul_f32 v[34:35], v[170:171], v[30:31]
	global_store_dwordx4 v[36:37], v[32:35], off
	v_pk_mul_f32 v[26:27], v[26:27], v[38:39] op_sel_hi:[1,0]
	v_pk_mul_f32 v[24:25], v[24:25], v[38:39] op_sel_hi:[1,0]
	v_pk_mul_f32 v[22:23], v[22:23], v[38:39] op_sel_hi:[1,0]
	v_pk_mul_f32 v[20:21], v[20:21], v[38:39] op_sel_hi:[1,0]
	v_pk_mul_f32 v[18:19], v[18:19], v[38:39] op_sel_hi:[1,0]
	v_pk_mul_f32 v[16:17], v[16:17], v[38:39] op_sel_hi:[1,0]
	v_pk_mul_f32 v[24:25], v[172:173], v[24:25]
	v_pk_mul_f32 v[26:27], v[174:175], v[26:27]
	global_store_dwordx4 v[36:37], v[24:27], off offset:16
	v_pk_mul_f32 v[20:21], v[176:177], v[20:21]
	v_pk_mul_f32 v[22:23], v[178:179], v[22:23]
	global_store_dwordx4 v[36:37], v[20:23], off offset:512
	v_pk_mul_f32 v[16:17], v[180:181], v[16:17]
	v_pk_mul_f32 v[18:19], v[182:183], v[18:19]
	global_store_dwordx4 v[36:37], v[16:19], off offset:528
	s_nop 0
	v_fmac_f32_e32 v150, 0x3a800000, v167
	v_rsq_f32_e32 v22, v150
	v_lshlrev_b64 v[20:21], 12, v[28:29]
	v_lshl_add_u64 v[20:21], s[10:11], 0, v[20:21]
	v_lshl_add_u64 v[20:21], v[20:21], 0, v[146:147]
	v_pk_mul_f32 v[12:13], v[12:13], v[22:23] op_sel_hi:[1,0]
	v_pk_mul_f32 v[14:15], v[14:15], v[22:23] op_sel_hi:[1,0]
	v_pk_mul_f32 v[12:13], v[168:169], v[12:13]
	v_pk_mul_f32 v[14:15], v[170:171], v[14:15]
	global_store_dwordx4 v[20:21], v[12:15], off
	v_pk_mul_f32 v[10:11], v[10:11], v[22:23] op_sel_hi:[1,0]
	v_pk_mul_f32 v[8:9], v[8:9], v[22:23] op_sel_hi:[1,0]
	v_pk_mul_f32 v[6:7], v[6:7], v[22:23] op_sel_hi:[1,0]
	v_pk_mul_f32 v[4:5], v[4:5], v[22:23] op_sel_hi:[1,0]
	v_pk_mul_f32 v[2:3], v[2:3], v[22:23] op_sel_hi:[1,0]
	v_pk_mul_f32 v[0:1], v[0:1], v[22:23] op_sel_hi:[1,0]
	v_pk_mul_f32 v[8:9], v[172:173], v[8:9]
	v_pk_mul_f32 v[10:11], v[174:175], v[10:11]
	global_store_dwordx4 v[20:21], v[8:11], off offset:16
	v_pk_mul_f32 v[4:5], v[176:177], v[4:5]
	v_pk_mul_f32 v[6:7], v[178:179], v[6:7]
	global_store_dwordx4 v[20:21], v[4:7], off offset:512
	v_pk_mul_f32 v[0:1], v[180:181], v[0:1]
	v_pk_mul_f32 v[2:3], v[182:183], v[2:3]
	global_store_dwordx4 v[20:21], v[0:3], off offset:528
